# GEMM K-loops: m0 write moved ahead of the address add so the s_nop before each second LDS-DMA load goes away (on top of no-setprio version)
# baseline (speedup 1.0000x reference)
; #define WAIT_V(n) asm volatile("s_waitcnt vmcnt(" #n ")" ::: "memory")
; #define WAIT_L(n) asm volatile("s_waitcnt lgkmcnt(" #n ")" ::: "memory")
; #define BAR __builtin_amdgcn_s_barrier()
; #define SCHED __builtin_amdgcn_sched_barrier(0)
; template <class Get, class Epi>
; DI void gemm_stream(LAS unsigned char* lds, const int K, const int ld, Get get, Epi epi) {
;     ...
;             LDB(B0, 0, 0); SCHED; LDA(At, 0, 0); STAGE(SAo(1, 1), a1 + hstep);
;             WAIT_L(8); BAR; WAIT_L(0); MMA(0, 0, At, B0); BAR; SCHED;
;             LDB(B1, 0, 1); STAGE(SBo(0, 0), b2);
;             BAR; WAIT_L(0); MMA(0, 1, At, B1); BAR;
;             LDA(At, 0, 1); STAGE(SAo(0, 0), a2);
;             BAR; WAIT_L(0); MMA(1, 0, At, B0); BAR; SCHED;
;             STAGE(SBo(0, 1), b2 + hstep);
;             WAIT_V(6); BAR; MMA(1, 1, At, B1); BAR;
;             LDB(B0, 1, 0); SCHED; LDA(At, 1, 0); STAGE(SAo(0, 1), a2 + hstep);
;             WAIT_L(8); BAR; WAIT_L(0); MMA(0, 0, At, B0); BAR; SCHED;
;             LDB(B1, 1, 1); STAGE(SBo(1, 0), b3);
.LBB0_726:
	ds_read_b128 v[128:131], v167
	ds_read_b128 v[132:135], v167 offset:1024
	ds_read_b128 v[136:139], v167 offset:2048
	ds_read_b128 v[154:157], v167 offset:3072
	s_add_u32 s6, s4, 0xfff80080
	s_addc_u32 s7, s5, -1
	s_cmp_eq_u32 vcc_lo, 28
	s_cselect_b32 s63, s59, s7
	s_cselect_b32 s62, s58, s6
	s_cselect_b32 s7, s61, s55
	s_cselect_b32 s6, s60, s29
	v_lshl_add_u64 v[140:141], s[4:5], 0, v[148:149]
	s_add_i32 m0, s74, 0xc000
	ds_read_b128 v[158:161], v168
	ds_read_b128 v[162:165], v168 offset:1024
	ds_read_b128 v[170:173], v168 offset:2048
	ds_read_b128 v[174:177], v168 offset:3072
	ds_read_b128 v[178:181], v168 offset:4096
	ds_read_b128 v[182:185], v168 offset:5120
	ds_read_b128 v[186:189], v168 offset:6144
	ds_read_b128 v[190:193], v168 offset:7168
	global_load_lds_dwordx4 v[140:141], off
	v_lshl_add_u64 v[140:141], s[4:5], 0, v[150:151]
	s_add_i32 m0, s74, 0xe000
	s_nop 0
	global_load_lds_dwordx4 v[140:141], off
	s_waitcnt lgkmcnt(8)
	s_barrier
	s_waitcnt lgkmcnt(0)
	v_mfma_f32_16x16x32_bf16 v[124:127], v[128:131], v[158:161], v[124:127]
	v_mfma_f32_16x16x32_bf16 v[120:123], v[136:139], v[158:161], v[120:123]
	v_mfma_f32_16x16x32_bf16 v[112:115], v[128:131], v[170:173], v[112:115]
	v_mfma_f32_16x16x32_bf16 v[108:111], v[136:139], v[170:173], v[108:111]
	v_mfma_f32_16x16x32_bf16 v[100:103], v[128:131], v[178:181], v[100:103]
	v_mfma_f32_16x16x32_bf16 v[92:95], v[136:139], v[178:181], v[92:95]
	v_mfma_f32_16x16x32_bf16 v[84:87], v[128:131], v[186:189], v[84:87]
	v_mfma_f32_16x16x32_bf16 v[76:79], v[136:139], v[186:189], v[76:79]
	v_mfma_f32_16x16x32_bf16 v[124:127], v[132:135], v[162:165], v[124:127]
	v_mfma_f32_16x16x32_bf16 v[120:123], v[154:157], v[162:165], v[120:123]
	v_mfma_f32_16x16x32_bf16 v[112:115], v[132:135], v[174:177], v[112:115]
	v_mfma_f32_16x16x32_bf16 v[108:111], v[154:157], v[174:177], v[108:111]
	v_mfma_f32_16x16x32_bf16 v[100:103], v[132:135], v[182:185], v[100:103]
	v_mfma_f32_16x16x32_bf16 v[92:95], v[154:157], v[182:185], v[92:95]
	v_mfma_f32_16x16x32_bf16 v[84:87], v[132:135], v[190:193], v[84:87]
	v_mfma_f32_16x16x32_bf16 v[76:79], v[154:157], v[190:193], v[76:79]
	s_barrier
	s_add_i32 s86, s85, s35
	v_lshl_add_u64 v[140:141], s[6:7], 0, v[142:143]
	s_mov_b32 m0, s86
	ds_read_b128 v[194:197], v169
	ds_read_b128 v[198:201], v169 offset:1024
	ds_read_b128 v[202:205], v169 offset:2048
	ds_read_b128 v[208:211], v169 offset:3072
	global_load_lds_dwordx4 v[140:141], off
	v_lshl_add_u64 v[212:213], s[6:7], 0, v[144:145]
	s_add_i32 m0, s86, 0x2000
	s_nop 0
	global_load_lds_dwordx4 v[212:213], off
	s_barrier
	s_waitcnt lgkmcnt(0)
	v_mfma_f32_16x16x32_bf16 v[116:119], v[194:197], v[158:161], v[116:119]
	v_mfma_f32_16x16x32_bf16 v[104:107], v[202:205], v[158:161], v[104:107]
	v_mfma_f32_16x16x32_bf16 v[96:99], v[194:197], v[170:173], v[96:99]
	v_mfma_f32_16x16x32_bf16 v[88:91], v[202:205], v[170:173], v[88:91]
	v_mfma_f32_16x16x32_bf16 v[80:83], v[194:197], v[178:181], v[80:83]
	v_mfma_f32_16x16x32_bf16 v[72:75], v[202:205], v[178:181], v[72:75]
	v_mfma_f32_16x16x32_bf16 v[68:71], v[194:197], v[186:189], v[68:71]
	v_mfma_f32_16x16x32_bf16 v[64:67], v[202:205], v[186:189], v[64:67]
	v_mfma_f32_16x16x32_bf16 v[116:119], v[198:201], v[162:165], v[116:119]
	v_mfma_f32_16x16x32_bf16 v[104:107], v[208:211], v[162:165], v[104:107]
	v_mfma_f32_16x16x32_bf16 v[96:99], v[198:201], v[174:177], v[96:99]
	v_mfma_f32_16x16x32_bf16 v[88:91], v[208:211], v[174:177], v[88:91]
	v_mfma_f32_16x16x32_bf16 v[80:83], v[198:201], v[182:185], v[80:83]
	v_mfma_f32_16x16x32_bf16 v[72:75], v[208:211], v[182:185], v[72:75]
	v_mfma_f32_16x16x32_bf16 v[68:71], v[198:201], v[190:193], v[68:71]
	v_mfma_f32_16x16x32_bf16 v[64:67], v[208:211], v[190:193], v[64:67]
	s_mov_b32 m0, s74
	v_lshl_add_u64 v[214:215], s[62:63], 0, v[142:143]
	s_barrier
	ds_read_b128 v[158:161], v168 offset:16384
	ds_read_b128 v[162:165], v168 offset:17408
	ds_read_b128 v[170:173], v168 offset:18432
	ds_read_b128 v[174:177], v168 offset:19456
	ds_read_b128 v[178:181], v168 offset:20480
	ds_read_b128 v[182:185], v168 offset:21504
	ds_read_b128 v[186:189], v168 offset:22528
	ds_read_b128 v[190:193], v168 offset:23552
	global_load_lds_dwordx4 v[214:215], off
	s_mov_b32 m0, s75
	v_lshl_add_u64 v[216:217], s[62:63], 0, v[144:145]
	global_load_lds_dwordx4 v[216:217], off
	s_barrier
	s_waitcnt lgkmcnt(0)
	v_mfma_f32_16x16x32_bf16 v[60:63], v[128:131], v[158:161], v[60:63]
	v_mfma_f32_16x16x32_bf16 v[56:59], v[136:139], v[158:161], v[56:59]
	v_mfma_f32_16x16x32_bf16 v[52:55], v[128:131], v[170:173], v[52:55]
	v_mfma_f32_16x16x32_bf16 v[44:47], v[136:139], v[170:173], v[44:47]
	v_mfma_f32_16x16x32_bf16 v[36:39], v[128:131], v[178:181], v[36:39]
	v_mfma_f32_16x16x32_bf16 v[28:31], v[136:139], v[178:181], v[28:31]
	v_mfma_f32_16x16x32_bf16 v[20:23], v[128:131], v[186:189], v[20:23]
	v_mfma_f32_16x16x32_bf16 v[12:15], v[136:139], v[186:189], v[12:15]
	v_mfma_f32_16x16x32_bf16 v[60:63], v[132:135], v[162:165], v[60:63]
	v_mfma_f32_16x16x32_bf16 v[56:59], v[154:157], v[162:165], v[56:59]
	v_mfma_f32_16x16x32_bf16 v[52:55], v[132:135], v[174:177], v[52:55]
	v_mfma_f32_16x16x32_bf16 v[44:47], v[154:157], v[174:177], v[44:47]
	v_mfma_f32_16x16x32_bf16 v[36:39], v[132:135], v[182:185], v[36:39]
	v_mfma_f32_16x16x32_bf16 v[28:31], v[154:157], v[182:185], v[28:31]
	v_mfma_f32_16x16x32_bf16 v[20:23], v[132:135], v[190:193], v[20:23]
	v_mfma_f32_16x16x32_bf16 v[12:15], v[154:157], v[190:193], v[12:15]
	s_barrier
	s_add_u32 s86, s6, 0x80000
	s_addc_u32 s87, s7, 0
	s_add_i32 s88, s96, s35
	s_mov_b32 m0, s88
	v_lshl_add_u64 v[128:129], s[86:87], 0, v[142:143]
	global_load_lds_dwordx4 v[128:129], off
	v_lshl_add_u64 v[128:129], s[86:87], 0, v[144:145]
	s_add_i32 m0, s88, 0x2000
	s_nop 0
	global_load_lds_dwordx4 v[128:129], off
	s_waitcnt vmcnt(6)
	s_barrier
; #define WAIT_V(n) asm volatile("s_waitcnt vmcnt(" #n ")" ::: "memory")
; #define WAIT_L(n) asm volatile("s_waitcnt lgkmcnt(" #n ")" ::: "memory")
; #define BAR __builtin_amdgcn_s_barrier()
; #define SCHED __builtin_amdgcn_sched_barrier(0)
; template <class Get, class Epi>
; DI void gemm_stream(LAS unsigned char* lds, const int K, const int ld, Get get, Epi epi) {
;     ...
;             WAIT_V(6); BAR; MMA(1, 1, At, B1); BAR;
;             LDB(B0, 1, 0); SCHED; LDA(At, 1, 0); STAGE(SAo(0, 1), a2 + hstep);
;             WAIT_L(8); BAR; WAIT_L(0); MMA(0, 0, At, B0); BAR; SCHED;
;             LDB(B1, 1, 1); STAGE(SBo(1, 0), b3);
;             BAR; WAIT_L(0); MMA(0, 1, At, B1); BAR;
;             LDA(At, 1, 1); STAGE(SAo(1, 0), a3);
;             BAR; WAIT_L(0); MMA(1, 0, At, B0); BAR; SCHED;
;             STAGE(SBo(1, 1), b3 + hstep);
;             WAIT_V(6); BAR; MMA(1, 1, At, B1); BAR;
	v_mfma_f32_16x16x32_bf16 v[48:51], v[194:197], v[158:161], v[48:51]
	v_mfma_f32_16x16x32_bf16 v[40:43], v[202:205], v[158:161], v[40:43]
	v_mfma_f32_16x16x32_bf16 v[32:35], v[194:197], v[170:173], v[32:35]
	v_mfma_f32_16x16x32_bf16 v[24:27], v[202:205], v[170:173], v[24:27]
	v_mfma_f32_16x16x32_bf16 v[16:19], v[194:197], v[178:181], v[16:19]
	v_mfma_f32_16x16x32_bf16 v[8:11], v[202:205], v[178:181], v[8:11]
	v_mfma_f32_16x16x32_bf16 v[4:7], v[194:197], v[186:189], v[4:7]
	v_mfma_f32_16x16x32_bf16 v[0:3], v[202:205], v[186:189], v[0:3]
	v_mfma_f32_16x16x32_bf16 v[48:51], v[198:201], v[162:165], v[48:51]
	v_mfma_f32_16x16x32_bf16 v[40:43], v[208:211], v[162:165], v[40:43]
	v_mfma_f32_16x16x32_bf16 v[32:35], v[198:201], v[174:177], v[32:35]
	v_mfma_f32_16x16x32_bf16 v[24:27], v[208:211], v[174:177], v[24:27]
	v_mfma_f32_16x16x32_bf16 v[16:19], v[198:201], v[182:185], v[16:19]
	v_mfma_f32_16x16x32_bf16 v[8:11], v[208:211], v[182:185], v[8:11]
	v_mfma_f32_16x16x32_bf16 v[4:7], v[198:201], v[190:193], v[4:7]
	v_mfma_f32_16x16x32_bf16 v[0:3], v[208:211], v[190:193], v[0:3]
	s_add_i32 s86, 16, 0x18000
	v_add_u32_e32 v146, s86, v166
	s_barrier
	ds_read_b128 v[128:131], v146
	ds_read_b128 v[132:135], v146 offset:1024
	ds_read_b128 v[136:139], v146 offset:2048
	ds_read_b128 v[154:157], v146 offset:3072
	s_add_u32 s62, s62, 0x80000
	s_addc_u32 s63, s63, 0
	s_mov_b32 m0, s76
	v_lshl_add_u64 v[194:195], s[62:63], 0, v[142:143]
	ds_read_b128 v[158:161], v168 offset:32768
	ds_read_b128 v[162:165], v168 offset:33792
	ds_read_b128 v[170:173], v168 offset:34816
	ds_read_b128 v[174:177], v168 offset:35840
	ds_read_b128 v[178:181], v168 offset:36864
	ds_read_b128 v[182:185], v168 offset:37888
	ds_read_b128 v[186:189], v168 offset:38912
	ds_read_b128 v[190:193], v168 offset:39936
	global_load_lds_dwordx4 v[194:195], off
	s_mov_b32 m0, s77
	v_lshl_add_u64 v[194:195], s[62:63], 0, v[144:145]
	global_load_lds_dwordx4 v[194:195], off
	s_waitcnt lgkmcnt(8)
	s_barrier
	s_waitcnt lgkmcnt(0)
	v_mfma_f32_16x16x32_bf16 v[124:127], v[128:131], v[158:161], v[124:127]
	v_mfma_f32_16x16x32_bf16 v[120:123], v[136:139], v[158:161], v[120:123]
	v_mfma_f32_16x16x32_bf16 v[112:115], v[128:131], v[170:173], v[112:115]
	v_mfma_f32_16x16x32_bf16 v[108:111], v[136:139], v[170:173], v[108:111]
	v_mfma_f32_16x16x32_bf16 v[100:103], v[128:131], v[178:181], v[100:103]
	v_mfma_f32_16x16x32_bf16 v[92:95], v[136:139], v[178:181], v[92:95]
	v_mfma_f32_16x16x32_bf16 v[84:87], v[128:131], v[186:189], v[84:87]
	v_mfma_f32_16x16x32_bf16 v[76:79], v[136:139], v[186:189], v[76:79]
	v_mfma_f32_16x16x32_bf16 v[124:127], v[132:135], v[162:165], v[124:127]
	v_mfma_f32_16x16x32_bf16 v[120:123], v[154:157], v[162:165], v[120:123]
	v_mfma_f32_16x16x32_bf16 v[112:115], v[132:135], v[174:177], v[112:115]
	v_mfma_f32_16x16x32_bf16 v[108:111], v[154:157], v[174:177], v[108:111]
	v_mfma_f32_16x16x32_bf16 v[100:103], v[132:135], v[182:185], v[100:103]
	v_mfma_f32_16x16x32_bf16 v[92:95], v[154:157], v[182:185], v[92:95]
	v_mfma_f32_16x16x32_bf16 v[84:87], v[132:135], v[190:193], v[84:87]
	v_mfma_f32_16x16x32_bf16 v[76:79], v[154:157], v[190:193], v[76:79]
	s_barrier
	s_add_i32 s62, 16, 0x1c000
	s_add_i32 s63, s86, s35
	v_add_u32_e32 v146, s62, v166
	v_lshl_add_u64 v[140:141], v[140:141], 0, s[0:1]
	s_mov_b32 m0, s63
	ds_read_b128 v[194:197], v146
	ds_read_b128 v[198:201], v146 offset:1024
	ds_read_b128 v[202:205], v146 offset:2048
	ds_read_b128 v[208:211], v146 offset:3072
	global_load_lds_dwordx4 v[140:141], off
	v_lshl_add_u64 v[140:141], v[212:213], 0, s[0:1]
	s_add_i32 m0, s63, 0x2000
	s_nop 0
	global_load_lds_dwordx4 v[140:141], off
	s_barrier
	s_waitcnt lgkmcnt(0)
	v_mfma_f32_16x16x32_bf16 v[116:119], v[194:197], v[158:161], v[116:119]
	v_mfma_f32_16x16x32_bf16 v[104:107], v[202:205], v[158:161], v[104:107]
	v_mfma_f32_16x16x32_bf16 v[96:99], v[194:197], v[170:173], v[96:99]
	v_mfma_f32_16x16x32_bf16 v[88:91], v[202:205], v[170:173], v[88:91]
	v_mfma_f32_16x16x32_bf16 v[80:83], v[194:197], v[178:181], v[80:83]
	v_mfma_f32_16x16x32_bf16 v[72:75], v[202:205], v[178:181], v[72:75]
	v_mfma_f32_16x16x32_bf16 v[68:71], v[194:197], v[186:189], v[68:71]
	v_mfma_f32_16x16x32_bf16 v[64:67], v[202:205], v[186:189], v[64:67]
	v_mfma_f32_16x16x32_bf16 v[116:119], v[198:201], v[162:165], v[116:119]
	v_mfma_f32_16x16x32_bf16 v[104:107], v[208:211], v[162:165], v[104:107]
	v_mfma_f32_16x16x32_bf16 v[96:99], v[198:201], v[174:177], v[96:99]
	v_mfma_f32_16x16x32_bf16 v[88:91], v[208:211], v[174:177], v[88:91]
	v_mfma_f32_16x16x32_bf16 v[80:83], v[198:201], v[182:185], v[80:83]
	v_mfma_f32_16x16x32_bf16 v[72:75], v[208:211], v[182:185], v[72:75]
	v_mfma_f32_16x16x32_bf16 v[68:71], v[198:201], v[190:193], v[68:71]
	v_mfma_f32_16x16x32_bf16 v[64:67], v[208:211], v[190:193], v[64:67]
	s_mov_b32 m0, s80
	v_lshl_add_u64 v[140:141], v[214:215], 0, s[0:1]
	s_barrier
; #define WAIT_V(n) asm volatile("s_waitcnt vmcnt(" #n ")" ::: "memory")
; #define WAIT_L(n) asm volatile("s_waitcnt lgkmcnt(" #n ")" ::: "memory")
; #define BAR __builtin_amdgcn_s_barrier()
; #define SCHED __builtin_amdgcn_sched_barrier(0)
; template <class Get, class Epi>
; DI void gemm_stream(LAS unsigned char* lds, const int K, const int ld, Get get, Epi epi) {
;     ...
;             BAR; WAIT_L(0); MMA(1, 0, At, B0); BAR; SCHED;
;             STAGE(SBo(1, 1), b3 + hstep);
;             WAIT_V(6); BAR; MMA(1, 1, At, B1); BAR;
;         }
; DI void phase_inproj0(const P& p, char* shm) {
;     ...
;         const int brow = u.pm * 256, pn = u.pn;
;         if (pn == 5) epi_T<64>(acc, 0, brow, (bf16_t*)(p.ws + O_VAT), 256, nullptr);
;         else if (pn < 4) epi_rope<128>(acc, p, brow, (bf16_t*)(p.ws + O_QA), 1024, pn * 256, 128, nullptr, 2);
;         else if (pn == 4) epi_rope<128>(acc, p, brow, (bf16_t*)(p.ws + O_KA), 256, 0, 128, nullptr, 2);
;         else if (pn < 8) epi_plain(acc, brow, (bf16_t*)(p.ws + O_QLAT), 512, (pn - 6) * 256, nullptr);
;         else if (pn == 8) epi_plain(acc, brow, (bf16_t*)(p.ws + O_KVLAT), 256, 0, nullptr);
;         else epi_rope<64>(acc, p, brow, (bf16_t*)(p.ws + O_KR), 64, 0, 64, nullptr, 1);
	ds_read_b128 v[158:161], v168 offset:49152
	ds_read_b128 v[162:165], v168 offset:50176
	ds_read_b128 v[170:173], v168 offset:51200
	ds_read_b128 v[174:177], v168 offset:52224
	ds_read_b128 v[178:181], v168 offset:53248
	ds_read_b128 v[182:185], v168 offset:54272
	ds_read_b128 v[186:189], v168 offset:55296
	ds_read_b128 v[190:193], v168 offset:56320
	global_load_lds_dwordx4 v[140:141], off
	s_mov_b32 m0, s81
	v_lshl_add_u64 v[140:141], v[216:217], 0, s[0:1]
	global_load_lds_dwordx4 v[140:141], off
	s_barrier
	s_waitcnt lgkmcnt(0)
	v_mfma_f32_16x16x32_bf16 v[60:63], v[128:131], v[158:161], v[60:63]
	v_mfma_f32_16x16x32_bf16 v[56:59], v[136:139], v[158:161], v[56:59]
	v_mfma_f32_16x16x32_bf16 v[52:55], v[128:131], v[170:173], v[52:55]
	v_mfma_f32_16x16x32_bf16 v[44:47], v[136:139], v[170:173], v[44:47]
	v_mfma_f32_16x16x32_bf16 v[36:39], v[128:131], v[178:181], v[36:39]
	v_mfma_f32_16x16x32_bf16 v[28:31], v[136:139], v[178:181], v[28:31]
	v_mfma_f32_16x16x32_bf16 v[20:23], v[128:131], v[186:189], v[20:23]
	v_mfma_f32_16x16x32_bf16 v[12:15], v[136:139], v[186:189], v[12:15]
	v_mfma_f32_16x16x32_bf16 v[60:63], v[132:135], v[162:165], v[60:63]
	v_mfma_f32_16x16x32_bf16 v[56:59], v[154:157], v[162:165], v[56:59]
	v_mfma_f32_16x16x32_bf16 v[52:55], v[132:135], v[174:177], v[52:55]
	v_mfma_f32_16x16x32_bf16 v[44:47], v[154:157], v[174:177], v[44:47]
	v_mfma_f32_16x16x32_bf16 v[36:39], v[132:135], v[182:185], v[36:39]
	v_mfma_f32_16x16x32_bf16 v[28:31], v[154:157], v[182:185], v[28:31]
	v_mfma_f32_16x16x32_bf16 v[20:23], v[132:135], v[190:193], v[20:23]
	v_mfma_f32_16x16x32_bf16 v[12:15], v[154:157], v[190:193], v[12:15]
	s_barrier
	s_add_u32 s6, s6, 0x80080
	s_addc_u32 s7, s7, 0
	s_add_i32 s62, s62, s35
	s_mov_b32 m0, s62
	v_lshl_add_u64 v[128:129], s[6:7], 0, v[142:143]
	global_load_lds_dwordx4 v[128:129], off
	v_lshl_add_u64 v[128:129], s[6:7], 0, v[144:145]
	s_add_i32 m0, s62, 0x2000
	s_nop 0
	global_load_lds_dwordx4 v[128:129], off
	s_waitcnt vmcnt(6)
	s_barrier
	v_mfma_f32_16x16x32_bf16 v[48:51], v[194:197], v[158:161], v[48:51]
	v_mfma_f32_16x16x32_bf16 v[40:43], v[202:205], v[158:161], v[40:43]
	v_mfma_f32_16x16x32_bf16 v[32:35], v[194:197], v[170:173], v[32:35]
	v_mfma_f32_16x16x32_bf16 v[24:27], v[202:205], v[170:173], v[24:27]
	v_mfma_f32_16x16x32_bf16 v[16:19], v[194:197], v[178:181], v[16:19]
	v_mfma_f32_16x16x32_bf16 v[8:11], v[202:205], v[178:181], v[8:11]
	v_mfma_f32_16x16x32_bf16 v[4:7], v[194:197], v[186:189], v[4:7]
	v_mfma_f32_16x16x32_bf16 v[0:3], v[202:205], v[186:189], v[0:3]
	v_mfma_f32_16x16x32_bf16 v[48:51], v[198:201], v[162:165], v[48:51]
	v_mfma_f32_16x16x32_bf16 v[40:43], v[208:211], v[162:165], v[40:43]
	v_mfma_f32_16x16x32_bf16 v[32:35], v[198:201], v[174:177], v[32:35]
	v_mfma_f32_16x16x32_bf16 v[24:27], v[208:211], v[174:177], v[24:27]
	v_mfma_f32_16x16x32_bf16 v[16:19], v[198:201], v[182:185], v[16:19]
	v_mfma_f32_16x16x32_bf16 v[8:11], v[208:211], v[182:185], v[8:11]
	v_mfma_f32_16x16x32_bf16 v[4:7], v[198:201], v[190:193], v[4:7]
	v_mfma_f32_16x16x32_bf16 v[0:3], v[208:211], v[190:193], v[0:3]
	s_add_i32 vcc_lo, vcc_lo, 2
	s_add_u32 s4, s4, 0x100
	s_addc_u32 s5, s5, 0
	s_add_u32 s29, s29, 0x100
	s_addc_u32 s55, s55, 0
	s_cmp_gt_u32 vcc_lo, 29
	s_barrier
	s_cbranch_scc0 .LBB0_726
	s_lshl_b32 s29, s21, 8
	s_cmp_lg_u32 s28, 5
	s_mov_b64 s[4:5], -1
	s_cbranch_scc0 .LBB0_849
	s_cmp_gt_i32 s28, 3
	s_cbranch_scc0 .LBB0_814
	s_cmp_lg_u32 s28, 4
	s_cbranch_scc0 .LBB0_779
	s_cmp_gt_u32 s28, 7
	s_cbranch_scc0 .LBB0_776
	s_cmp_lg_u32 s28, 8
	s_cbranch_scc0 .LBB0_773
	s_mul_hi_i32 s4, s29, 0x78787879
	s_lshr_b32 s5, s4, 31
	s_ashr_i32 s4, s4, 11
	v_mov_b32_e32 v128, v206
	s_add_i32 s4, s4, s5
	s_mulk_i32 s4, 0x1100
	v_and_b32_e32 v129, 15, v128
	v_ashrrev_i32_e32 v130, 2, v128
	s_sub_i32 s55, s29, s4
	v_and_or_b32 v154, v130, s97, v129
	v_lshrrev_b32_e32 v129, 2, v128
	s_cmpk_gt_i32 s55, 0xff
	v_and_b32_e32 v129, 28, v129
	s_cselect_b64 s[4:5], -1, 0
	v_lshlrev_b32_e32 v146, 2, v129
	v_and_b32_e32 v128, 0x80, v128
	v_lshl_add_u64 v[138:139], s[14:15], 0, v[146:147]
	v_lshl_add_u64 v[140:141], s[12:13], 0, v[146:147]
	v_lshlrev_b32_e32 v146, 1, v129
	v_cmp_eq_u32_e64 s[6:7], 0, v128
	v_cndmask_b32_e64 v128, 0, 1, s[4:5]
	s_addk_i32 s55, 0xff00
	v_lshl_add_u64 v[136:137], s[10:11], 0, v[146:147]
	v_cmp_ne_u32_e64 s[4:5], 1, v128
	s_and_saveexec_b64 s[62:63], s[6:7]
	s_cbranch_execz .LBB0_737
	s_and_b64 vcc, exec, s[4:5]
	s_cbranch_vccnz .LBB0_735
	v_add_u32_e32 v128, s55, v154
	v_ashrrev_i32_e32 v129, 31, v128
	v_lshlrev_b64 v[128:129], 7, v[128:129]
	v_lshl_add_u64 v[132:133], v[138:139], 0, v[128:129]
	v_lshl_add_u64 v[128:129], v[140:141], 0, v[128:129]
	global_load_dwordx4 v[128:131], v[128:129], off
	s_nop 0
	global_load_dwordx4 v[132:135], v[132:133], off
	s_branch .LBB0_736

; #define WAIT_V(n) asm volatile("s_waitcnt vmcnt(" #n ")" ::: "memory")
; #define WAIT_L(n) asm volatile("s_waitcnt lgkmcnt(" #n ")" ::: "memory")
; #define BAR __builtin_amdgcn_s_barrier()
; #define SCHED __builtin_amdgcn_sched_barrier(0)
; DI void gemm_tile(const bf16_t* __restrict__ A, const bf16_t* __restrict__ Bt, const int K, const int brow, const int bcol, LAS unsigned char* lds, Acc& acc) {
;     ...
;         LDB(B0, 0, 0); SCHED; LDA(At, 0, 0); STAGE(SAo(1, 1), a1 + hstep);
;         WAIT_L(8); BAR; WAIT_L(0); MMA(0, 0, At, B0); BAR; SCHED;
;         LDB(B1, 0, 1); STAGE(SBo(0, 0), b2);
;         BAR; WAIT_L(0); MMA(0, 1, At, B1); BAR;
;         LDA(At, 0, 1); STAGE(SAo(0, 0), a2);
;         BAR; WAIT_L(0); MMA(1, 0, At, B0); BAR; SCHED;
;         STAGE(SBo(0, 1), b2 + hstep);
;         WAIT_V(6); BAR; MMA(1, 1, At, B1); BAR;
;         LDB(B0, 1, 0); SCHED; LDA(At, 1, 0); STAGE(SAo(0, 1), a2 + hstep);
;         WAIT_L(8); BAR; WAIT_L(0); MMA(0, 0, At, B0); BAR; SCHED;
.LBB0_930:
	s_add_i32 s6, 16, 0x10000
	v_add_u32_e32 v154, s6, v149
	ds_read_b128 v[150:153], v154
	ds_read_b128 v[160:163], v154 offset:1024
	ds_read_b128 v[164:167], v154 offset:2048
	ds_read_b128 v[168:171], v154 offset:3072
	s_add_i32 s62, s62, 2
	v_lshl_add_u64 v[154:155], v[134:135], 0, s[60:61]
	s_add_i32 s81, s86, 0xc000
	v_lshl_add_u64 v[204:205], v[154:155], 0, s[36:37]
	s_mov_b32 m0, s81
	ds_read_b128 v[172:175], v148
	ds_read_b128 v[176:179], v148 offset:1024
	ds_read_b128 v[180:183], v148 offset:2048
	ds_read_b128 v[184:187], v148 offset:3072
	ds_read_b128 v[188:191], v148 offset:4096
	ds_read_b128 v[192:195], v148 offset:5120
	ds_read_b128 v[196:199], v148 offset:6144
	ds_read_b128 v[200:203], v148 offset:7168
	global_load_lds_dwordx4 v[204:205], off
	v_lshl_add_u64 v[204:205], v[136:137], 0, s[60:61]
	s_add_i32 s63, s86, 0xe000
	s_mov_b32 m0, s63
	v_lshl_add_u64 v[208:209], v[204:205], 0, s[36:37]
	global_load_lds_dwordx4 v[208:209], off
	s_waitcnt lgkmcnt(8)
	s_barrier
	s_waitcnt lgkmcnt(0)
	v_mfma_f32_16x16x32_bf16 v[124:127], v[150:153], v[172:175], v[124:127]
	v_mfma_f32_16x16x32_bf16 v[120:123], v[164:167], v[172:175], v[120:123]
	v_mfma_f32_16x16x32_bf16 v[116:119], v[150:153], v[180:183], v[116:119]
	v_mfma_f32_16x16x32_bf16 v[112:115], v[164:167], v[180:183], v[112:115]
	v_mfma_f32_16x16x32_bf16 v[108:111], v[150:153], v[188:191], v[108:111]
	v_mfma_f32_16x16x32_bf16 v[104:107], v[164:167], v[188:191], v[104:107]
	v_mfma_f32_16x16x32_bf16 v[100:103], v[150:153], v[196:199], v[100:103]
	v_mfma_f32_16x16x32_bf16 v[96:99], v[164:167], v[196:199], v[96:99]
	v_mfma_f32_16x16x32_bf16 v[124:127], v[160:163], v[176:179], v[124:127]
	v_mfma_f32_16x16x32_bf16 v[120:123], v[168:171], v[176:179], v[120:123]
	v_mfma_f32_16x16x32_bf16 v[116:119], v[160:163], v[184:187], v[116:119]
	v_mfma_f32_16x16x32_bf16 v[112:115], v[168:171], v[184:187], v[112:115]
	v_mfma_f32_16x16x32_bf16 v[108:111], v[160:163], v[192:195], v[108:111]
	v_mfma_f32_16x16x32_bf16 v[104:107], v[168:171], v[192:195], v[104:107]
	v_mfma_f32_16x16x32_bf16 v[100:103], v[160:163], v[200:203], v[100:103]
	v_mfma_f32_16x16x32_bf16 v[96:99], v[168:171], v[200:203], v[96:99]
	s_barrier
	s_add_i32 s7, 16, 0x14000
	v_lshl_add_u64 v[224:225], v[138:139], 0, s[60:61]
	s_add_i32 s6, s6, s18
	v_add_u32_e32 v159, s7, v149
	v_lshl_add_u64 v[226:227], v[224:225], 0, s[38:39]
	s_mov_b32 m0, s6
	ds_read_b128 v[208:211], v159
	ds_read_b128 v[212:215], v159 offset:1024
	ds_read_b128 v[216:219], v159 offset:2048
	ds_read_b128 v[220:223], v159 offset:3072
	global_load_lds_dwordx4 v[226:227], off
	v_lshl_add_u64 v[226:227], v[140:141], 0, s[60:61]
	v_lshl_add_u64 v[228:229], v[226:227], 0, s[38:39]
	s_add_i32 m0, s6, 0x2000
	s_nop 0
	global_load_lds_dwordx4 v[228:229], off
	s_barrier
	s_waitcnt lgkmcnt(0)
	v_mfma_f32_16x16x32_bf16 v[92:95], v[208:211], v[172:175], v[92:95]
	v_mfma_f32_16x16x32_bf16 v[88:91], v[216:219], v[172:175], v[88:91]
	v_mfma_f32_16x16x32_bf16 v[84:87], v[208:211], v[180:183], v[84:87]
	v_mfma_f32_16x16x32_bf16 v[80:83], v[216:219], v[180:183], v[80:83]
	v_mfma_f32_16x16x32_bf16 v[76:79], v[208:211], v[188:191], v[76:79]
	v_mfma_f32_16x16x32_bf16 v[72:75], v[216:219], v[188:191], v[72:75]
	v_mfma_f32_16x16x32_bf16 v[68:71], v[208:211], v[196:199], v[68:71]
	v_mfma_f32_16x16x32_bf16 v[64:67], v[216:219], v[196:199], v[64:67]
	v_mfma_f32_16x16x32_bf16 v[92:95], v[212:215], v[176:179], v[92:95]
	v_mfma_f32_16x16x32_bf16 v[88:91], v[220:223], v[176:179], v[88:91]
	v_mfma_f32_16x16x32_bf16 v[84:87], v[212:215], v[184:187], v[84:87]
	v_mfma_f32_16x16x32_bf16 v[80:83], v[220:223], v[184:187], v[80:83]
	v_mfma_f32_16x16x32_bf16 v[76:79], v[212:215], v[192:195], v[76:79]
	v_mfma_f32_16x16x32_bf16 v[72:75], v[220:223], v[192:195], v[72:75]
	v_mfma_f32_16x16x32_bf16 v[68:71], v[212:215], v[200:203], v[68:71]
	v_mfma_f32_16x16x32_bf16 v[64:67], v[220:223], v[200:203], v[64:67]
	v_lshl_add_u64 v[228:229], v[130:131], 0, s[60:61]
	s_mov_b32 m0, s86
	v_lshl_add_u64 v[230:231], v[228:229], 0, s[38:39]
	s_barrier
	ds_read_b128 v[172:175], v148 offset:16384
	ds_read_b128 v[176:179], v148 offset:17408
	ds_read_b128 v[180:183], v148 offset:18432
	ds_read_b128 v[184:187], v148 offset:19456
	ds_read_b128 v[188:191], v148 offset:20480
	ds_read_b128 v[192:195], v148 offset:21504
	ds_read_b128 v[196:199], v148 offset:22528
	ds_read_b128 v[200:203], v148 offset:23552
	global_load_lds_dwordx4 v[230:231], off
	v_lshl_add_u64 v[230:231], v[132:133], 0, s[60:61]
	s_mov_b32 m0, s82
	v_lshl_add_u64 v[232:233], v[230:231], 0, s[38:39]
	global_load_lds_dwordx4 v[232:233], off
	s_barrier
	s_waitcnt lgkmcnt(0)
	v_mfma_f32_16x16x32_bf16 v[60:63], v[150:153], v[172:175], v[60:63]
	v_mfma_f32_16x16x32_bf16 v[56:59], v[164:167], v[172:175], v[56:59]
	v_mfma_f32_16x16x32_bf16 v[52:55], v[150:153], v[180:183], v[52:55]
	v_mfma_f32_16x16x32_bf16 v[48:51], v[164:167], v[180:183], v[48:51]
	v_mfma_f32_16x16x32_bf16 v[44:47], v[150:153], v[188:191], v[44:47]
	v_mfma_f32_16x16x32_bf16 v[40:43], v[164:167], v[188:191], v[40:43]
	v_mfma_f32_16x16x32_bf16 v[36:39], v[150:153], v[196:199], v[36:39]
	v_mfma_f32_16x16x32_bf16 v[32:35], v[164:167], v[196:199], v[32:35]
	v_mfma_f32_16x16x32_bf16 v[60:63], v[160:163], v[176:179], v[60:63]
	v_mfma_f32_16x16x32_bf16 v[56:59], v[168:171], v[176:179], v[56:59]
	v_mfma_f32_16x16x32_bf16 v[52:55], v[160:163], v[184:187], v[52:55]
	v_mfma_f32_16x16x32_bf16 v[48:51], v[168:171], v[184:187], v[48:51]
	v_mfma_f32_16x16x32_bf16 v[44:47], v[160:163], v[192:195], v[44:47]
	v_mfma_f32_16x16x32_bf16 v[40:43], v[168:171], v[192:195], v[40:43]
	v_mfma_f32_16x16x32_bf16 v[36:39], v[160:163], v[200:203], v[36:39]
	v_mfma_f32_16x16x32_bf16 v[32:35], v[168:171], v[200:203], v[32:35]
	s_barrier
; #define WAIT_V(n) asm volatile("s_waitcnt vmcnt(" #n ")" ::: "memory")
; #define WAIT_L(n) asm volatile("s_waitcnt lgkmcnt(" #n ")" ::: "memory")
; #define BAR __builtin_amdgcn_s_barrier()
; #define SCHED __builtin_amdgcn_sched_barrier(0)
; DI void gemm_tile(const bf16_t* __restrict__ A, const bf16_t* __restrict__ Bt, const int K, const int brow, const int bcol, LAS unsigned char* lds, Acc& acc) {
;     ...
;         LDB(B1, 0, 1); STAGE(SBo(0, 0), b2);
;         BAR; WAIT_L(0); MMA(0, 1, At, B1); BAR;
;         LDA(At, 0, 1); STAGE(SAo(0, 0), a2);
;         BAR; WAIT_L(0); MMA(1, 0, At, B0); BAR; SCHED;
;         STAGE(SBo(0, 1), b2 + hstep);
;         WAIT_V(6); BAR; MMA(1, 1, At, B1); BAR;
;         LDB(B0, 1, 0); SCHED; LDA(At, 1, 0); STAGE(SAo(0, 1), a2 + hstep);
;         WAIT_L(8); BAR; WAIT_L(0); MMA(0, 0, At, B0); BAR; SCHED;
	v_lshl_add_u64 v[232:233], v[144:145], 0, s[60:61]
	s_add_i32 s6, s7, s18
	v_lshl_add_u64 v[150:151], v[232:233], 0, s[38:39]
	s_mov_b32 m0, s6
	v_lshl_add_u64 v[234:235], v[146:147], 0, s[60:61]
	global_load_lds_dwordx4 v[150:151], off
	v_lshl_add_u64 v[150:151], v[234:235], 0, s[38:39]
	s_add_i32 m0, s6, 0x2000
	s_nop 0
	global_load_lds_dwordx4 v[150:151], off
	s_waitcnt vmcnt(6)
	s_barrier
	v_mfma_f32_16x16x32_bf16 v[28:31], v[208:211], v[172:175], v[28:31]
	v_mfma_f32_16x16x32_bf16 v[24:27], v[216:219], v[172:175], v[24:27]
	v_mfma_f32_16x16x32_bf16 v[20:23], v[208:211], v[180:183], v[20:23]
	v_mfma_f32_16x16x32_bf16 v[16:19], v[216:219], v[180:183], v[16:19]
	v_mfma_f32_16x16x32_bf16 v[12:15], v[208:211], v[188:191], v[12:15]
	v_mfma_f32_16x16x32_bf16 v[8:11], v[216:219], v[188:191], v[8:11]
	v_mfma_f32_16x16x32_bf16 v[4:7], v[208:211], v[196:199], v[4:7]
	v_mfma_f32_16x16x32_bf16 v[0:3], v[216:219], v[196:199], v[0:3]
	v_mfma_f32_16x16x32_bf16 v[28:31], v[212:215], v[176:179], v[28:31]
	v_mfma_f32_16x16x32_bf16 v[24:27], v[220:223], v[176:179], v[24:27]
	v_mfma_f32_16x16x32_bf16 v[20:23], v[212:215], v[184:187], v[20:23]
	v_mfma_f32_16x16x32_bf16 v[16:19], v[220:223], v[184:187], v[16:19]
	v_mfma_f32_16x16x32_bf16 v[12:15], v[212:215], v[192:195], v[12:15]
	v_mfma_f32_16x16x32_bf16 v[8:11], v[220:223], v[192:195], v[8:11]
	v_mfma_f32_16x16x32_bf16 v[4:7], v[212:215], v[200:203], v[4:7]
	v_mfma_f32_16x16x32_bf16 v[0:3], v[220:223], v[200:203], v[0:3]
	s_add_i32 s6, 16, 0x18000
	v_add_u32_e32 v159, s6, v149
	s_barrier
	ds_read_b128 v[150:153], v159
	ds_read_b128 v[160:163], v159 offset:1024
	ds_read_b128 v[164:167], v159 offset:2048
	ds_read_b128 v[168:171], v159 offset:3072
	s_mov_b32 m0, s83
	v_lshl_add_u64 v[154:155], v[154:155], 0, s[38:39]
	ds_read_b128 v[172:175], v148 offset:32768
	ds_read_b128 v[176:179], v148 offset:33792
	ds_read_b128 v[180:183], v148 offset:34816
	ds_read_b128 v[184:187], v148 offset:35840
	ds_read_b128 v[188:191], v148 offset:36864
	ds_read_b128 v[192:195], v148 offset:37888
	ds_read_b128 v[196:199], v148 offset:38912
	ds_read_b128 v[200:203], v148 offset:39936
	global_load_lds_dwordx4 v[154:155], off
	s_mov_b32 m0, s85
	v_lshl_add_u64 v[154:155], v[204:205], 0, s[38:39]
	global_load_lds_dwordx4 v[154:155], off
	s_waitcnt lgkmcnt(8)
	s_barrier
	s_waitcnt lgkmcnt(0)
	v_mfma_f32_16x16x32_bf16 v[124:127], v[150:153], v[172:175], v[124:127]
	v_mfma_f32_16x16x32_bf16 v[120:123], v[164:167], v[172:175], v[120:123]
	v_mfma_f32_16x16x32_bf16 v[116:119], v[150:153], v[180:183], v[116:119]
	v_mfma_f32_16x16x32_bf16 v[112:115], v[164:167], v[180:183], v[112:115]
	v_mfma_f32_16x16x32_bf16 v[108:111], v[150:153], v[188:191], v[108:111]
	v_mfma_f32_16x16x32_bf16 v[104:107], v[164:167], v[188:191], v[104:107]
	v_mfma_f32_16x16x32_bf16 v[100:103], v[150:153], v[196:199], v[100:103]
	v_mfma_f32_16x16x32_bf16 v[96:99], v[164:167], v[196:199], v[96:99]
	v_mfma_f32_16x16x32_bf16 v[124:127], v[160:163], v[176:179], v[124:127]
	v_mfma_f32_16x16x32_bf16 v[120:123], v[168:171], v[176:179], v[120:123]
	v_mfma_f32_16x16x32_bf16 v[116:119], v[160:163], v[184:187], v[116:119]
	v_mfma_f32_16x16x32_bf16 v[112:115], v[168:171], v[184:187], v[112:115]
	v_mfma_f32_16x16x32_bf16 v[108:111], v[160:163], v[192:195], v[108:111]
	v_mfma_f32_16x16x32_bf16 v[104:107], v[168:171], v[192:195], v[104:107]
	v_mfma_f32_16x16x32_bf16 v[100:103], v[160:163], v[200:203], v[100:103]
	v_mfma_f32_16x16x32_bf16 v[96:99], v[168:171], v[200:203], v[96:99]
	s_barrier
	s_add_i32 s7, 16, 0x1c000
	v_add_u32_e32 v154, s7, v149
	s_add_i32 s6, s6, s18
	ds_read_b128 v[208:211], v154
	ds_read_b128 v[212:215], v154 offset:1024
	ds_read_b128 v[216:219], v154 offset:2048
	ds_read_b128 v[220:223], v154 offset:3072
	s_mov_b32 m0, s6
	v_lshl_add_u64 v[154:155], v[224:225], 0, s[40:41]
	global_load_lds_dwordx4 v[154:155], off
	v_lshl_add_u64 v[154:155], v[226:227], 0, s[40:41]
	s_add_i32 m0, s6, 0x2000
	s_nop 0
	global_load_lds_dwordx4 v[154:155], off
	s_barrier
	s_waitcnt lgkmcnt(0)
	v_mfma_f32_16x16x32_bf16 v[92:95], v[208:211], v[172:175], v[92:95]
	v_mfma_f32_16x16x32_bf16 v[88:91], v[216:219], v[172:175], v[88:91]
	v_mfma_f32_16x16x32_bf16 v[84:87], v[208:211], v[180:183], v[84:87]
	v_mfma_f32_16x16x32_bf16 v[80:83], v[216:219], v[180:183], v[80:83]
	v_mfma_f32_16x16x32_bf16 v[76:79], v[208:211], v[188:191], v[76:79]
	v_mfma_f32_16x16x32_bf16 v[72:75], v[216:219], v[188:191], v[72:75]
	v_mfma_f32_16x16x32_bf16 v[68:71], v[208:211], v[196:199], v[68:71]
	v_mfma_f32_16x16x32_bf16 v[64:67], v[216:219], v[196:199], v[64:67]
	v_mfma_f32_16x16x32_bf16 v[92:95], v[212:215], v[176:179], v[92:95]
	v_mfma_f32_16x16x32_bf16 v[88:91], v[220:223], v[176:179], v[88:91]
	v_mfma_f32_16x16x32_bf16 v[84:87], v[212:215], v[184:187], v[84:87]
	v_mfma_f32_16x16x32_bf16 v[80:83], v[220:223], v[184:187], v[80:83]
	v_mfma_f32_16x16x32_bf16 v[76:79], v[212:215], v[192:195], v[76:79]
	v_mfma_f32_16x16x32_bf16 v[72:75], v[220:223], v[192:195], v[72:75]
	v_mfma_f32_16x16x32_bf16 v[68:71], v[212:215], v[200:203], v[68:71]
	v_mfma_f32_16x16x32_bf16 v[64:67], v[220:223], v[200:203], v[64:67]
	s_mov_b32 m0, s97
	v_lshl_add_u64 v[154:155], v[228:229], 0, s[40:41]
	s_barrier
	ds_read_b128 v[172:175], v148 offset:49152
	ds_read_b128 v[176:179], v148 offset:50176
	ds_read_b128 v[180:183], v148 offset:51200
	ds_read_b128 v[184:187], v148 offset:52224
	ds_read_b128 v[188:191], v148 offset:53248
	ds_read_b128 v[192:195], v148 offset:54272
	ds_read_b128 v[196:199], v148 offset:55296
	ds_read_b128 v[200:203], v148 offset:56320
	global_load_lds_dwordx4 v[154:155], off
	v_lshl_add_u64 v[154:155], v[230:231], 0, s[40:41]
	s_mov_b32 m0, vcc_lo
	s_nop 0
	global_load_lds_dwordx4 v[154:155], off
	s_barrier
; #define WAIT_V(n) asm volatile("s_waitcnt vmcnt(" #n ")" ::: "memory")
; #define WAIT_L(n) asm volatile("s_waitcnt lgkmcnt(" #n ")" ::: "memory")
; #define BAR __builtin_amdgcn_s_barrier()
; #define SCHED __builtin_amdgcn_sched_barrier(0)
; DI void gemm_tile(const bf16_t* __restrict__ A, const bf16_t* __restrict__ Bt, const int K, const int brow, const int bcol, LAS unsigned char* lds, Acc& acc) {
;     ...
;         WAIT_L(8); BAR; WAIT_L(0); MMA(0, 0, At, B0); BAR; SCHED;
;         LDB(B1, 1, 1); STAGE(SBo(1, 0), b3);
;         BAR; WAIT_L(0); MMA(0, 1, At, B1); BAR;
;         LDA(At, 1, 1); STAGE(SAo(1, 0), a3);
;         BAR; WAIT_L(0); MMA(1, 0, At, B0); BAR; SCHED;
;         STAGE(SBo(1, 1), b3 + hstep);
;         WAIT_V(6); BAR; MMA(1, 1, At, B1); BAR;
;     }
;     { LDB(B0, 0, 0); LDA(At, 0, 0); STAGE(SAo(1, 1), cA + (size_t)(nt - 1) * kstep + hstep);
;       BAR; WAIT_L(0); MMA(0, 0, At, B0); BAR;
;       LDB(B1, 0, 1); BAR; WAIT_L(0); MMA(0, 1, At, B1); BAR;
	s_waitcnt lgkmcnt(0)
	v_mfma_f32_16x16x32_bf16 v[60:63], v[150:153], v[172:175], v[60:63]
	v_mfma_f32_16x16x32_bf16 v[56:59], v[164:167], v[172:175], v[56:59]
	v_mfma_f32_16x16x32_bf16 v[52:55], v[150:153], v[180:183], v[52:55]
	v_mfma_f32_16x16x32_bf16 v[48:51], v[164:167], v[180:183], v[48:51]
	v_mfma_f32_16x16x32_bf16 v[44:47], v[150:153], v[188:191], v[44:47]
	v_mfma_f32_16x16x32_bf16 v[40:43], v[164:167], v[188:191], v[40:43]
	v_mfma_f32_16x16x32_bf16 v[36:39], v[150:153], v[196:199], v[36:39]
	v_mfma_f32_16x16x32_bf16 v[32:35], v[164:167], v[196:199], v[32:35]
	v_mfma_f32_16x16x32_bf16 v[60:63], v[160:163], v[176:179], v[60:63]
	v_mfma_f32_16x16x32_bf16 v[56:59], v[168:171], v[176:179], v[56:59]
	v_mfma_f32_16x16x32_bf16 v[52:55], v[160:163], v[184:187], v[52:55]
	v_mfma_f32_16x16x32_bf16 v[48:51], v[168:171], v[184:187], v[48:51]
	v_mfma_f32_16x16x32_bf16 v[44:47], v[160:163], v[192:195], v[44:47]
	v_mfma_f32_16x16x32_bf16 v[40:43], v[168:171], v[192:195], v[40:43]
	v_mfma_f32_16x16x32_bf16 v[36:39], v[160:163], v[200:203], v[36:39]
	v_mfma_f32_16x16x32_bf16 v[32:35], v[168:171], v[200:203], v[32:35]
	s_barrier
	s_add_i32 s6, s7, s18
	s_mov_b32 m0, s6
	v_lshl_add_u64 v[150:151], v[232:233], 0, s[40:41]
	global_load_lds_dwordx4 v[150:151], off
	v_lshl_add_u64 v[150:151], v[234:235], 0, s[40:41]
	s_add_i32 m0, s6, 0x2000
	s_nop 0
	global_load_lds_dwordx4 v[150:151], off
	s_waitcnt vmcnt(6)
	s_barrier
	v_mfma_f32_16x16x32_bf16 v[28:31], v[208:211], v[172:175], v[28:31]
	v_mfma_f32_16x16x32_bf16 v[24:27], v[216:219], v[172:175], v[24:27]
	v_mfma_f32_16x16x32_bf16 v[20:23], v[208:211], v[180:183], v[20:23]
	v_mfma_f32_16x16x32_bf16 v[16:19], v[216:219], v[180:183], v[16:19]
	v_mfma_f32_16x16x32_bf16 v[12:15], v[208:211], v[188:191], v[12:15]
	v_mfma_f32_16x16x32_bf16 v[8:11], v[216:219], v[188:191], v[8:11]
	v_mfma_f32_16x16x32_bf16 v[4:7], v[208:211], v[196:199], v[4:7]
	v_mfma_f32_16x16x32_bf16 v[0:3], v[216:219], v[196:199], v[0:3]
	v_mfma_f32_16x16x32_bf16 v[28:31], v[212:215], v[176:179], v[28:31]
	v_mfma_f32_16x16x32_bf16 v[24:27], v[220:223], v[176:179], v[24:27]
	v_mfma_f32_16x16x32_bf16 v[20:23], v[212:215], v[184:187], v[20:23]
	v_mfma_f32_16x16x32_bf16 v[16:19], v[220:223], v[184:187], v[16:19]
	v_mfma_f32_16x16x32_bf16 v[12:15], v[212:215], v[192:195], v[12:15]
	v_mfma_f32_16x16x32_bf16 v[8:11], v[220:223], v[192:195], v[8:11]
	v_mfma_f32_16x16x32_bf16 v[4:7], v[212:215], v[200:203], v[4:7]
	v_mfma_f32_16x16x32_bf16 v[0:3], v[220:223], v[200:203], v[0:3]
	s_add_u32 s60, s60, 0x100
	s_addc_u32 s61, s61, 0
	s_cmp_ge_u32 s62, vcc_hi
	s_barrier
	s_cbranch_scc0 .LBB0_930
	s_add_i32 s18, s96, -1
	s_lshl_b64 s[6:7], s[18:19], 7
	s_add_u32 s4, s4, s6
	s_addc_u32 s5, s5, s7
	s_add_u32 s4, s4, s55
	v_add_u32_e32 v149, 16, v149
	s_addc_u32 s5, s5, 0
	s_mov_b32 m0, s81
	v_add_u32_e32 v144, 0x10000, v149
	v_lshl_add_u64 v[154:155], s[4:5], 0, v[142:143]
	ds_read_b128 v[130:133], v144
	ds_read_b128 v[134:137], v144 offset:1024
	ds_read_b128 v[138:141], v144 offset:2048
	ds_read_b128 v[144:147], v144 offset:3072
	ds_read_b128 v[150:153], v148
	ds_read_b128 v[160:163], v148 offset:1024
	ds_read_b128 v[164:167], v148 offset:2048
	ds_read_b128 v[168:171], v148 offset:3072
	ds_read_b128 v[172:175], v148 offset:4096
	ds_read_b128 v[176:179], v148 offset:5120
	ds_read_b128 v[180:183], v148 offset:6144
	ds_read_b128 v[184:187], v148 offset:7168
	global_load_lds_dwordx4 v[154:155], off
	s_mov_b32 m0, s63
	v_lshl_add_u64 v[128:129], s[4:5], 0, v[128:129]
	global_load_lds_dwordx4 v[128:129], off
	s_barrier
	s_waitcnt lgkmcnt(0)
	v_mfma_f32_16x16x32_bf16 v[124:127], v[130:133], v[150:153], v[124:127]
	v_mfma_f32_16x16x32_bf16 v[120:123], v[138:141], v[150:153], v[120:123]
	v_mfma_f32_16x16x32_bf16 v[116:119], v[130:133], v[164:167], v[116:119]
	v_mfma_f32_16x16x32_bf16 v[112:115], v[138:141], v[164:167], v[112:115]
	v_mfma_f32_16x16x32_bf16 v[100:103], v[130:133], v[180:183], v[100:103]
	v_mfma_f32_16x16x32_bf16 v[96:99], v[138:141], v[180:183], v[96:99]
	v_mfma_f32_16x16x32_bf16 v[124:127], v[134:137], v[160:163], v[124:127]
	v_mfma_f32_16x16x32_bf16 v[120:123], v[144:147], v[160:163], v[120:123]
	v_mfma_f32_16x16x32_bf16 v[116:119], v[134:137], v[168:171], v[116:119]
	v_mfma_f32_16x16x32_bf16 v[112:115], v[144:147], v[168:171], v[112:115]
	v_mfma_f32_16x16x32_bf16 v[108:111], v[130:133], v[172:175], v[108:111]
	v_mfma_f32_16x16x32_bf16 v[104:107], v[138:141], v[172:175], v[104:107]
	v_mfma_f32_16x16x32_bf16 v[100:103], v[134:137], v[184:187], v[100:103]
	v_mfma_f32_16x16x32_bf16 v[96:99], v[144:147], v[184:187], v[96:99]
	v_mfma_f32_16x16x32_bf16 v[188:191], v[134:137], v[176:179], v[108:111]
	v_mfma_f32_16x16x32_bf16 v[192:195], v[144:147], v[176:179], v[104:107]
	v_add_u32_e32 v128, 0x14000, v149
	s_barrier
	s_nop 0
	ds_read_b128 v[104:107], v128
	ds_read_b128 v[108:111], v128 offset:1024
	ds_read_b128 v[196:199], v128 offset:2048
	ds_read_b128 v[200:203], v128 offset:3072
	s_barrier
	s_waitcnt lgkmcnt(0)
	v_mfma_f32_16x16x32_bf16 v[84:87], v[104:107], v[164:167], v[84:87]
	v_mfma_f32_16x16x32_bf16 v[80:83], v[196:199], v[164:167], v[80:83]
	v_mfma_f32_16x16x32_bf16 v[68:71], v[104:107], v[180:183], v[68:71]
	v_mfma_f32_16x16x32_bf16 v[64:67], v[196:199], v[180:183], v[64:67]
	v_mfma_f32_16x16x32_bf16 v[92:95], v[104:107], v[150:153], v[92:95]
	v_mfma_f32_16x16x32_bf16 v[88:91], v[196:199], v[150:153], v[88:91]
	v_mfma_f32_16x16x32_bf16 v[84:87], v[108:111], v[168:171], v[84:87]
	v_mfma_f32_16x16x32_bf16 v[80:83], v[200:203], v[168:171], v[80:83]
	v_mfma_f32_16x16x32_bf16 v[76:79], v[104:107], v[172:175], v[76:79]
	v_mfma_f32_16x16x32_bf16 v[72:75], v[196:199], v[172:175], v[72:75]
	v_mfma_f32_16x16x32_bf16 v[68:71], v[108:111], v[184:187], v[68:71]
	v_mfma_f32_16x16x32_bf16 v[64:67], v[200:203], v[184:187], v[64:67]
	v_mfma_f32_16x16x32_bf16 v[208:211], v[108:111], v[160:163], v[92:95]
	v_mfma_f32_16x16x32_bf16 v[150:153], v[200:203], v[160:163], v[88:91]
	v_mfma_f32_16x16x32_bf16 v[160:163], v[108:111], v[176:179], v[76:79]
	v_mfma_f32_16x16x32_bf16 v[164:167], v[200:203], v[176:179], v[72:75]
	s_barrier
; #define WAIT_V(n) asm volatile("s_waitcnt vmcnt(" #n ")" ::: "memory")
; #define WAIT_L(n) asm volatile("s_waitcnt lgkmcnt(" #n ")" ::: "memory")
; #define BAR __builtin_amdgcn_s_barrier()
; DI void gemm_tile(const bf16_t* __restrict__ A, const bf16_t* __restrict__ Bt, const int K, const int brow, const int bcol, LAS unsigned char* lds, Acc& acc) {
;     ...
;     { LDB(B0, 0, 0); LDA(At, 0, 0); STAGE(SAo(1, 1), cA + (size_t)(nt - 1) * kstep + hstep);
;       BAR; WAIT_L(0); MMA(0, 0, At, B0); BAR;
;       LDB(B1, 0, 1); BAR; WAIT_L(0); MMA(0, 1, At, B1); BAR;
;       LDA(At, 0, 1); WAIT_V(4); BAR; WAIT_L(0); MMA(1, 0, At, B0); MMA(1, 1, At, B1); BAR; }
;     { LDB(B0, 1, 0); LDA(At, 1, 0); WAIT_V(2); BAR; WAIT_L(0); MMA(0, 0, At, B0); BAR;
;       LDB(B1, 1, 1); WAIT_V(0); BAR; WAIT_L(0); MMA(0, 1, At, B1); BAR;
	s_nop 0
	ds_read_b128 v[72:75], v148 offset:16384
	ds_read_b128 v[76:79], v148 offset:17408
	ds_read_b128 v[88:91], v148 offset:18432
	ds_read_b128 v[92:95], v148 offset:19456
	ds_read_b128 v[168:171], v148 offset:20480
	ds_read_b128 v[172:175], v148 offset:21504
	ds_read_b128 v[176:179], v148 offset:22528
	ds_read_b128 v[180:183], v148 offset:23552
	s_waitcnt vmcnt(4)
	s_barrier
	s_waitcnt lgkmcnt(0)
	v_mfma_f32_16x16x32_bf16 v[60:63], v[130:133], v[72:75], v[60:63]
	v_mfma_f32_16x16x32_bf16 v[56:59], v[138:141], v[72:75], v[56:59]
	v_mfma_f32_16x16x32_bf16 v[52:55], v[130:133], v[88:91], v[52:55]
	v_mfma_f32_16x16x32_bf16 v[48:51], v[138:141], v[88:91], v[48:51]
	v_mfma_f32_16x16x32_bf16 v[36:39], v[130:133], v[176:179], v[36:39]
	v_mfma_f32_16x16x32_bf16 v[32:35], v[138:141], v[176:179], v[32:35]
	v_mfma_f32_16x16x32_bf16 v[60:63], v[134:137], v[76:79], v[60:63]
	v_mfma_f32_16x16x32_bf16 v[56:59], v[144:147], v[76:79], v[56:59]
	v_mfma_f32_16x16x32_bf16 v[52:55], v[134:137], v[92:95], v[52:55]
	v_mfma_f32_16x16x32_bf16 v[48:51], v[144:147], v[92:95], v[48:51]
	v_mfma_f32_16x16x32_bf16 v[44:47], v[130:133], v[168:171], v[44:47]
	v_mfma_f32_16x16x32_bf16 v[40:43], v[138:141], v[168:171], v[40:43]
	v_mfma_f32_16x16x32_bf16 v[36:39], v[134:137], v[180:183], v[36:39]
	v_mfma_f32_16x16x32_bf16 v[32:35], v[144:147], v[180:183], v[32:35]
	v_mfma_f32_16x16x32_bf16 v[184:187], v[134:137], v[172:175], v[44:47]
	v_mfma_f32_16x16x32_bf16 v[212:215], v[144:147], v[172:175], v[40:43]
	v_mfma_f32_16x16x32_bf16 v[20:23], v[104:107], v[88:91], v[20:23]
	v_mfma_f32_16x16x32_bf16 v[16:19], v[196:199], v[88:91], v[16:19]
	v_mfma_f32_16x16x32_bf16 v[4:7], v[104:107], v[176:179], v[4:7]
	v_mfma_f32_16x16x32_bf16 v[0:3], v[196:199], v[176:179], v[0:3]
	v_mfma_f32_16x16x32_bf16 v[28:31], v[104:107], v[72:75], v[28:31]
	v_mfma_f32_16x16x32_bf16 v[24:27], v[196:199], v[72:75], v[24:27]
	v_mfma_f32_16x16x32_bf16 v[20:23], v[108:111], v[92:95], v[20:23]
	v_mfma_f32_16x16x32_bf16 v[16:19], v[200:203], v[92:95], v[16:19]
	v_mfma_f32_16x16x32_bf16 v[12:15], v[104:107], v[168:171], v[12:15]
	v_mfma_f32_16x16x32_bf16 v[8:11], v[196:199], v[168:171], v[8:11]
	v_mfma_f32_16x16x32_bf16 v[4:7], v[108:111], v[180:183], v[4:7]
	v_mfma_f32_16x16x32_bf16 v[0:3], v[200:203], v[180:183], v[0:3]
	v_mfma_f32_16x16x32_bf16 v[128:131], v[108:111], v[76:79], v[28:31]
	v_mfma_f32_16x16x32_bf16 v[132:135], v[200:203], v[76:79], v[24:27]
	v_mfma_f32_16x16x32_bf16 v[136:139], v[108:111], v[172:175], v[12:15]
	v_mfma_f32_16x16x32_bf16 v[144:147], v[200:203], v[172:175], v[8:11]
	v_add_u32_e32 v24, 0x18000, v149
	s_barrier
	ds_read_b128 v[8:11], v24
	ds_read_b128 v[12:15], v24 offset:1024
	ds_read_b128 v[168:171], v24 offset:2048
	ds_read_b128 v[172:175], v24 offset:3072
	ds_read_b128 v[24:27], v148 offset:32768
	ds_read_b128 v[28:31], v148 offset:33792
	ds_read_b128 v[40:43], v148 offset:34816
	ds_read_b128 v[44:47], v148 offset:35840
	ds_read_b128 v[176:179], v148 offset:36864
	ds_read_b128 v[180:183], v148 offset:37888
	ds_read_b128 v[196:199], v148 offset:38912
	ds_read_b128 v[200:203], v148 offset:39936
	s_waitcnt vmcnt(2)
	s_barrier
	s_waitcnt lgkmcnt(0)
	v_mfma_f32_16x16x32_bf16 v[72:75], v[8:11], v[24:27], v[124:127]
	v_mfma_f32_16x16x32_bf16 v[124:127], v[12:15], v[28:31], v[72:75]
	v_mfma_f32_16x16x32_bf16 v[72:75], v[168:171], v[24:27], v[120:123]
	v_mfma_f32_16x16x32_bf16 v[120:123], v[172:175], v[28:31], v[72:75]
	v_mfma_f32_16x16x32_bf16 v[72:75], v[8:11], v[40:43], v[116:119]
	v_mfma_f32_16x16x32_bf16 v[108:111], v[12:15], v[44:47], v[72:75]
	v_mfma_f32_16x16x32_bf16 v[72:75], v[168:171], v[40:43], v[112:115]
	v_mfma_f32_16x16x32_bf16 v[104:107], v[172:175], v[44:47], v[72:75]
	v_mfma_f32_16x16x32_bf16 v[72:75], v[8:11], v[176:179], v[188:191]
	v_mfma_f32_16x16x32_bf16 v[92:95], v[12:15], v[180:183], v[72:75]
	v_mfma_f32_16x16x32_bf16 v[72:75], v[168:171], v[176:179], v[192:195]
	v_mfma_f32_16x16x32_bf16 v[88:91], v[172:175], v[180:183], v[72:75]
	v_mfma_f32_16x16x32_bf16 v[72:75], v[8:11], v[196:199], v[100:103]
	v_mfma_f32_16x16x32_bf16 v[76:79], v[12:15], v[200:203], v[72:75]
	v_mfma_f32_16x16x32_bf16 v[72:75], v[168:171], v[196:199], v[96:99]
	v_mfma_f32_16x16x32_bf16 v[72:75], v[172:175], v[200:203], v[72:75]
	s_nop 0
	v_add_u32_e32 v96, 0x1c000, v149
	s_barrier
; #define WAIT_V(n) asm volatile("s_waitcnt vmcnt(" #n ")" ::: "memory")
; #define WAIT_L(n) asm volatile("s_waitcnt lgkmcnt(" #n ")" ::: "memory")
; #define BAR __builtin_amdgcn_s_barrier()
; DI void gemm_tile(const bf16_t* __restrict__ A, const bf16_t* __restrict__ Bt, const int K, const int brow, const int bcol, LAS unsigned char* lds, Acc& acc) {
;     ...
;       LDA(At, 0, 1); WAIT_V(4); BAR; WAIT_L(0); MMA(1, 0, At, B0); MMA(1, 1, At, B1); BAR; }
;     { LDB(B0, 1, 0); LDA(At, 1, 0); WAIT_V(2); BAR; WAIT_L(0); MMA(0, 0, At, B0); BAR;
;       LDB(B1, 1, 1); WAIT_V(0); BAR; WAIT_L(0); MMA(0, 1, At, B1); BAR;
;       LDA(At, 1, 1); BAR; WAIT_L(0); MMA(1, 0, At, B0); MMA(1, 1, At, B1); BAR; }
;     if (wr == 0) BAR;
	ds_read_b128 v[188:191], v96
	ds_read_b128 v[192:195], v96 offset:1024
	ds_read_b128 v[216:219], v96 offset:2048
	ds_read_b128 v[220:223], v96 offset:3072
	s_waitcnt vmcnt(0)
	s_barrier
	s_waitcnt lgkmcnt(0)
	v_mfma_f32_16x16x32_bf16 v[96:99], v[188:191], v[24:27], v[208:211]
	v_mfma_f32_16x16x32_bf16 v[24:27], v[216:219], v[24:27], v[150:153]
	v_mfma_f32_16x16x32_bf16 v[112:115], v[220:223], v[28:31], v[24:27]
	v_mfma_f32_16x16x32_bf16 v[24:27], v[188:191], v[40:43], v[84:87]
	v_mfma_f32_16x16x32_bf16 v[100:103], v[192:195], v[44:47], v[24:27]
	v_mfma_f32_16x16x32_bf16 v[24:27], v[216:219], v[40:43], v[80:83]
	v_mfma_f32_16x16x32_bf16 v[116:119], v[192:195], v[28:31], v[96:99]
	v_mfma_f32_16x16x32_bf16 v[96:99], v[220:223], v[44:47], v[24:27]
	v_mfma_f32_16x16x32_bf16 v[24:27], v[188:191], v[176:179], v[160:163]
	v_mfma_f32_16x16x32_bf16 v[84:87], v[192:195], v[180:183], v[24:27]
	v_mfma_f32_16x16x32_bf16 v[24:27], v[216:219], v[176:179], v[164:167]
	v_mfma_f32_16x16x32_bf16 v[80:83], v[220:223], v[180:183], v[24:27]
	v_mfma_f32_16x16x32_bf16 v[24:27], v[188:191], v[196:199], v[68:71]
	v_mfma_f32_16x16x32_bf16 v[68:71], v[192:195], v[200:203], v[24:27]
	v_mfma_f32_16x16x32_bf16 v[24:27], v[216:219], v[196:199], v[64:67]
	v_mfma_f32_16x16x32_bf16 v[64:67], v[220:223], v[200:203], v[24:27]
	s_barrier
	ds_read_b128 v[150:153], v148 offset:49152
	ds_read_b128 v[160:163], v148 offset:50176
	ds_read_b128 v[164:167], v148 offset:51200
	ds_read_b128 v[176:179], v148 offset:52224
	ds_read_b128 v[180:183], v148 offset:53248
	ds_read_b128 v[196:199], v148 offset:54272
	ds_read_b128 v[200:203], v148 offset:55296
	ds_read_b128 v[208:211], v148 offset:56320
	s_barrier
	s_waitcnt lgkmcnt(0)
	v_mfma_f32_16x16x32_bf16 v[24:27], v[8:11], v[150:153], v[60:63]
	v_mfma_f32_16x16x32_bf16 v[60:63], v[12:15], v[160:163], v[24:27]
	v_mfma_f32_16x16x32_bf16 v[24:27], v[168:171], v[150:153], v[56:59]
	v_mfma_f32_16x16x32_bf16 v[56:59], v[172:175], v[160:163], v[24:27]
	v_mfma_f32_16x16x32_bf16 v[24:27], v[8:11], v[164:167], v[52:55]
	v_mfma_f32_16x16x32_bf16 v[44:47], v[12:15], v[176:179], v[24:27]
	v_mfma_f32_16x16x32_bf16 v[24:27], v[168:171], v[164:167], v[48:51]
	v_mfma_f32_16x16x32_bf16 v[40:43], v[172:175], v[176:179], v[24:27]
	v_mfma_f32_16x16x32_bf16 v[24:27], v[8:11], v[180:183], v[184:187]
	v_mfma_f32_16x16x32_bf16 v[8:11], v[8:11], v[200:203], v[36:39]
	v_mfma_f32_16x16x32_bf16 v[28:31], v[12:15], v[196:199], v[24:27]
	v_mfma_f32_16x16x32_bf16 v[24:27], v[168:171], v[180:183], v[212:215]
	v_mfma_f32_16x16x32_bf16 v[12:15], v[12:15], v[208:211], v[8:11]
	v_mfma_f32_16x16x32_bf16 v[8:11], v[168:171], v[200:203], v[32:35]
	v_mfma_f32_16x16x32_bf16 v[24:27], v[172:175], v[196:199], v[24:27]
	v_mfma_f32_16x16x32_bf16 v[8:11], v[172:175], v[208:211], v[8:11]
	v_mfma_f32_16x16x32_bf16 v[32:35], v[188:191], v[150:153], v[128:131]
	v_mfma_f32_16x16x32_bf16 v[52:55], v[192:195], v[160:163], v[32:35]
	v_mfma_f32_16x16x32_bf16 v[32:35], v[216:219], v[150:153], v[132:135]
	v_mfma_f32_16x16x32_bf16 v[16:19], v[216:219], v[164:167], v[16:19]
	v_mfma_f32_16x16x32_bf16 v[48:51], v[220:223], v[160:163], v[32:35]
	v_mfma_f32_16x16x32_bf16 v[20:23], v[188:191], v[164:167], v[20:23]
	v_mfma_f32_16x16x32_bf16 v[32:35], v[220:223], v[176:179], v[16:19]
	v_mfma_f32_16x16x32_bf16 v[16:19], v[188:191], v[180:183], v[136:139]
	v_mfma_f32_16x16x32_bf16 v[36:39], v[192:195], v[176:179], v[20:23]
	v_mfma_f32_16x16x32_bf16 v[20:23], v[192:195], v[196:199], v[16:19]
	v_mfma_f32_16x16x32_bf16 v[16:19], v[216:219], v[180:183], v[144:147]
	v_mfma_f32_16x16x32_bf16 v[4:7], v[188:191], v[200:203], v[4:7]
	v_mfma_f32_16x16x32_bf16 v[0:3], v[216:219], v[200:203], v[0:3]
	v_mfma_f32_16x16x32_bf16 v[16:19], v[220:223], v[196:199], v[16:19]
	v_mfma_f32_16x16x32_bf16 v[4:7], v[192:195], v[208:211], v[4:7]
	v_mfma_f32_16x16x32_bf16 v[0:3], v[220:223], v[208:211], v[0:3]
	s_cmpk_lt_u32 s29, 0x100
	s_mov_b32 s89, s23
	s_mov_b32 s90, s35
	s_mov_b32 s91, s8
	s_barrier
	s_cbranch_scc0 .LBB0_934
	s_barrier
	s_and_b64 vcc, exec, s[2:3]
	s_mov_b64 s[2:3], -1
	s_cbranch_vccz .LBB0_935

; #define WAIT_V(n) asm volatile("s_waitcnt vmcnt(" #n ")" ::: "memory")
; #define WAIT_L(n) asm volatile("s_waitcnt lgkmcnt(" #n ")" ::: "memory")
; #define BAR __builtin_amdgcn_s_barrier()
; #define SCHED __builtin_amdgcn_sched_barrier(0)
; template <class Get, class Epi>
; DI void gemm_stream(LAS unsigned char* lds, const int K, const int ld, Get get, Epi epi) {
;     ...
;             LDB(B0, 0, 0); SCHED; LDA(At, 0, 0); STAGE(SAo(1, 1), a1 + hstep);
;             WAIT_L(8); BAR; WAIT_L(0); MMA(0, 0, At, B0); BAR; SCHED;
;             LDB(B1, 0, 1); STAGE(SBo(0, 0), b2);
;             BAR; WAIT_L(0); MMA(0, 1, At, B1); BAR;
;             LDA(At, 0, 1); STAGE(SAo(0, 0), a2);
;             BAR; WAIT_L(0); MMA(1, 0, At, B0); BAR; SCHED;
;             STAGE(SBo(0, 1), b2 + hstep);
;             WAIT_V(6); BAR; MMA(1, 1, At, B1); BAR;
;             LDB(B0, 1, 0); SCHED; LDA(At, 1, 0); STAGE(SAo(0, 1), a2 + hstep);
;             WAIT_L(8); BAR; WAIT_L(0); MMA(0, 0, At, B0); BAR; SCHED;
;             LDB(B1, 1, 1); STAGE(SBo(1, 0), b3);
.LBB0_1238:
	ds_read_b128 v[128:131], v198
	ds_read_b128 v[132:135], v198 offset:1024
	ds_read_b128 v[136:139], v198 offset:2048
	ds_read_b128 v[140:143], v198 offset:3072
	s_add_u32 s8, s6, 0x100
	s_addc_u32 s9, s7, 0
	s_cmp_eq_u32 s18, 28
	s_cselect_b32 s13, s39, s9
	s_cselect_b32 s12, s38, s8
	s_cselect_b32 s11, s41, s17
	s_cselect_b32 s10, s40, s16
	s_mov_b32 m0, s74
	v_lshl_add_u64 v[186:187], s[6:7], 0, v[168:169]
	ds_read_b128 v[144:147], v199
	ds_read_b128 v[148:151], v199 offset:1024
	ds_read_b128 v[152:155], v199 offset:2048
	ds_read_b128 v[156:159], v199 offset:3072
	ds_read_b128 v[160:163], v199 offset:4096
	ds_read_b128 v[174:177], v199 offset:5120
	ds_read_b128 v[178:181], v199 offset:6144
	ds_read_b128 v[182:185], v199 offset:7168
	global_load_lds_dwordx4 v[186:187], off
	s_mov_b32 m0, s75
	v_lshl_add_u64 v[186:187], s[6:7], 0, v[170:171]
	global_load_lds_dwordx4 v[186:187], off
	s_waitcnt lgkmcnt(8)
	s_barrier
	s_waitcnt lgkmcnt(0)
	v_mfma_f32_16x16x32_bf16 v[124:127], v[128:131], v[144:147], v[124:127]
	v_mfma_f32_16x16x32_bf16 v[92:95], v[136:139], v[144:147], v[92:95]
	v_mfma_f32_16x16x32_bf16 v[120:123], v[128:131], v[152:155], v[120:123]
	v_mfma_f32_16x16x32_bf16 v[88:91], v[136:139], v[152:155], v[88:91]
	v_mfma_f32_16x16x32_bf16 v[116:119], v[128:131], v[160:163], v[116:119]
	v_mfma_f32_16x16x32_bf16 v[84:87], v[136:139], v[160:163], v[84:87]
	v_mfma_f32_16x16x32_bf16 v[112:115], v[128:131], v[178:181], v[112:115]
	v_mfma_f32_16x16x32_bf16 v[80:83], v[136:139], v[178:181], v[80:83]
	v_mfma_f32_16x16x32_bf16 v[124:127], v[132:135], v[148:151], v[124:127]
	v_mfma_f32_16x16x32_bf16 v[92:95], v[140:143], v[148:151], v[92:95]
	v_mfma_f32_16x16x32_bf16 v[120:123], v[132:135], v[156:159], v[120:123]
	v_mfma_f32_16x16x32_bf16 v[88:91], v[140:143], v[156:159], v[88:91]
	v_mfma_f32_16x16x32_bf16 v[116:119], v[132:135], v[174:177], v[116:119]
	v_mfma_f32_16x16x32_bf16 v[84:87], v[140:143], v[174:177], v[84:87]
	v_mfma_f32_16x16x32_bf16 v[112:115], v[132:135], v[182:185], v[112:115]
	v_mfma_f32_16x16x32_bf16 v[80:83], v[140:143], v[182:185], v[80:83]
	s_barrier
	s_mov_b32 m0, s80
	v_lshl_add_u64 v[204:205], s[10:11], 0, v[164:165]
	ds_read_b128 v[186:189], v200
	ds_read_b128 v[190:193], v200 offset:1024
	ds_read_b128 v[194:197], v200 offset:2048
	ds_read_b128 v[208:211], v200 offset:3072
	global_load_lds_dwordx4 v[204:205], off
	s_mov_b32 m0, s81
	v_lshl_add_u64 v[212:213], s[10:11], 0, v[166:167]
	global_load_lds_dwordx4 v[212:213], off
	s_barrier
	s_waitcnt lgkmcnt(0)
	v_mfma_f32_16x16x32_bf16 v[60:63], v[186:189], v[144:147], v[60:63]
	v_mfma_f32_16x16x32_bf16 v[28:31], v[194:197], v[144:147], v[28:31]
	v_mfma_f32_16x16x32_bf16 v[56:59], v[186:189], v[152:155], v[56:59]
	v_mfma_f32_16x16x32_bf16 v[24:27], v[194:197], v[152:155], v[24:27]
	v_mfma_f32_16x16x32_bf16 v[52:55], v[186:189], v[160:163], v[52:55]
	v_mfma_f32_16x16x32_bf16 v[20:23], v[194:197], v[160:163], v[20:23]
	v_mfma_f32_16x16x32_bf16 v[48:51], v[186:189], v[178:181], v[48:51]
	v_mfma_f32_16x16x32_bf16 v[16:19], v[194:197], v[178:181], v[16:19]
	v_mfma_f32_16x16x32_bf16 v[60:63], v[190:193], v[148:151], v[60:63]
	v_mfma_f32_16x16x32_bf16 v[28:31], v[208:211], v[148:151], v[28:31]
	v_mfma_f32_16x16x32_bf16 v[56:59], v[190:193], v[156:159], v[56:59]
	v_mfma_f32_16x16x32_bf16 v[24:27], v[208:211], v[156:159], v[24:27]
	v_mfma_f32_16x16x32_bf16 v[52:55], v[190:193], v[174:177], v[52:55]
	v_mfma_f32_16x16x32_bf16 v[20:23], v[208:211], v[174:177], v[20:23]
	v_mfma_f32_16x16x32_bf16 v[48:51], v[190:193], v[182:185], v[48:51]
	v_mfma_f32_16x16x32_bf16 v[16:19], v[208:211], v[182:185], v[16:19]
	s_mov_b32 m0, s21
	v_lshl_add_u64 v[214:215], s[12:13], 0, v[164:165]
	s_barrier
	ds_read_b128 v[144:147], v199 offset:16384
	ds_read_b128 v[148:151], v199 offset:17408
	ds_read_b128 v[152:155], v199 offset:18432
	ds_read_b128 v[156:159], v199 offset:19456
	ds_read_b128 v[160:163], v199 offset:20480
	ds_read_b128 v[174:177], v199 offset:21504
	ds_read_b128 v[178:181], v199 offset:22528
	ds_read_b128 v[182:185], v199 offset:23552
	global_load_lds_dwordx4 v[214:215], off
	s_mov_b32 m0, s58
	v_lshl_add_u64 v[216:217], s[12:13], 0, v[166:167]
	global_load_lds_dwordx4 v[216:217], off
	s_barrier
	s_waitcnt lgkmcnt(0)
	v_mfma_f32_16x16x32_bf16 v[108:111], v[128:131], v[144:147], v[108:111]
	v_mfma_f32_16x16x32_bf16 v[76:79], v[136:139], v[144:147], v[76:79]
	v_mfma_f32_16x16x32_bf16 v[104:107], v[128:131], v[152:155], v[104:107]
	v_mfma_f32_16x16x32_bf16 v[72:75], v[136:139], v[152:155], v[72:75]
	v_mfma_f32_16x16x32_bf16 v[100:103], v[128:131], v[160:163], v[100:103]
	v_mfma_f32_16x16x32_bf16 v[68:71], v[136:139], v[160:163], v[68:71]
	v_mfma_f32_16x16x32_bf16 v[96:99], v[128:131], v[178:181], v[96:99]
	v_mfma_f32_16x16x32_bf16 v[64:67], v[136:139], v[178:181], v[64:67]
	v_mfma_f32_16x16x32_bf16 v[108:111], v[132:135], v[148:151], v[108:111]
	v_mfma_f32_16x16x32_bf16 v[76:79], v[140:143], v[148:151], v[76:79]
	v_mfma_f32_16x16x32_bf16 v[104:107], v[132:135], v[156:159], v[104:107]
	v_mfma_f32_16x16x32_bf16 v[72:75], v[140:143], v[156:159], v[72:75]
	v_mfma_f32_16x16x32_bf16 v[100:103], v[132:135], v[174:177], v[100:103]
	v_mfma_f32_16x16x32_bf16 v[68:71], v[140:143], v[174:177], v[68:71]
	v_mfma_f32_16x16x32_bf16 v[96:99], v[132:135], v[182:185], v[96:99]
	v_mfma_f32_16x16x32_bf16 v[64:67], v[140:143], v[182:185], v[64:67]
	s_barrier
	s_add_u32 s6, s10, 0x80000
	s_addc_u32 s7, s11, 0
	s_mov_b32 m0, s82
	v_lshl_add_u64 v[128:129], s[6:7], 0, v[164:165]
	global_load_lds_dwordx4 v[128:129], off
	s_mov_b32 m0, s83
	v_lshl_add_u64 v[128:129], s[6:7], 0, v[166:167]
	global_load_lds_dwordx4 v[128:129], off
	s_waitcnt vmcnt(6)
	s_barrier
; #define WAIT_V(n) asm volatile("s_waitcnt vmcnt(" #n ")" ::: "memory")
; #define WAIT_L(n) asm volatile("s_waitcnt lgkmcnt(" #n ")" ::: "memory")
; #define BAR __builtin_amdgcn_s_barrier()
; #define SCHED __builtin_amdgcn_sched_barrier(0)
; template <class Get, class Epi>
; DI void gemm_stream(LAS unsigned char* lds, const int K, const int ld, Get get, Epi epi) {
;     ...
;             WAIT_V(6); BAR; MMA(1, 1, At, B1); BAR;
;             LDB(B0, 1, 0); SCHED; LDA(At, 1, 0); STAGE(SAo(0, 1), a2 + hstep);
;             WAIT_L(8); BAR; WAIT_L(0); MMA(0, 0, At, B0); BAR; SCHED;
;             LDB(B1, 1, 1); STAGE(SBo(1, 0), b3);
;             BAR; WAIT_L(0); MMA(0, 1, At, B1); BAR;
;             LDA(At, 1, 1); STAGE(SAo(1, 0), a3);
;             BAR; WAIT_L(0); MMA(1, 0, At, B0); BAR; SCHED;
;             STAGE(SBo(1, 1), b3 + hstep);
	v_mfma_f32_16x16x32_bf16 v[44:47], v[186:189], v[144:147], v[44:47]
	v_mfma_f32_16x16x32_bf16 v[12:15], v[194:197], v[144:147], v[12:15]
	v_mfma_f32_16x16x32_bf16 v[40:43], v[186:189], v[152:155], v[40:43]
	v_mfma_f32_16x16x32_bf16 v[8:11], v[194:197], v[152:155], v[8:11]
	v_mfma_f32_16x16x32_bf16 v[36:39], v[186:189], v[160:163], v[36:39]
	v_mfma_f32_16x16x32_bf16 v[4:7], v[194:197], v[160:163], v[4:7]
	v_mfma_f32_16x16x32_bf16 v[32:35], v[186:189], v[178:181], v[32:35]
	v_mfma_f32_16x16x32_bf16 v[0:3], v[194:197], v[178:181], v[0:3]
	v_mfma_f32_16x16x32_bf16 v[44:47], v[190:193], v[148:151], v[44:47]
	v_mfma_f32_16x16x32_bf16 v[12:15], v[208:211], v[148:151], v[12:15]
	v_mfma_f32_16x16x32_bf16 v[40:43], v[190:193], v[156:159], v[40:43]
	v_mfma_f32_16x16x32_bf16 v[8:11], v[208:211], v[156:159], v[8:11]
	v_mfma_f32_16x16x32_bf16 v[36:39], v[190:193], v[174:177], v[36:39]
	v_mfma_f32_16x16x32_bf16 v[4:7], v[208:211], v[174:177], v[4:7]
	v_mfma_f32_16x16x32_bf16 v[32:35], v[190:193], v[182:185], v[32:35]
	v_mfma_f32_16x16x32_bf16 v[0:3], v[208:211], v[182:185], v[0:3]
	s_barrier
	ds_read_b128 v[128:131], v201
	ds_read_b128 v[132:135], v201 offset:1024
	ds_read_b128 v[136:139], v201 offset:2048
	ds_read_b128 v[140:143], v201 offset:3072
	s_add_u32 s6, s12, 0x80000
	s_addc_u32 s7, s13, 0
	s_mov_b32 m0, s59
	v_lshl_add_u64 v[186:187], s[6:7], 0, v[164:165]
	ds_read_b128 v[144:147], v199 offset:32768
	ds_read_b128 v[148:151], v199 offset:33792
	ds_read_b128 v[152:155], v199 offset:34816
	ds_read_b128 v[156:159], v199 offset:35840
	ds_read_b128 v[160:163], v199 offset:36864
	ds_read_b128 v[174:177], v199 offset:37888
	ds_read_b128 v[178:181], v199 offset:38912
	ds_read_b128 v[182:185], v199 offset:39936
	global_load_lds_dwordx4 v[186:187], off
	s_mov_b32 m0, s60
	v_lshl_add_u64 v[186:187], s[6:7], 0, v[166:167]
	global_load_lds_dwordx4 v[186:187], off
	s_waitcnt lgkmcnt(8)
	s_barrier
	s_waitcnt lgkmcnt(0)
	v_mfma_f32_16x16x32_bf16 v[124:127], v[128:131], v[144:147], v[124:127]
	v_mfma_f32_16x16x32_bf16 v[92:95], v[136:139], v[144:147], v[92:95]
	v_mfma_f32_16x16x32_bf16 v[120:123], v[128:131], v[152:155], v[120:123]
	v_mfma_f32_16x16x32_bf16 v[88:91], v[136:139], v[152:155], v[88:91]
	v_mfma_f32_16x16x32_bf16 v[116:119], v[128:131], v[160:163], v[116:119]
	v_mfma_f32_16x16x32_bf16 v[84:87], v[136:139], v[160:163], v[84:87]
	v_mfma_f32_16x16x32_bf16 v[112:115], v[128:131], v[178:181], v[112:115]
	v_mfma_f32_16x16x32_bf16 v[80:83], v[136:139], v[178:181], v[80:83]
	v_mfma_f32_16x16x32_bf16 v[124:127], v[132:135], v[148:151], v[124:127]
	v_mfma_f32_16x16x32_bf16 v[92:95], v[140:143], v[148:151], v[92:95]
	v_mfma_f32_16x16x32_bf16 v[120:123], v[132:135], v[156:159], v[120:123]
	v_mfma_f32_16x16x32_bf16 v[88:91], v[140:143], v[156:159], v[88:91]
	v_mfma_f32_16x16x32_bf16 v[116:119], v[132:135], v[174:177], v[116:119]
	v_mfma_f32_16x16x32_bf16 v[84:87], v[140:143], v[174:177], v[84:87]
	v_mfma_f32_16x16x32_bf16 v[112:115], v[132:135], v[182:185], v[112:115]
	v_mfma_f32_16x16x32_bf16 v[80:83], v[140:143], v[182:185], v[80:83]
	s_barrier
	s_mov_b32 m0, s85
	v_lshl_add_u64 v[204:205], v[204:205], 0, s[0:1]
	ds_read_b128 v[186:189], v202
	ds_read_b128 v[190:193], v202 offset:1024
	ds_read_b128 v[194:197], v202 offset:2048
	ds_read_b128 v[208:211], v202 offset:3072
	global_load_lds_dwordx4 v[204:205], off
	s_mov_b32 m0, s96
	v_lshl_add_u64 v[204:205], v[212:213], 0, s[0:1]
	global_load_lds_dwordx4 v[204:205], off
	s_barrier
	s_waitcnt lgkmcnt(0)
	v_mfma_f32_16x16x32_bf16 v[60:63], v[186:189], v[144:147], v[60:63]
	v_mfma_f32_16x16x32_bf16 v[28:31], v[194:197], v[144:147], v[28:31]
	v_mfma_f32_16x16x32_bf16 v[56:59], v[186:189], v[152:155], v[56:59]
	v_mfma_f32_16x16x32_bf16 v[24:27], v[194:197], v[152:155], v[24:27]
	v_mfma_f32_16x16x32_bf16 v[52:55], v[186:189], v[160:163], v[52:55]
	v_mfma_f32_16x16x32_bf16 v[20:23], v[194:197], v[160:163], v[20:23]
	v_mfma_f32_16x16x32_bf16 v[48:51], v[186:189], v[178:181], v[48:51]
	v_mfma_f32_16x16x32_bf16 v[16:19], v[194:197], v[178:181], v[16:19]
	v_mfma_f32_16x16x32_bf16 v[60:63], v[190:193], v[148:151], v[60:63]
	v_mfma_f32_16x16x32_bf16 v[28:31], v[208:211], v[148:151], v[28:31]
	v_mfma_f32_16x16x32_bf16 v[56:59], v[190:193], v[156:159], v[56:59]
	v_mfma_f32_16x16x32_bf16 v[24:27], v[208:211], v[156:159], v[24:27]
	v_mfma_f32_16x16x32_bf16 v[52:55], v[190:193], v[174:177], v[52:55]
	v_mfma_f32_16x16x32_bf16 v[20:23], v[208:211], v[174:177], v[20:23]
	v_mfma_f32_16x16x32_bf16 v[48:51], v[190:193], v[182:185], v[48:51]
	v_mfma_f32_16x16x32_bf16 v[16:19], v[208:211], v[182:185], v[16:19]
	s_mov_b32 m0, s61
	v_lshl_add_u64 v[204:205], v[214:215], 0, s[0:1]
	s_barrier
	ds_read_b128 v[144:147], v199 offset:49152
	ds_read_b128 v[148:151], v199 offset:50176
	ds_read_b128 v[152:155], v199 offset:51200
	ds_read_b128 v[156:159], v199 offset:52224
	ds_read_b128 v[160:163], v199 offset:53248
	ds_read_b128 v[174:177], v199 offset:54272
	ds_read_b128 v[178:181], v199 offset:55296
	ds_read_b128 v[182:185], v199 offset:56320
	global_load_lds_dwordx4 v[204:205], off
	s_mov_b32 m0, s62
	v_lshl_add_u64 v[204:205], v[216:217], 0, s[0:1]
	global_load_lds_dwordx4 v[204:205], off
	s_barrier
; #define WAIT_V(n) asm volatile("s_waitcnt vmcnt(" #n ")" ::: "memory")
; #define WAIT_L(n) asm volatile("s_waitcnt lgkmcnt(" #n ")" ::: "memory")
; #define BAR __builtin_amdgcn_s_barrier()
; #define SCHED __builtin_amdgcn_sched_barrier(0)
; template <class Get, class Epi>
; DI void gemm_stream(LAS unsigned char* lds, const int K, const int ld, Get get, Epi epi) {
;     ...
;             BAR; WAIT_L(0); MMA(1, 0, At, B0); BAR; SCHED;
;             STAGE(SBo(1, 1), b3 + hstep);
;             WAIT_V(6); BAR; MMA(1, 1, At, B1); BAR;
;         }
;         epi(acc, cur);
; DI void epi_resid(const Acc& acc, const P& p, int brow, int bcol, int layer, int gch, bool from_input) {
;     ...
;     const float* gate = modv(p, layer, brow, gch);
; #pragma unroll
;     for (int bj = 0; bj < 2; ++bj)
; #pragma unroll
;         for (int n = 0; n < 2; ++n) {
;             const int c0 = bcol + bj * 128 + wc * 32 + n * 16 + fq * 4;
;             const f32x4 g = *(const f32x4*)(gate + c0);
;             f32x4 xv[2][4];
; #pragma unroll
;             for (int ai = 0; ai < 2; ++ai)
; #pragma unroll
;                 for (int m = 0; m < 4; ++m) {
;                     const int r = brow + ai * 128 + wr * 64 + m * 16 + fr;
;                     const float* sp = (from_input ? inrow(p, r) : xrow(p, r)) + c0;
;                     xv[ai][m] = *(const f32x4*)sp;
	s_waitcnt lgkmcnt(0)
	v_mfma_f32_16x16x32_bf16 v[108:111], v[128:131], v[144:147], v[108:111]
	v_mfma_f32_16x16x32_bf16 v[76:79], v[136:139], v[144:147], v[76:79]
	v_mfma_f32_16x16x32_bf16 v[104:107], v[128:131], v[152:155], v[104:107]
	v_mfma_f32_16x16x32_bf16 v[72:75], v[136:139], v[152:155], v[72:75]
	v_mfma_f32_16x16x32_bf16 v[100:103], v[128:131], v[160:163], v[100:103]
	v_mfma_f32_16x16x32_bf16 v[68:71], v[136:139], v[160:163], v[68:71]
	v_mfma_f32_16x16x32_bf16 v[96:99], v[128:131], v[178:181], v[96:99]
	v_mfma_f32_16x16x32_bf16 v[64:67], v[136:139], v[178:181], v[64:67]
	v_mfma_f32_16x16x32_bf16 v[108:111], v[132:135], v[148:151], v[108:111]
	v_mfma_f32_16x16x32_bf16 v[76:79], v[140:143], v[148:151], v[76:79]
	v_mfma_f32_16x16x32_bf16 v[104:107], v[132:135], v[156:159], v[104:107]
	v_mfma_f32_16x16x32_bf16 v[72:75], v[140:143], v[156:159], v[72:75]
	v_mfma_f32_16x16x32_bf16 v[100:103], v[132:135], v[174:177], v[100:103]
	v_mfma_f32_16x16x32_bf16 v[68:71], v[140:143], v[174:177], v[68:71]
	v_mfma_f32_16x16x32_bf16 v[96:99], v[132:135], v[182:185], v[96:99]
	v_mfma_f32_16x16x32_bf16 v[64:67], v[140:143], v[182:185], v[64:67]
	s_barrier
	s_add_u32 s6, s10, 0x80080
	s_addc_u32 s7, s11, 0
	s_mov_b32 m0, s97
	v_lshl_add_u64 v[128:129], s[6:7], 0, v[164:165]
	global_load_lds_dwordx4 v[128:129], off
	v_lshl_add_u64 v[128:129], s[6:7], 0, v[166:167]
	s_add_i32 m0, s97, 0x2000
	s_nop 0
	global_load_lds_dwordx4 v[128:129], off
	s_waitcnt vmcnt(6)
	s_barrier
	v_mfma_f32_16x16x32_bf16 v[44:47], v[186:189], v[144:147], v[44:47]
	v_mfma_f32_16x16x32_bf16 v[12:15], v[194:197], v[144:147], v[12:15]
	v_mfma_f32_16x16x32_bf16 v[40:43], v[186:189], v[152:155], v[40:43]
	v_mfma_f32_16x16x32_bf16 v[8:11], v[194:197], v[152:155], v[8:11]
	v_mfma_f32_16x16x32_bf16 v[36:39], v[186:189], v[160:163], v[36:39]
	v_mfma_f32_16x16x32_bf16 v[4:7], v[194:197], v[160:163], v[4:7]
	v_mfma_f32_16x16x32_bf16 v[32:35], v[186:189], v[178:181], v[32:35]
	v_mfma_f32_16x16x32_bf16 v[0:3], v[194:197], v[178:181], v[0:3]
	v_mfma_f32_16x16x32_bf16 v[44:47], v[190:193], v[148:151], v[44:47]
	v_mfma_f32_16x16x32_bf16 v[12:15], v[208:211], v[148:151], v[12:15]
	v_mfma_f32_16x16x32_bf16 v[40:43], v[190:193], v[156:159], v[40:43]
	v_mfma_f32_16x16x32_bf16 v[8:11], v[208:211], v[156:159], v[8:11]
	v_mfma_f32_16x16x32_bf16 v[36:39], v[190:193], v[174:177], v[36:39]
	v_mfma_f32_16x16x32_bf16 v[4:7], v[208:211], v[174:177], v[4:7]
	v_mfma_f32_16x16x32_bf16 v[32:35], v[190:193], v[182:185], v[32:35]
	v_mfma_f32_16x16x32_bf16 v[0:3], v[208:211], v[182:185], v[0:3]
	s_add_i32 s18, s18, 2
	s_add_u32 s16, s16, 0x100
	s_addc_u32 s17, s17, 0
	s_cmp_gt_u32 s18, 29
	s_mov_b64 s[6:7], s[8:9]
	s_barrier
	s_cbranch_scc0 .LBB0_1238
	s_lshr_b32 s6, s15, 4
	s_lshl_b32 s7, s15, 8
	s_mulk_i32 s6, 0x1100
	s_and_b32 s7, s7, 0xf00
	s_add_i32 s6, s6, s7
	s_add_i32 s8, s6, 0x100
	s_mul_hi_i32 s6, s8, 0x78787879
	s_lshr_b32 s7, s6, 31
	s_ashr_i32 s6, s6, 11
	s_add_i32 s6, s6, s7
	s_mul_i32 s7, s6, 0xffffef00
	s_mul_i32 s6, s6, 6
	s_lshl_b32 s9, s14, 8
	s_add_i32 s7, s7, s8
	s_add_i32 s6, s6, 2
	s_cmpk_gt_i32 s7, 0xff
	v_mov_b32_e32 v132, v206
	s_cselect_b32 s6, s6, 26
	s_ashr_i32 s7, s6, 31
	v_lshrrev_b32_e32 v128, 1, v132
	v_lshrrev_b32_e32 v129, 2, v132
	s_lshl_b64 s[6:7], s[6:7], 13
	v_and_b32_e32 v128, 0x60, v128
	v_and_b32_e32 v129, 12, v129
	s_add_u32 s6, s26, s6
	v_or3_b32 v174, v128, s9, v129
	s_addc_u32 s7, s27, s7
	v_ashrrev_i32_e32 v175, 31, v174
	v_lshl_add_u64 v[192:193], v[174:175], 2, s[6:7]
	global_load_dwordx4 v[128:131], v[192:193], off
	v_ashrrev_i32_e32 v133, 2, v132
	v_and_b32_e32 v133, 0xffffffc0, v133
	v_and_or_b32 v132, v132, 15, s8
	v_add_u32_e32 v176, v132, v133
	v_mul_hi_i32 v132, v176, s76
	v_lshrrev_b32_e32 v133, 31, v132
	v_ashrrev_i32_e32 v132, 11, v132
	v_add_u32_e32 v203, v132, v133
	v_mad_i32_i24 v204, v203, s77, v176
	v_lshlrev_b32_e32 v211, 12, v203
	v_cmp_lt_i32_e64 s[18:19], s78, v204
	v_mov_b64_e32 v[132:133], s[56:57]
	v_add3_u32 v190, v211, v204, s79
	s_and_saveexec_b64 s[6:7], s[18:19]
	s_xor_b64 s[6:7], exec, s[6:7]
	v_add3_u32 v134, v211, v204, s79
	v_mov_b64_e32 v[132:133], s[52:53]
	s_or_saveexec_b64 s[6:7], s[6:7]
	v_lshl_add_u32 v191, v203, 8, v204
	s_xor_b64 exec, exec, s[6:7]
	v_lshl_add_u32 v134, v203, 8, v204
	s_or_b64 exec, exec, s[6:7]
	v_ashrrev_i32_e32 v135, 31, v134
	v_lshlrev_b64 v[134:135], 13, v[134:135]
	v_lshl_add_u64 v[132:133], v[132:133], 0, v[134:135]
	v_lshl_add_u64 v[132:133], v[174:175], 2, v[132:133]
	global_load_dwordx4 v[160:163], v[132:133], off
	v_or_b32_e32 v132, 16, v176
	v_mul_hi_i32 v133, v132, s76
	v_lshrrev_b32_e32 v134, 31, v133
	v_ashrrev_i32_e32 v133, 11, v133
	v_add_u32_e32 v205, v133, v134
	v_mad_i32_i24 v208, v205, s77, v132
	v_lshlrev_b32_e32 v216, 12, v205
	v_cmp_lt_i32_e64 s[16:17], s78, v208
	v_mov_b64_e32 v[132:133], s[56:57]
	v_add3_u32 v188, v216, v208, s79
	s_and_saveexec_b64 s[6:7], s[16:17]
	s_xor_b64 s[6:7], exec, s[6:7]
	v_add3_u32 v134, v216, v208, s79
	v_mov_b64_e32 v[132:133], s[52:53]
	s_or_saveexec_b64 s[6:7], s[6:7]
	v_lshl_add_u32 v189, v205, 8, v208
	s_xor_b64 exec, exec, s[6:7]
	v_lshl_add_u32 v134, v205, 8, v208
	s_or_b64 exec, exec, s[6:7]
	v_ashrrev_i32_e32 v135, 31, v134
	v_lshlrev_b64 v[134:135], 13, v[134:135]
	v_lshl_add_u64 v[132:133], v[132:133], 0, v[134:135]
	v_lshl_add_u64 v[132:133], v[174:175], 2, v[132:133]
	global_load_dwordx4 v[156:159], v[132:133], off
	v_or_b32_e32 v132, 32, v176
	v_mul_hi_i32 v133, v132, s76
	v_lshrrev_b32_e32 v134, 31, v133
	v_ashrrev_i32_e32 v133, 11, v133
	v_add_u32_e32 v209, v133, v134
	v_mad_i32_i24 v210, v209, s77, v132
	v_lshlrev_b32_e32 v219, 12, v209
; DI void epi_resid(const Acc& acc, const P& p, int brow, int bcol, int layer, int gch, bool from_input) {
;     ...
; #pragma unroll
;             for (int ai = 0; ai < 2; ++ai)
; #pragma unroll
;                 for (int m = 0; m < 4; ++m) {
;                     const int r = brow + ai * 128 + wr * 64 + m * 16 + fr;
;                     const float* sp = (from_input ? inrow(p, r) : xrow(p, r)) + c0;
;                     xv[ai][m] = *(const f32x4*)sp;
;                 }
	v_cmp_lt_i32_e64 s[14:15], s78, v210
	v_mov_b64_e32 v[132:133], s[56:57]
	v_add3_u32 v186, v219, v210, s79
	s_and_saveexec_b64 s[6:7], s[14:15]
	s_xor_b64 s[6:7], exec, s[6:7]
	v_add3_u32 v134, v219, v210, s79
	v_mov_b64_e32 v[132:133], s[52:53]
	s_or_saveexec_b64 s[6:7], s[6:7]
	v_lshl_add_u32 v187, v209, 8, v210
	s_xor_b64 exec, exec, s[6:7]
	v_lshl_add_u32 v134, v209, 8, v210
	s_or_b64 exec, exec, s[6:7]
	v_ashrrev_i32_e32 v135, 31, v134
	v_lshlrev_b64 v[134:135], 13, v[134:135]
	v_lshl_add_u64 v[132:133], v[132:133], 0, v[134:135]
	v_lshl_add_u64 v[132:133], v[174:175], 2, v[132:133]
	global_load_dwordx4 v[152:155], v[132:133], off
	v_or_b32_e32 v132, 48, v176
	v_mul_hi_i32 v133, v132, s76
	v_lshrrev_b32_e32 v134, 31, v133
	v_ashrrev_i32_e32 v133, 11, v133
	v_add_u32_e32 v212, v133, v134
	v_mad_i32_i24 v213, v212, s77, v132
	v_lshlrev_b32_e32 v222, 12, v212
	v_cmp_lt_i32_e64 s[12:13], s78, v213
	v_mov_b64_e32 v[132:133], s[56:57]
	v_add3_u32 v184, v222, v213, s79
	s_and_saveexec_b64 s[6:7], s[12:13]
	s_xor_b64 s[6:7], exec, s[6:7]
	v_add3_u32 v134, v222, v213, s79
	v_mov_b64_e32 v[132:133], s[52:53]
	s_or_saveexec_b64 s[6:7], s[6:7]
	v_lshl_add_u32 v185, v212, 8, v213
	s_xor_b64 exec, exec, s[6:7]
	v_lshl_add_u32 v134, v212, 8, v213
	s_or_b64 exec, exec, s[6:7]
	v_ashrrev_i32_e32 v135, 31, v134
	v_lshlrev_b64 v[134:135], 13, v[134:135]
	v_lshl_add_u64 v[132:133], v[132:133], 0, v[134:135]
	v_lshl_add_u64 v[132:133], v[174:175], 2, v[132:133]
	global_load_dwordx4 v[148:151], v[132:133], off
	v_add_u32_e32 v132, 0x80, v176
	v_mul_hi_i32 v133, v132, s76
	v_lshrrev_b32_e32 v134, 31, v133
	v_ashrrev_i32_e32 v133, 11, v133
	v_add_u32_e32 v214, v133, v134
	v_mad_i32_i24 v215, v214, s77, v132
	v_lshlrev_b32_e32 v225, 12, v214
	v_cmp_lt_i32_e64 s[10:11], s78, v215
	v_mov_b64_e32 v[132:133], s[56:57]
	v_add3_u32 v182, v225, v215, s79
	s_and_saveexec_b64 s[6:7], s[10:11]
	s_xor_b64 s[6:7], exec, s[6:7]
	v_add3_u32 v134, v225, v215, s79
	v_mov_b64_e32 v[132:133], s[52:53]
	s_or_saveexec_b64 s[6:7], s[6:7]
	v_lshl_add_u32 v183, v214, 8, v215
	s_xor_b64 exec, exec, s[6:7]
	v_lshl_add_u32 v134, v214, 8, v215
	s_or_b64 exec, exec, s[6:7]
	v_ashrrev_i32_e32 v135, 31, v134
	v_lshlrev_b64 v[134:135], 13, v[134:135]
	v_lshl_add_u64 v[132:133], v[132:133], 0, v[134:135]
	v_lshl_add_u64 v[132:133], v[174:175], 2, v[132:133]
	global_load_dwordx4 v[144:147], v[132:133], off
	v_add_u32_e32 v132, 0x90, v176
	v_mul_hi_i32 v133, v132, s76
	v_lshrrev_b32_e32 v134, 31, v133
	v_ashrrev_i32_e32 v133, 11, v133
	v_add_u32_e32 v217, v133, v134
	v_mad_i32_i24 v218, v217, s77, v132
	v_lshlrev_b32_e32 v226, 12, v217
	v_cmp_lt_i32_e64 s[8:9], s78, v218
	v_mov_b64_e32 v[132:133], s[56:57]
	v_add3_u32 v180, v226, v218, s79
	s_and_saveexec_b64 s[6:7], s[8:9]
	s_xor_b64 s[6:7], exec, s[6:7]
	v_add3_u32 v134, v226, v218, s79
	v_mov_b64_e32 v[132:133], s[52:53]
	s_or_saveexec_b64 s[6:7], s[6:7]
	v_lshl_add_u32 v181, v217, 8, v218
	s_xor_b64 exec, exec, s[6:7]
	v_lshl_add_u32 v134, v217, 8, v218
	s_or_b64 exec, exec, s[6:7]
	v_ashrrev_i32_e32 v135, 31, v134
	v_lshlrev_b64 v[134:135], 13, v[134:135]
	v_lshl_add_u64 v[132:133], v[132:133], 0, v[134:135]
	v_lshl_add_u64 v[132:133], v[174:175], 2, v[132:133]
	global_load_dwordx4 v[140:143], v[132:133], off
	v_add_u32_e32 v132, 0xa0, v176
	v_mul_hi_i32 v133, v132, s76
	v_lshrrev_b32_e32 v134, 31, v133
	v_ashrrev_i32_e32 v133, 11, v133
	v_add_u32_e32 v220, v133, v134
	v_mad_i32_i24 v221, v220, s77, v132
	v_lshlrev_b32_e32 v227, 12, v220
	v_cmp_lt_i32_e64 s[6:7], s78, v221
	v_mov_b64_e32 v[132:133], s[56:57]
	v_add3_u32 v178, v227, v221, s79
	s_and_saveexec_b64 s[28:29], s[6:7]
	s_xor_b64 s[54:55], exec, s[28:29]
	v_add3_u32 v134, v227, v221, s79
	v_mov_b64_e32 v[132:133], s[52:53]
	s_or_saveexec_b64 s[54:55], s[54:55]
	v_lshl_add_u32 v179, v220, 8, v221
	s_xor_b64 exec, exec, s[54:55]
	v_lshl_add_u32 v134, v220, 8, v221
	s_or_b64 exec, exec, s[54:55]
	v_ashrrev_i32_e32 v135, 31, v134
	v_lshlrev_b64 v[134:135], 13, v[134:135]
	v_lshl_add_u64 v[132:133], v[132:133], 0, v[134:135]
	v_lshl_add_u64 v[132:133], v[174:175], 2, v[132:133]
	global_load_dwordx4 v[136:139], v[132:133], off
	v_add_u32_e32 v132, 0xb0, v176
	v_mul_hi_i32 v133, v132, s76
	v_lshrrev_b32_e32 v134, 31, v133
	v_ashrrev_i32_e32 v133, 11, v133
	v_add_u32_e32 v223, v133, v134
	v_mad_i32_i24 v224, v223, s77, v132
	v_lshlrev_b32_e32 v228, 12, v223
	v_cmp_lt_i32_e32 vcc, s78, v224
	v_mov_b64_e32 v[132:133], s[56:57]
	v_add3_u32 v176, v228, v224, s79
	s_and_saveexec_b64 s[28:29], vcc
	s_xor_b64 s[54:55], exec, s[28:29]
	v_add3_u32 v134, v228, v224, s79
	v_mov_b64_e32 v[132:133], s[52:53]
	s_or_saveexec_b64 s[54:55], s[54:55]
	v_lshl_add_u32 v177, v223, 8, v224
	s_xor_b64 exec, exec, s[54:55]
	v_lshl_add_u32 v134, v223, 8, v224
	s_or_b64 exec, exec, s[54:55]
	v_ashrrev_i32_e32 v135, 31, v134
	v_lshlrev_b64 v[134:135], 13, v[134:135]
	v_lshl_add_u64 v[132:133], v[132:133], 0, v[134:135]
	v_lshl_add_u64 v[132:133], v[174:175], 2, v[132:133]
	global_load_dwordx4 v[132:135], v[132:133], off
	s_and_saveexec_b64 s[28:29], s[18:19]
	s_xor_b64 s[54:55], exec, s[28:29]
	v_add3_u32 v194, v211, v204, s79
	s_or_saveexec_b64 s[54:55], s[54:55]
	v_mov_b64_e32 v[196:197], s[24:25]
	s_xor_b64 exec, exec, s[54:55]
	v_lshl_add_u32 v194, v203, 8, v204
	v_mov_b64_e32 v[196:197], s[36:37]
	s_or_b64 exec, exec, s[54:55]
	v_ashrrev_i32_e32 v195, 31, v194
	s_waitcnt vmcnt(0)
; DI void epi_resid(const Acc& acc, const P& p, int brow, int bcol, int layer, int gch, bool from_input) {
;     ...
;     for (int bj = 0; bj < 2; ++bj)
; #pragma unroll
;         for (int n = 0; n < 2; ++n) {
;             const int c0 = bcol + bj * 128 + wc * 32 + n * 16 + fq * 4;
;             const f32x4 g = *(const f32x4*)(gate + c0);
;             f32x4 xv[2][4];
; #pragma unroll
;             for (int ai = 0; ai < 2; ++ai)
; #pragma unroll
;                 for (int m = 0; m < 4; ++m) {
;                     const int r = brow + ai * 128 + wr * 64 + m * 16 + fr;
;                     const float* sp = (from_input ? inrow(p, r) : xrow(p, r)) + c0;
;                     xv[ai][m] = *(const f32x4*)sp;
;                 }
;             __builtin_amdgcn_sched_barrier(0);
; #pragma unroll
;             for (int ai = 0; ai < 2; ++ai)
; #pragma unroll
;                 for (int m = 0; m < 4; ++m) {
;                     const int r = brow + ai * 128 + wr * 64 + m * 16 + fr;
;                     *(f32x4*)(xrow(p, r) + c0) = xv[ai][m] + g * acc[ai][bj][m][n];
;                 }
;             __builtin_amdgcn_sched_barrier(0);
	v_pk_fma_f32 v[124:125], v[124:125], v[128:129], v[160:161]
	v_lshlrev_b64 v[160:161], 13, v[194:195]
	v_lshl_add_u64 v[160:161], v[196:197], 0, v[160:161]
	v_pk_fma_f32 v[126:127], v[126:127], v[130:131], v[162:163]
	v_lshl_add_u64 v[160:161], v[174:175], 2, v[160:161]
	global_store_dwordx4 v[160:161], v[124:127], off
	s_and_saveexec_b64 s[28:29], s[16:17]
	s_xor_b64 s[54:55], exec, s[28:29]
	v_add3_u32 v124, v216, v208, s79
	s_or_saveexec_b64 s[54:55], s[54:55]
	v_mov_b64_e32 v[126:127], s[24:25]
	s_xor_b64 exec, exec, s[54:55]
	v_lshl_add_u32 v124, v205, 8, v208
	v_mov_b64_e32 v[126:127], s[36:37]
	s_or_b64 exec, exec, s[54:55]
	v_ashrrev_i32_e32 v125, 31, v124
	v_lshlrev_b64 v[124:125], 13, v[124:125]
	v_lshl_add_u64 v[124:125], v[126:127], 0, v[124:125]
	v_pk_fma_f32 v[122:123], v[122:123], v[130:131], v[158:159]
	v_pk_fma_f32 v[120:121], v[120:121], v[128:129], v[156:157]
	v_lshl_add_u64 v[124:125], v[174:175], 2, v[124:125]
	global_store_dwordx4 v[124:125], v[120:123], off
	s_and_saveexec_b64 s[28:29], s[14:15]
	s_xor_b64 s[54:55], exec, s[28:29]
	v_add3_u32 v120, v219, v210, s79
	s_or_saveexec_b64 s[54:55], s[54:55]
	v_mov_b64_e32 v[122:123], s[24:25]
	s_xor_b64 exec, exec, s[54:55]
	v_lshl_add_u32 v120, v209, 8, v210
	v_mov_b64_e32 v[122:123], s[36:37]
	s_or_b64 exec, exec, s[54:55]
	v_ashrrev_i32_e32 v121, 31, v120
	v_lshlrev_b64 v[120:121], 13, v[120:121]
	v_lshl_add_u64 v[120:121], v[122:123], 0, v[120:121]
	v_pk_fma_f32 v[118:119], v[118:119], v[130:131], v[154:155]
	v_pk_fma_f32 v[116:117], v[116:117], v[128:129], v[152:153]
	v_lshl_add_u64 v[120:121], v[174:175], 2, v[120:121]
	global_store_dwordx4 v[120:121], v[116:119], off
	s_and_saveexec_b64 s[28:29], s[12:13]
	s_xor_b64 s[54:55], exec, s[28:29]
	v_add3_u32 v116, v222, v213, s79
	s_or_saveexec_b64 s[54:55], s[54:55]
	v_mov_b64_e32 v[118:119], s[24:25]
	s_xor_b64 exec, exec, s[54:55]
	v_lshl_add_u32 v116, v212, 8, v213
	v_mov_b64_e32 v[118:119], s[36:37]
	s_or_b64 exec, exec, s[54:55]
	v_ashrrev_i32_e32 v117, 31, v116
	v_lshlrev_b64 v[116:117], 13, v[116:117]
	v_lshl_add_u64 v[116:117], v[118:119], 0, v[116:117]
	v_pk_fma_f32 v[114:115], v[114:115], v[130:131], v[150:151]
	v_pk_fma_f32 v[112:113], v[112:113], v[128:129], v[148:149]
	v_lshl_add_u64 v[116:117], v[174:175], 2, v[116:117]
	global_store_dwordx4 v[116:117], v[112:115], off
	s_and_saveexec_b64 s[28:29], s[10:11]
	s_xor_b64 s[54:55], exec, s[28:29]
	v_add3_u32 v112, v225, v215, s79
	s_or_saveexec_b64 s[54:55], s[54:55]
	v_mov_b64_e32 v[114:115], s[24:25]
	s_xor_b64 exec, exec, s[54:55]
	v_lshl_add_u32 v112, v214, 8, v215
	v_mov_b64_e32 v[114:115], s[36:37]
	s_or_b64 exec, exec, s[54:55]
	v_ashrrev_i32_e32 v113, 31, v112
	v_lshlrev_b64 v[112:113], 13, v[112:113]
	v_lshl_add_u64 v[112:113], v[114:115], 0, v[112:113]
	v_pk_fma_f32 v[110:111], v[110:111], v[130:131], v[146:147]
	v_pk_fma_f32 v[108:109], v[108:109], v[128:129], v[144:145]
	v_lshl_add_u64 v[112:113], v[174:175], 2, v[112:113]
	global_store_dwordx4 v[112:113], v[108:111], off
	s_and_saveexec_b64 s[28:29], s[8:9]
	s_xor_b64 s[54:55], exec, s[28:29]
	v_add3_u32 v108, v226, v218, s79
	s_or_saveexec_b64 s[54:55], s[54:55]
	v_mov_b64_e32 v[110:111], s[24:25]
	s_xor_b64 exec, exec, s[54:55]
	v_lshl_add_u32 v108, v217, 8, v218
	v_mov_b64_e32 v[110:111], s[36:37]
	s_or_b64 exec, exec, s[54:55]
	v_ashrrev_i32_e32 v109, 31, v108
	v_lshlrev_b64 v[108:109], 13, v[108:109]
	v_lshl_add_u64 v[108:109], v[110:111], 0, v[108:109]
	v_pk_fma_f32 v[106:107], v[106:107], v[130:131], v[142:143]
	v_pk_fma_f32 v[104:105], v[104:105], v[128:129], v[140:141]
	v_lshl_add_u64 v[108:109], v[174:175], 2, v[108:109]
	global_store_dwordx4 v[108:109], v[104:107], off
	s_and_saveexec_b64 s[28:29], s[6:7]
	s_xor_b64 s[54:55], exec, s[28:29]
	v_add3_u32 v104, v227, v221, s79
	s_or_saveexec_b64 s[54:55], s[54:55]
	v_mov_b64_e32 v[106:107], s[24:25]
	s_xor_b64 exec, exec, s[54:55]
	v_lshl_add_u32 v104, v220, 8, v221
	v_mov_b64_e32 v[106:107], s[36:37]
	s_or_b64 exec, exec, s[54:55]
	v_ashrrev_i32_e32 v105, 31, v104
	v_lshlrev_b64 v[104:105], 13, v[104:105]
	v_lshl_add_u64 v[104:105], v[106:107], 0, v[104:105]
	v_pk_fma_f32 v[102:103], v[102:103], v[130:131], v[138:139]
	v_pk_fma_f32 v[100:101], v[100:101], v[128:129], v[136:137]
	v_lshl_add_u64 v[104:105], v[174:175], 2, v[104:105]
	global_store_dwordx4 v[104:105], v[100:103], off
	s_and_saveexec_b64 s[28:29], vcc
	s_xor_b64 s[54:55], exec, s[28:29]
	v_add3_u32 v100, v228, v224, s79
	s_or_saveexec_b64 s[54:55], s[54:55]
	v_mov_b64_e32 v[102:103], s[24:25]
	s_xor_b64 exec, exec, s[54:55]
	v_lshl_add_u32 v100, v223, 8, v224
	v_mov_b64_e32 v[102:103], s[36:37]
	s_or_b64 exec, exec, s[54:55]
	v_ashrrev_i32_e32 v101, 31, v100
	v_lshlrev_b64 v[100:101], 13, v[100:101]
	v_lshl_add_u64 v[100:101], v[102:103], 0, v[100:101]
	v_pk_fma_f32 v[98:99], v[98:99], v[130:131], v[134:135]
	v_pk_fma_f32 v[96:97], v[96:97], v[128:129], v[132:133]
	v_lshl_add_u64 v[100:101], v[174:175], 2, v[100:101]
	global_store_dwordx4 v[100:101], v[96:99], off
	global_load_dwordx4 v[96:99], v[192:193], off offset:64
	v_mov_b64_e32 v[100:101], s[56:57]
	s_and_saveexec_b64 s[28:29], s[18:19]
	s_xor_b64 s[54:55], exec, s[28:29]
	v_add3_u32 v102, v211, v204, s79
	v_mov_b64_e32 v[100:101], s[52:53]
	s_andn2_saveexec_b64 s[54:55], s[54:55]
	v_lshl_add_u32 v102, v203, 8, v204
	s_or_b64 exec, exec, s[54:55]
	v_ashrrev_i32_e32 v103, 31, v102
	v_lshlrev_b64 v[102:103], 13, v[102:103]
	v_lshl_add_u64 v[100:101], v[100:101], 0, v[102:103]
	v_lshl_add_u64 v[100:101], v[174:175], 2, v[100:101]
	global_load_dwordx4 v[128:131], v[100:101], off offset:64
	v_mov_b64_e32 v[100:101], s[56:57]
; DI void epi_resid(const Acc& acc, const P& p, int brow, int bcol, int layer, int gch, bool from_input) {
;     ...
;     for (int bj = 0; bj < 2; ++bj)
; #pragma unroll
;         for (int n = 0; n < 2; ++n) {
;             const int c0 = bcol + bj * 128 + wc * 32 + n * 16 + fq * 4;
;             const f32x4 g = *(const f32x4*)(gate + c0);
;             f32x4 xv[2][4];
; #pragma unroll
;             for (int ai = 0; ai < 2; ++ai)
; #pragma unroll
;                 for (int m = 0; m < 4; ++m) {
;                     const int r = brow + ai * 128 + wr * 64 + m * 16 + fr;
;                     const float* sp = (from_input ? inrow(p, r) : xrow(p, r)) + c0;
;                     xv[ai][m] = *(const f32x4*)sp;
;                 }
;             __builtin_amdgcn_sched_barrier(0);
; #pragma unroll
;             for (int ai = 0; ai < 2; ++ai)
; #pragma unroll
;                 for (int m = 0; m < 4; ++m) {
;                     const int r = brow + ai * 128 + wr * 64 + m * 16 + fr;
;                     *(f32x4*)(xrow(p, r) + c0) = xv[ai][m] + g * acc[ai][bj][m][n];
;                 }
;             __builtin_amdgcn_sched_barrier(0);
	s_and_saveexec_b64 s[28:29], s[16:17]
	s_xor_b64 s[54:55], exec, s[28:29]
	v_add3_u32 v102, v216, v208, s79
	v_mov_b64_e32 v[100:101], s[52:53]
	s_andn2_saveexec_b64 s[54:55], s[54:55]
	v_lshl_add_u32 v102, v205, 8, v208
	s_or_b64 exec, exec, s[54:55]
	v_ashrrev_i32_e32 v103, 31, v102
	v_lshlrev_b64 v[102:103], 13, v[102:103]
	v_lshl_add_u64 v[100:101], v[100:101], 0, v[102:103]
	v_lshl_add_u64 v[100:101], v[174:175], 2, v[100:101]
	global_load_dwordx4 v[124:127], v[100:101], off offset:64
	v_mov_b64_e32 v[100:101], s[56:57]
	s_and_saveexec_b64 s[28:29], s[14:15]
	s_xor_b64 s[54:55], exec, s[28:29]
	v_add3_u32 v102, v219, v210, s79
	v_mov_b64_e32 v[100:101], s[52:53]
	s_andn2_saveexec_b64 s[54:55], s[54:55]
	v_lshl_add_u32 v102, v209, 8, v210
	s_or_b64 exec, exec, s[54:55]
	v_ashrrev_i32_e32 v103, 31, v102
	v_lshlrev_b64 v[102:103], 13, v[102:103]
	v_lshl_add_u64 v[100:101], v[100:101], 0, v[102:103]
	v_lshl_add_u64 v[100:101], v[174:175], 2, v[100:101]
	global_load_dwordx4 v[120:123], v[100:101], off offset:64
	v_mov_b64_e32 v[100:101], s[56:57]
	s_and_saveexec_b64 s[28:29], s[12:13]
	s_xor_b64 s[54:55], exec, s[28:29]
	v_add3_u32 v102, v222, v213, s79
	v_mov_b64_e32 v[100:101], s[52:53]
	s_andn2_saveexec_b64 s[54:55], s[54:55]
	v_lshl_add_u32 v102, v212, 8, v213
	s_or_b64 exec, exec, s[54:55]
	v_ashrrev_i32_e32 v103, 31, v102
	v_lshlrev_b64 v[102:103], 13, v[102:103]
	v_lshl_add_u64 v[100:101], v[100:101], 0, v[102:103]
	v_lshl_add_u64 v[100:101], v[174:175], 2, v[100:101]
	global_load_dwordx4 v[116:119], v[100:101], off offset:64
	v_mov_b64_e32 v[100:101], s[56:57]
	s_and_saveexec_b64 s[28:29], s[10:11]
	s_xor_b64 s[54:55], exec, s[28:29]
	v_add3_u32 v102, v225, v215, s79
	v_mov_b64_e32 v[100:101], s[52:53]
	s_andn2_saveexec_b64 s[54:55], s[54:55]
	v_lshl_add_u32 v102, v214, 8, v215
	s_or_b64 exec, exec, s[54:55]
	v_ashrrev_i32_e32 v103, 31, v102
	v_lshlrev_b64 v[102:103], 13, v[102:103]
	v_lshl_add_u64 v[100:101], v[100:101], 0, v[102:103]
	v_lshl_add_u64 v[100:101], v[174:175], 2, v[100:101]
	global_load_dwordx4 v[112:115], v[100:101], off offset:64
	v_mov_b64_e32 v[100:101], s[56:57]
	s_and_saveexec_b64 s[28:29], s[8:9]
	s_xor_b64 s[54:55], exec, s[28:29]
	v_add3_u32 v102, v226, v218, s79
	v_mov_b64_e32 v[100:101], s[52:53]
	s_andn2_saveexec_b64 s[54:55], s[54:55]
	v_lshl_add_u32 v102, v217, 8, v218
	s_or_b64 exec, exec, s[54:55]
	v_ashrrev_i32_e32 v103, 31, v102
	v_lshlrev_b64 v[102:103], 13, v[102:103]
	v_lshl_add_u64 v[100:101], v[100:101], 0, v[102:103]
	v_lshl_add_u64 v[100:101], v[174:175], 2, v[100:101]
	global_load_dwordx4 v[108:111], v[100:101], off offset:64
	v_mov_b64_e32 v[100:101], s[56:57]
	s_and_saveexec_b64 s[28:29], s[6:7]
	s_xor_b64 s[54:55], exec, s[28:29]
	v_add3_u32 v102, v227, v221, s79
	v_mov_b64_e32 v[100:101], s[52:53]
	s_andn2_saveexec_b64 s[54:55], s[54:55]
	v_lshl_add_u32 v102, v220, 8, v221
	s_or_b64 exec, exec, s[54:55]
	v_ashrrev_i32_e32 v103, 31, v102
	v_lshlrev_b64 v[102:103], 13, v[102:103]
	v_lshl_add_u64 v[100:101], v[100:101], 0, v[102:103]
	v_lshl_add_u64 v[100:101], v[174:175], 2, v[100:101]
	global_load_dwordx4 v[104:107], v[100:101], off offset:64
	v_mov_b64_e32 v[100:101], s[56:57]
	s_and_saveexec_b64 s[28:29], vcc
	s_xor_b64 s[54:55], exec, s[28:29]
	v_add3_u32 v102, v228, v224, s79
	v_mov_b64_e32 v[100:101], s[52:53]
	s_andn2_saveexec_b64 s[54:55], s[54:55]
	v_lshl_add_u32 v102, v223, 8, v224
	s_or_b64 exec, exec, s[54:55]
	v_ashrrev_i32_e32 v103, 31, v102
	v_lshlrev_b64 v[102:103], 13, v[102:103]
	v_lshl_add_u64 v[100:101], v[100:101], 0, v[102:103]
	v_lshl_add_u64 v[100:101], v[174:175], 2, v[100:101]
	global_load_dwordx4 v[100:103], v[100:101], off offset:64
	s_and_saveexec_b64 s[28:29], s[18:19]
	s_xor_b64 s[54:55], exec, s[28:29]
	v_add3_u32 v132, v211, v204, s79
	s_or_saveexec_b64 s[54:55], s[54:55]
	v_mov_b64_e32 v[134:135], s[24:25]
	s_xor_b64 exec, exec, s[54:55]
	v_lshl_add_u32 v132, v203, 8, v204
	v_mov_b64_e32 v[134:135], s[36:37]
	s_or_b64 exec, exec, s[54:55]
	v_ashrrev_i32_e32 v133, 31, v132
	s_waitcnt vmcnt(0)
	v_pk_fma_f32 v[92:93], v[92:93], v[96:97], v[128:129]
	v_lshlrev_b64 v[128:129], 13, v[132:133]
	v_lshl_add_u64 v[128:129], v[134:135], 0, v[128:129]
	v_pk_fma_f32 v[94:95], v[94:95], v[98:99], v[130:131]
	v_lshl_add_u64 v[128:129], v[174:175], 2, v[128:129]
	global_store_dwordx4 v[128:129], v[92:95], off offset:64
	s_and_saveexec_b64 s[28:29], s[16:17]
	s_xor_b64 s[54:55], exec, s[28:29]
	v_add3_u32 v92, v216, v208, s79
	s_or_saveexec_b64 s[54:55], s[54:55]
	v_mov_b64_e32 v[94:95], s[24:25]
	s_xor_b64 exec, exec, s[54:55]
	v_lshl_add_u32 v92, v205, 8, v208
	v_mov_b64_e32 v[94:95], s[36:37]
	s_or_b64 exec, exec, s[54:55]
	v_ashrrev_i32_e32 v93, 31, v92
	v_lshlrev_b64 v[92:93], 13, v[92:93]
	v_lshl_add_u64 v[92:93], v[94:95], 0, v[92:93]
	v_pk_fma_f32 v[90:91], v[90:91], v[98:99], v[126:127]
	v_pk_fma_f32 v[88:89], v[88:89], v[96:97], v[124:125]
	v_lshl_add_u64 v[92:93], v[174:175], 2, v[92:93]
	global_store_dwordx4 v[92:93], v[88:91], off offset:64
	s_and_saveexec_b64 s[28:29], s[14:15]
	s_xor_b64 s[54:55], exec, s[28:29]
	v_add3_u32 v88, v219, v210, s79
	s_or_saveexec_b64 s[54:55], s[54:55]
	v_mov_b64_e32 v[90:91], s[24:25]
	s_xor_b64 exec, exec, s[54:55]
	v_lshl_add_u32 v88, v209, 8, v210
	v_mov_b64_e32 v[90:91], s[36:37]
	s_or_b64 exec, exec, s[54:55]
	v_ashrrev_i32_e32 v89, 31, v88
	v_lshlrev_b64 v[88:89], 13, v[88:89]
	v_lshl_add_u64 v[88:89], v[90:91], 0, v[88:89]
	v_pk_fma_f32 v[86:87], v[86:87], v[98:99], v[122:123]
	v_pk_fma_f32 v[84:85], v[84:85], v[96:97], v[120:121]
	v_lshl_add_u64 v[88:89], v[174:175], 2, v[88:89]
	global_store_dwordx4 v[88:89], v[84:87], off offset:64
; DI void epi_resid(const Acc& acc, const P& p, int brow, int bcol, int layer, int gch, bool from_input) {
;     ...
;     for (int bj = 0; bj < 2; ++bj)
; #pragma unroll
;         for (int n = 0; n < 2; ++n) {
;             const int c0 = bcol + bj * 128 + wc * 32 + n * 16 + fq * 4;
;             const f32x4 g = *(const f32x4*)(gate + c0);
;             f32x4 xv[2][4];
; #pragma unroll
;             for (int ai = 0; ai < 2; ++ai)
; #pragma unroll
;                 for (int m = 0; m < 4; ++m) {
;                     const int r = brow + ai * 128 + wr * 64 + m * 16 + fr;
;                     const float* sp = (from_input ? inrow(p, r) : xrow(p, r)) + c0;
;                     xv[ai][m] = *(const f32x4*)sp;
;                 }
;             __builtin_amdgcn_sched_barrier(0);
; #pragma unroll
;             for (int ai = 0; ai < 2; ++ai)
; #pragma unroll
;                 for (int m = 0; m < 4; ++m) {
;                     const int r = brow + ai * 128 + wr * 64 + m * 16 + fr;
;                     *(f32x4*)(xrow(p, r) + c0) = xv[ai][m] + g * acc[ai][bj][m][n];
;                 }
;             __builtin_amdgcn_sched_barrier(0);
	s_and_saveexec_b64 s[28:29], s[12:13]
	s_xor_b64 s[54:55], exec, s[28:29]
	v_add3_u32 v84, v222, v213, s79
	s_or_saveexec_b64 s[54:55], s[54:55]
	v_mov_b64_e32 v[86:87], s[24:25]
	s_xor_b64 exec, exec, s[54:55]
	v_lshl_add_u32 v84, v212, 8, v213
	v_mov_b64_e32 v[86:87], s[36:37]
	s_or_b64 exec, exec, s[54:55]
	v_ashrrev_i32_e32 v85, 31, v84
	v_lshlrev_b64 v[84:85], 13, v[84:85]
	v_lshl_add_u64 v[84:85], v[86:87], 0, v[84:85]
	v_pk_fma_f32 v[82:83], v[82:83], v[98:99], v[118:119]
	v_pk_fma_f32 v[80:81], v[80:81], v[96:97], v[116:117]
	v_lshl_add_u64 v[84:85], v[174:175], 2, v[84:85]
	global_store_dwordx4 v[84:85], v[80:83], off offset:64
	s_and_saveexec_b64 s[28:29], s[10:11]
	s_xor_b64 s[54:55], exec, s[28:29]
	v_add3_u32 v80, v225, v215, s79
	s_or_saveexec_b64 s[54:55], s[54:55]
	v_mov_b64_e32 v[82:83], s[24:25]
	s_xor_b64 exec, exec, s[54:55]
	v_lshl_add_u32 v80, v214, 8, v215
	v_mov_b64_e32 v[82:83], s[36:37]
	s_or_b64 exec, exec, s[54:55]
	v_ashrrev_i32_e32 v81, 31, v80
	v_lshlrev_b64 v[80:81], 13, v[80:81]
	v_lshl_add_u64 v[80:81], v[82:83], 0, v[80:81]
	v_pk_fma_f32 v[78:79], v[78:79], v[98:99], v[114:115]
	v_pk_fma_f32 v[76:77], v[76:77], v[96:97], v[112:113]
	v_lshl_add_u64 v[80:81], v[174:175], 2, v[80:81]
	global_store_dwordx4 v[80:81], v[76:79], off offset:64
	s_and_saveexec_b64 s[28:29], s[8:9]
	s_xor_b64 s[54:55], exec, s[28:29]
	v_add3_u32 v76, v226, v218, s79
	s_or_saveexec_b64 s[54:55], s[54:55]
	v_mov_b64_e32 v[78:79], s[24:25]
	s_xor_b64 exec, exec, s[54:55]
	v_lshl_add_u32 v76, v217, 8, v218
	v_mov_b64_e32 v[78:79], s[36:37]
	s_or_b64 exec, exec, s[54:55]
	v_ashrrev_i32_e32 v77, 31, v76
	v_lshlrev_b64 v[76:77], 13, v[76:77]
	v_lshl_add_u64 v[76:77], v[78:79], 0, v[76:77]
	v_pk_fma_f32 v[74:75], v[74:75], v[98:99], v[110:111]
	v_pk_fma_f32 v[72:73], v[72:73], v[96:97], v[108:109]
	v_lshl_add_u64 v[76:77], v[174:175], 2, v[76:77]
	global_store_dwordx4 v[76:77], v[72:75], off offset:64
	s_and_saveexec_b64 s[28:29], s[6:7]
	s_xor_b64 s[54:55], exec, s[28:29]
	v_add3_u32 v72, v227, v221, s79
	s_or_saveexec_b64 s[54:55], s[54:55]
	v_mov_b64_e32 v[74:75], s[24:25]
	s_xor_b64 exec, exec, s[54:55]
	v_lshl_add_u32 v72, v220, 8, v221
	v_mov_b64_e32 v[74:75], s[36:37]
	s_or_b64 exec, exec, s[54:55]
	v_ashrrev_i32_e32 v73, 31, v72
	v_lshlrev_b64 v[72:73], 13, v[72:73]
	v_lshl_add_u64 v[72:73], v[74:75], 0, v[72:73]
	v_pk_fma_f32 v[70:71], v[70:71], v[98:99], v[106:107]
	v_pk_fma_f32 v[68:69], v[68:69], v[96:97], v[104:105]
	v_lshl_add_u64 v[72:73], v[174:175], 2, v[72:73]
	global_store_dwordx4 v[72:73], v[68:71], off offset:64
	s_and_saveexec_b64 s[28:29], vcc
	s_xor_b64 s[54:55], exec, s[28:29]
	v_add3_u32 v68, v228, v224, s79
	s_or_saveexec_b64 s[54:55], s[54:55]
	v_mov_b64_e32 v[70:71], s[24:25]
	s_xor_b64 exec, exec, s[54:55]
	v_lshl_add_u32 v68, v223, 8, v224
	v_mov_b64_e32 v[70:71], s[36:37]
	s_or_b64 exec, exec, s[54:55]
	v_ashrrev_i32_e32 v69, 31, v68
	v_lshlrev_b64 v[68:69], 13, v[68:69]
	v_lshl_add_u64 v[68:69], v[70:71], 0, v[68:69]
	v_pk_fma_f32 v[66:67], v[66:67], v[98:99], v[102:103]
	v_pk_fma_f32 v[64:65], v[64:65], v[96:97], v[100:101]
	v_lshl_add_u64 v[68:69], v[174:175], 2, v[68:69]
	global_store_dwordx4 v[68:69], v[64:67], off offset:64
	global_load_dwordx4 v[64:67], v[192:193], off offset:512
	v_mov_b64_e32 v[68:69], s[56:57]
	s_and_saveexec_b64 s[28:29], s[18:19]
	s_xor_b64 s[54:55], exec, s[28:29]
	v_add3_u32 v70, v211, v204, s79
	v_mov_b64_e32 v[68:69], s[52:53]
	s_andn2_saveexec_b64 s[54:55], s[54:55]
	v_lshl_add_u32 v70, v203, 8, v204
	s_or_b64 exec, exec, s[54:55]
	v_ashrrev_i32_e32 v71, 31, v70
	v_lshlrev_b64 v[70:71], 13, v[70:71]
	v_lshl_add_u64 v[68:69], v[68:69], 0, v[70:71]
	v_lshl_add_u64 v[68:69], v[174:175], 2, v[68:69]
	global_load_dwordx4 v[96:99], v[68:69], off offset:512
	v_mov_b64_e32 v[68:69], s[56:57]
	s_and_saveexec_b64 s[28:29], s[16:17]
	s_xor_b64 s[54:55], exec, s[28:29]
	v_add3_u32 v70, v216, v208, s79
	v_mov_b64_e32 v[68:69], s[52:53]
	s_andn2_saveexec_b64 s[54:55], s[54:55]
	v_lshl_add_u32 v70, v205, 8, v208
	s_or_b64 exec, exec, s[54:55]
	v_ashrrev_i32_e32 v71, 31, v70
	v_lshlrev_b64 v[70:71], 13, v[70:71]
	v_lshl_add_u64 v[68:69], v[68:69], 0, v[70:71]
	v_lshl_add_u64 v[68:69], v[174:175], 2, v[68:69]
	global_load_dwordx4 v[92:95], v[68:69], off offset:512
	v_mov_b64_e32 v[68:69], s[56:57]
	s_and_saveexec_b64 s[28:29], s[14:15]
	s_xor_b64 s[54:55], exec, s[28:29]
	v_add3_u32 v70, v219, v210, s79
	v_mov_b64_e32 v[68:69], s[52:53]
	s_andn2_saveexec_b64 s[54:55], s[54:55]
	v_lshl_add_u32 v70, v209, 8, v210
	s_or_b64 exec, exec, s[54:55]
	v_ashrrev_i32_e32 v71, 31, v70
	v_lshlrev_b64 v[70:71], 13, v[70:71]
	v_lshl_add_u64 v[68:69], v[68:69], 0, v[70:71]
	v_lshl_add_u64 v[68:69], v[174:175], 2, v[68:69]
	global_load_dwordx4 v[88:91], v[68:69], off offset:512
	v_mov_b64_e32 v[68:69], s[56:57]
	s_and_saveexec_b64 s[28:29], s[12:13]
	s_xor_b64 s[54:55], exec, s[28:29]
	v_add3_u32 v70, v222, v213, s79
	v_mov_b64_e32 v[68:69], s[52:53]
	s_andn2_saveexec_b64 s[54:55], s[54:55]
	v_lshl_add_u32 v70, v212, 8, v213
	s_or_b64 exec, exec, s[54:55]
	v_ashrrev_i32_e32 v71, 31, v70
	v_lshlrev_b64 v[70:71], 13, v[70:71]
	v_lshl_add_u64 v[68:69], v[68:69], 0, v[70:71]
	v_lshl_add_u64 v[68:69], v[174:175], 2, v[68:69]
	global_load_dwordx4 v[84:87], v[68:69], off offset:512
	v_mov_b64_e32 v[68:69], s[56:57]
	s_and_saveexec_b64 s[28:29], s[10:11]
	s_xor_b64 s[54:55], exec, s[28:29]
	v_add3_u32 v70, v225, v215, s79
	v_mov_b64_e32 v[68:69], s[52:53]
	s_andn2_saveexec_b64 s[54:55], s[54:55]
	v_lshl_add_u32 v70, v214, 8, v215
	s_or_b64 exec, exec, s[54:55]
	v_ashrrev_i32_e32 v71, 31, v70
; DI void epi_resid(const Acc& acc, const P& p, int brow, int bcol, int layer, int gch, bool from_input) {
;     ...
;     for (int bj = 0; bj < 2; ++bj)
; #pragma unroll
;         for (int n = 0; n < 2; ++n) {
;             const int c0 = bcol + bj * 128 + wc * 32 + n * 16 + fq * 4;
;             const f32x4 g = *(const f32x4*)(gate + c0);
;             f32x4 xv[2][4];
; #pragma unroll
;             for (int ai = 0; ai < 2; ++ai)
; #pragma unroll
;                 for (int m = 0; m < 4; ++m) {
;                     const int r = brow + ai * 128 + wr * 64 + m * 16 + fr;
;                     const float* sp = (from_input ? inrow(p, r) : xrow(p, r)) + c0;
;                     xv[ai][m] = *(const f32x4*)sp;
;                 }
;             __builtin_amdgcn_sched_barrier(0);
; #pragma unroll
;             for (int ai = 0; ai < 2; ++ai)
; #pragma unroll
;                 for (int m = 0; m < 4; ++m) {
;                     const int r = brow + ai * 128 + wr * 64 + m * 16 + fr;
;                     *(f32x4*)(xrow(p, r) + c0) = xv[ai][m] + g * acc[ai][bj][m][n];
;                 }
;             __builtin_amdgcn_sched_barrier(0);
	v_lshlrev_b64 v[70:71], 13, v[70:71]
	v_lshl_add_u64 v[68:69], v[68:69], 0, v[70:71]
	v_lshl_add_u64 v[68:69], v[174:175], 2, v[68:69]
	global_load_dwordx4 v[80:83], v[68:69], off offset:512
	v_mov_b64_e32 v[68:69], s[56:57]
	s_and_saveexec_b64 s[28:29], s[8:9]
	s_xor_b64 s[54:55], exec, s[28:29]
	v_add3_u32 v70, v226, v218, s79
	v_mov_b64_e32 v[68:69], s[52:53]
	s_andn2_saveexec_b64 s[54:55], s[54:55]
	v_lshl_add_u32 v70, v217, 8, v218
	s_or_b64 exec, exec, s[54:55]
	v_ashrrev_i32_e32 v71, 31, v70
	v_lshlrev_b64 v[70:71], 13, v[70:71]
	v_lshl_add_u64 v[68:69], v[68:69], 0, v[70:71]
	v_lshl_add_u64 v[68:69], v[174:175], 2, v[68:69]
	global_load_dwordx4 v[76:79], v[68:69], off offset:512
	v_mov_b64_e32 v[68:69], s[56:57]
	s_and_saveexec_b64 s[28:29], s[6:7]
	s_xor_b64 s[54:55], exec, s[28:29]
	v_add3_u32 v70, v227, v221, s79
	v_mov_b64_e32 v[68:69], s[52:53]
	s_andn2_saveexec_b64 s[54:55], s[54:55]
	v_lshl_add_u32 v70, v220, 8, v221
	s_or_b64 exec, exec, s[54:55]
	v_ashrrev_i32_e32 v71, 31, v70
	v_lshlrev_b64 v[70:71], 13, v[70:71]
	v_lshl_add_u64 v[68:69], v[68:69], 0, v[70:71]
	v_lshl_add_u64 v[68:69], v[174:175], 2, v[68:69]
	global_load_dwordx4 v[72:75], v[68:69], off offset:512
	v_mov_b64_e32 v[68:69], s[56:57]
	s_and_saveexec_b64 s[28:29], vcc
	s_xor_b64 s[54:55], exec, s[28:29]
	v_add3_u32 v70, v228, v224, s79
	v_mov_b64_e32 v[68:69], s[52:53]
	s_andn2_saveexec_b64 s[54:55], s[54:55]
	v_lshl_add_u32 v70, v223, 8, v224
	s_or_b64 exec, exec, s[54:55]
	v_ashrrev_i32_e32 v71, 31, v70
	v_lshlrev_b64 v[70:71], 13, v[70:71]
	v_lshl_add_u64 v[68:69], v[68:69], 0, v[70:71]
	v_lshl_add_u64 v[68:69], v[174:175], 2, v[68:69]
	global_load_dwordx4 v[68:71], v[68:69], off offset:512
	s_and_saveexec_b64 s[28:29], s[18:19]
	s_xor_b64 s[54:55], exec, s[28:29]
	v_add3_u32 v100, v211, v204, s79
	s_or_saveexec_b64 s[54:55], s[54:55]
	v_mov_b64_e32 v[102:103], s[24:25]
	s_xor_b64 exec, exec, s[54:55]
	v_lshl_add_u32 v100, v203, 8, v204
	v_mov_b64_e32 v[102:103], s[36:37]
	s_or_b64 exec, exec, s[54:55]
	v_ashrrev_i32_e32 v101, 31, v100
	s_waitcnt vmcnt(0)
	v_pk_fma_f32 v[60:61], v[60:61], v[64:65], v[96:97]
	v_lshlrev_b64 v[96:97], 13, v[100:101]
	v_lshl_add_u64 v[96:97], v[102:103], 0, v[96:97]
	v_pk_fma_f32 v[62:63], v[62:63], v[66:67], v[98:99]
	v_lshl_add_u64 v[96:97], v[174:175], 2, v[96:97]
	global_store_dwordx4 v[96:97], v[60:63], off offset:512
	s_and_saveexec_b64 s[28:29], s[16:17]
	s_xor_b64 s[54:55], exec, s[28:29]
	v_add3_u32 v60, v216, v208, s79
	s_or_saveexec_b64 s[54:55], s[54:55]
	v_mov_b64_e32 v[62:63], s[24:25]
	s_xor_b64 exec, exec, s[54:55]
	v_lshl_add_u32 v60, v205, 8, v208
	v_mov_b64_e32 v[62:63], s[36:37]
	s_or_b64 exec, exec, s[54:55]
	v_ashrrev_i32_e32 v61, 31, v60
	v_lshlrev_b64 v[60:61], 13, v[60:61]
	v_lshl_add_u64 v[60:61], v[62:63], 0, v[60:61]
	v_pk_fma_f32 v[58:59], v[58:59], v[66:67], v[94:95]
	v_pk_fma_f32 v[56:57], v[56:57], v[64:65], v[92:93]
	v_lshl_add_u64 v[60:61], v[174:175], 2, v[60:61]
	global_store_dwordx4 v[60:61], v[56:59], off offset:512
	s_and_saveexec_b64 s[28:29], s[14:15]
	s_xor_b64 s[54:55], exec, s[28:29]
	v_add3_u32 v56, v219, v210, s79
	s_or_saveexec_b64 s[54:55], s[54:55]
	v_mov_b64_e32 v[58:59], s[24:25]
	s_xor_b64 exec, exec, s[54:55]
	v_lshl_add_u32 v56, v209, 8, v210
	v_mov_b64_e32 v[58:59], s[36:37]
	s_or_b64 exec, exec, s[54:55]
	v_ashrrev_i32_e32 v57, 31, v56
	v_lshlrev_b64 v[56:57], 13, v[56:57]
	v_lshl_add_u64 v[56:57], v[58:59], 0, v[56:57]
	v_pk_fma_f32 v[54:55], v[54:55], v[66:67], v[90:91]
	v_pk_fma_f32 v[52:53], v[52:53], v[64:65], v[88:89]
	v_lshl_add_u64 v[56:57], v[174:175], 2, v[56:57]
	global_store_dwordx4 v[56:57], v[52:55], off offset:512
	s_and_saveexec_b64 s[28:29], s[12:13]
	s_xor_b64 s[54:55], exec, s[28:29]
	v_add3_u32 v52, v222, v213, s79
	s_or_saveexec_b64 s[54:55], s[54:55]
	v_mov_b64_e32 v[54:55], s[24:25]
	s_xor_b64 exec, exec, s[54:55]
	v_lshl_add_u32 v52, v212, 8, v213
	v_mov_b64_e32 v[54:55], s[36:37]
	s_or_b64 exec, exec, s[54:55]
	v_ashrrev_i32_e32 v53, 31, v52
	v_lshlrev_b64 v[52:53], 13, v[52:53]
	v_lshl_add_u64 v[52:53], v[54:55], 0, v[52:53]
	v_pk_fma_f32 v[50:51], v[50:51], v[66:67], v[86:87]
	v_pk_fma_f32 v[48:49], v[48:49], v[64:65], v[84:85]
	v_lshl_add_u64 v[52:53], v[174:175], 2, v[52:53]
	global_store_dwordx4 v[52:53], v[48:51], off offset:512
	s_and_saveexec_b64 s[28:29], s[10:11]
	s_xor_b64 s[54:55], exec, s[28:29]
	v_add3_u32 v48, v225, v215, s79
	s_or_saveexec_b64 s[54:55], s[54:55]
	v_mov_b64_e32 v[50:51], s[24:25]
	s_xor_b64 exec, exec, s[54:55]
	v_lshl_add_u32 v48, v214, 8, v215
	v_mov_b64_e32 v[50:51], s[36:37]
	s_or_b64 exec, exec, s[54:55]
	v_ashrrev_i32_e32 v49, 31, v48
	v_lshlrev_b64 v[48:49], 13, v[48:49]
	v_lshl_add_u64 v[48:49], v[50:51], 0, v[48:49]
	v_pk_fma_f32 v[46:47], v[46:47], v[66:67], v[82:83]
	v_pk_fma_f32 v[44:45], v[44:45], v[64:65], v[80:81]
	v_lshl_add_u64 v[48:49], v[174:175], 2, v[48:49]
	global_store_dwordx4 v[48:49], v[44:47], off offset:512
	s_and_saveexec_b64 s[28:29], s[8:9]
	s_xor_b64 s[54:55], exec, s[28:29]
	v_add3_u32 v44, v226, v218, s79
	s_or_saveexec_b64 s[54:55], s[54:55]
	v_mov_b64_e32 v[46:47], s[24:25]
	s_xor_b64 exec, exec, s[54:55]
	v_lshl_add_u32 v44, v217, 8, v218
	v_mov_b64_e32 v[46:47], s[36:37]
	s_or_b64 exec, exec, s[54:55]
	v_ashrrev_i32_e32 v45, 31, v44
	v_lshlrev_b64 v[44:45], 13, v[44:45]
	v_lshl_add_u64 v[44:45], v[46:47], 0, v[44:45]
	v_pk_fma_f32 v[42:43], v[42:43], v[66:67], v[78:79]
	v_pk_fma_f32 v[40:41], v[40:41], v[64:65], v[76:77]
	v_lshl_add_u64 v[44:45], v[174:175], 2, v[44:45]
	global_store_dwordx4 v[44:45], v[40:43], off offset:512
	s_and_saveexec_b64 s[28:29], s[6:7]
; DI void epi_resid(const Acc& acc, const P& p, int brow, int bcol, int layer, int gch, bool from_input) {
;     ...
;     for (int bj = 0; bj < 2; ++bj)
; #pragma unroll
;         for (int n = 0; n < 2; ++n) {
;             const int c0 = bcol + bj * 128 + wc * 32 + n * 16 + fq * 4;
;             const f32x4 g = *(const f32x4*)(gate + c0);
;             f32x4 xv[2][4];
; #pragma unroll
;             for (int ai = 0; ai < 2; ++ai)
; #pragma unroll
;                 for (int m = 0; m < 4; ++m) {
;                     const int r = brow + ai * 128 + wr * 64 + m * 16 + fr;
;                     const float* sp = (from_input ? inrow(p, r) : xrow(p, r)) + c0;
;                     xv[ai][m] = *(const f32x4*)sp;
;                 }
;             __builtin_amdgcn_sched_barrier(0);
; #pragma unroll
;             for (int ai = 0; ai < 2; ++ai)
; #pragma unroll
;                 for (int m = 0; m < 4; ++m) {
;                     const int r = brow + ai * 128 + wr * 64 + m * 16 + fr;
;                     *(f32x4*)(xrow(p, r) + c0) = xv[ai][m] + g * acc[ai][bj][m][n];
;                 }
;             __builtin_amdgcn_sched_barrier(0);
	s_xor_b64 s[54:55], exec, s[28:29]
	v_add3_u32 v40, v227, v221, s79
	s_or_saveexec_b64 s[54:55], s[54:55]
	v_mov_b64_e32 v[42:43], s[24:25]
	s_xor_b64 exec, exec, s[54:55]
	v_lshl_add_u32 v40, v220, 8, v221
	v_mov_b64_e32 v[42:43], s[36:37]
	s_or_b64 exec, exec, s[54:55]
	v_ashrrev_i32_e32 v41, 31, v40
	v_lshlrev_b64 v[40:41], 13, v[40:41]
	v_lshl_add_u64 v[40:41], v[42:43], 0, v[40:41]
	v_pk_fma_f32 v[38:39], v[38:39], v[66:67], v[74:75]
	v_pk_fma_f32 v[36:37], v[36:37], v[64:65], v[72:73]
	v_lshl_add_u64 v[40:41], v[174:175], 2, v[40:41]
	global_store_dwordx4 v[40:41], v[36:39], off offset:512
	s_and_saveexec_b64 s[28:29], vcc
	s_xor_b64 s[54:55], exec, s[28:29]
	v_add3_u32 v36, v228, v224, s79
	s_or_saveexec_b64 s[54:55], s[54:55]
	v_mov_b64_e32 v[38:39], s[24:25]
	s_xor_b64 exec, exec, s[54:55]
	v_lshl_add_u32 v36, v223, 8, v224
	v_mov_b64_e32 v[38:39], s[36:37]
	s_or_b64 exec, exec, s[54:55]
	v_ashrrev_i32_e32 v37, 31, v36
	v_lshlrev_b64 v[36:37], 13, v[36:37]
	v_lshl_add_u64 v[36:37], v[38:39], 0, v[36:37]
	v_pk_fma_f32 v[34:35], v[34:35], v[66:67], v[70:71]
	v_pk_fma_f32 v[32:33], v[32:33], v[64:65], v[68:69]
	v_lshl_add_u64 v[36:37], v[174:175], 2, v[36:37]
	global_store_dwordx4 v[36:37], v[32:35], off offset:512
	global_load_dwordx4 v[32:35], v[192:193], off offset:576
	v_mov_b64_e32 v[36:37], s[56:57]
	s_and_saveexec_b64 s[28:29], s[18:19]
	s_xor_b64 s[54:55], exec, s[28:29]
	v_add3_u32 v38, v211, v204, s79
	v_mov_b64_e32 v[36:37], s[52:53]
	s_andn2_saveexec_b64 s[54:55], s[54:55]
	v_lshl_add_u32 v38, v203, 8, v204
	s_or_b64 exec, exec, s[54:55]
	v_ashrrev_i32_e32 v39, 31, v38
	v_lshlrev_b64 v[38:39], 13, v[38:39]
	v_lshl_add_u64 v[36:37], v[36:37], 0, v[38:39]
	v_lshl_add_u64 v[36:37], v[174:175], 2, v[36:37]
	global_load_dwordx4 v[64:67], v[36:37], off offset:576
	v_mov_b64_e32 v[36:37], s[56:57]
	s_and_saveexec_b64 s[28:29], s[16:17]
	s_xor_b64 s[54:55], exec, s[28:29]
	v_add3_u32 v38, v216, v208, s79
	v_mov_b64_e32 v[36:37], s[52:53]
	s_andn2_saveexec_b64 s[54:55], s[54:55]
	v_lshl_add_u32 v38, v205, 8, v208
	s_or_b64 exec, exec, s[54:55]
	v_ashrrev_i32_e32 v39, 31, v38
	v_lshlrev_b64 v[38:39], 13, v[38:39]
	v_lshl_add_u64 v[36:37], v[36:37], 0, v[38:39]
	v_lshl_add_u64 v[36:37], v[174:175], 2, v[36:37]
	global_load_dwordx4 v[60:63], v[36:37], off offset:576
	v_mov_b64_e32 v[36:37], s[56:57]
	s_and_saveexec_b64 s[28:29], s[14:15]
	s_xor_b64 s[54:55], exec, s[28:29]
	v_add3_u32 v38, v219, v210, s79
	v_mov_b64_e32 v[36:37], s[52:53]
	s_andn2_saveexec_b64 s[54:55], s[54:55]
	v_lshl_add_u32 v38, v209, 8, v210
	s_or_b64 exec, exec, s[54:55]
	v_ashrrev_i32_e32 v39, 31, v38
	v_lshlrev_b64 v[38:39], 13, v[38:39]
	v_lshl_add_u64 v[36:37], v[36:37], 0, v[38:39]
	v_lshl_add_u64 v[36:37], v[174:175], 2, v[36:37]
	global_load_dwordx4 v[56:59], v[36:37], off offset:576
	v_mov_b64_e32 v[36:37], s[56:57]
	s_and_saveexec_b64 s[28:29], s[12:13]
	s_xor_b64 s[54:55], exec, s[28:29]
	v_add3_u32 v38, v222, v213, s79
	v_mov_b64_e32 v[36:37], s[52:53]
	s_andn2_saveexec_b64 s[54:55], s[54:55]
	v_lshl_add_u32 v38, v212, 8, v213
	s_or_b64 exec, exec, s[54:55]
	v_ashrrev_i32_e32 v39, 31, v38
	v_lshlrev_b64 v[38:39], 13, v[38:39]
	v_lshl_add_u64 v[36:37], v[36:37], 0, v[38:39]
	v_lshl_add_u64 v[36:37], v[174:175], 2, v[36:37]
	global_load_dwordx4 v[52:55], v[36:37], off offset:576
	v_mov_b64_e32 v[36:37], s[56:57]
	s_and_saveexec_b64 s[28:29], s[10:11]
	s_xor_b64 s[54:55], exec, s[28:29]
	v_add3_u32 v38, v225, v215, s79
	v_mov_b64_e32 v[36:37], s[52:53]
	s_andn2_saveexec_b64 s[54:55], s[54:55]
	v_lshl_add_u32 v38, v214, 8, v215
	s_or_b64 exec, exec, s[54:55]
	v_ashrrev_i32_e32 v39, 31, v38
	v_lshlrev_b64 v[38:39], 13, v[38:39]
	v_lshl_add_u64 v[36:37], v[36:37], 0, v[38:39]
	v_lshl_add_u64 v[36:37], v[174:175], 2, v[36:37]
	global_load_dwordx4 v[48:51], v[36:37], off offset:576
	v_mov_b64_e32 v[36:37], s[56:57]
	s_and_saveexec_b64 s[28:29], s[8:9]
	s_xor_b64 s[54:55], exec, s[28:29]
	v_add3_u32 v38, v226, v218, s79
	v_mov_b64_e32 v[36:37], s[52:53]
	s_andn2_saveexec_b64 s[54:55], s[54:55]
	v_lshl_add_u32 v38, v217, 8, v218
	s_or_b64 exec, exec, s[54:55]
	v_ashrrev_i32_e32 v39, 31, v38
	v_lshlrev_b64 v[38:39], 13, v[38:39]
	v_lshl_add_u64 v[36:37], v[36:37], 0, v[38:39]
	v_lshl_add_u64 v[36:37], v[174:175], 2, v[36:37]
	global_load_dwordx4 v[44:47], v[36:37], off offset:576
	v_mov_b64_e32 v[36:37], s[56:57]
	s_and_saveexec_b64 s[28:29], s[6:7]
	s_xor_b64 s[54:55], exec, s[28:29]
	v_add3_u32 v38, v227, v221, s79
	v_mov_b64_e32 v[36:37], s[52:53]
	s_andn2_saveexec_b64 s[54:55], s[54:55]
	v_lshl_add_u32 v38, v220, 8, v221
	s_or_b64 exec, exec, s[54:55]
	v_ashrrev_i32_e32 v39, 31, v38
	v_lshlrev_b64 v[38:39], 13, v[38:39]
	v_lshl_add_u64 v[36:37], v[36:37], 0, v[38:39]
	v_lshl_add_u64 v[36:37], v[174:175], 2, v[36:37]
	global_load_dwordx4 v[40:43], v[36:37], off offset:576
	v_mov_b64_e32 v[36:37], s[56:57]
	s_and_saveexec_b64 s[28:29], vcc
	s_xor_b64 s[54:55], exec, s[28:29]
	v_add3_u32 v38, v228, v224, s79
	v_mov_b64_e32 v[36:37], s[52:53]
	s_andn2_saveexec_b64 s[54:55], s[54:55]
	v_lshl_add_u32 v38, v223, 8, v224
	s_or_b64 exec, exec, s[54:55]
	v_ashrrev_i32_e32 v39, 31, v38
	v_lshlrev_b64 v[38:39], 13, v[38:39]
	v_lshl_add_u64 v[36:37], v[36:37], 0, v[38:39]
	v_lshl_add_u64 v[36:37], v[174:175], 2, v[36:37]
	global_load_dwordx4 v[36:39], v[36:37], off offset:576
	s_and_saveexec_b64 s[28:29], s[18:19]
	s_xor_b64 s[18:19], exec, s[28:29]
	s_or_saveexec_b64 s[18:19], s[18:19]
	v_mov_b64_e32 v[68:69], s[24:25]
	s_xor_b64 exec, exec, s[18:19]
	v_mov_b64_e32 v[68:69], s[36:37]
	v_mov_b32_e32 v190, v191
	s_or_b64 exec, exec, s[18:19]
	v_ashrrev_i32_e32 v191, 31, v190
	s_waitcnt vmcnt(0)
; DI void epi_resid(const Acc& acc, const P& p, int brow, int bcol, int layer, int gch, bool from_input) {
;     ...
; #pragma unroll
;             for (int ai = 0; ai < 2; ++ai)
; #pragma unroll
;                 for (int m = 0; m < 4; ++m) {
;                     const int r = brow + ai * 128 + wr * 64 + m * 16 + fr;
;                     *(f32x4*)(xrow(p, r) + c0) = xv[ai][m] + g * acc[ai][bj][m][n];
;                 }
;             __builtin_amdgcn_sched_barrier(0);
	v_pk_fma_f32 v[28:29], v[28:29], v[32:33], v[64:65]
	v_lshlrev_b64 v[64:65], 13, v[190:191]
	v_lshl_add_u64 v[64:65], v[68:69], 0, v[64:65]
	v_pk_fma_f32 v[30:31], v[30:31], v[34:35], v[66:67]
	v_lshl_add_u64 v[64:65], v[174:175], 2, v[64:65]
	global_store_dwordx4 v[64:65], v[28:31], off offset:576
	s_and_saveexec_b64 s[18:19], s[16:17]
	s_xor_b64 s[16:17], exec, s[18:19]
	s_or_saveexec_b64 s[16:17], s[16:17]
	v_mov_b64_e32 v[28:29], s[24:25]
	s_xor_b64 exec, exec, s[16:17]
	v_mov_b64_e32 v[28:29], s[36:37]
	v_mov_b32_e32 v188, v189
	s_or_b64 exec, exec, s[16:17]
	v_ashrrev_i32_e32 v189, 31, v188
	v_lshlrev_b64 v[30:31], 13, v[188:189]
	v_lshl_add_u64 v[28:29], v[28:29], 0, v[30:31]
	v_pk_fma_f32 v[26:27], v[26:27], v[34:35], v[62:63]
	v_pk_fma_f32 v[24:25], v[24:25], v[32:33], v[60:61]
	v_lshl_add_u64 v[28:29], v[174:175], 2, v[28:29]
	global_store_dwordx4 v[28:29], v[24:27], off offset:576
	s_and_saveexec_b64 s[16:17], s[14:15]
	s_xor_b64 s[14:15], exec, s[16:17]
	s_or_saveexec_b64 s[14:15], s[14:15]
	v_mov_b64_e32 v[24:25], s[24:25]
	s_xor_b64 exec, exec, s[14:15]
	v_mov_b64_e32 v[24:25], s[36:37]
	v_mov_b32_e32 v186, v187
	s_or_b64 exec, exec, s[14:15]
	v_ashrrev_i32_e32 v187, 31, v186
	v_lshlrev_b64 v[26:27], 13, v[186:187]
	v_lshl_add_u64 v[24:25], v[24:25], 0, v[26:27]
	v_pk_fma_f32 v[22:23], v[22:23], v[34:35], v[58:59]
	v_pk_fma_f32 v[20:21], v[20:21], v[32:33], v[56:57]
	v_lshl_add_u64 v[24:25], v[174:175], 2, v[24:25]
	global_store_dwordx4 v[24:25], v[20:23], off offset:576
	s_and_saveexec_b64 s[14:15], s[12:13]
	s_xor_b64 s[12:13], exec, s[14:15]
	s_or_saveexec_b64 s[12:13], s[12:13]
	v_mov_b64_e32 v[20:21], s[24:25]
	s_xor_b64 exec, exec, s[12:13]
	v_mov_b64_e32 v[20:21], s[36:37]
	v_mov_b32_e32 v184, v185
	s_or_b64 exec, exec, s[12:13]
	v_ashrrev_i32_e32 v185, 31, v184
	v_lshlrev_b64 v[22:23], 13, v[184:185]
	v_lshl_add_u64 v[20:21], v[20:21], 0, v[22:23]
	v_pk_fma_f32 v[18:19], v[18:19], v[34:35], v[54:55]
	v_pk_fma_f32 v[16:17], v[16:17], v[32:33], v[52:53]
	v_lshl_add_u64 v[20:21], v[174:175], 2, v[20:21]
	global_store_dwordx4 v[20:21], v[16:19], off offset:576
	s_and_saveexec_b64 s[12:13], s[10:11]
	s_xor_b64 s[10:11], exec, s[12:13]
	s_or_saveexec_b64 s[10:11], s[10:11]
	v_mov_b64_e32 v[16:17], s[24:25]
	s_xor_b64 exec, exec, s[10:11]
	v_mov_b64_e32 v[16:17], s[36:37]
	v_mov_b32_e32 v182, v183
	s_or_b64 exec, exec, s[10:11]
	v_ashrrev_i32_e32 v183, 31, v182
	v_lshlrev_b64 v[18:19], 13, v[182:183]
	v_lshl_add_u64 v[16:17], v[16:17], 0, v[18:19]
	v_pk_fma_f32 v[14:15], v[14:15], v[34:35], v[50:51]
	v_pk_fma_f32 v[12:13], v[12:13], v[32:33], v[48:49]
	v_lshl_add_u64 v[16:17], v[174:175], 2, v[16:17]
	global_store_dwordx4 v[16:17], v[12:15], off offset:576
	s_and_saveexec_b64 s[10:11], s[8:9]
	s_xor_b64 s[8:9], exec, s[10:11]
	s_or_saveexec_b64 s[8:9], s[8:9]
	v_mov_b64_e32 v[12:13], s[24:25]
	s_xor_b64 exec, exec, s[8:9]
	v_mov_b64_e32 v[12:13], s[36:37]
	v_mov_b32_e32 v180, v181
	s_or_b64 exec, exec, s[8:9]
	v_ashrrev_i32_e32 v181, 31, v180
	v_lshlrev_b64 v[14:15], 13, v[180:181]
	v_lshl_add_u64 v[12:13], v[12:13], 0, v[14:15]
	v_pk_fma_f32 v[10:11], v[10:11], v[34:35], v[46:47]
	v_pk_fma_f32 v[8:9], v[8:9], v[32:33], v[44:45]
	v_lshl_add_u64 v[12:13], v[174:175], 2, v[12:13]
	global_store_dwordx4 v[12:13], v[8:11], off offset:576
	s_and_saveexec_b64 s[8:9], s[6:7]
	s_xor_b64 s[6:7], exec, s[8:9]
	s_or_saveexec_b64 s[6:7], s[6:7]
	v_mov_b64_e32 v[8:9], s[24:25]
	s_xor_b64 exec, exec, s[6:7]
	v_mov_b64_e32 v[8:9], s[36:37]
	v_mov_b32_e32 v178, v179
	s_or_b64 exec, exec, s[6:7]
	v_ashrrev_i32_e32 v179, 31, v178
	v_lshlrev_b64 v[10:11], 13, v[178:179]
	v_lshl_add_u64 v[8:9], v[8:9], 0, v[10:11]
	v_pk_fma_f32 v[6:7], v[6:7], v[34:35], v[42:43]
	v_pk_fma_f32 v[4:5], v[4:5], v[32:33], v[40:41]
	v_lshl_add_u64 v[8:9], v[174:175], 2, v[8:9]
	global_store_dwordx4 v[8:9], v[4:7], off offset:576
	s_and_saveexec_b64 s[6:7], vcc
	s_xor_b64 s[6:7], exec, s[6:7]
	s_or_saveexec_b64 s[6:7], s[6:7]
	v_mov_b64_e32 v[4:5], s[24:25]
	s_xor_b64 exec, exec, s[6:7]
	s_cbranch_execz .LBB0_1234
	v_mov_b64_e32 v[4:5], s[36:37]
	v_mov_b32_e32 v176, v177
	s_branch .LBB0_1234

; #define WAIT_V(n) asm volatile("s_waitcnt vmcnt(" #n ")" ::: "memory")
; #define WAIT_L(n) asm volatile("s_waitcnt lgkmcnt(" #n ")" ::: "memory")
; #define BAR __builtin_amdgcn_s_barrier()
; #define SCHED __builtin_amdgcn_sched_barrier(0)
; template <class Get, class Epi>
; DI void gemm_stream(LAS unsigned char* lds, const int K, const int ld, Get get, Epi epi) {
;     ...
;         for (int t = 0; t < nt; t += 2) {
;             const bool last = (t == nt - 2);
;             const char* a1 = cA + (size_t)(t + 1) * kstep;
;             const char* a2 = last ? nA : cA + (size_t)(t + 2) * kstep;
;             const char* b2 = last ? nB : cB + (size_t)(t + 2) * kstep;
;             const char* a3 = a2 + kstep;
;             const char* b3 = b2 + kstep;
;             LDB(B0, 0, 0); SCHED; LDA(At, 0, 0); STAGE(SAo(1, 1), a1 + hstep);
;             WAIT_L(8); BAR; WAIT_L(0); MMA(0, 0, At, B0); BAR; SCHED;
;             LDB(B1, 0, 1); STAGE(SBo(0, 0), b2);
;             BAR; WAIT_L(0); MMA(0, 1, At, B1); BAR;
;             LDA(At, 0, 1); STAGE(SAo(0, 0), a2);
;             BAR; WAIT_L(0); MMA(1, 0, At, B0); BAR; SCHED;
;             STAGE(SBo(0, 1), b2 + hstep);
;             WAIT_V(6); BAR; MMA(1, 1, At, B1); BAR;
.LBB0_1505:
	s_add_u32 s38, s8, s0
	s_addc_u32 s39, s9, 0
	s_add_u32 s40, s38, 0x100
	s_addc_u32 s41, s39, 0
	s_and_b64 s[36:37], s[18:19], exec
	s_cselect_b32 s41, s13, s41
	s_cselect_b32 s40, s12, s40
	s_add_u32 s0, s10, s0
	s_addc_u32 s36, s11, 0
	s_add_u32 s0, s0, 0x100
	s_addc_u32 s36, s36, 0
	s_and_b64 s[18:19], s[18:19], exec
	s_cselect_b32 s53, s15, s36
	s_cselect_b32 s52, s14, s0
	s_add_u32 s54, s38, 0x80080
	s_addc_u32 s55, s39, 0
	s_add_i32 s87, s63, 0x2000
	s_add_u32 s38, s52, 0x80000
	s_addc_u32 s39, s53, 0
	s_add_i32 s86, s60, s3
	s_add_i32 s85, s86, 0x2000
	s_add_i32 s83, 16, 0x18000
	ds_read_b128 v[140:143], v137
	ds_read_b128 v[144:147], v137 offset:1024
	ds_read_b128 v[148:151], v137 offset:2048
	ds_read_b128 v[152:155], v137 offset:3072
	s_add_u32 s36, s40, 0x80000
	s_addc_u32 s37, s41, 0
	s_add_i32 s82, s83, s3
	s_add_i32 s81, 16, 0x1c000
	s_add_i32 s80, s82, 0x2000
	s_add_u32 s18, s52, 0x80080
	s_addc_u32 s19, s53, 0
	s_add_i32 s79, s81, s3
	s_add_i32 s0, s79, 0x2000
	s_mov_b32 m0, s61
	v_lshl_add_u64 v[188:189], s[54:55], 0, v[130:131]
	ds_read_b128 v[156:159], v138
	ds_read_b128 v[160:163], v138 offset:1024
	ds_read_b128 v[164:167], v138 offset:2048
	ds_read_b128 v[168:171], v138 offset:3072
	ds_read_b128 v[172:175], v138 offset:4096
	ds_read_b128 v[176:179], v138 offset:5120
	ds_read_b128 v[180:183], v138 offset:6144
	ds_read_b128 v[184:187], v138 offset:7168
	global_load_lds_dwordx4 v[188:189], off
	s_mov_b32 m0, s62
	v_lshl_add_u64 v[188:189], s[54:55], 0, v[128:129]
	global_load_lds_dwordx4 v[188:189], off
	s_waitcnt lgkmcnt(8)
	s_barrier
	s_waitcnt lgkmcnt(0)
	v_mfma_f32_16x16x32_bf16 v[124:127], v[140:143], v[156:159], v[124:127]
	v_mfma_f32_16x16x32_bf16 v[120:123], v[148:151], v[156:159], v[120:123]
	v_mfma_f32_16x16x32_bf16 v[116:119], v[140:143], v[164:167], v[116:119]
	v_mfma_f32_16x16x32_bf16 v[112:115], v[148:151], v[164:167], v[112:115]
	v_mfma_f32_16x16x32_bf16 v[104:107], v[140:143], v[172:175], v[104:107]
	v_mfma_f32_16x16x32_bf16 v[96:99], v[148:151], v[172:175], v[96:99]
	v_mfma_f32_16x16x32_bf16 v[88:91], v[140:143], v[180:183], v[88:91]
	v_mfma_f32_16x16x32_bf16 v[80:83], v[148:151], v[180:183], v[80:83]
	v_mfma_f32_16x16x32_bf16 v[124:127], v[144:147], v[160:163], v[124:127]
	v_mfma_f32_16x16x32_bf16 v[120:123], v[152:155], v[160:163], v[120:123]
	v_mfma_f32_16x16x32_bf16 v[116:119], v[144:147], v[168:171], v[116:119]
	v_mfma_f32_16x16x32_bf16 v[112:115], v[152:155], v[168:171], v[112:115]
	v_mfma_f32_16x16x32_bf16 v[104:107], v[144:147], v[176:179], v[104:107]
	v_mfma_f32_16x16x32_bf16 v[96:99], v[152:155], v[176:179], v[96:99]
	v_mfma_f32_16x16x32_bf16 v[88:91], v[144:147], v[184:187], v[88:91]
	v_mfma_f32_16x16x32_bf16 v[80:83], v[152:155], v[184:187], v[80:83]
	s_barrier
	s_mov_b32 m0, s63
	v_lshl_add_u64 v[204:205], s[52:53], 0, v[130:131]
	ds_read_b128 v[188:191], v139
	ds_read_b128 v[192:195], v139 offset:1024
	ds_read_b128 v[196:199], v139 offset:2048
	ds_read_b128 v[200:203], v139 offset:3072
	global_load_lds_dwordx4 v[204:205], off
	s_mov_b32 m0, s87
	v_lshl_add_u64 v[208:209], s[52:53], 0, v[128:129]
	global_load_lds_dwordx4 v[208:209], off
	s_barrier
	s_waitcnt lgkmcnt(0)
	v_mfma_f32_16x16x32_bf16 v[108:111], v[188:191], v[156:159], v[108:111]
	v_mfma_f32_16x16x32_bf16 v[100:103], v[196:199], v[156:159], v[100:103]
	v_mfma_f32_16x16x32_bf16 v[92:95], v[188:191], v[164:167], v[92:95]
	v_mfma_f32_16x16x32_bf16 v[84:87], v[196:199], v[164:167], v[84:87]
	v_mfma_f32_16x16x32_bf16 v[76:79], v[188:191], v[172:175], v[76:79]
	v_mfma_f32_16x16x32_bf16 v[72:75], v[196:199], v[172:175], v[72:75]
	v_mfma_f32_16x16x32_bf16 v[68:71], v[188:191], v[180:183], v[68:71]
	v_mfma_f32_16x16x32_bf16 v[64:67], v[196:199], v[180:183], v[64:67]
	v_mfma_f32_16x16x32_bf16 v[108:111], v[192:195], v[160:163], v[108:111]
	v_mfma_f32_16x16x32_bf16 v[100:103], v[200:203], v[160:163], v[100:103]
	v_mfma_f32_16x16x32_bf16 v[92:95], v[192:195], v[168:171], v[92:95]
	v_mfma_f32_16x16x32_bf16 v[84:87], v[200:203], v[168:171], v[84:87]
	v_mfma_f32_16x16x32_bf16 v[76:79], v[192:195], v[176:179], v[76:79]
	v_mfma_f32_16x16x32_bf16 v[72:75], v[200:203], v[176:179], v[72:75]
	v_mfma_f32_16x16x32_bf16 v[68:71], v[192:195], v[184:187], v[68:71]
	v_mfma_f32_16x16x32_bf16 v[64:67], v[200:203], v[184:187], v[64:67]
	s_mov_b32 m0, s20
	v_lshl_add_u64 v[210:211], s[40:41], 0, v[130:131]
	s_barrier
	ds_read_b128 v[156:159], v138 offset:16384
	ds_read_b128 v[160:163], v138 offset:17408
	ds_read_b128 v[164:167], v138 offset:18432
	ds_read_b128 v[168:171], v138 offset:19456
	ds_read_b128 v[172:175], v138 offset:20480
	ds_read_b128 v[176:179], v138 offset:21504
	ds_read_b128 v[180:183], v138 offset:22528
	ds_read_b128 v[184:187], v138 offset:23552
	global_load_lds_dwordx4 v[210:211], off
	s_mov_b32 m0, s21
	v_lshl_add_u64 v[212:213], s[40:41], 0, v[128:129]
	global_load_lds_dwordx4 v[212:213], off
	s_barrier
	s_waitcnt lgkmcnt(0)
	v_mfma_f32_16x16x32_bf16 v[60:63], v[140:143], v[156:159], v[60:63]
	v_mfma_f32_16x16x32_bf16 v[56:59], v[148:151], v[156:159], v[56:59]
	v_mfma_f32_16x16x32_bf16 v[52:55], v[140:143], v[164:167], v[52:55]
	v_mfma_f32_16x16x32_bf16 v[48:51], v[148:151], v[164:167], v[48:51]
	v_mfma_f32_16x16x32_bf16 v[40:43], v[140:143], v[172:175], v[40:43]
	v_mfma_f32_16x16x32_bf16 v[32:35], v[148:151], v[172:175], v[32:35]
	v_mfma_f32_16x16x32_bf16 v[24:27], v[140:143], v[180:183], v[24:27]
	v_mfma_f32_16x16x32_bf16 v[16:19], v[148:151], v[180:183], v[16:19]
	v_mfma_f32_16x16x32_bf16 v[60:63], v[144:147], v[160:163], v[60:63]
	v_mfma_f32_16x16x32_bf16 v[56:59], v[152:155], v[160:163], v[56:59]
	v_mfma_f32_16x16x32_bf16 v[52:55], v[144:147], v[168:171], v[52:55]
	v_mfma_f32_16x16x32_bf16 v[48:51], v[152:155], v[168:171], v[48:51]
	v_mfma_f32_16x16x32_bf16 v[40:43], v[144:147], v[176:179], v[40:43]
	v_mfma_f32_16x16x32_bf16 v[32:35], v[152:155], v[176:179], v[32:35]
	v_mfma_f32_16x16x32_bf16 v[24:27], v[144:147], v[184:187], v[24:27]
	v_mfma_f32_16x16x32_bf16 v[16:19], v[152:155], v[184:187], v[16:19]
	s_barrier
; #define WAIT_V(n) asm volatile("s_waitcnt vmcnt(" #n ")" ::: "memory")
; #define WAIT_L(n) asm volatile("s_waitcnt lgkmcnt(" #n ")" ::: "memory")
; #define BAR __builtin_amdgcn_s_barrier()
; #define SCHED __builtin_amdgcn_sched_barrier(0)
; template <class Get, class Epi>
; DI void gemm_stream(LAS unsigned char* lds, const int K, const int ld, Get get, Epi epi) {
;     ...
;             STAGE(SBo(0, 1), b2 + hstep);
;             WAIT_V(6); BAR; MMA(1, 1, At, B1); BAR;
;             LDB(B0, 1, 0); SCHED; LDA(At, 1, 0); STAGE(SAo(0, 1), a2 + hstep);
;             WAIT_L(8); BAR; WAIT_L(0); MMA(0, 0, At, B0); BAR; SCHED;
;             LDB(B1, 1, 1); STAGE(SBo(1, 0), b3);
;             BAR; WAIT_L(0); MMA(0, 1, At, B1); BAR;
;             LDA(At, 1, 1); STAGE(SAo(1, 0), a3);
;             BAR; WAIT_L(0); MMA(1, 0, At, B0); BAR; SCHED;
	s_mov_b32 m0, s86
	v_lshl_add_u64 v[140:141], s[38:39], 0, v[130:131]
	global_load_lds_dwordx4 v[140:141], off
	s_mov_b32 m0, s85
	v_lshl_add_u64 v[140:141], s[38:39], 0, v[128:129]
	global_load_lds_dwordx4 v[140:141], off
	s_waitcnt vmcnt(6)
	s_barrier
	v_mfma_f32_16x16x32_bf16 v[44:47], v[188:191], v[156:159], v[44:47]
	v_mfma_f32_16x16x32_bf16 v[36:39], v[196:199], v[156:159], v[36:39]
	v_mfma_f32_16x16x32_bf16 v[28:31], v[188:191], v[164:167], v[28:31]
	v_mfma_f32_16x16x32_bf16 v[20:23], v[196:199], v[164:167], v[20:23]
	v_mfma_f32_16x16x32_bf16 v[12:15], v[188:191], v[172:175], v[12:15]
	v_mfma_f32_16x16x32_bf16 v[8:11], v[196:199], v[172:175], v[8:11]
	v_mfma_f32_16x16x32_bf16 v[4:7], v[188:191], v[180:183], v[4:7]
	v_mfma_f32_16x16x32_bf16 v[0:3], v[196:199], v[180:183], v[0:3]
	v_mfma_f32_16x16x32_bf16 v[44:47], v[192:195], v[160:163], v[44:47]
	v_mfma_f32_16x16x32_bf16 v[36:39], v[200:203], v[160:163], v[36:39]
	v_mfma_f32_16x16x32_bf16 v[28:31], v[192:195], v[168:171], v[28:31]
	v_mfma_f32_16x16x32_bf16 v[20:23], v[200:203], v[168:171], v[20:23]
	v_mfma_f32_16x16x32_bf16 v[12:15], v[192:195], v[176:179], v[12:15]
	v_mfma_f32_16x16x32_bf16 v[8:11], v[200:203], v[176:179], v[8:11]
	v_mfma_f32_16x16x32_bf16 v[4:7], v[192:195], v[184:187], v[4:7]
	v_mfma_f32_16x16x32_bf16 v[0:3], v[200:203], v[184:187], v[0:3]
	v_add_u32_e32 v132, s83, v136
	s_barrier
	ds_read_b128 v[140:143], v132
	ds_read_b128 v[144:147], v132 offset:1024
	ds_read_b128 v[148:151], v132 offset:2048
	ds_read_b128 v[152:155], v132 offset:3072
	s_mov_b32 m0, s28
	v_lshl_add_u64 v[188:189], s[36:37], 0, v[130:131]
	ds_read_b128 v[156:159], v138 offset:32768
	ds_read_b128 v[160:163], v138 offset:33792
	ds_read_b128 v[164:167], v138 offset:34816
	ds_read_b128 v[168:171], v138 offset:35840
	ds_read_b128 v[172:175], v138 offset:36864
	ds_read_b128 v[176:179], v138 offset:37888
	ds_read_b128 v[180:183], v138 offset:38912
	ds_read_b128 v[184:187], v138 offset:39936
	global_load_lds_dwordx4 v[188:189], off
	s_mov_b32 m0, s29
	v_lshl_add_u64 v[188:189], s[36:37], 0, v[128:129]
	global_load_lds_dwordx4 v[188:189], off
	s_waitcnt lgkmcnt(8)
	s_barrier
	s_waitcnt lgkmcnt(0)
	v_mfma_f32_16x16x32_bf16 v[124:127], v[140:143], v[156:159], v[124:127]
	v_mfma_f32_16x16x32_bf16 v[120:123], v[148:151], v[156:159], v[120:123]
	v_mfma_f32_16x16x32_bf16 v[116:119], v[140:143], v[164:167], v[116:119]
	v_mfma_f32_16x16x32_bf16 v[112:115], v[148:151], v[164:167], v[112:115]
	v_mfma_f32_16x16x32_bf16 v[104:107], v[140:143], v[172:175], v[104:107]
	v_mfma_f32_16x16x32_bf16 v[96:99], v[148:151], v[172:175], v[96:99]
	v_mfma_f32_16x16x32_bf16 v[88:91], v[140:143], v[180:183], v[88:91]
	v_mfma_f32_16x16x32_bf16 v[80:83], v[148:151], v[180:183], v[80:83]
	v_mfma_f32_16x16x32_bf16 v[124:127], v[144:147], v[160:163], v[124:127]
	v_mfma_f32_16x16x32_bf16 v[120:123], v[152:155], v[160:163], v[120:123]
	v_mfma_f32_16x16x32_bf16 v[116:119], v[144:147], v[168:171], v[116:119]
	v_mfma_f32_16x16x32_bf16 v[112:115], v[152:155], v[168:171], v[112:115]
	v_mfma_f32_16x16x32_bf16 v[104:107], v[144:147], v[176:179], v[104:107]
	v_mfma_f32_16x16x32_bf16 v[96:99], v[152:155], v[176:179], v[96:99]
	v_mfma_f32_16x16x32_bf16 v[88:91], v[144:147], v[184:187], v[88:91]
	v_mfma_f32_16x16x32_bf16 v[80:83], v[152:155], v[184:187], v[80:83]
	s_barrier
	s_mov_b32 m0, s82
	v_add_u32_e32 v132, s81, v136
	v_lshl_add_u64 v[204:205], v[204:205], 0, s[6:7]
	ds_read_b128 v[188:191], v132
	ds_read_b128 v[192:195], v132 offset:1024
	ds_read_b128 v[196:199], v132 offset:2048
	ds_read_b128 v[200:203], v132 offset:3072
	global_load_lds_dwordx4 v[204:205], off
	s_mov_b32 m0, s80
	v_lshl_add_u64 v[204:205], v[208:209], 0, s[6:7]
	global_load_lds_dwordx4 v[204:205], off
	s_barrier
	s_waitcnt lgkmcnt(0)
	v_mfma_f32_16x16x32_bf16 v[108:111], v[188:191], v[156:159], v[108:111]
	v_mfma_f32_16x16x32_bf16 v[100:103], v[196:199], v[156:159], v[100:103]
	v_mfma_f32_16x16x32_bf16 v[92:95], v[188:191], v[164:167], v[92:95]
	v_mfma_f32_16x16x32_bf16 v[84:87], v[196:199], v[164:167], v[84:87]
	v_mfma_f32_16x16x32_bf16 v[76:79], v[188:191], v[172:175], v[76:79]
	v_mfma_f32_16x16x32_bf16 v[72:75], v[196:199], v[172:175], v[72:75]
	v_mfma_f32_16x16x32_bf16 v[68:71], v[188:191], v[180:183], v[68:71]
	v_mfma_f32_16x16x32_bf16 v[64:67], v[196:199], v[180:183], v[64:67]
	v_mfma_f32_16x16x32_bf16 v[108:111], v[192:195], v[160:163], v[108:111]
	v_mfma_f32_16x16x32_bf16 v[100:103], v[200:203], v[160:163], v[100:103]
	v_mfma_f32_16x16x32_bf16 v[92:95], v[192:195], v[168:171], v[92:95]
	v_mfma_f32_16x16x32_bf16 v[84:87], v[200:203], v[168:171], v[84:87]
	v_mfma_f32_16x16x32_bf16 v[76:79], v[192:195], v[176:179], v[76:79]
	v_mfma_f32_16x16x32_bf16 v[72:75], v[200:203], v[176:179], v[72:75]
	v_mfma_f32_16x16x32_bf16 v[68:71], v[192:195], v[184:187], v[68:71]
	v_mfma_f32_16x16x32_bf16 v[64:67], v[200:203], v[184:187], v[64:67]
	s_mov_b32 m0, s56
	v_lshl_add_u64 v[204:205], v[210:211], 0, s[6:7]
	s_barrier
	ds_read_b128 v[156:159], v138 offset:49152
	ds_read_b128 v[160:163], v138 offset:50176
	ds_read_b128 v[164:167], v138 offset:51200
	ds_read_b128 v[168:171], v138 offset:52224
	ds_read_b128 v[172:175], v138 offset:53248
	ds_read_b128 v[176:179], v138 offset:54272
	ds_read_b128 v[180:183], v138 offset:55296
	ds_read_b128 v[184:187], v138 offset:56320
	global_load_lds_dwordx4 v[204:205], off
	s_mov_b32 m0, s57
	v_lshl_add_u64 v[204:205], v[212:213], 0, s[6:7]
	global_load_lds_dwordx4 v[204:205], off
	s_barrier
; #define WAIT_V(n) asm volatile("s_waitcnt vmcnt(" #n ")" ::: "memory")
; #define WAIT_L(n) asm volatile("s_waitcnt lgkmcnt(" #n ")" ::: "memory")
; #define BAR __builtin_amdgcn_s_barrier()
; #define SCHED __builtin_amdgcn_sched_barrier(0)
; #define EPI_DONE do { } while (0)
; template <class Get, class Epi>
; DI void gemm_stream(LAS unsigned char* lds, const int K, const int ld, Get get, Epi epi) {
;     ...
;             BAR; WAIT_L(0); MMA(1, 0, At, B0); BAR; SCHED;
;             STAGE(SBo(1, 1), b3 + hstep);
;             WAIT_V(6); BAR; MMA(1, 1, At, B1); BAR;
;         }
; DI void epi_part(const Acc& acc, const P& p, int brow, int bcol, int sl) {
;     EPI_IDX
;     const int b = brow / PB;
;     float* part = (float*)(p.ws + O_PART) + ((size_t)sl * (NBATCH * CTXL) + b * CTXL) * DM;
; #pragma unroll
;     for (int ai = 0; ai < 2; ++ai)
; #pragma unroll
;         for (int m = 0; m < 4; ++m) {
;             float* rp = part + (size_t)(ai * 128 + wr * 64 + m * 16 + fr) * DM + bcol + wc * 32 + fq * 4;
; #pragma unroll
;             for (int bj = 0; bj < 2; ++bj)
; #pragma unroll
;                 for (int n = 0; n < 2; ++n) *(f32x4*)(rp + bj * 128 + n * 16) = acc[ai][bj][m][n];
;         }
;     EPI_DONE;
; }
	s_waitcnt lgkmcnt(0)
	v_mfma_f32_16x16x32_bf16 v[60:63], v[140:143], v[156:159], v[60:63]
	v_mfma_f32_16x16x32_bf16 v[56:59], v[148:151], v[156:159], v[56:59]
	v_mfma_f32_16x16x32_bf16 v[52:55], v[140:143], v[164:167], v[52:55]
	v_mfma_f32_16x16x32_bf16 v[48:51], v[148:151], v[164:167], v[48:51]
	v_mfma_f32_16x16x32_bf16 v[40:43], v[140:143], v[172:175], v[40:43]
	v_mfma_f32_16x16x32_bf16 v[32:35], v[148:151], v[172:175], v[32:35]
	v_mfma_f32_16x16x32_bf16 v[24:27], v[140:143], v[180:183], v[24:27]
	v_mfma_f32_16x16x32_bf16 v[16:19], v[148:151], v[180:183], v[16:19]
	v_mfma_f32_16x16x32_bf16 v[60:63], v[144:147], v[160:163], v[60:63]
	v_mfma_f32_16x16x32_bf16 v[56:59], v[152:155], v[160:163], v[56:59]
	v_mfma_f32_16x16x32_bf16 v[52:55], v[144:147], v[168:171], v[52:55]
	v_mfma_f32_16x16x32_bf16 v[48:51], v[152:155], v[168:171], v[48:51]
	v_mfma_f32_16x16x32_bf16 v[40:43], v[144:147], v[176:179], v[40:43]
	v_mfma_f32_16x16x32_bf16 v[32:35], v[152:155], v[176:179], v[32:35]
	v_mfma_f32_16x16x32_bf16 v[24:27], v[144:147], v[184:187], v[24:27]
	v_mfma_f32_16x16x32_bf16 v[16:19], v[152:155], v[184:187], v[16:19]
	s_barrier
	s_mov_b32 m0, s79
	v_lshl_add_u64 v[140:141], s[18:19], 0, v[130:131]
	global_load_lds_dwordx4 v[140:141], off
	s_mov_b32 m0, s0
	v_lshl_add_u64 v[140:141], s[18:19], 0, v[128:129]
	global_load_lds_dwordx4 v[140:141], off
	s_waitcnt vmcnt(6)
	s_barrier
	v_mfma_f32_16x16x32_bf16 v[44:47], v[188:191], v[156:159], v[44:47]
	v_mfma_f32_16x16x32_bf16 v[36:39], v[196:199], v[156:159], v[36:39]
	v_mfma_f32_16x16x32_bf16 v[28:31], v[188:191], v[164:167], v[28:31]
	v_mfma_f32_16x16x32_bf16 v[20:23], v[196:199], v[164:167], v[20:23]
	v_mfma_f32_16x16x32_bf16 v[12:15], v[188:191], v[172:175], v[12:15]
	v_mfma_f32_16x16x32_bf16 v[8:11], v[196:199], v[172:175], v[8:11]
	v_mfma_f32_16x16x32_bf16 v[4:7], v[188:191], v[180:183], v[4:7]
	v_mfma_f32_16x16x32_bf16 v[0:3], v[196:199], v[180:183], v[0:3]
	v_mfma_f32_16x16x32_bf16 v[44:47], v[192:195], v[160:163], v[44:47]
	v_mfma_f32_16x16x32_bf16 v[36:39], v[200:203], v[160:163], v[36:39]
	v_mfma_f32_16x16x32_bf16 v[28:31], v[192:195], v[168:171], v[28:31]
	v_mfma_f32_16x16x32_bf16 v[20:23], v[200:203], v[168:171], v[20:23]
	v_mfma_f32_16x16x32_bf16 v[12:15], v[192:195], v[176:179], v[12:15]
	v_mfma_f32_16x16x32_bf16 v[8:11], v[200:203], v[176:179], v[8:11]
	v_mfma_f32_16x16x32_bf16 v[4:7], v[192:195], v[184:187], v[4:7]
	v_mfma_f32_16x16x32_bf16 v[0:3], v[200:203], v[184:187], v[0:3]
	s_movk_i32 s0, 0x100
	s_andn2_b64 vcc, exec, s[16:17]
	s_mov_b64 s[18:19], -1
	s_mov_b64 s[16:17], 0
	s_barrier
	s_cbranch_vccz .LBB0_1505
	s_mul_hi_i32 s0, s78, 0x78787879
	s_lshr_b32 s9, s0, 31
	s_lshr_b32 s0, s0, 3
	s_ashr_i32 s8, s77, 4
	s_add_i32 s0, s0, s9
	s_ashr_i32 s9, s8, 31
	s_lshl_b32 s10, s0, 8
	s_ashr_i32 s11, s10, 31
	s_lshl_b64 s[8:9], s[8:9], 23
	s_add_u32 s0, s58, s8
	v_mov_b32_e32 v141, v206
	s_addc_u32 s16, s59, s9
	s_lshl_b64 s[8:9], s[10:11], 13
	s_add_u32 s0, s0, s8
	v_and_b32_e32 v132, 15, v141
	v_ashrrev_i32_e32 v140, 2, v141
	s_movk_i32 s8, 0xffc0
	s_addc_u32 s9, s16, s9
	v_and_or_b32 v140, v140, s8, v132
	s_lshl_b32 s8, s77, 10
	s_and_b32 s8, s8, 0x3c00
	s_add_u32 s8, s0, s8
	v_lshlrev_b32_e32 v132, 1, v141
	s_addc_u32 s9, s9, 0
	v_and_b32_e32 v132, 0x180, v132
	v_lshl_add_u64 v[142:143], s[8:9], 0, v[132:133]
	v_and_b32_e32 v132, 48, v141
	v_ashrrev_i32_e32 v141, 31, v140
	v_lshl_add_u64 v[142:143], v[142:143], 0, v[132:133]
	v_lshlrev_b64 v[144:145], 13, v[140:141]
	v_lshl_add_u64 v[144:145], v[142:143], 0, v[144:145]
	global_store_dwordx4 v[144:145], v[124:127], off
	global_store_dwordx4 v[144:145], v[120:123], off offset:64
	global_store_dwordx4 v[144:145], v[108:111], off offset:512
	global_store_dwordx4 v[144:145], v[100:103], off offset:576
	s_mov_b32 s0, 0x100000
	s_mov_b64 s[8:9], 0x100000
	v_or_b32_e32 v100, 16, v140
	v_ashrrev_i32_e32 v101, 31, v100
	v_lshlrev_b64 v[100:101], 13, v[100:101]
	v_lshl_add_u64 v[100:101], v[142:143], 0, v[100:101]
	global_store_dwordx4 v[100:101], v[116:119], off
	global_store_dwordx4 v[100:101], v[112:115], off offset:64
	global_store_dwordx4 v[100:101], v[92:95], off offset:512
	global_store_dwordx4 v[100:101], v[84:87], off offset:576
	s_mov_b32 s77, s76
	s_mov_b32 s78, s74
	v_or_b32_e32 v84, 32, v140
	v_ashrrev_i32_e32 v85, 31, v84
	v_lshlrev_b64 v[84:85], 13, v[84:85]
	v_lshl_add_u64 v[84:85], v[142:143], 0, v[84:85]
	global_store_dwordx4 v[84:85], v[104:107], off
	global_store_dwordx4 v[84:85], v[96:99], off offset:64
	global_store_dwordx4 v[84:85], v[76:79], off offset:512
	global_store_dwordx4 v[84:85], v[72:75], off offset:576
	s_mov_b64 s[10:11], s[14:15]
	s_nop 0
	v_or_b32_e32 v72, 48, v140
	v_ashrrev_i32_e32 v73, 31, v72
	v_lshlrev_b64 v[72:73], 13, v[72:73]
	v_lshl_add_u64 v[72:73], v[142:143], 0, v[72:73]
	global_store_dwordx4 v[72:73], v[88:91], off
	global_store_dwordx4 v[72:73], v[80:83], off offset:64
	global_store_dwordx4 v[72:73], v[68:71], off offset:512
	global_store_dwordx4 v[72:73], v[64:67], off offset:576
	s_nop 1
	v_add_co_u32_e32 v66, vcc, s0, v144
	s_mov_b32 s0, 0x120000
	s_nop 0
	v_addc_co_u32_e32 v67, vcc, 0, v145, vcc
	v_lshl_add_u64 v[64:65], v[144:145], 0, s[8:9]
	global_store_dwordx4 v[66:67], v[60:63], off
	global_store_dwordx4 v[64:65], v[56:59], off offset:64
	global_store_dwordx4 v[64:65], v[44:47], off offset:512
	global_store_dwordx4 v[64:65], v[36:39], off offset:576
	s_mov_b64 s[8:9], 0x120000
	s_nop 0
	v_add_co_u32_e32 v38, vcc, s0, v144
	s_mov_b32 s0, 0x140000
	s_nop 0
	v_addc_co_u32_e32 v39, vcc, 0, v145, vcc
	v_lshl_add_u64 v[36:37], v[144:145], 0, s[8:9]
	global_store_dwordx4 v[38:39], v[52:55], off
	global_store_dwordx4 v[36:37], v[48:51], off offset:64
	global_store_dwordx4 v[36:37], v[28:31], off offset:512
	global_store_dwordx4 v[36:37], v[20:23], off offset:576
	s_mov_b64 s[8:9], 0x140000
	s_nop 0
	v_add_co_u32_e32 v22, vcc, s0, v144
	v_lshl_add_u64 v[20:21], v[144:145], 0, s[8:9]
	s_nop 0
	v_addc_co_u32_e32 v23, vcc, 0, v145, vcc
	global_store_dwordx4 v[22:23], v[40:43], off
	global_store_dwordx4 v[20:21], v[32:35], off offset:64
	global_store_dwordx4 v[20:21], v[12:15], off offset:512
	global_store_dwordx4 v[20:21], v[8:11], off offset:576
	s_mov_b64 s[8:9], 0x160000
	s_nop 0
	v_add_co_u32_e32 v10, vcc, 0x160000, v144
	v_lshl_add_u64 v[8:9], v[144:145], 0, s[8:9]
	s_nop 0
	v_addc_co_u32_e32 v11, vcc, 0, v145, vcc
	s_and_b64 vcc, exec, s[4:5]
	s_mov_b64 s[8:9], s[12:13]
	global_store_dwordx4 v[10:11], v[24:27], off
	global_store_dwordx4 v[8:9], v[16:19], off offset:64
	global_store_dwordx4 v[8:9], v[4:7], off offset:512
	global_store_dwordx4 v[8:9], v[0:3], off offset:576
	s_cbranch_vccz .LBB0_1502
	s_waitcnt vmcnt(0)
	s_cmpk_gt_u32 s2, 0xff
	v_readlane_b32 s76, v254, 10
	s_cbranch_scc1 .LBB0_1509
	s_barrier

; #define WAIT_V(n) asm volatile("s_waitcnt vmcnt(" #n ")" ::: "memory")
; #define WAIT_L(n) asm volatile("s_waitcnt lgkmcnt(" #n ")" ::: "memory")
; #define BAR __builtin_amdgcn_s_barrier()
; #define SCHED __builtin_amdgcn_sched_barrier(0)
; template <class Get, class Epi>
; DI void gemm_stream(LAS unsigned char* lds, const int K, const int ld, Get get, Epi epi) {
;     ...
;             LDB(B0, 0, 0); SCHED; LDA(At, 0, 0); STAGE(SAo(1, 1), a1 + hstep);
;             WAIT_L(8); BAR; WAIT_L(0); MMA(0, 0, At, B0); BAR; SCHED;
;             LDB(B1, 0, 1); STAGE(SBo(0, 0), b2);
;             BAR; WAIT_L(0); MMA(0, 1, At, B1); BAR;
;             LDA(At, 0, 1); STAGE(SAo(0, 0), a2);
;             BAR; WAIT_L(0); MMA(1, 0, At, B0); BAR; SCHED;
;             STAGE(SBo(0, 1), b2 + hstep);
;             WAIT_V(6); BAR; MMA(1, 1, At, B1); BAR;
;             LDB(B0, 1, 0); SCHED; LDA(At, 1, 0); STAGE(SAo(0, 1), a2 + hstep);
;             WAIT_L(8); BAR; WAIT_L(0); MMA(0, 0, At, B0); BAR; SCHED;
.LBB0_1630:
	ds_read_b128 v[148:151], v142
	ds_read_b128 v[152:155], v142 offset:1024
	ds_read_b128 v[156:159], v142 offset:2048
	ds_read_b128 v[160:163], v142 offset:3072
	s_add_u32 s12, s10, 0xfff80080
	s_addc_u32 s13, s11, -1
	s_cmp_eq_u32 s59, 28
	s_cselect_b32 s15, s7, s13
	s_cselect_b32 s14, s6, s12
	s_cselect_b32 s13, s9, s58
	s_cselect_b32 s12, s8, s57
	s_mov_b32 m0, s28
	v_lshl_add_u64 v[140:141], s[10:11], 0, v[134:135]
	ds_read_b128 v[164:167], v143
	ds_read_b128 v[168:171], v143 offset:1024
	ds_read_b128 v[172:175], v143 offset:2048
	ds_read_b128 v[176:179], v143 offset:3072
	ds_read_b128 v[180:183], v143 offset:4096
	ds_read_b128 v[184:187], v143 offset:5120
	ds_read_b128 v[188:191], v143 offset:6144
	ds_read_b128 v[192:195], v143 offset:7168
	global_load_lds_dwordx4 v[140:141], off
	s_mov_b32 m0, s29
	v_lshl_add_u64 v[140:141], s[10:11], 0, v[136:137]
	global_load_lds_dwordx4 v[140:141], off
	s_waitcnt lgkmcnt(8)
	s_barrier
	s_waitcnt lgkmcnt(0)
	v_mfma_f32_16x16x32_bf16 v[124:127], v[148:151], v[164:167], v[124:127]
	v_mfma_f32_16x16x32_bf16 v[116:119], v[156:159], v[164:167], v[116:119]
	v_mfma_f32_16x16x32_bf16 v[108:111], v[148:151], v[172:175], v[108:111]
	v_mfma_f32_16x16x32_bf16 v[100:103], v[156:159], v[172:175], v[100:103]
	v_mfma_f32_16x16x32_bf16 v[92:95], v[148:151], v[180:183], v[92:95]
	v_mfma_f32_16x16x32_bf16 v[84:87], v[156:159], v[180:183], v[84:87]
	v_mfma_f32_16x16x32_bf16 v[76:79], v[148:151], v[188:191], v[76:79]
	v_mfma_f32_16x16x32_bf16 v[68:71], v[156:159], v[188:191], v[68:71]
	v_mfma_f32_16x16x32_bf16 v[124:127], v[152:155], v[168:171], v[124:127]
	v_mfma_f32_16x16x32_bf16 v[116:119], v[160:163], v[168:171], v[116:119]
	v_mfma_f32_16x16x32_bf16 v[108:111], v[152:155], v[176:179], v[108:111]
	v_mfma_f32_16x16x32_bf16 v[100:103], v[160:163], v[176:179], v[100:103]
	v_mfma_f32_16x16x32_bf16 v[92:95], v[152:155], v[184:187], v[92:95]
	v_mfma_f32_16x16x32_bf16 v[84:87], v[160:163], v[184:187], v[84:87]
	v_mfma_f32_16x16x32_bf16 v[76:79], v[152:155], v[192:195], v[76:79]
	v_mfma_f32_16x16x32_bf16 v[68:71], v[160:163], v[192:195], v[68:71]
	s_barrier
	s_mov_b32 m0, s35
	v_lshl_add_u64 v[140:141], s[12:13], 0, v[130:131]
	ds_read_b128 v[196:199], v144
	ds_read_b128 v[200:203], v144 offset:1024
	ds_read_b128 v[208:211], v144 offset:2048
	ds_read_b128 v[212:215], v144 offset:3072
	global_load_lds_dwordx4 v[140:141], off
	s_mov_b32 m0, s36
	v_lshl_add_u64 v[204:205], s[12:13], 0, v[128:129]
	global_load_lds_dwordx4 v[204:205], off
	s_barrier
	s_waitcnt lgkmcnt(0)
	v_mfma_f32_16x16x32_bf16 v[120:123], v[196:199], v[164:167], v[120:123]
	v_mfma_f32_16x16x32_bf16 v[112:115], v[208:211], v[164:167], v[112:115]
	v_mfma_f32_16x16x32_bf16 v[104:107], v[196:199], v[172:175], v[104:107]
	v_mfma_f32_16x16x32_bf16 v[96:99], v[208:211], v[172:175], v[96:99]
	v_mfma_f32_16x16x32_bf16 v[88:91], v[196:199], v[180:183], v[88:91]
	v_mfma_f32_16x16x32_bf16 v[80:83], v[208:211], v[180:183], v[80:83]
	v_mfma_f32_16x16x32_bf16 v[72:75], v[196:199], v[188:191], v[72:75]
	v_mfma_f32_16x16x32_bf16 v[64:67], v[208:211], v[188:191], v[64:67]
	v_mfma_f32_16x16x32_bf16 v[120:123], v[200:203], v[168:171], v[120:123]
	v_mfma_f32_16x16x32_bf16 v[112:115], v[212:215], v[168:171], v[112:115]
	v_mfma_f32_16x16x32_bf16 v[104:107], v[200:203], v[176:179], v[104:107]
	v_mfma_f32_16x16x32_bf16 v[96:99], v[212:215], v[176:179], v[96:99]
	v_mfma_f32_16x16x32_bf16 v[88:91], v[200:203], v[184:187], v[88:91]
	v_mfma_f32_16x16x32_bf16 v[80:83], v[212:215], v[184:187], v[80:83]
	v_mfma_f32_16x16x32_bf16 v[72:75], v[200:203], v[192:195], v[72:75]
	v_mfma_f32_16x16x32_bf16 v[64:67], v[212:215], v[192:195], v[64:67]
	s_mov_b32 m0, s3
	v_lshl_add_u64 v[216:217], s[14:15], 0, v[130:131]
	s_barrier
	ds_read_b128 v[164:167], v143 offset:16384
	ds_read_b128 v[168:171], v143 offset:17408
	ds_read_b128 v[172:175], v143 offset:18432
	ds_read_b128 v[176:179], v143 offset:19456
	ds_read_b128 v[180:183], v143 offset:20480
	ds_read_b128 v[184:187], v143 offset:21504
	ds_read_b128 v[188:191], v143 offset:22528
	ds_read_b128 v[192:195], v143 offset:23552
	global_load_lds_dwordx4 v[216:217], off
	s_mov_b32 m0, s16
	v_lshl_add_u64 v[218:219], s[14:15], 0, v[128:129]
	global_load_lds_dwordx4 v[218:219], off
	s_barrier
	s_waitcnt lgkmcnt(0)
	v_mfma_f32_16x16x32_bf16 v[60:63], v[148:151], v[164:167], v[60:63]
	v_mfma_f32_16x16x32_bf16 v[52:55], v[156:159], v[164:167], v[52:55]
	v_mfma_f32_16x16x32_bf16 v[44:47], v[148:151], v[172:175], v[44:47]
	v_mfma_f32_16x16x32_bf16 v[36:39], v[156:159], v[172:175], v[36:39]
	v_mfma_f32_16x16x32_bf16 v[28:31], v[148:151], v[180:183], v[28:31]
	v_mfma_f32_16x16x32_bf16 v[20:23], v[156:159], v[180:183], v[20:23]
	v_mfma_f32_16x16x32_bf16 v[12:15], v[148:151], v[188:191], v[12:15]
	v_mfma_f32_16x16x32_bf16 v[4:7], v[156:159], v[188:191], v[4:7]
	v_mfma_f32_16x16x32_bf16 v[60:63], v[152:155], v[168:171], v[60:63]
	v_mfma_f32_16x16x32_bf16 v[52:55], v[160:163], v[168:171], v[52:55]
	v_mfma_f32_16x16x32_bf16 v[44:47], v[152:155], v[176:179], v[44:47]
	v_mfma_f32_16x16x32_bf16 v[36:39], v[160:163], v[176:179], v[36:39]
	v_mfma_f32_16x16x32_bf16 v[28:31], v[152:155], v[184:187], v[28:31]
	v_mfma_f32_16x16x32_bf16 v[20:23], v[160:163], v[184:187], v[20:23]
	v_mfma_f32_16x16x32_bf16 v[12:15], v[152:155], v[192:195], v[12:15]
	v_mfma_f32_16x16x32_bf16 v[4:7], v[160:163], v[192:195], v[4:7]
	s_barrier
	s_add_u32 s60, s12, 0x80000
	s_addc_u32 s61, s13, 0
	s_mov_b32 m0, s37
	v_lshl_add_u64 v[148:149], s[60:61], 0, v[130:131]
	global_load_lds_dwordx4 v[148:149], off
	s_mov_b32 m0, s38
	v_lshl_add_u64 v[148:149], s[60:61], 0, v[128:129]
	global_load_lds_dwordx4 v[148:149], off
	s_waitcnt vmcnt(6)
	s_barrier
; #define WAIT_V(n) asm volatile("s_waitcnt vmcnt(" #n ")" ::: "memory")
; #define WAIT_L(n) asm volatile("s_waitcnt lgkmcnt(" #n ")" ::: "memory")
; #define BAR __builtin_amdgcn_s_barrier()
; #define SCHED __builtin_amdgcn_sched_barrier(0)
; template <class Get, class Epi>
; DI void gemm_stream(LAS unsigned char* lds, const int K, const int ld, Get get, Epi epi) {
;     ...
;             WAIT_V(6); BAR; MMA(1, 1, At, B1); BAR;
;             LDB(B0, 1, 0); SCHED; LDA(At, 1, 0); STAGE(SAo(0, 1), a2 + hstep);
;             WAIT_L(8); BAR; WAIT_L(0); MMA(0, 0, At, B0); BAR; SCHED;
;             LDB(B1, 1, 1); STAGE(SBo(1, 0), b3);
;             BAR; WAIT_L(0); MMA(0, 1, At, B1); BAR;
;             LDA(At, 1, 1); STAGE(SAo(1, 0), a3);
;             BAR; WAIT_L(0); MMA(1, 0, At, B0); BAR; SCHED;
;             STAGE(SBo(1, 1), b3 + hstep);
;             WAIT_V(6); BAR; MMA(1, 1, At, B1); BAR;
	v_mfma_f32_16x16x32_bf16 v[56:59], v[196:199], v[164:167], v[56:59]
	v_mfma_f32_16x16x32_bf16 v[48:51], v[208:211], v[164:167], v[48:51]
	v_mfma_f32_16x16x32_bf16 v[40:43], v[196:199], v[172:175], v[40:43]
	v_mfma_f32_16x16x32_bf16 v[32:35], v[208:211], v[172:175], v[32:35]
	v_mfma_f32_16x16x32_bf16 v[24:27], v[196:199], v[180:183], v[24:27]
	v_mfma_f32_16x16x32_bf16 v[16:19], v[208:211], v[180:183], v[16:19]
	v_mfma_f32_16x16x32_bf16 v[8:11], v[196:199], v[188:191], v[8:11]
	v_mfma_f32_16x16x32_bf16 v[0:3], v[208:211], v[188:191], v[0:3]
	v_mfma_f32_16x16x32_bf16 v[56:59], v[200:203], v[168:171], v[56:59]
	v_mfma_f32_16x16x32_bf16 v[48:51], v[212:215], v[168:171], v[48:51]
	v_mfma_f32_16x16x32_bf16 v[40:43], v[200:203], v[176:179], v[40:43]
	v_mfma_f32_16x16x32_bf16 v[32:35], v[212:215], v[176:179], v[32:35]
	v_mfma_f32_16x16x32_bf16 v[24:27], v[200:203], v[184:187], v[24:27]
	v_mfma_f32_16x16x32_bf16 v[16:19], v[212:215], v[184:187], v[16:19]
	v_mfma_f32_16x16x32_bf16 v[8:11], v[200:203], v[192:195], v[8:11]
	v_mfma_f32_16x16x32_bf16 v[0:3], v[212:215], v[192:195], v[0:3]
	s_barrier
	ds_read_b128 v[148:151], v145
	ds_read_b128 v[152:155], v145 offset:1024
	ds_read_b128 v[156:159], v145 offset:2048
	ds_read_b128 v[160:163], v145 offset:3072
	s_add_u32 s14, s14, 0x80000
	s_addc_u32 s15, s15, 0
	s_mov_b32 m0, s17
	v_lshl_add_u64 v[196:197], s[14:15], 0, v[130:131]
	ds_read_b128 v[164:167], v143 offset:32768
	ds_read_b128 v[168:171], v143 offset:33792
	ds_read_b128 v[172:175], v143 offset:34816
	ds_read_b128 v[176:179], v143 offset:35840
	ds_read_b128 v[180:183], v143 offset:36864
	ds_read_b128 v[184:187], v143 offset:37888
	ds_read_b128 v[188:191], v143 offset:38912
	ds_read_b128 v[192:195], v143 offset:39936
	global_load_lds_dwordx4 v[196:197], off
	s_mov_b32 m0, s18
	v_lshl_add_u64 v[196:197], s[14:15], 0, v[128:129]
	global_load_lds_dwordx4 v[196:197], off
	s_waitcnt lgkmcnt(8)
	s_barrier
	s_waitcnt lgkmcnt(0)
	v_mfma_f32_16x16x32_bf16 v[124:127], v[148:151], v[164:167], v[124:127]
	v_mfma_f32_16x16x32_bf16 v[116:119], v[156:159], v[164:167], v[116:119]
	v_mfma_f32_16x16x32_bf16 v[108:111], v[148:151], v[172:175], v[108:111]
	v_mfma_f32_16x16x32_bf16 v[100:103], v[156:159], v[172:175], v[100:103]
	v_mfma_f32_16x16x32_bf16 v[92:95], v[148:151], v[180:183], v[92:95]
	v_mfma_f32_16x16x32_bf16 v[84:87], v[156:159], v[180:183], v[84:87]
	v_mfma_f32_16x16x32_bf16 v[76:79], v[148:151], v[188:191], v[76:79]
	v_mfma_f32_16x16x32_bf16 v[68:71], v[156:159], v[188:191], v[68:71]
	v_mfma_f32_16x16x32_bf16 v[124:127], v[152:155], v[168:171], v[124:127]
	v_mfma_f32_16x16x32_bf16 v[116:119], v[160:163], v[168:171], v[116:119]
	v_mfma_f32_16x16x32_bf16 v[108:111], v[152:155], v[176:179], v[108:111]
	v_mfma_f32_16x16x32_bf16 v[100:103], v[160:163], v[176:179], v[100:103]
	v_mfma_f32_16x16x32_bf16 v[92:95], v[152:155], v[184:187], v[92:95]
	v_mfma_f32_16x16x32_bf16 v[84:87], v[160:163], v[184:187], v[84:87]
	v_mfma_f32_16x16x32_bf16 v[76:79], v[152:155], v[192:195], v[76:79]
	v_mfma_f32_16x16x32_bf16 v[68:71], v[160:163], v[192:195], v[68:71]
	s_barrier
	s_mov_b32 m0, s39
	v_lshl_add_u64 v[140:141], v[140:141], 0, s[0:1]
	ds_read_b128 v[196:199], v146
	ds_read_b128 v[200:203], v146 offset:1024
	ds_read_b128 v[208:211], v146 offset:2048
	ds_read_b128 v[212:215], v146 offset:3072
	global_load_lds_dwordx4 v[140:141], off
	s_mov_b32 m0, s40
	v_lshl_add_u64 v[140:141], v[204:205], 0, s[0:1]
	global_load_lds_dwordx4 v[140:141], off
	s_barrier
	s_waitcnt lgkmcnt(0)
	v_mfma_f32_16x16x32_bf16 v[120:123], v[196:199], v[164:167], v[120:123]
	v_mfma_f32_16x16x32_bf16 v[112:115], v[208:211], v[164:167], v[112:115]
	v_mfma_f32_16x16x32_bf16 v[104:107], v[196:199], v[172:175], v[104:107]
	v_mfma_f32_16x16x32_bf16 v[96:99], v[208:211], v[172:175], v[96:99]
	v_mfma_f32_16x16x32_bf16 v[88:91], v[196:199], v[180:183], v[88:91]
	v_mfma_f32_16x16x32_bf16 v[80:83], v[208:211], v[180:183], v[80:83]
	v_mfma_f32_16x16x32_bf16 v[72:75], v[196:199], v[188:191], v[72:75]
	v_mfma_f32_16x16x32_bf16 v[64:67], v[208:211], v[188:191], v[64:67]
	v_mfma_f32_16x16x32_bf16 v[120:123], v[200:203], v[168:171], v[120:123]
	v_mfma_f32_16x16x32_bf16 v[112:115], v[212:215], v[168:171], v[112:115]
	v_mfma_f32_16x16x32_bf16 v[104:107], v[200:203], v[176:179], v[104:107]
	v_mfma_f32_16x16x32_bf16 v[96:99], v[212:215], v[176:179], v[96:99]
	v_mfma_f32_16x16x32_bf16 v[88:91], v[200:203], v[184:187], v[88:91]
	v_mfma_f32_16x16x32_bf16 v[80:83], v[212:215], v[184:187], v[80:83]
	v_mfma_f32_16x16x32_bf16 v[72:75], v[200:203], v[192:195], v[72:75]
	v_mfma_f32_16x16x32_bf16 v[64:67], v[212:215], v[192:195], v[64:67]
	s_mov_b32 m0, s20
	v_lshl_add_u64 v[140:141], v[216:217], 0, s[0:1]
	s_barrier
	ds_read_b128 v[164:167], v143 offset:49152
	ds_read_b128 v[168:171], v143 offset:50176
	ds_read_b128 v[172:175], v143 offset:51200
	ds_read_b128 v[176:179], v143 offset:52224
	ds_read_b128 v[180:183], v143 offset:53248
	ds_read_b128 v[184:187], v143 offset:54272
	ds_read_b128 v[188:191], v143 offset:55296
	ds_read_b128 v[192:195], v143 offset:56320
	global_load_lds_dwordx4 v[140:141], off
	s_mov_b32 m0, s21
	v_lshl_add_u64 v[140:141], v[218:219], 0, s[0:1]
	global_load_lds_dwordx4 v[140:141], off
	s_barrier
; DI float silu_f(float g) { return g * __builtin_amdgcn_rcpf(1.f + __builtin_amdgcn_exp2f(-LOG2E * g)); }
; #define WAIT_V(n) asm volatile("s_waitcnt vmcnt(" #n ")" ::: "memory")
; #define WAIT_L(n) asm volatile("s_waitcnt lgkmcnt(" #n ")" ::: "memory")
; #define BAR __builtin_amdgcn_s_barrier()
; #define SCHED __builtin_amdgcn_sched_barrier(0)
; #define EPI_DONE do { } while (0)
; template <class Get, class Epi>
; DI void gemm_stream(LAS unsigned char* lds, const int K, const int ld, Get get, Epi epi) {
;     ...
;             BAR; WAIT_L(0); MMA(1, 0, At, B0); BAR; SCHED;
;             STAGE(SBo(1, 1), b3 + hstep);
;             WAIT_V(6); BAR; MMA(1, 1, At, B1); BAR;
;         }
; DI void epi_swiglu(const Acc& acc, int brow, int pn, bf16_t* hid) {
;     EPI_IDX
; #pragma unroll
;     for (int ai = 0; ai < 2; ++ai)
; #pragma unroll
;         for (int m = 0; m < 4; ++m) {
;             const int r = brow + ai * 128 + wr * 64 + m * 16 + fr;
;             bf16_t* rp = hid + (size_t)r * FF + pn * 128 + wc * 32 + fq * 4;
; #pragma unroll
;             for (int n = 0; n < 2; ++n) {
;                 const f32x4 g = acc[ai][0][m][n], u = acc[ai][1][m][n];
;                 float o[4];
; #pragma unroll
;                 for (int j = 0; j < 4; ++j) o[j] = silu_f(g[j]) * u[j];
;                 st4(rp + n * 16, o[0], o[1], o[2], o[3]);
;             }
;         }
;     EPI_DONE;
; }
	s_waitcnt lgkmcnt(0)
	v_mfma_f32_16x16x32_bf16 v[60:63], v[148:151], v[164:167], v[60:63]
	v_mfma_f32_16x16x32_bf16 v[52:55], v[156:159], v[164:167], v[52:55]
	v_mfma_f32_16x16x32_bf16 v[44:47], v[148:151], v[172:175], v[44:47]
	v_mfma_f32_16x16x32_bf16 v[36:39], v[156:159], v[172:175], v[36:39]
	v_mfma_f32_16x16x32_bf16 v[28:31], v[148:151], v[180:183], v[28:31]
	v_mfma_f32_16x16x32_bf16 v[20:23], v[156:159], v[180:183], v[20:23]
	v_mfma_f32_16x16x32_bf16 v[12:15], v[148:151], v[188:191], v[12:15]
	v_mfma_f32_16x16x32_bf16 v[4:7], v[156:159], v[188:191], v[4:7]
	v_mfma_f32_16x16x32_bf16 v[60:63], v[152:155], v[168:171], v[60:63]
	v_mfma_f32_16x16x32_bf16 v[52:55], v[160:163], v[168:171], v[52:55]
	v_mfma_f32_16x16x32_bf16 v[44:47], v[152:155], v[176:179], v[44:47]
	v_mfma_f32_16x16x32_bf16 v[36:39], v[160:163], v[176:179], v[36:39]
	v_mfma_f32_16x16x32_bf16 v[28:31], v[152:155], v[184:187], v[28:31]
	v_mfma_f32_16x16x32_bf16 v[20:23], v[160:163], v[184:187], v[20:23]
	v_mfma_f32_16x16x32_bf16 v[12:15], v[152:155], v[192:195], v[12:15]
	v_mfma_f32_16x16x32_bf16 v[4:7], v[160:163], v[192:195], v[4:7]
	s_barrier
	s_add_u32 s12, s12, 0x80080
	s_addc_u32 s13, s13, 0
	s_mov_b32 m0, s41
	v_lshl_add_u64 v[140:141], s[12:13], 0, v[130:131]
	global_load_lds_dwordx4 v[140:141], off
	s_mov_b32 m0, s52
	v_lshl_add_u64 v[140:141], s[12:13], 0, v[128:129]
	global_load_lds_dwordx4 v[140:141], off
	s_waitcnt vmcnt(6)
	s_barrier
	v_mfma_f32_16x16x32_bf16 v[56:59], v[196:199], v[164:167], v[56:59]
	v_mfma_f32_16x16x32_bf16 v[48:51], v[208:211], v[164:167], v[48:51]
	v_mfma_f32_16x16x32_bf16 v[40:43], v[196:199], v[172:175], v[40:43]
	v_mfma_f32_16x16x32_bf16 v[32:35], v[208:211], v[172:175], v[32:35]
	v_mfma_f32_16x16x32_bf16 v[24:27], v[196:199], v[180:183], v[24:27]
	v_mfma_f32_16x16x32_bf16 v[16:19], v[208:211], v[180:183], v[16:19]
	v_mfma_f32_16x16x32_bf16 v[8:11], v[196:199], v[188:191], v[8:11]
	v_mfma_f32_16x16x32_bf16 v[0:3], v[208:211], v[188:191], v[0:3]
	v_mfma_f32_16x16x32_bf16 v[56:59], v[200:203], v[168:171], v[56:59]
	v_mfma_f32_16x16x32_bf16 v[48:51], v[212:215], v[168:171], v[48:51]
	v_mfma_f32_16x16x32_bf16 v[40:43], v[200:203], v[176:179], v[40:43]
	v_mfma_f32_16x16x32_bf16 v[32:35], v[212:215], v[176:179], v[32:35]
	v_mfma_f32_16x16x32_bf16 v[24:27], v[200:203], v[184:187], v[24:27]
	v_mfma_f32_16x16x32_bf16 v[16:19], v[212:215], v[184:187], v[16:19]
	v_mfma_f32_16x16x32_bf16 v[8:11], v[200:203], v[192:195], v[8:11]
	v_mfma_f32_16x16x32_bf16 v[0:3], v[212:215], v[192:195], v[0:3]
	s_add_i32 s59, s59, 2
	s_add_u32 s10, s10, 0x100
	s_addc_u32 s11, s11, 0
	s_add_u32 s57, s57, 0x100
	s_addc_u32 s58, s58, 0
	s_cmp_gt_u32 s59, 29
	s_barrier
	s_cbranch_scc0 .LBB0_1630
	s_lshl_b32 s10, s55, 8
	v_mov_b32_e32 v132, v206
	v_mul_f32_e32 v149, 0xbfb8aa3b, v125
	v_and_or_b32 v141, v132, 15, s10
	s_lshl_b32 s10, s56, 7
	s_ashr_i32 s11, s10, 31
	s_lshl_b64 s[10:11], s[10:11], 1
	v_ashrrev_i32_e32 v140, 2, v132
	s_add_u32 s10, s80, s10
	v_and_b32_e32 v140, 0xffffffc0, v140
	s_addc_u32 s11, s81, s11
	v_lshrrev_b32_e32 v148, 1, v132
	v_and_b32_e32 v132, 0xc0, v132
	v_add_u32_e32 v147, v141, v140
	v_lshl_add_u64 v[140:141], s[10:11], 0, v[132:133]
	v_and_b32_e32 v132, 24, v148
	v_mul_f32_e32 v148, 0xbfb8aa3b, v124
	v_exp_f32_e32 v148, v148
	v_exp_f32_e32 v149, v149
	v_lshl_add_u64 v[140:141], v[140:141], 0, v[132:133]
	v_mad_i64_i32 v[152:153], s[10:11], v147, s23, v[140:141]
	v_add_f32_e32 v132, 1.0, v148
	v_rcp_f32_e32 v148, v132
	v_add_f32_e32 v132, 1.0, v149
	v_mul_f32_e32 v149, 0xbfb8aa3b, v126
	v_exp_f32_e32 v150, v149
	v_mul_f32_e32 v149, 0xbfb8aa3b, v127
	v_exp_f32_e32 v151, v149
	v_rcp_f32_e32 v149, v132
	v_add_f32_e32 v132, 1.0, v150
	v_rcp_f32_e32 v150, v132
	v_add_f32_e32 v132, 1.0, v151
	v_rcp_f32_e32 v151, v132
	v_pk_mul_f32 v[124:125], v[124:125], v[148:149]
	s_and_b64 vcc, exec, s[4:5]
	v_pk_mul_f32 v[120:121], v[124:125], v[120:121]
	v_pk_mul_f32 v[124:125], v[126:127], v[150:151]
	v_cvt_pk_bf16_f32 v120, v120, v121
	v_mul_f32_e32 v121, 0xbfb8aa3b, v116
	v_pk_mul_f32 v[122:123], v[124:125], v[122:123]
	v_exp_f32_e32 v124, v121
	v_mul_f32_e32 v121, 0xbfb8aa3b, v117
	v_exp_f32_e32 v125, v121
	v_cvt_pk_bf16_f32 v121, v122, v123
	v_add_f32_e32 v122, 1.0, v124
	v_mul_f32_e32 v124, 0xbfb8aa3b, v118
	v_add_f32_e32 v123, 1.0, v125
	v_mul_f32_e32 v125, 0xbfb8aa3b, v119
	v_exp_f32_e32 v124, v124
	v_exp_f32_e32 v125, v125
	v_rcp_f32_e32 v122, v122
	v_rcp_f32_e32 v123, v123
	v_add_f32_e32 v124, 1.0, v124
	v_add_f32_e32 v125, 1.0, v125
	v_rcp_f32_e32 v124, v124
	v_rcp_f32_e32 v125, v125
	v_pk_mul_f32 v[116:117], v[116:117], v[122:123]
	s_mov_b32 s56, s53
	v_pk_mul_f32 v[112:113], v[116:117], v[112:113]
	v_pk_mul_f32 v[116:117], v[118:119], v[124:125]
	v_cvt_pk_bf16_f32 v112, v112, v113
	v_pk_mul_f32 v[114:115], v[116:117], v[114:115]
	v_or_b32_e32 v116, 16, v147
	v_cvt_pk_bf16_f32 v113, v114, v115
	global_store_dwordx2 v[152:153], v[112:113], off offset:32
	v_mul_f32_e32 v112, 0xbfb8aa3b, v108
	v_mul_f32_e32 v113, 0xbfb8aa3b, v109
	v_exp_f32_e32 v112, v112
	v_exp_f32_e32 v113, v113
	v_mul_f32_e32 v114, 0xbfb8aa3b, v110
	v_mul_f32_e32 v115, 0xbfb8aa3b, v111
	v_exp_f32_e32 v114, v114
	v_exp_f32_e32 v115, v115
	v_add_f32_e32 v112, 1.0, v112
	v_add_f32_e32 v113, 1.0, v113
	v_rcp_f32_e32 v112, v112
	v_rcp_f32_e32 v113, v113
	v_add_f32_e32 v114, 1.0, v114
	v_add_f32_e32 v115, 1.0, v115
	v_rcp_f32_e32 v114, v114
	v_rcp_f32_e32 v115, v115
	v_pk_mul_f32 v[108:109], v[108:109], v[112:113]
	v_mad_i64_i32 v[116:117], s[10:11], v116, s23, v[140:141]
	v_pk_mul_f32 v[104:105], v[108:109], v[104:105]
	v_pk_mul_f32 v[108:109], v[110:111], v[114:115]
; DI float silu_f(float g) { return g * __builtin_amdgcn_rcpf(1.f + __builtin_amdgcn_exp2f(-LOG2E * g)); }
; #define EPI_DONE do { } while (0)
; DI void epi_swiglu(const Acc& acc, int brow, int pn, bf16_t* hid) {
;     EPI_IDX
; #pragma unroll
;     for (int ai = 0; ai < 2; ++ai)
; #pragma unroll
;         for (int m = 0; m < 4; ++m) {
;             const int r = brow + ai * 128 + wr * 64 + m * 16 + fr;
;             bf16_t* rp = hid + (size_t)r * FF + pn * 128 + wc * 32 + fq * 4;
; #pragma unroll
;             for (int n = 0; n < 2; ++n) {
;                 const f32x4 g = acc[ai][0][m][n], u = acc[ai][1][m][n];
;                 float o[4];
; #pragma unroll
;                 for (int j = 0; j < 4; ++j) o[j] = silu_f(g[j]) * u[j];
;                 st4(rp + n * 16, o[0], o[1], o[2], o[3]);
;             }
;         }
;     EPI_DONE;
; }
	v_cvt_pk_bf16_f32 v104, v104, v105
	v_mul_f32_e32 v105, 0xbfb8aa3b, v100
	v_pk_mul_f32 v[106:107], v[108:109], v[106:107]
	v_exp_f32_e32 v108, v105
	v_mul_f32_e32 v105, 0xbfb8aa3b, v101
	v_exp_f32_e32 v109, v105
	v_cvt_pk_bf16_f32 v105, v106, v107
	v_add_f32_e32 v106, 1.0, v108
	v_mul_f32_e32 v108, 0xbfb8aa3b, v102
	v_add_f32_e32 v107, 1.0, v109
	v_mul_f32_e32 v109, 0xbfb8aa3b, v103
	v_exp_f32_e32 v108, v108
	v_exp_f32_e32 v109, v109
	v_rcp_f32_e32 v106, v106
	v_rcp_f32_e32 v107, v107
	v_add_f32_e32 v108, 1.0, v108
	v_add_f32_e32 v109, 1.0, v109
	v_rcp_f32_e32 v108, v108
	v_rcp_f32_e32 v109, v109
	v_pk_mul_f32 v[100:101], v[100:101], v[106:107]
	s_mov_b32 s55, s54
	v_pk_mul_f32 v[96:97], v[100:101], v[96:97]
	v_pk_mul_f32 v[100:101], v[102:103], v[108:109]
	v_cvt_pk_bf16_f32 v96, v96, v97
	v_pk_mul_f32 v[98:99], v[100:101], v[98:99]
	v_or_b32_e32 v100, 32, v147
	v_cvt_pk_bf16_f32 v97, v98, v99
	global_store_dwordx2 v[116:117], v[96:97], off offset:32
	v_mul_f32_e32 v96, 0xbfb8aa3b, v92
	v_mul_f32_e32 v97, 0xbfb8aa3b, v93
	v_exp_f32_e32 v96, v96
	v_exp_f32_e32 v97, v97
	v_mul_f32_e32 v98, 0xbfb8aa3b, v94
	v_mul_f32_e32 v99, 0xbfb8aa3b, v95
	v_exp_f32_e32 v98, v98
	v_exp_f32_e32 v99, v99
	v_add_f32_e32 v96, 1.0, v96
	v_add_f32_e32 v97, 1.0, v97
	v_rcp_f32_e32 v96, v96
	v_rcp_f32_e32 v97, v97
	v_add_f32_e32 v98, 1.0, v98
	v_add_f32_e32 v99, 1.0, v99
	v_rcp_f32_e32 v98, v98
	v_rcp_f32_e32 v99, v99
	v_pk_mul_f32 v[92:93], v[92:93], v[96:97]
	v_mad_i64_i32 v[100:101], s[10:11], v100, s23, v[140:141]
	v_pk_mul_f32 v[88:89], v[92:93], v[88:89]
	v_pk_mul_f32 v[92:93], v[94:95], v[98:99]
	v_cvt_pk_bf16_f32 v88, v88, v89
	v_mul_f32_e32 v89, 0xbfb8aa3b, v84
	v_pk_mul_f32 v[90:91], v[92:93], v[90:91]
	v_exp_f32_e32 v92, v89
	v_mul_f32_e32 v89, 0xbfb8aa3b, v85
	v_exp_f32_e32 v93, v89
	v_cvt_pk_bf16_f32 v89, v90, v91
	v_add_f32_e32 v90, 1.0, v92
	v_mul_f32_e32 v92, 0xbfb8aa3b, v86
	v_add_f32_e32 v91, 1.0, v93
	v_mul_f32_e32 v93, 0xbfb8aa3b, v87
	v_exp_f32_e32 v92, v92
	v_exp_f32_e32 v93, v93
	v_rcp_f32_e32 v90, v90
	v_rcp_f32_e32 v91, v91
	v_add_f32_e32 v92, 1.0, v92
	v_add_f32_e32 v93, 1.0, v93
	v_rcp_f32_e32 v92, v92
	v_rcp_f32_e32 v93, v93
	v_pk_mul_f32 v[84:85], v[84:85], v[90:91]
	s_mov_b64 s[12:13], s[8:9]
	v_pk_mul_f32 v[80:81], v[84:85], v[80:81]
	v_pk_mul_f32 v[84:85], v[86:87], v[92:93]
	v_cvt_pk_bf16_f32 v80, v80, v81
	v_pk_mul_f32 v[82:83], v[84:85], v[82:83]
	v_or_b32_e32 v84, 48, v147
	v_cvt_pk_bf16_f32 v81, v82, v83
	global_store_dwordx2 v[100:101], v[80:81], off offset:32
	v_mul_f32_e32 v80, 0xbfb8aa3b, v76
	v_mul_f32_e32 v81, 0xbfb8aa3b, v77
	v_exp_f32_e32 v80, v80
	v_exp_f32_e32 v81, v81
	v_mul_f32_e32 v82, 0xbfb8aa3b, v78
	v_mul_f32_e32 v83, 0xbfb8aa3b, v79
	v_exp_f32_e32 v82, v82
	v_exp_f32_e32 v83, v83
	v_add_f32_e32 v80, 1.0, v80
	v_add_f32_e32 v81, 1.0, v81
	v_rcp_f32_e32 v80, v80
	v_rcp_f32_e32 v81, v81
	v_add_f32_e32 v82, 1.0, v82
	v_add_f32_e32 v83, 1.0, v83
	v_rcp_f32_e32 v82, v82
	v_rcp_f32_e32 v83, v83
	v_pk_mul_f32 v[76:77], v[76:77], v[80:81]
	v_mad_i64_i32 v[84:85], s[10:11], v84, s23, v[140:141]
	v_pk_mul_f32 v[72:73], v[76:77], v[72:73]
	v_pk_mul_f32 v[76:77], v[78:79], v[82:83]
	v_cvt_pk_bf16_f32 v72, v72, v73
	v_mul_f32_e32 v73, 0xbfb8aa3b, v68
	v_pk_mul_f32 v[74:75], v[76:77], v[74:75]
	v_exp_f32_e32 v76, v73
	v_mul_f32_e32 v73, 0xbfb8aa3b, v69
	v_exp_f32_e32 v77, v73
	v_cvt_pk_bf16_f32 v73, v74, v75
	v_add_f32_e32 v74, 1.0, v76
	v_mul_f32_e32 v76, 0xbfb8aa3b, v70
	v_add_f32_e32 v75, 1.0, v77
	v_mul_f32_e32 v77, 0xbfb8aa3b, v71
	v_exp_f32_e32 v76, v76
	v_exp_f32_e32 v77, v77
	v_rcp_f32_e32 v74, v74
	v_rcp_f32_e32 v75, v75
	v_add_f32_e32 v76, 1.0, v76
	v_add_f32_e32 v77, 1.0, v77
	v_rcp_f32_e32 v76, v76
	v_rcp_f32_e32 v77, v77
	v_pk_mul_f32 v[68:69], v[68:69], v[74:75]
	global_store_dwordx2 v[152:153], v[120:121], off
	v_pk_mul_f32 v[64:65], v[68:69], v[64:65]
	v_pk_mul_f32 v[68:69], v[70:71], v[76:77]
	v_cvt_pk_bf16_f32 v64, v64, v65
	v_pk_mul_f32 v[66:67], v[68:69], v[66:67]
	v_add_u32_e32 v68, 0x80, v147
	v_cvt_pk_bf16_f32 v65, v66, v67
	global_store_dwordx2 v[84:85], v[64:65], off offset:32
	v_mul_f32_e32 v64, 0xbfb8aa3b, v60
	v_mul_f32_e32 v65, 0xbfb8aa3b, v61
	v_exp_f32_e32 v64, v64
	v_exp_f32_e32 v65, v65
	v_mul_f32_e32 v66, 0xbfb8aa3b, v62
	v_mul_f32_e32 v67, 0xbfb8aa3b, v63
	v_exp_f32_e32 v66, v66
	v_exp_f32_e32 v67, v67
	v_add_f32_e32 v64, 1.0, v64
	v_add_f32_e32 v65, 1.0, v65
	v_rcp_f32_e32 v64, v64
	v_rcp_f32_e32 v65, v65
	v_add_f32_e32 v66, 1.0, v66
	v_add_f32_e32 v67, 1.0, v67
	v_rcp_f32_e32 v66, v66
	v_rcp_f32_e32 v67, v67
	v_pk_mul_f32 v[60:61], v[60:61], v[64:65]
	v_mad_i64_i32 v[68:69], s[10:11], v68, s23, v[140:141]
	v_pk_mul_f32 v[56:57], v[60:61], v[56:57]
	v_pk_mul_f32 v[60:61], v[62:63], v[66:67]
	v_cvt_pk_bf16_f32 v56, v56, v57
	v_mul_f32_e32 v57, 0xbfb8aa3b, v52
	v_pk_mul_f32 v[58:59], v[60:61], v[58:59]
	v_exp_f32_e32 v60, v57
	v_mul_f32_e32 v57, 0xbfb8aa3b, v53
	v_exp_f32_e32 v61, v57
	v_cvt_pk_bf16_f32 v57, v58, v59
	v_add_f32_e32 v58, 1.0, v60
	v_mul_f32_e32 v60, 0xbfb8aa3b, v54
	v_add_f32_e32 v59, 1.0, v61
	v_mul_f32_e32 v61, 0xbfb8aa3b, v55
	v_exp_f32_e32 v60, v60
	v_exp_f32_e32 v61, v61
	v_rcp_f32_e32 v58, v58
	v_rcp_f32_e32 v59, v59
	v_add_f32_e32 v60, 1.0, v60
	v_add_f32_e32 v61, 1.0, v61
	v_rcp_f32_e32 v60, v60
	v_rcp_f32_e32 v61, v61
; DI float silu_f(float g) { return g * __builtin_amdgcn_rcpf(1.f + __builtin_amdgcn_exp2f(-LOG2E * g)); }
; #define EPI_DONE do { } while (0)
; DI void epi_swiglu(const Acc& acc, int brow, int pn, bf16_t* hid) {
;     EPI_IDX
; #pragma unroll
;     for (int ai = 0; ai < 2; ++ai)
; #pragma unroll
;         for (int m = 0; m < 4; ++m) {
;             const int r = brow + ai * 128 + wr * 64 + m * 16 + fr;
;             bf16_t* rp = hid + (size_t)r * FF + pn * 128 + wc * 32 + fq * 4;
; #pragma unroll
;             for (int n = 0; n < 2; ++n) {
;                 const f32x4 g = acc[ai][0][m][n], u = acc[ai][1][m][n];
;                 float o[4];
; #pragma unroll
;                 for (int j = 0; j < 4; ++j) o[j] = silu_f(g[j]) * u[j];
;                 st4(rp + n * 16, o[0], o[1], o[2], o[3]);
;             }
;         }
;     EPI_DONE;
; }
	v_pk_mul_f32 v[52:53], v[52:53], v[58:59]
	global_store_dwordx2 v[116:117], v[104:105], off
	v_pk_mul_f32 v[48:49], v[52:53], v[48:49]
	v_pk_mul_f32 v[52:53], v[54:55], v[60:61]
	v_cvt_pk_bf16_f32 v48, v48, v49
	v_pk_mul_f32 v[50:51], v[52:53], v[50:51]
	v_add_u32_e32 v52, 0x90, v147
	v_cvt_pk_bf16_f32 v49, v50, v51
	global_store_dwordx2 v[68:69], v[48:49], off offset:32
	v_mul_f32_e32 v48, 0xbfb8aa3b, v44
	v_mul_f32_e32 v49, 0xbfb8aa3b, v45
	v_exp_f32_e32 v48, v48
	v_exp_f32_e32 v49, v49
	v_mul_f32_e32 v50, 0xbfb8aa3b, v46
	v_mul_f32_e32 v51, 0xbfb8aa3b, v47
	v_exp_f32_e32 v50, v50
	v_exp_f32_e32 v51, v51
	v_add_f32_e32 v48, 1.0, v48
	v_add_f32_e32 v49, 1.0, v49
	v_rcp_f32_e32 v48, v48
	v_rcp_f32_e32 v49, v49
	v_add_f32_e32 v50, 1.0, v50
	v_add_f32_e32 v51, 1.0, v51
	v_rcp_f32_e32 v50, v50
	v_rcp_f32_e32 v51, v51
	v_pk_mul_f32 v[44:45], v[44:45], v[48:49]
	v_mad_i64_i32 v[52:53], s[10:11], v52, s23, v[140:141]
	v_pk_mul_f32 v[40:41], v[44:45], v[40:41]
	v_pk_mul_f32 v[44:45], v[46:47], v[50:51]
	v_cvt_pk_bf16_f32 v40, v40, v41
	v_mul_f32_e32 v41, 0xbfb8aa3b, v36
	v_pk_mul_f32 v[42:43], v[44:45], v[42:43]
	v_exp_f32_e32 v44, v41
	v_mul_f32_e32 v41, 0xbfb8aa3b, v37
	v_exp_f32_e32 v45, v41
	v_cvt_pk_bf16_f32 v41, v42, v43
	v_add_f32_e32 v42, 1.0, v44
	v_mul_f32_e32 v44, 0xbfb8aa3b, v38
	v_add_f32_e32 v43, 1.0, v45
	v_mul_f32_e32 v45, 0xbfb8aa3b, v39
	v_exp_f32_e32 v44, v44
	v_exp_f32_e32 v45, v45
	v_rcp_f32_e32 v42, v42
	v_rcp_f32_e32 v43, v43
	v_add_f32_e32 v44, 1.0, v44
	v_add_f32_e32 v45, 1.0, v45
	v_rcp_f32_e32 v44, v44
	v_rcp_f32_e32 v45, v45
	v_pk_mul_f32 v[36:37], v[36:37], v[42:43]
	global_store_dwordx2 v[100:101], v[88:89], off
	v_pk_mul_f32 v[32:33], v[36:37], v[32:33]
	v_pk_mul_f32 v[36:37], v[38:39], v[44:45]
	v_cvt_pk_bf16_f32 v32, v32, v33
	v_pk_mul_f32 v[34:35], v[36:37], v[34:35]
	v_add_u32_e32 v36, 0xa0, v147
	v_cvt_pk_bf16_f32 v33, v34, v35
	global_store_dwordx2 v[52:53], v[32:33], off offset:32
	v_mul_f32_e32 v32, 0xbfb8aa3b, v28
	v_mul_f32_e32 v33, 0xbfb8aa3b, v29
	v_exp_f32_e32 v32, v32
	v_exp_f32_e32 v33, v33
	v_mul_f32_e32 v34, 0xbfb8aa3b, v30
	v_mul_f32_e32 v35, 0xbfb8aa3b, v31
	v_exp_f32_e32 v34, v34
	v_exp_f32_e32 v35, v35
	v_add_f32_e32 v32, 1.0, v32
	v_add_f32_e32 v33, 1.0, v33
	v_rcp_f32_e32 v32, v32
	v_rcp_f32_e32 v33, v33
	v_add_f32_e32 v34, 1.0, v34
	v_add_f32_e32 v35, 1.0, v35
	v_rcp_f32_e32 v34, v34
	v_rcp_f32_e32 v35, v35
	v_pk_mul_f32 v[28:29], v[28:29], v[32:33]
	v_mad_i64_i32 v[36:37], s[10:11], v36, s23, v[140:141]
	v_pk_mul_f32 v[24:25], v[28:29], v[24:25]
	v_pk_mul_f32 v[28:29], v[30:31], v[34:35]
	v_cvt_pk_bf16_f32 v24, v24, v25
	v_mul_f32_e32 v25, 0xbfb8aa3b, v20
	v_pk_mul_f32 v[26:27], v[28:29], v[26:27]
	v_exp_f32_e32 v28, v25
	v_mul_f32_e32 v25, 0xbfb8aa3b, v21
	v_exp_f32_e32 v29, v25
	v_cvt_pk_bf16_f32 v25, v26, v27
	v_add_f32_e32 v26, 1.0, v28
	v_mul_f32_e32 v28, 0xbfb8aa3b, v22
	v_add_f32_e32 v27, 1.0, v29
	v_mul_f32_e32 v29, 0xbfb8aa3b, v23
	v_exp_f32_e32 v28, v28
	v_exp_f32_e32 v29, v29
	v_rcp_f32_e32 v26, v26
	v_rcp_f32_e32 v27, v27
	v_add_f32_e32 v28, 1.0, v28
	v_add_f32_e32 v29, 1.0, v29
	v_rcp_f32_e32 v28, v28
	v_rcp_f32_e32 v29, v29
	v_pk_mul_f32 v[20:21], v[20:21], v[26:27]
	global_store_dwordx2 v[84:85], v[72:73], off
	v_pk_mul_f32 v[16:17], v[20:21], v[16:17]
	v_pk_mul_f32 v[20:21], v[22:23], v[28:29]
	v_cvt_pk_bf16_f32 v16, v16, v17
	v_pk_mul_f32 v[18:19], v[20:21], v[18:19]
	v_add_u32_e32 v20, 0xb0, v147
	v_cvt_pk_bf16_f32 v17, v18, v19
	global_store_dwordx2 v[36:37], v[16:17], off offset:32
	v_mul_f32_e32 v16, 0xbfb8aa3b, v12
	v_mul_f32_e32 v17, 0xbfb8aa3b, v13
	v_exp_f32_e32 v16, v16
	v_exp_f32_e32 v17, v17
	v_mul_f32_e32 v18, 0xbfb8aa3b, v14
	v_mul_f32_e32 v19, 0xbfb8aa3b, v15
	v_exp_f32_e32 v18, v18
	v_exp_f32_e32 v19, v19
	v_add_f32_e32 v16, 1.0, v16
	v_add_f32_e32 v17, 1.0, v17
	v_rcp_f32_e32 v16, v16
	v_rcp_f32_e32 v17, v17
	v_add_f32_e32 v18, 1.0, v18
	v_add_f32_e32 v19, 1.0, v19
	v_rcp_f32_e32 v18, v18
	v_rcp_f32_e32 v19, v19
	v_pk_mul_f32 v[12:13], v[12:13], v[16:17]
	v_mad_i64_i32 v[20:21], s[10:11], v20, s23, v[140:141]
	v_pk_mul_f32 v[8:9], v[12:13], v[8:9]
	v_pk_mul_f32 v[12:13], v[14:15], v[18:19]
	v_cvt_pk_bf16_f32 v8, v8, v9
	v_mul_f32_e32 v9, 0xbfb8aa3b, v4
	v_pk_mul_f32 v[10:11], v[12:13], v[10:11]
	v_exp_f32_e32 v12, v9
	v_mul_f32_e32 v9, 0xbfb8aa3b, v5
	v_exp_f32_e32 v13, v9
	v_cvt_pk_bf16_f32 v9, v10, v11
	v_add_f32_e32 v10, 1.0, v12
	v_mul_f32_e32 v12, 0xbfb8aa3b, v6
	v_add_f32_e32 v11, 1.0, v13
	v_mul_f32_e32 v13, 0xbfb8aa3b, v7
	v_exp_f32_e32 v12, v12
	v_exp_f32_e32 v13, v13
	v_rcp_f32_e32 v10, v10
	v_rcp_f32_e32 v11, v11
	v_add_f32_e32 v12, 1.0, v12
	v_add_f32_e32 v13, 1.0, v13
	v_rcp_f32_e32 v12, v12
	v_rcp_f32_e32 v13, v13
	v_pk_mul_f32 v[4:5], v[4:5], v[10:11]
	s_mov_b64 s[10:11], s[6:7]
	v_pk_mul_f32 v[0:1], v[4:5], v[0:1]
	v_pk_mul_f32 v[4:5], v[6:7], v[12:13]
	v_cvt_pk_bf16_f32 v0, v0, v1
	v_pk_mul_f32 v[2:3], v[4:5], v[2:3]
	global_store_dwordx2 v[68:69], v[56:57], off
	v_cvt_pk_bf16_f32 v1, v2, v3
	global_store_dwordx2 v[52:53], v[40:41], off
	global_store_dwordx2 v[36:37], v[24:25], off
	global_store_dwordx2 v[20:21], v[8:9], off
	global_store_dwordx2 v[20:21], v[0:1], off offset:32
	s_cbranch_vccz .LBB0_1627
	s_waitcnt vmcnt(0)
	s_cmpk_gt_u32 s2, 0xff
	s_cbranch_scc1 .LBB0_1634
	s_barrier

; #define WAIT_V(n) asm volatile("s_waitcnt vmcnt(" #n ")" ::: "memory")
; #define WAIT_L(n) asm volatile("s_waitcnt lgkmcnt(" #n ")" ::: "memory")
; #define BAR __builtin_amdgcn_s_barrier()
; #define SCHED __builtin_amdgcn_sched_barrier(0)
; template <class Get, class Epi>
; DI void gemm_stream(LAS unsigned char* lds, const int K, const int ld, Get get, Epi epi) {
;     ...
;             LDB(B0, 0, 0); SCHED; LDA(At, 0, 0); STAGE(SAo(1, 1), a1 + hstep);
;             WAIT_L(8); BAR; WAIT_L(0); MMA(0, 0, At, B0); BAR; SCHED;
;             LDB(B1, 0, 1); STAGE(SBo(0, 0), b2);
;             BAR; WAIT_L(0); MMA(0, 1, At, B1); BAR;
;             LDA(At, 0, 1); STAGE(SAo(0, 0), a2);
;             BAR; WAIT_L(0); MMA(1, 0, At, B0); BAR; SCHED;
;             STAGE(SBo(0, 1), b2 + hstep);
;             WAIT_V(6); BAR; MMA(1, 1, At, B1); BAR;
;             LDB(B0, 1, 0); SCHED; LDA(At, 1, 0); STAGE(SAo(0, 1), a2 + hstep);
;             WAIT_L(8); BAR; WAIT_L(0); MMA(0, 0, At, B0); BAR; SCHED;
.LBB0_1697:
	ds_read_b128 v[128:131], v199
	ds_read_b128 v[132:135], v199 offset:1024
	ds_read_b128 v[136:139], v199 offset:2048
	ds_read_b128 v[140:143], v199 offset:3072
	s_add_u32 s8, s6, 0x100
	s_addc_u32 s9, s7, 0
	s_cmpk_eq_i32 s16, 0x54
	s_cselect_b32 s13, s39, s9
	s_cselect_b32 s12, s38, s8
	s_cselect_b32 s11, s41, s15
	s_cselect_b32 s10, s40, s14
	s_mov_b32 m0, s63
	v_lshl_add_u64 v[186:187], s[6:7], 0, v[168:169]
	ds_read_b128 v[144:147], v200
	ds_read_b128 v[148:151], v200 offset:1024
	ds_read_b128 v[152:155], v200 offset:2048
	ds_read_b128 v[156:159], v200 offset:3072
	ds_read_b128 v[160:163], v200 offset:4096
	ds_read_b128 v[174:177], v200 offset:5120
	ds_read_b128 v[178:181], v200 offset:6144
	ds_read_b128 v[182:185], v200 offset:7168
	global_load_lds_dwordx4 v[186:187], off
	s_mov_b32 m0, s74
	v_lshl_add_u64 v[186:187], s[6:7], 0, v[170:171]
	global_load_lds_dwordx4 v[186:187], off
	s_waitcnt lgkmcnt(8)
	s_barrier
	s_waitcnt lgkmcnt(0)
	v_mfma_f32_16x16x32_bf16 v[124:127], v[128:131], v[144:147], v[124:127]
	v_mfma_f32_16x16x32_bf16 v[92:95], v[136:139], v[144:147], v[92:95]
	v_mfma_f32_16x16x32_bf16 v[120:123], v[128:131], v[152:155], v[120:123]
	v_mfma_f32_16x16x32_bf16 v[88:91], v[136:139], v[152:155], v[88:91]
	v_mfma_f32_16x16x32_bf16 v[116:119], v[128:131], v[160:163], v[116:119]
	v_mfma_f32_16x16x32_bf16 v[84:87], v[136:139], v[160:163], v[84:87]
	v_mfma_f32_16x16x32_bf16 v[112:115], v[128:131], v[178:181], v[112:115]
	v_mfma_f32_16x16x32_bf16 v[80:83], v[136:139], v[178:181], v[80:83]
	v_mfma_f32_16x16x32_bf16 v[124:127], v[132:135], v[148:151], v[124:127]
	v_mfma_f32_16x16x32_bf16 v[92:95], v[140:143], v[148:151], v[92:95]
	v_mfma_f32_16x16x32_bf16 v[120:123], v[132:135], v[156:159], v[120:123]
	v_mfma_f32_16x16x32_bf16 v[88:91], v[140:143], v[156:159], v[88:91]
	v_mfma_f32_16x16x32_bf16 v[116:119], v[132:135], v[174:177], v[116:119]
	v_mfma_f32_16x16x32_bf16 v[84:87], v[140:143], v[174:177], v[84:87]
	v_mfma_f32_16x16x32_bf16 v[112:115], v[132:135], v[182:185], v[112:115]
	v_mfma_f32_16x16x32_bf16 v[80:83], v[140:143], v[182:185], v[80:83]
	s_barrier
	s_mov_b32 m0, s75
	v_lshl_add_u64 v[208:209], s[10:11], 0, v[164:165]
	ds_read_b128 v[186:189], v201
	ds_read_b128 v[190:193], v201 offset:1024
	ds_read_b128 v[194:197], v201 offset:2048
	ds_read_b128 v[202:205], v201 offset:3072
	global_load_lds_dwordx4 v[208:209], off
	s_mov_b32 m0, s76
	v_lshl_add_u64 v[210:211], s[10:11], 0, v[166:167]
	global_load_lds_dwordx4 v[210:211], off
	s_barrier
	s_waitcnt lgkmcnt(0)
	v_mfma_f32_16x16x32_bf16 v[60:63], v[186:189], v[144:147], v[60:63]
	v_mfma_f32_16x16x32_bf16 v[28:31], v[194:197], v[144:147], v[28:31]
	v_mfma_f32_16x16x32_bf16 v[56:59], v[186:189], v[152:155], v[56:59]
	v_mfma_f32_16x16x32_bf16 v[24:27], v[194:197], v[152:155], v[24:27]
	v_mfma_f32_16x16x32_bf16 v[52:55], v[186:189], v[160:163], v[52:55]
	v_mfma_f32_16x16x32_bf16 v[20:23], v[194:197], v[160:163], v[20:23]
	v_mfma_f32_16x16x32_bf16 v[48:51], v[186:189], v[178:181], v[48:51]
	v_mfma_f32_16x16x32_bf16 v[16:19], v[194:197], v[178:181], v[16:19]
	v_mfma_f32_16x16x32_bf16 v[60:63], v[190:193], v[148:151], v[60:63]
	v_mfma_f32_16x16x32_bf16 v[28:31], v[202:205], v[148:151], v[28:31]
	v_mfma_f32_16x16x32_bf16 v[56:59], v[190:193], v[156:159], v[56:59]
	v_mfma_f32_16x16x32_bf16 v[24:27], v[202:205], v[156:159], v[24:27]
	v_mfma_f32_16x16x32_bf16 v[52:55], v[190:193], v[174:177], v[52:55]
	v_mfma_f32_16x16x32_bf16 v[20:23], v[202:205], v[174:177], v[20:23]
	v_mfma_f32_16x16x32_bf16 v[48:51], v[190:193], v[182:185], v[48:51]
	v_mfma_f32_16x16x32_bf16 v[16:19], v[202:205], v[182:185], v[16:19]
	s_mov_b32 m0, s23
	v_lshl_add_u64 v[212:213], s[12:13], 0, v[164:165]
	s_barrier
	ds_read_b128 v[144:147], v200 offset:16384
	ds_read_b128 v[148:151], v200 offset:17408
	ds_read_b128 v[152:155], v200 offset:18432
	ds_read_b128 v[156:159], v200 offset:19456
	ds_read_b128 v[160:163], v200 offset:20480
	ds_read_b128 v[174:177], v200 offset:21504
	ds_read_b128 v[178:181], v200 offset:22528
	ds_read_b128 v[182:185], v200 offset:23552
	global_load_lds_dwordx4 v[212:213], off
	s_mov_b32 m0, s35
	v_lshl_add_u64 v[214:215], s[12:13], 0, v[166:167]
	global_load_lds_dwordx4 v[214:215], off
	s_barrier
	s_waitcnt lgkmcnt(0)
	v_mfma_f32_16x16x32_bf16 v[108:111], v[128:131], v[144:147], v[108:111]
	v_mfma_f32_16x16x32_bf16 v[76:79], v[136:139], v[144:147], v[76:79]
	v_mfma_f32_16x16x32_bf16 v[104:107], v[128:131], v[152:155], v[104:107]
	v_mfma_f32_16x16x32_bf16 v[72:75], v[136:139], v[152:155], v[72:75]
	v_mfma_f32_16x16x32_bf16 v[100:103], v[128:131], v[160:163], v[100:103]
	v_mfma_f32_16x16x32_bf16 v[68:71], v[136:139], v[160:163], v[68:71]
	v_mfma_f32_16x16x32_bf16 v[96:99], v[128:131], v[178:181], v[96:99]
	v_mfma_f32_16x16x32_bf16 v[64:67], v[136:139], v[178:181], v[64:67]
	v_mfma_f32_16x16x32_bf16 v[108:111], v[132:135], v[148:151], v[108:111]
	v_mfma_f32_16x16x32_bf16 v[76:79], v[140:143], v[148:151], v[76:79]
	v_mfma_f32_16x16x32_bf16 v[104:107], v[132:135], v[156:159], v[104:107]
	v_mfma_f32_16x16x32_bf16 v[72:75], v[140:143], v[156:159], v[72:75]
	v_mfma_f32_16x16x32_bf16 v[100:103], v[132:135], v[174:177], v[100:103]
	v_mfma_f32_16x16x32_bf16 v[68:71], v[140:143], v[174:177], v[68:71]
	v_mfma_f32_16x16x32_bf16 v[96:99], v[132:135], v[182:185], v[96:99]
	v_mfma_f32_16x16x32_bf16 v[64:67], v[140:143], v[182:185], v[64:67]
	s_barrier
	s_add_u32 s6, s10, 0x160000
	s_addc_u32 s7, s11, 0
	s_mov_b32 m0, s77
	v_lshl_add_u64 v[128:129], s[6:7], 0, v[164:165]
	global_load_lds_dwordx4 v[128:129], off
	s_mov_b32 m0, s78
	v_lshl_add_u64 v[128:129], s[6:7], 0, v[166:167]
	global_load_lds_dwordx4 v[128:129], off
	s_waitcnt vmcnt(6)
	s_barrier
; #define WAIT_V(n) asm volatile("s_waitcnt vmcnt(" #n ")" ::: "memory")
; #define WAIT_L(n) asm volatile("s_waitcnt lgkmcnt(" #n ")" ::: "memory")
; #define BAR __builtin_amdgcn_s_barrier()
; #define SCHED __builtin_amdgcn_sched_barrier(0)
; template <class Get, class Epi>
; DI void gemm_stream(LAS unsigned char* lds, const int K, const int ld, Get get, Epi epi) {
;     ...
;             WAIT_V(6); BAR; MMA(1, 1, At, B1); BAR;
;             LDB(B0, 1, 0); SCHED; LDA(At, 1, 0); STAGE(SAo(0, 1), a2 + hstep);
;             WAIT_L(8); BAR; WAIT_L(0); MMA(0, 0, At, B0); BAR; SCHED;
;             LDB(B1, 1, 1); STAGE(SBo(1, 0), b3);
;             BAR; WAIT_L(0); MMA(0, 1, At, B1); BAR;
;             LDA(At, 1, 1); STAGE(SAo(1, 0), a3);
;             BAR; WAIT_L(0); MMA(1, 0, At, B0); BAR; SCHED;
	v_mfma_f32_16x16x32_bf16 v[44:47], v[186:189], v[144:147], v[44:47]
	v_mfma_f32_16x16x32_bf16 v[12:15], v[194:197], v[144:147], v[12:15]
	v_mfma_f32_16x16x32_bf16 v[40:43], v[186:189], v[152:155], v[40:43]
	v_mfma_f32_16x16x32_bf16 v[8:11], v[194:197], v[152:155], v[8:11]
	v_mfma_f32_16x16x32_bf16 v[36:39], v[186:189], v[160:163], v[36:39]
	v_mfma_f32_16x16x32_bf16 v[4:7], v[194:197], v[160:163], v[4:7]
	v_mfma_f32_16x16x32_bf16 v[32:35], v[186:189], v[178:181], v[32:35]
	v_mfma_f32_16x16x32_bf16 v[0:3], v[194:197], v[178:181], v[0:3]
	v_mfma_f32_16x16x32_bf16 v[44:47], v[190:193], v[148:151], v[44:47]
	v_mfma_f32_16x16x32_bf16 v[12:15], v[202:205], v[148:151], v[12:15]
	v_mfma_f32_16x16x32_bf16 v[40:43], v[190:193], v[156:159], v[40:43]
	v_mfma_f32_16x16x32_bf16 v[8:11], v[202:205], v[156:159], v[8:11]
	v_mfma_f32_16x16x32_bf16 v[36:39], v[190:193], v[174:177], v[36:39]
	v_mfma_f32_16x16x32_bf16 v[4:7], v[202:205], v[174:177], v[4:7]
	v_mfma_f32_16x16x32_bf16 v[32:35], v[190:193], v[182:185], v[32:35]
	v_mfma_f32_16x16x32_bf16 v[0:3], v[202:205], v[182:185], v[0:3]
	s_add_i32 s17, 16, 0x18000
	v_add_u32_e32 v140, s17, v198
	s_barrier
	ds_read_b128 v[128:131], v140
	ds_read_b128 v[132:135], v140 offset:1024
	ds_read_b128 v[136:139], v140 offset:2048
	ds_read_b128 v[140:143], v140 offset:3072
	s_add_u32 s6, s12, 0x160000
	s_addc_u32 s7, s13, 0
	s_mov_b32 m0, s54
	v_lshl_add_u64 v[186:187], s[6:7], 0, v[164:165]
	ds_read_b128 v[144:147], v200 offset:32768
	ds_read_b128 v[148:151], v200 offset:33792
	ds_read_b128 v[152:155], v200 offset:34816
	ds_read_b128 v[156:159], v200 offset:35840
	ds_read_b128 v[160:163], v200 offset:36864
	ds_read_b128 v[174:177], v200 offset:37888
	ds_read_b128 v[178:181], v200 offset:38912
	ds_read_b128 v[182:185], v200 offset:39936
	global_load_lds_dwordx4 v[186:187], off
	s_mov_b32 m0, s55
	v_lshl_add_u64 v[186:187], s[6:7], 0, v[166:167]
	global_load_lds_dwordx4 v[186:187], off
	s_waitcnt lgkmcnt(8)
	s_barrier
	s_waitcnt lgkmcnt(0)
	v_mfma_f32_16x16x32_bf16 v[124:127], v[128:131], v[144:147], v[124:127]
	v_mfma_f32_16x16x32_bf16 v[92:95], v[136:139], v[144:147], v[92:95]
	v_mfma_f32_16x16x32_bf16 v[120:123], v[128:131], v[152:155], v[120:123]
	v_mfma_f32_16x16x32_bf16 v[88:91], v[136:139], v[152:155], v[88:91]
	v_mfma_f32_16x16x32_bf16 v[116:119], v[128:131], v[160:163], v[116:119]
	v_mfma_f32_16x16x32_bf16 v[84:87], v[136:139], v[160:163], v[84:87]
	v_mfma_f32_16x16x32_bf16 v[112:115], v[128:131], v[178:181], v[112:115]
	v_mfma_f32_16x16x32_bf16 v[80:83], v[136:139], v[178:181], v[80:83]
	v_mfma_f32_16x16x32_bf16 v[124:127], v[132:135], v[148:151], v[124:127]
	v_mfma_f32_16x16x32_bf16 v[92:95], v[140:143], v[148:151], v[92:95]
	v_mfma_f32_16x16x32_bf16 v[120:123], v[132:135], v[156:159], v[120:123]
	v_mfma_f32_16x16x32_bf16 v[88:91], v[140:143], v[156:159], v[88:91]
	v_mfma_f32_16x16x32_bf16 v[116:119], v[132:135], v[174:177], v[116:119]
	v_mfma_f32_16x16x32_bf16 v[84:87], v[140:143], v[174:177], v[84:87]
	v_mfma_f32_16x16x32_bf16 v[112:115], v[132:135], v[182:185], v[112:115]
	v_mfma_f32_16x16x32_bf16 v[80:83], v[140:143], v[182:185], v[80:83]
	s_barrier
	s_add_i32 s12, 16, 0x1c000
	s_add_i32 s6, s17, s21
	v_add_u32_e32 v202, s12, v198
	v_lshl_add_u64 v[208:209], v[208:209], 0, s[0:1]
	s_mov_b32 m0, s6
	ds_read_b128 v[186:189], v202
	ds_read_b128 v[190:193], v202 offset:1024
	ds_read_b128 v[194:197], v202 offset:2048
	ds_read_b128 v[202:205], v202 offset:3072
	global_load_lds_dwordx4 v[208:209], off
	v_lshl_add_u64 v[208:209], v[210:211], 0, s[0:1]
	s_add_i32 m0, s6, 0x2000
	s_nop 0
	global_load_lds_dwordx4 v[208:209], off
	s_barrier
	s_waitcnt lgkmcnt(0)
	v_mfma_f32_16x16x32_bf16 v[60:63], v[186:189], v[144:147], v[60:63]
	v_mfma_f32_16x16x32_bf16 v[28:31], v[194:197], v[144:147], v[28:31]
	v_mfma_f32_16x16x32_bf16 v[56:59], v[186:189], v[152:155], v[56:59]
	v_mfma_f32_16x16x32_bf16 v[24:27], v[194:197], v[152:155], v[24:27]
	v_mfma_f32_16x16x32_bf16 v[52:55], v[186:189], v[160:163], v[52:55]
	v_mfma_f32_16x16x32_bf16 v[20:23], v[194:197], v[160:163], v[20:23]
	v_mfma_f32_16x16x32_bf16 v[48:51], v[186:189], v[178:181], v[48:51]
	v_mfma_f32_16x16x32_bf16 v[16:19], v[194:197], v[178:181], v[16:19]
	v_mfma_f32_16x16x32_bf16 v[60:63], v[190:193], v[148:151], v[60:63]
	v_mfma_f32_16x16x32_bf16 v[28:31], v[202:205], v[148:151], v[28:31]
	v_mfma_f32_16x16x32_bf16 v[56:59], v[190:193], v[156:159], v[56:59]
	v_mfma_f32_16x16x32_bf16 v[24:27], v[202:205], v[156:159], v[24:27]
	v_mfma_f32_16x16x32_bf16 v[52:55], v[190:193], v[174:177], v[52:55]
	v_mfma_f32_16x16x32_bf16 v[20:23], v[202:205], v[174:177], v[20:23]
	v_mfma_f32_16x16x32_bf16 v[48:51], v[190:193], v[182:185], v[48:51]
	v_mfma_f32_16x16x32_bf16 v[16:19], v[202:205], v[182:185], v[16:19]
	s_mov_b32 m0, s56
	v_lshl_add_u64 v[208:209], v[212:213], 0, s[0:1]
	s_barrier
	ds_read_b128 v[144:147], v200 offset:49152
	ds_read_b128 v[148:151], v200 offset:50176
	ds_read_b128 v[152:155], v200 offset:51200
	ds_read_b128 v[156:159], v200 offset:52224
	ds_read_b128 v[160:163], v200 offset:53248
	ds_read_b128 v[174:177], v200 offset:54272
	ds_read_b128 v[178:181], v200 offset:55296
	ds_read_b128 v[182:185], v200 offset:56320
	global_load_lds_dwordx4 v[208:209], off
	s_mov_b32 m0, s57
	v_lshl_add_u64 v[208:209], v[214:215], 0, s[0:1]
	global_load_lds_dwordx4 v[208:209], off
	s_barrier
; #define WAIT_V(n) asm volatile("s_waitcnt vmcnt(" #n ")" ::: "memory")
; #define WAIT_L(n) asm volatile("s_waitcnt lgkmcnt(" #n ")" ::: "memory")
; #define BAR __builtin_amdgcn_s_barrier()
; #define SCHED __builtin_amdgcn_sched_barrier(0)
; template <class Get, class Epi>
; DI void gemm_stream(LAS unsigned char* lds, const int K, const int ld, Get get, Epi epi) {
;     ...
;             BAR; WAIT_L(0); MMA(1, 0, At, B0); BAR; SCHED;
;             STAGE(SBo(1, 1), b3 + hstep);
;             WAIT_V(6); BAR; MMA(1, 1, At, B1); BAR;
;         }
; DI void epi_resid(const Acc& acc, const P& p, int brow, int bcol, int layer, int gch, bool from_input) {
;     EPI_IDX
;     const float* gate = modv(p, layer, brow, gch);
; #pragma unroll
;     for (int bj = 0; bj < 2; ++bj)
; #pragma unroll
;         for (int n = 0; n < 2; ++n) {
;             const int c0 = bcol + bj * 128 + wc * 32 + n * 16 + fq * 4;
;             const f32x4 g = *(const f32x4*)(gate + c0);
;             f32x4 xv[2][4];
; #pragma unroll
;             for (int ai = 0; ai < 2; ++ai)
; #pragma unroll
;                 for (int m = 0; m < 4; ++m) {
;                     const int r = brow + ai * 128 + wr * 64 + m * 16 + fr;
;                     const float* sp = (from_input ? inrow(p, r) : xrow(p, r)) + c0;
;                     xv[ai][m] = *(const f32x4*)sp;
	s_waitcnt lgkmcnt(0)
	v_mfma_f32_16x16x32_bf16 v[108:111], v[128:131], v[144:147], v[108:111]
	v_mfma_f32_16x16x32_bf16 v[76:79], v[136:139], v[144:147], v[76:79]
	v_mfma_f32_16x16x32_bf16 v[104:107], v[128:131], v[152:155], v[104:107]
	v_mfma_f32_16x16x32_bf16 v[72:75], v[136:139], v[152:155], v[72:75]
	v_mfma_f32_16x16x32_bf16 v[100:103], v[128:131], v[160:163], v[100:103]
	v_mfma_f32_16x16x32_bf16 v[68:71], v[136:139], v[160:163], v[68:71]
	v_mfma_f32_16x16x32_bf16 v[96:99], v[128:131], v[178:181], v[96:99]
	v_mfma_f32_16x16x32_bf16 v[64:67], v[136:139], v[178:181], v[64:67]
	v_mfma_f32_16x16x32_bf16 v[108:111], v[132:135], v[148:151], v[108:111]
	v_mfma_f32_16x16x32_bf16 v[76:79], v[140:143], v[148:151], v[76:79]
	v_mfma_f32_16x16x32_bf16 v[104:107], v[132:135], v[156:159], v[104:107]
	v_mfma_f32_16x16x32_bf16 v[72:75], v[140:143], v[156:159], v[72:75]
	v_mfma_f32_16x16x32_bf16 v[100:103], v[132:135], v[174:177], v[100:103]
	v_mfma_f32_16x16x32_bf16 v[68:71], v[140:143], v[174:177], v[68:71]
	v_mfma_f32_16x16x32_bf16 v[96:99], v[132:135], v[182:185], v[96:99]
	v_mfma_f32_16x16x32_bf16 v[64:67], v[140:143], v[182:185], v[64:67]
	s_barrier
	s_add_u32 s6, s10, 0x160080
	s_addc_u32 s7, s11, 0
	s_add_i32 s10, s12, s21
	s_mov_b32 m0, s10
	v_lshl_add_u64 v[128:129], s[6:7], 0, v[164:165]
	global_load_lds_dwordx4 v[128:129], off
	v_lshl_add_u64 v[128:129], s[6:7], 0, v[166:167]
	s_add_i32 m0, s10, 0x2000
	s_nop 0
	global_load_lds_dwordx4 v[128:129], off
	s_waitcnt vmcnt(6)
	s_barrier
	v_mfma_f32_16x16x32_bf16 v[44:47], v[186:189], v[144:147], v[44:47]
	v_mfma_f32_16x16x32_bf16 v[12:15], v[194:197], v[144:147], v[12:15]
	v_mfma_f32_16x16x32_bf16 v[40:43], v[186:189], v[152:155], v[40:43]
	v_mfma_f32_16x16x32_bf16 v[8:11], v[194:197], v[152:155], v[8:11]
	v_mfma_f32_16x16x32_bf16 v[36:39], v[186:189], v[160:163], v[36:39]
	v_mfma_f32_16x16x32_bf16 v[4:7], v[194:197], v[160:163], v[4:7]
	v_mfma_f32_16x16x32_bf16 v[32:35], v[186:189], v[178:181], v[32:35]
	v_mfma_f32_16x16x32_bf16 v[0:3], v[194:197], v[178:181], v[0:3]
	v_mfma_f32_16x16x32_bf16 v[44:47], v[190:193], v[148:151], v[44:47]
	v_mfma_f32_16x16x32_bf16 v[12:15], v[202:205], v[148:151], v[12:15]
	v_mfma_f32_16x16x32_bf16 v[40:43], v[190:193], v[156:159], v[40:43]
	v_mfma_f32_16x16x32_bf16 v[8:11], v[202:205], v[156:159], v[8:11]
	v_mfma_f32_16x16x32_bf16 v[36:39], v[190:193], v[174:177], v[36:39]
	v_mfma_f32_16x16x32_bf16 v[4:7], v[202:205], v[174:177], v[4:7]
	v_mfma_f32_16x16x32_bf16 v[32:35], v[190:193], v[182:185], v[32:35]
	v_mfma_f32_16x16x32_bf16 v[0:3], v[202:205], v[182:185], v[0:3]
	s_add_i32 s16, s16, 2
	s_add_u32 s14, s14, 0x100
	s_addc_u32 s15, s15, 0
	s_cmpk_gt_u32 s16, 0x55
	s_mov_b64 s[6:7], s[8:9]
	s_barrier
	s_cbranch_scc0 .LBB0_1697
	s_lshr_b32 s6, s3, 4
	s_lshl_b32 s3, s3, 8
	s_mulk_i32 s6, 0x1100
	s_and_b32 s3, s3, 0xf00
	s_add_i32 s3, s6, s3
	s_add_i32 s6, s3, 0x100
	s_lshl_b32 s7, s2, 8
	s_mul_hi_i32 s2, s6, 0x78787879
	s_lshr_b32 s3, s2, 31
	s_ashr_i32 s2, s2, 11
	s_add_i32 s2, s2, s3
	s_mul_i32 s3, s2, 0xffffef00
	s_mul_i32 s2, s2, 6
	s_add_i32 s3, s3, s6
	s_add_i32 s2, s2, 5
	s_cmpk_gt_i32 s3, 0xff
	v_mov_b32_e32 v132, v206
	s_cselect_b32 s2, s2, 29
	s_ashr_i32 s3, s2, 31
	v_lshrrev_b32_e32 v128, 1, v132
	v_lshrrev_b32_e32 v129, 2, v132
	s_lshl_b64 s[2:3], s[2:3], 13
	v_and_b32_e32 v128, 0x60, v128
	v_and_b32_e32 v129, 12, v129
	s_add_u32 s2, s26, s2
	v_or3_b32 v174, v128, s7, v129
	s_addc_u32 s3, s27, s3
	v_ashrrev_i32_e32 v175, 31, v174
	v_lshl_add_u64 v[192:193], v[174:175], 2, s[2:3]
	global_load_dwordx4 v[128:131], v[192:193], off
	v_ashrrev_i32_e32 v133, 2, v132
	v_and_b32_e32 v133, 0xffffffc0, v133
	v_and_or_b32 v132, v132, 15, s6
	v_add_u32_e32 v176, v132, v133
	v_mul_hi_i32 v132, v176, s59
	v_lshrrev_b32_e32 v133, 31, v132
	v_ashrrev_i32_e32 v132, 11, v132
	v_add_u32_e32 v203, v132, v133
	v_mad_i32_i24 v202, v203, s60, v176
	v_lshlrev_b32_e32 v212, 12, v203
	v_cmp_lt_i32_e64 s[18:19], s61, v202
	v_add3_u32 v190, v212, v202, s62
	s_and_saveexec_b64 s[2:3], s[18:19]
	s_xor_b64 s[6:7], exec, s[2:3]
	v_add3_u32 v132, v212, v202, s62
	s_or_saveexec_b64 s[6:7], s[6:7]
	v_mov_b64_e32 v[134:135], s[24:25]
	v_lshl_add_u32 v191, v203, 8, v202
	s_xor_b64 exec, exec, s[6:7]
	v_lshl_add_u32 v132, v203, 8, v202
	v_mov_b64_e32 v[134:135], s[36:37]
	s_or_b64 exec, exec, s[6:7]
	v_ashrrev_i32_e32 v133, 31, v132
	v_lshlrev_b64 v[132:133], 13, v[132:133]
	v_lshl_add_u64 v[132:133], v[134:135], 0, v[132:133]
	v_lshl_add_u64 v[132:133], v[174:175], 2, v[132:133]
	global_load_dwordx4 v[160:163], v[132:133], off
	v_or_b32_e32 v132, 16, v176
	v_mul_hi_i32 v133, v132, s59
	v_lshrrev_b32_e32 v134, 31, v133
	v_ashrrev_i32_e32 v133, 11, v133
	v_add_u32_e32 v205, v133, v134
	v_mad_i32_i24 v204, v205, s60, v132
	v_lshlrev_b32_e32 v217, 12, v205
	v_cmp_lt_i32_e64 s[16:17], s61, v204
	v_add3_u32 v188, v217, v204, s62
	s_and_saveexec_b64 s[2:3], s[16:17]
	s_xor_b64 s[6:7], exec, s[2:3]
	v_add3_u32 v132, v217, v204, s62
	s_or_saveexec_b64 s[6:7], s[6:7]
	v_mov_b64_e32 v[134:135], s[24:25]
	v_lshl_add_u32 v189, v205, 8, v204
	s_xor_b64 exec, exec, s[6:7]
	v_lshl_add_u32 v132, v205, 8, v204
	v_mov_b64_e32 v[134:135], s[36:37]
	s_or_b64 exec, exec, s[6:7]
	v_ashrrev_i32_e32 v133, 31, v132
	v_lshlrev_b64 v[132:133], 13, v[132:133]
	v_lshl_add_u64 v[132:133], v[134:135], 0, v[132:133]
	v_lshl_add_u64 v[132:133], v[174:175], 2, v[132:133]
	global_load_dwordx4 v[156:159], v[132:133], off
	v_or_b32_e32 v132, 32, v176
	v_mul_hi_i32 v133, v132, s59
	v_lshrrev_b32_e32 v134, 31, v133
	v_ashrrev_i32_e32 v133, 11, v133
	v_add_u32_e32 v209, v133, v134
	v_mad_i32_i24 v208, v209, s60, v132
; DI void epi_resid(const Acc& acc, const P& p, int brow, int bcol, int layer, int gch, bool from_input) {
;     ...
;             const f32x4 g = *(const f32x4*)(gate + c0);
;             f32x4 xv[2][4];
; #pragma unroll
;             for (int ai = 0; ai < 2; ++ai)
; #pragma unroll
;                 for (int m = 0; m < 4; ++m) {
;                     const int r = brow + ai * 128 + wr * 64 + m * 16 + fr;
;                     const float* sp = (from_input ? inrow(p, r) : xrow(p, r)) + c0;
;                     xv[ai][m] = *(const f32x4*)sp;
;                 }
	v_lshlrev_b32_e32 v220, 12, v209
	v_cmp_lt_i32_e64 s[14:15], s61, v208
	v_add3_u32 v186, v220, v208, s62
	s_and_saveexec_b64 s[2:3], s[14:15]
	s_xor_b64 s[6:7], exec, s[2:3]
	v_add3_u32 v132, v220, v208, s62
	s_or_saveexec_b64 s[6:7], s[6:7]
	v_mov_b64_e32 v[134:135], s[24:25]
	v_lshl_add_u32 v187, v209, 8, v208
	s_xor_b64 exec, exec, s[6:7]
	v_lshl_add_u32 v132, v209, 8, v208
	v_mov_b64_e32 v[134:135], s[36:37]
	s_or_b64 exec, exec, s[6:7]
	v_ashrrev_i32_e32 v133, 31, v132
	v_lshlrev_b64 v[132:133], 13, v[132:133]
	v_lshl_add_u64 v[132:133], v[134:135], 0, v[132:133]
	v_lshl_add_u64 v[132:133], v[174:175], 2, v[132:133]
	global_load_dwordx4 v[152:155], v[132:133], off
	v_or_b32_e32 v132, 48, v176
	v_mul_hi_i32 v133, v132, s59
	v_lshrrev_b32_e32 v134, 31, v133
	v_ashrrev_i32_e32 v133, 11, v133
	v_add_u32_e32 v211, v133, v134
	v_mad_i32_i24 v210, v211, s60, v132
	v_lshlrev_b32_e32 v223, 12, v211
	v_cmp_lt_i32_e64 s[12:13], s61, v210
	v_add3_u32 v184, v223, v210, s62
	s_and_saveexec_b64 s[2:3], s[12:13]
	s_xor_b64 s[6:7], exec, s[2:3]
	v_add3_u32 v132, v223, v210, s62
	s_or_saveexec_b64 s[6:7], s[6:7]
	v_mov_b64_e32 v[134:135], s[24:25]
	v_lshl_add_u32 v185, v211, 8, v210
	s_xor_b64 exec, exec, s[6:7]
	v_lshl_add_u32 v132, v211, 8, v210
	v_mov_b64_e32 v[134:135], s[36:37]
	s_or_b64 exec, exec, s[6:7]
	v_ashrrev_i32_e32 v133, 31, v132
	v_lshlrev_b64 v[132:133], 13, v[132:133]
	v_lshl_add_u64 v[132:133], v[134:135], 0, v[132:133]
	v_lshl_add_u64 v[132:133], v[174:175], 2, v[132:133]
	global_load_dwordx4 v[148:151], v[132:133], off
	v_add_u32_e32 v132, 0x80, v176
	v_mul_hi_i32 v133, v132, s59
	v_lshrrev_b32_e32 v134, 31, v133
	v_ashrrev_i32_e32 v133, 11, v133
	v_add_u32_e32 v214, v133, v134
	v_mad_i32_i24 v213, v214, s60, v132
	v_lshlrev_b32_e32 v224, 12, v214
	v_cmp_lt_i32_e64 s[10:11], s61, v213
	v_add3_u32 v182, v224, v213, s62
	s_and_saveexec_b64 s[2:3], s[10:11]
	s_xor_b64 s[6:7], exec, s[2:3]
	v_add3_u32 v132, v224, v213, s62
	s_or_saveexec_b64 s[6:7], s[6:7]
	v_mov_b64_e32 v[134:135], s[24:25]
	v_lshl_add_u32 v183, v214, 8, v213
	s_xor_b64 exec, exec, s[6:7]
	v_lshl_add_u32 v132, v214, 8, v213
	v_mov_b64_e32 v[134:135], s[36:37]
	s_or_b64 exec, exec, s[6:7]
	v_ashrrev_i32_e32 v133, 31, v132
	v_lshlrev_b64 v[132:133], 13, v[132:133]
	v_lshl_add_u64 v[132:133], v[134:135], 0, v[132:133]
	v_lshl_add_u64 v[132:133], v[174:175], 2, v[132:133]
	global_load_dwordx4 v[144:147], v[132:133], off
	v_add_u32_e32 v132, 0x90, v176
	v_mul_hi_i32 v133, v132, s59
	v_lshrrev_b32_e32 v134, 31, v133
	v_ashrrev_i32_e32 v133, 11, v133
	v_add_u32_e32 v216, v133, v134
	v_mad_i32_i24 v215, v216, s60, v132
	v_lshlrev_b32_e32 v225, 12, v216
	v_cmp_lt_i32_e64 s[8:9], s61, v215
	v_add3_u32 v180, v225, v215, s62
	s_and_saveexec_b64 s[2:3], s[8:9]
	s_xor_b64 s[6:7], exec, s[2:3]
	v_add3_u32 v132, v225, v215, s62
	s_or_saveexec_b64 s[6:7], s[6:7]
	v_mov_b64_e32 v[134:135], s[24:25]
	v_lshl_add_u32 v181, v216, 8, v215
	s_xor_b64 exec, exec, s[6:7]
	v_lshl_add_u32 v132, v216, 8, v215
	v_mov_b64_e32 v[134:135], s[36:37]
	s_or_b64 exec, exec, s[6:7]
	v_ashrrev_i32_e32 v133, 31, v132
	v_lshlrev_b64 v[132:133], 13, v[132:133]
	v_lshl_add_u64 v[132:133], v[134:135], 0, v[132:133]
	v_lshl_add_u64 v[132:133], v[174:175], 2, v[132:133]
	global_load_dwordx4 v[140:143], v[132:133], off
	v_add_u32_e32 v132, 0xa0, v176
	v_mul_hi_i32 v133, v132, s59
	v_lshrrev_b32_e32 v134, 31, v133
	v_ashrrev_i32_e32 v133, 11, v133
	v_add_u32_e32 v219, v133, v134
	v_mad_i32_i24 v218, v219, s60, v132
	v_lshlrev_b32_e32 v226, 12, v219
	v_cmp_lt_i32_e64 s[6:7], s61, v218
	v_add3_u32 v178, v226, v218, s62
	s_and_saveexec_b64 s[2:3], s[6:7]
	s_xor_b64 s[52:53], exec, s[2:3]
	v_add3_u32 v132, v226, v218, s62
	s_or_saveexec_b64 s[52:53], s[52:53]
	v_mov_b64_e32 v[134:135], s[24:25]
	v_lshl_add_u32 v179, v219, 8, v218
	s_xor_b64 exec, exec, s[52:53]
	v_lshl_add_u32 v132, v219, 8, v218
	v_mov_b64_e32 v[134:135], s[36:37]
	s_or_b64 exec, exec, s[52:53]
	v_ashrrev_i32_e32 v133, 31, v132
	v_lshlrev_b64 v[132:133], 13, v[132:133]
	v_lshl_add_u64 v[132:133], v[134:135], 0, v[132:133]
	v_lshl_add_u64 v[132:133], v[174:175], 2, v[132:133]
	global_load_dwordx4 v[136:139], v[132:133], off
	v_add_u32_e32 v132, 0xb0, v176
	v_mul_hi_i32 v133, v132, s59
	v_lshrrev_b32_e32 v134, 31, v133
	v_ashrrev_i32_e32 v133, 11, v133
	v_add_u32_e32 v222, v133, v134
	v_mad_i32_i24 v221, v222, s60, v132
	v_lshlrev_b32_e32 v227, 12, v222
	v_cmp_lt_i32_e32 vcc, s61, v221
	v_add3_u32 v176, v227, v221, s62
	s_and_saveexec_b64 s[2:3], vcc
	s_xor_b64 s[52:53], exec, s[2:3]
	v_add3_u32 v132, v227, v221, s62
	s_or_saveexec_b64 s[52:53], s[52:53]
	v_mov_b64_e32 v[134:135], s[24:25]
	v_lshl_add_u32 v177, v222, 8, v221
	s_xor_b64 exec, exec, s[52:53]
	v_lshl_add_u32 v132, v222, 8, v221
	v_mov_b64_e32 v[134:135], s[36:37]
	s_or_b64 exec, exec, s[52:53]
	v_ashrrev_i32_e32 v133, 31, v132
	v_lshlrev_b64 v[132:133], 13, v[132:133]
	v_lshl_add_u64 v[132:133], v[134:135], 0, v[132:133]
	v_lshl_add_u64 v[132:133], v[174:175], 2, v[132:133]
	global_load_dwordx4 v[132:135], v[132:133], off
	s_and_saveexec_b64 s[2:3], s[18:19]
	s_xor_b64 s[52:53], exec, s[2:3]
	v_add3_u32 v194, v212, v202, s62
	s_or_saveexec_b64 s[52:53], s[52:53]
	v_mov_b64_e32 v[196:197], s[24:25]
	s_xor_b64 exec, exec, s[52:53]
	v_lshl_add_u32 v194, v203, 8, v202
	v_mov_b64_e32 v[196:197], s[36:37]
	s_or_b64 exec, exec, s[52:53]
	v_ashrrev_i32_e32 v195, 31, v194
	s_waitcnt vmcnt(0)
; DI void epi_resid(const Acc& acc, const P& p, int brow, int bcol, int layer, int gch, bool from_input) {
;     ...
;             for (int ai = 0; ai < 2; ++ai)
; #pragma unroll
;                 for (int m = 0; m < 4; ++m) {
;                     const int r = brow + ai * 128 + wr * 64 + m * 16 + fr;
;                     const float* sp = (from_input ? inrow(p, r) : xrow(p, r)) + c0;
;                     xv[ai][m] = *(const f32x4*)sp;
;                 }
;             __builtin_amdgcn_sched_barrier(0);
; #pragma unroll
;             for (int ai = 0; ai < 2; ++ai)
; #pragma unroll
;                 for (int m = 0; m < 4; ++m) {
;                     const int r = brow + ai * 128 + wr * 64 + m * 16 + fr;
;                     *(f32x4*)(xrow(p, r) + c0) = xv[ai][m] + g * acc[ai][bj][m][n];
;                 }
;             __builtin_amdgcn_sched_barrier(0);
	v_pk_fma_f32 v[124:125], v[124:125], v[128:129], v[160:161]
	v_lshlrev_b64 v[160:161], 13, v[194:195]
	v_lshl_add_u64 v[160:161], v[196:197], 0, v[160:161]
	v_pk_fma_f32 v[126:127], v[126:127], v[130:131], v[162:163]
	v_lshl_add_u64 v[160:161], v[174:175], 2, v[160:161]
	global_store_dwordx4 v[160:161], v[124:127], off
	s_and_saveexec_b64 s[2:3], s[16:17]
	s_xor_b64 s[52:53], exec, s[2:3]
	v_add3_u32 v124, v217, v204, s62
	s_or_saveexec_b64 s[52:53], s[52:53]
	v_mov_b64_e32 v[126:127], s[24:25]
	s_xor_b64 exec, exec, s[52:53]
	v_lshl_add_u32 v124, v205, 8, v204
	v_mov_b64_e32 v[126:127], s[36:37]
	s_or_b64 exec, exec, s[52:53]
	v_ashrrev_i32_e32 v125, 31, v124
	v_lshlrev_b64 v[124:125], 13, v[124:125]
	v_lshl_add_u64 v[124:125], v[126:127], 0, v[124:125]
	v_pk_fma_f32 v[122:123], v[122:123], v[130:131], v[158:159]
	v_pk_fma_f32 v[120:121], v[120:121], v[128:129], v[156:157]
	v_lshl_add_u64 v[124:125], v[174:175], 2, v[124:125]
	global_store_dwordx4 v[124:125], v[120:123], off
	s_and_saveexec_b64 s[2:3], s[14:15]
	s_xor_b64 s[52:53], exec, s[2:3]
	v_add3_u32 v120, v220, v208, s62
	s_or_saveexec_b64 s[52:53], s[52:53]
	v_mov_b64_e32 v[122:123], s[24:25]
	s_xor_b64 exec, exec, s[52:53]
	v_lshl_add_u32 v120, v209, 8, v208
	v_mov_b64_e32 v[122:123], s[36:37]
	s_or_b64 exec, exec, s[52:53]
	v_ashrrev_i32_e32 v121, 31, v120
	v_lshlrev_b64 v[120:121], 13, v[120:121]
	v_lshl_add_u64 v[120:121], v[122:123], 0, v[120:121]
	v_pk_fma_f32 v[118:119], v[118:119], v[130:131], v[154:155]
	v_pk_fma_f32 v[116:117], v[116:117], v[128:129], v[152:153]
	v_lshl_add_u64 v[120:121], v[174:175], 2, v[120:121]
	global_store_dwordx4 v[120:121], v[116:119], off
	s_and_saveexec_b64 s[2:3], s[12:13]
	s_xor_b64 s[52:53], exec, s[2:3]
	v_add3_u32 v116, v223, v210, s62
	s_or_saveexec_b64 s[52:53], s[52:53]
	v_mov_b64_e32 v[118:119], s[24:25]
	s_xor_b64 exec, exec, s[52:53]
	v_lshl_add_u32 v116, v211, 8, v210
	v_mov_b64_e32 v[118:119], s[36:37]
	s_or_b64 exec, exec, s[52:53]
	v_ashrrev_i32_e32 v117, 31, v116
	v_lshlrev_b64 v[116:117], 13, v[116:117]
	v_lshl_add_u64 v[116:117], v[118:119], 0, v[116:117]
	v_pk_fma_f32 v[114:115], v[114:115], v[130:131], v[150:151]
	v_pk_fma_f32 v[112:113], v[112:113], v[128:129], v[148:149]
	v_lshl_add_u64 v[116:117], v[174:175], 2, v[116:117]
	global_store_dwordx4 v[116:117], v[112:115], off
	s_and_saveexec_b64 s[2:3], s[10:11]
	s_xor_b64 s[52:53], exec, s[2:3]
	v_add3_u32 v112, v224, v213, s62
	s_or_saveexec_b64 s[52:53], s[52:53]
	v_mov_b64_e32 v[114:115], s[24:25]
	s_xor_b64 exec, exec, s[52:53]
	v_lshl_add_u32 v112, v214, 8, v213
	v_mov_b64_e32 v[114:115], s[36:37]
	s_or_b64 exec, exec, s[52:53]
	v_ashrrev_i32_e32 v113, 31, v112
	v_lshlrev_b64 v[112:113], 13, v[112:113]
	v_lshl_add_u64 v[112:113], v[114:115], 0, v[112:113]
	v_pk_fma_f32 v[110:111], v[110:111], v[130:131], v[146:147]
	v_pk_fma_f32 v[108:109], v[108:109], v[128:129], v[144:145]
	v_lshl_add_u64 v[112:113], v[174:175], 2, v[112:113]
	global_store_dwordx4 v[112:113], v[108:111], off
	s_and_saveexec_b64 s[2:3], s[8:9]
	s_xor_b64 s[52:53], exec, s[2:3]
	v_add3_u32 v108, v225, v215, s62
	s_or_saveexec_b64 s[52:53], s[52:53]
	v_mov_b64_e32 v[110:111], s[24:25]
	s_xor_b64 exec, exec, s[52:53]
	v_lshl_add_u32 v108, v216, 8, v215
	v_mov_b64_e32 v[110:111], s[36:37]
	s_or_b64 exec, exec, s[52:53]
	v_ashrrev_i32_e32 v109, 31, v108
	v_lshlrev_b64 v[108:109], 13, v[108:109]
	v_lshl_add_u64 v[108:109], v[110:111], 0, v[108:109]
	v_pk_fma_f32 v[106:107], v[106:107], v[130:131], v[142:143]
	v_pk_fma_f32 v[104:105], v[104:105], v[128:129], v[140:141]
	v_lshl_add_u64 v[108:109], v[174:175], 2, v[108:109]
	global_store_dwordx4 v[108:109], v[104:107], off
	s_and_saveexec_b64 s[2:3], s[6:7]
	s_xor_b64 s[52:53], exec, s[2:3]
	v_add3_u32 v104, v226, v218, s62
	s_or_saveexec_b64 s[52:53], s[52:53]
	v_mov_b64_e32 v[106:107], s[24:25]
	s_xor_b64 exec, exec, s[52:53]
	v_lshl_add_u32 v104, v219, 8, v218
	v_mov_b64_e32 v[106:107], s[36:37]
	s_or_b64 exec, exec, s[52:53]
	v_ashrrev_i32_e32 v105, 31, v104
	v_lshlrev_b64 v[104:105], 13, v[104:105]
	v_lshl_add_u64 v[104:105], v[106:107], 0, v[104:105]
	v_pk_fma_f32 v[102:103], v[102:103], v[130:131], v[138:139]
	v_pk_fma_f32 v[100:101], v[100:101], v[128:129], v[136:137]
	v_lshl_add_u64 v[104:105], v[174:175], 2, v[104:105]
	global_store_dwordx4 v[104:105], v[100:103], off
	s_and_saveexec_b64 s[2:3], vcc
	s_xor_b64 s[52:53], exec, s[2:3]
	v_add3_u32 v100, v227, v221, s62
	s_or_saveexec_b64 s[52:53], s[52:53]
	v_mov_b64_e32 v[102:103], s[24:25]
	s_xor_b64 exec, exec, s[52:53]
	v_lshl_add_u32 v100, v222, 8, v221
	v_mov_b64_e32 v[102:103], s[36:37]
	s_or_b64 exec, exec, s[52:53]
	v_ashrrev_i32_e32 v101, 31, v100
	v_lshlrev_b64 v[100:101], 13, v[100:101]
	v_lshl_add_u64 v[100:101], v[102:103], 0, v[100:101]
	v_pk_fma_f32 v[98:99], v[98:99], v[130:131], v[134:135]
	v_pk_fma_f32 v[96:97], v[96:97], v[128:129], v[132:133]
	v_lshl_add_u64 v[100:101], v[174:175], 2, v[100:101]
	global_store_dwordx4 v[100:101], v[96:99], off
	global_load_dwordx4 v[96:99], v[192:193], off offset:64
	s_and_saveexec_b64 s[2:3], s[18:19]
	s_xor_b64 s[52:53], exec, s[2:3]
	v_add3_u32 v100, v212, v202, s62
	s_or_saveexec_b64 s[52:53], s[52:53]
	v_mov_b64_e32 v[102:103], s[24:25]
	s_xor_b64 exec, exec, s[52:53]
	v_lshl_add_u32 v100, v203, 8, v202
	v_mov_b64_e32 v[102:103], s[36:37]
	s_or_b64 exec, exec, s[52:53]
	v_ashrrev_i32_e32 v101, 31, v100
	v_lshlrev_b64 v[100:101], 13, v[100:101]
	v_lshl_add_u64 v[100:101], v[102:103], 0, v[100:101]
	v_lshl_add_u64 v[100:101], v[174:175], 2, v[100:101]
	global_load_dwordx4 v[128:131], v[100:101], off offset:64
	s_and_saveexec_b64 s[2:3], s[16:17]
; DI void epi_resid(const Acc& acc, const P& p, int brow, int bcol, int layer, int gch, bool from_input) {
;     ...
;     for (int bj = 0; bj < 2; ++bj)
; #pragma unroll
;         for (int n = 0; n < 2; ++n) {
;             const int c0 = bcol + bj * 128 + wc * 32 + n * 16 + fq * 4;
;             const f32x4 g = *(const f32x4*)(gate + c0);
;             f32x4 xv[2][4];
; #pragma unroll
;             for (int ai = 0; ai < 2; ++ai)
; #pragma unroll
;                 for (int m = 0; m < 4; ++m) {
;                     const int r = brow + ai * 128 + wr * 64 + m * 16 + fr;
;                     const float* sp = (from_input ? inrow(p, r) : xrow(p, r)) + c0;
;                     xv[ai][m] = *(const f32x4*)sp;
;                 }
;             __builtin_amdgcn_sched_barrier(0);
; #pragma unroll
;             for (int ai = 0; ai < 2; ++ai)
; #pragma unroll
;                 for (int m = 0; m < 4; ++m) {
;                     const int r = brow + ai * 128 + wr * 64 + m * 16 + fr;
;                     *(f32x4*)(xrow(p, r) + c0) = xv[ai][m] + g * acc[ai][bj][m][n];
;                 }
;             __builtin_amdgcn_sched_barrier(0);
;         }
	s_xor_b64 s[52:53], exec, s[2:3]
	v_add3_u32 v100, v217, v204, s62
	s_or_saveexec_b64 s[52:53], s[52:53]
	v_mov_b64_e32 v[102:103], s[24:25]
	s_xor_b64 exec, exec, s[52:53]
	v_lshl_add_u32 v100, v205, 8, v204
	v_mov_b64_e32 v[102:103], s[36:37]
	s_or_b64 exec, exec, s[52:53]
	v_ashrrev_i32_e32 v101, 31, v100
	v_lshlrev_b64 v[100:101], 13, v[100:101]
	v_lshl_add_u64 v[100:101], v[102:103], 0, v[100:101]
	v_lshl_add_u64 v[100:101], v[174:175], 2, v[100:101]
	global_load_dwordx4 v[124:127], v[100:101], off offset:64
	s_and_saveexec_b64 s[2:3], s[14:15]
	s_xor_b64 s[52:53], exec, s[2:3]
	v_add3_u32 v100, v220, v208, s62
	s_or_saveexec_b64 s[52:53], s[52:53]
	v_mov_b64_e32 v[102:103], s[24:25]
	s_xor_b64 exec, exec, s[52:53]
	v_lshl_add_u32 v100, v209, 8, v208
	v_mov_b64_e32 v[102:103], s[36:37]
	s_or_b64 exec, exec, s[52:53]
	v_ashrrev_i32_e32 v101, 31, v100
	v_lshlrev_b64 v[100:101], 13, v[100:101]
	v_lshl_add_u64 v[100:101], v[102:103], 0, v[100:101]
	v_lshl_add_u64 v[100:101], v[174:175], 2, v[100:101]
	global_load_dwordx4 v[120:123], v[100:101], off offset:64
	s_and_saveexec_b64 s[2:3], s[12:13]
	s_xor_b64 s[52:53], exec, s[2:3]
	v_add3_u32 v100, v223, v210, s62
	s_or_saveexec_b64 s[52:53], s[52:53]
	v_mov_b64_e32 v[102:103], s[24:25]
	s_xor_b64 exec, exec, s[52:53]
	v_lshl_add_u32 v100, v211, 8, v210
	v_mov_b64_e32 v[102:103], s[36:37]
	s_or_b64 exec, exec, s[52:53]
	v_ashrrev_i32_e32 v101, 31, v100
	v_lshlrev_b64 v[100:101], 13, v[100:101]
	v_lshl_add_u64 v[100:101], v[102:103], 0, v[100:101]
	v_lshl_add_u64 v[100:101], v[174:175], 2, v[100:101]
	global_load_dwordx4 v[116:119], v[100:101], off offset:64
	s_and_saveexec_b64 s[2:3], s[10:11]
	s_xor_b64 s[52:53], exec, s[2:3]
	v_add3_u32 v100, v224, v213, s62
	s_or_saveexec_b64 s[52:53], s[52:53]
	v_mov_b64_e32 v[102:103], s[24:25]
	s_xor_b64 exec, exec, s[52:53]
	v_lshl_add_u32 v100, v214, 8, v213
	v_mov_b64_e32 v[102:103], s[36:37]
	s_or_b64 exec, exec, s[52:53]
	v_ashrrev_i32_e32 v101, 31, v100
	v_lshlrev_b64 v[100:101], 13, v[100:101]
	v_lshl_add_u64 v[100:101], v[102:103], 0, v[100:101]
	v_lshl_add_u64 v[100:101], v[174:175], 2, v[100:101]
	global_load_dwordx4 v[112:115], v[100:101], off offset:64
	s_and_saveexec_b64 s[2:3], s[8:9]
	s_xor_b64 s[52:53], exec, s[2:3]
	v_add3_u32 v100, v225, v215, s62
	s_or_saveexec_b64 s[52:53], s[52:53]
	v_mov_b64_e32 v[102:103], s[24:25]
	s_xor_b64 exec, exec, s[52:53]
	v_lshl_add_u32 v100, v216, 8, v215
	v_mov_b64_e32 v[102:103], s[36:37]
	s_or_b64 exec, exec, s[52:53]
	v_ashrrev_i32_e32 v101, 31, v100
	v_lshlrev_b64 v[100:101], 13, v[100:101]
	v_lshl_add_u64 v[100:101], v[102:103], 0, v[100:101]
	v_lshl_add_u64 v[100:101], v[174:175], 2, v[100:101]
	global_load_dwordx4 v[108:111], v[100:101], off offset:64
	s_and_saveexec_b64 s[2:3], s[6:7]
	s_xor_b64 s[52:53], exec, s[2:3]
	v_add3_u32 v100, v226, v218, s62
	s_or_saveexec_b64 s[52:53], s[52:53]
	v_mov_b64_e32 v[102:103], s[24:25]
	s_xor_b64 exec, exec, s[52:53]
	v_lshl_add_u32 v100, v219, 8, v218
	v_mov_b64_e32 v[102:103], s[36:37]
	s_or_b64 exec, exec, s[52:53]
	v_ashrrev_i32_e32 v101, 31, v100
	v_lshlrev_b64 v[100:101], 13, v[100:101]
	v_lshl_add_u64 v[100:101], v[102:103], 0, v[100:101]
	v_lshl_add_u64 v[100:101], v[174:175], 2, v[100:101]
	global_load_dwordx4 v[104:107], v[100:101], off offset:64
	s_and_saveexec_b64 s[2:3], vcc
	s_xor_b64 s[52:53], exec, s[2:3]
	v_add3_u32 v100, v227, v221, s62
	s_or_saveexec_b64 s[52:53], s[52:53]
	v_mov_b64_e32 v[102:103], s[24:25]
	s_xor_b64 exec, exec, s[52:53]
	v_lshl_add_u32 v100, v222, 8, v221
	v_mov_b64_e32 v[102:103], s[36:37]
	s_or_b64 exec, exec, s[52:53]
	v_ashrrev_i32_e32 v101, 31, v100
	v_lshlrev_b64 v[100:101], 13, v[100:101]
	v_lshl_add_u64 v[100:101], v[102:103], 0, v[100:101]
	v_lshl_add_u64 v[100:101], v[174:175], 2, v[100:101]
	global_load_dwordx4 v[100:103], v[100:101], off offset:64
	s_and_saveexec_b64 s[2:3], s[18:19]
	s_xor_b64 s[52:53], exec, s[2:3]
	v_add3_u32 v132, v212, v202, s62
	s_or_saveexec_b64 s[52:53], s[52:53]
	v_mov_b64_e32 v[134:135], s[24:25]
	s_xor_b64 exec, exec, s[52:53]
	v_lshl_add_u32 v132, v203, 8, v202
	v_mov_b64_e32 v[134:135], s[36:37]
	s_or_b64 exec, exec, s[52:53]
	v_ashrrev_i32_e32 v133, 31, v132
	s_waitcnt vmcnt(0)
	v_pk_fma_f32 v[92:93], v[92:93], v[96:97], v[128:129]
	v_lshlrev_b64 v[128:129], 13, v[132:133]
	v_lshl_add_u64 v[128:129], v[134:135], 0, v[128:129]
	v_pk_fma_f32 v[94:95], v[94:95], v[98:99], v[130:131]
	v_lshl_add_u64 v[128:129], v[174:175], 2, v[128:129]
	global_store_dwordx4 v[128:129], v[92:95], off offset:64
	s_and_saveexec_b64 s[2:3], s[16:17]
	s_xor_b64 s[52:53], exec, s[2:3]
	v_add3_u32 v92, v217, v204, s62
	s_or_saveexec_b64 s[52:53], s[52:53]
	v_mov_b64_e32 v[94:95], s[24:25]
	s_xor_b64 exec, exec, s[52:53]
	v_lshl_add_u32 v92, v205, 8, v204
	v_mov_b64_e32 v[94:95], s[36:37]
	s_or_b64 exec, exec, s[52:53]
	v_ashrrev_i32_e32 v93, 31, v92
	v_lshlrev_b64 v[92:93], 13, v[92:93]
	v_lshl_add_u64 v[92:93], v[94:95], 0, v[92:93]
	v_pk_fma_f32 v[90:91], v[90:91], v[98:99], v[126:127]
	v_pk_fma_f32 v[88:89], v[88:89], v[96:97], v[124:125]
	v_lshl_add_u64 v[92:93], v[174:175], 2, v[92:93]
	global_store_dwordx4 v[92:93], v[88:91], off offset:64
	s_and_saveexec_b64 s[2:3], s[14:15]
	s_xor_b64 s[52:53], exec, s[2:3]
	v_add3_u32 v88, v220, v208, s62
	s_or_saveexec_b64 s[52:53], s[52:53]
	v_mov_b64_e32 v[90:91], s[24:25]
	s_xor_b64 exec, exec, s[52:53]
	v_lshl_add_u32 v88, v209, 8, v208
	v_mov_b64_e32 v[90:91], s[36:37]
	s_or_b64 exec, exec, s[52:53]
	v_ashrrev_i32_e32 v89, 31, v88
	v_lshlrev_b64 v[88:89], 13, v[88:89]
	v_lshl_add_u64 v[88:89], v[90:91], 0, v[88:89]
	v_pk_fma_f32 v[86:87], v[86:87], v[98:99], v[122:123]
; DI void epi_resid(const Acc& acc, const P& p, int brow, int bcol, int layer, int gch, bool from_input) {
;     ...
;     for (int bj = 0; bj < 2; ++bj)
; #pragma unroll
;         for (int n = 0; n < 2; ++n) {
;             const int c0 = bcol + bj * 128 + wc * 32 + n * 16 + fq * 4;
;             const f32x4 g = *(const f32x4*)(gate + c0);
;             f32x4 xv[2][4];
; #pragma unroll
;             for (int ai = 0; ai < 2; ++ai)
; #pragma unroll
;                 for (int m = 0; m < 4; ++m) {
;                     const int r = brow + ai * 128 + wr * 64 + m * 16 + fr;
;                     const float* sp = (from_input ? inrow(p, r) : xrow(p, r)) + c0;
;                     xv[ai][m] = *(const f32x4*)sp;
;                 }
;             __builtin_amdgcn_sched_barrier(0);
; #pragma unroll
;             for (int ai = 0; ai < 2; ++ai)
; #pragma unroll
;                 for (int m = 0; m < 4; ++m) {
;                     const int r = brow + ai * 128 + wr * 64 + m * 16 + fr;
;                     *(f32x4*)(xrow(p, r) + c0) = xv[ai][m] + g * acc[ai][bj][m][n];
;                 }
;             __builtin_amdgcn_sched_barrier(0);
;         }
	v_pk_fma_f32 v[84:85], v[84:85], v[96:97], v[120:121]
	v_lshl_add_u64 v[88:89], v[174:175], 2, v[88:89]
	global_store_dwordx4 v[88:89], v[84:87], off offset:64
	s_and_saveexec_b64 s[2:3], s[12:13]
	s_xor_b64 s[52:53], exec, s[2:3]
	v_add3_u32 v84, v223, v210, s62
	s_or_saveexec_b64 s[52:53], s[52:53]
	v_mov_b64_e32 v[86:87], s[24:25]
	s_xor_b64 exec, exec, s[52:53]
	v_lshl_add_u32 v84, v211, 8, v210
	v_mov_b64_e32 v[86:87], s[36:37]
	s_or_b64 exec, exec, s[52:53]
	v_ashrrev_i32_e32 v85, 31, v84
	v_lshlrev_b64 v[84:85], 13, v[84:85]
	v_lshl_add_u64 v[84:85], v[86:87], 0, v[84:85]
	v_pk_fma_f32 v[82:83], v[82:83], v[98:99], v[118:119]
	v_pk_fma_f32 v[80:81], v[80:81], v[96:97], v[116:117]
	v_lshl_add_u64 v[84:85], v[174:175], 2, v[84:85]
	global_store_dwordx4 v[84:85], v[80:83], off offset:64
	s_and_saveexec_b64 s[2:3], s[10:11]
	s_xor_b64 s[52:53], exec, s[2:3]
	v_add3_u32 v80, v224, v213, s62
	s_or_saveexec_b64 s[52:53], s[52:53]
	v_mov_b64_e32 v[82:83], s[24:25]
	s_xor_b64 exec, exec, s[52:53]
	v_lshl_add_u32 v80, v214, 8, v213
	v_mov_b64_e32 v[82:83], s[36:37]
	s_or_b64 exec, exec, s[52:53]
	v_ashrrev_i32_e32 v81, 31, v80
	v_lshlrev_b64 v[80:81], 13, v[80:81]
	v_lshl_add_u64 v[80:81], v[82:83], 0, v[80:81]
	v_pk_fma_f32 v[78:79], v[78:79], v[98:99], v[114:115]
	v_pk_fma_f32 v[76:77], v[76:77], v[96:97], v[112:113]
	v_lshl_add_u64 v[80:81], v[174:175], 2, v[80:81]
	global_store_dwordx4 v[80:81], v[76:79], off offset:64
	s_and_saveexec_b64 s[2:3], s[8:9]
	s_xor_b64 s[52:53], exec, s[2:3]
	v_add3_u32 v76, v225, v215, s62
	s_or_saveexec_b64 s[52:53], s[52:53]
	v_mov_b64_e32 v[78:79], s[24:25]
	s_xor_b64 exec, exec, s[52:53]
	v_lshl_add_u32 v76, v216, 8, v215
	v_mov_b64_e32 v[78:79], s[36:37]
	s_or_b64 exec, exec, s[52:53]
	v_ashrrev_i32_e32 v77, 31, v76
	v_lshlrev_b64 v[76:77], 13, v[76:77]
	v_lshl_add_u64 v[76:77], v[78:79], 0, v[76:77]
	v_pk_fma_f32 v[74:75], v[74:75], v[98:99], v[110:111]
	v_pk_fma_f32 v[72:73], v[72:73], v[96:97], v[108:109]
	v_lshl_add_u64 v[76:77], v[174:175], 2, v[76:77]
	global_store_dwordx4 v[76:77], v[72:75], off offset:64
	s_and_saveexec_b64 s[2:3], s[6:7]
	s_xor_b64 s[52:53], exec, s[2:3]
	v_add3_u32 v72, v226, v218, s62
	s_or_saveexec_b64 s[52:53], s[52:53]
	v_mov_b64_e32 v[74:75], s[24:25]
	s_xor_b64 exec, exec, s[52:53]
	v_lshl_add_u32 v72, v219, 8, v218
	v_mov_b64_e32 v[74:75], s[36:37]
	s_or_b64 exec, exec, s[52:53]
	v_ashrrev_i32_e32 v73, 31, v72
	v_lshlrev_b64 v[72:73], 13, v[72:73]
	v_lshl_add_u64 v[72:73], v[74:75], 0, v[72:73]
	v_pk_fma_f32 v[70:71], v[70:71], v[98:99], v[106:107]
	v_pk_fma_f32 v[68:69], v[68:69], v[96:97], v[104:105]
	v_lshl_add_u64 v[72:73], v[174:175], 2, v[72:73]
	global_store_dwordx4 v[72:73], v[68:71], off offset:64
	s_and_saveexec_b64 s[2:3], vcc
	s_xor_b64 s[52:53], exec, s[2:3]
	v_add3_u32 v68, v227, v221, s62
	s_or_saveexec_b64 s[52:53], s[52:53]
	v_mov_b64_e32 v[70:71], s[24:25]
	s_xor_b64 exec, exec, s[52:53]
	v_lshl_add_u32 v68, v222, 8, v221
	v_mov_b64_e32 v[70:71], s[36:37]
	s_or_b64 exec, exec, s[52:53]
	v_ashrrev_i32_e32 v69, 31, v68
	v_lshlrev_b64 v[68:69], 13, v[68:69]
	v_lshl_add_u64 v[68:69], v[70:71], 0, v[68:69]
	v_pk_fma_f32 v[66:67], v[66:67], v[98:99], v[102:103]
	v_pk_fma_f32 v[64:65], v[64:65], v[96:97], v[100:101]
	v_lshl_add_u64 v[68:69], v[174:175], 2, v[68:69]
	global_store_dwordx4 v[68:69], v[64:67], off offset:64
	global_load_dwordx4 v[64:67], v[192:193], off offset:512
	s_and_saveexec_b64 s[2:3], s[18:19]
	s_xor_b64 s[52:53], exec, s[2:3]
	v_add3_u32 v68, v212, v202, s62
	s_or_saveexec_b64 s[52:53], s[52:53]
	v_mov_b64_e32 v[70:71], s[24:25]
	s_xor_b64 exec, exec, s[52:53]
	v_lshl_add_u32 v68, v203, 8, v202
	v_mov_b64_e32 v[70:71], s[36:37]
	s_or_b64 exec, exec, s[52:53]
	v_ashrrev_i32_e32 v69, 31, v68
	v_lshlrev_b64 v[68:69], 13, v[68:69]
	v_lshl_add_u64 v[68:69], v[70:71], 0, v[68:69]
	v_lshl_add_u64 v[68:69], v[174:175], 2, v[68:69]
	global_load_dwordx4 v[96:99], v[68:69], off offset:512
	s_and_saveexec_b64 s[2:3], s[16:17]
	s_xor_b64 s[52:53], exec, s[2:3]
	v_add3_u32 v68, v217, v204, s62
	s_or_saveexec_b64 s[52:53], s[52:53]
	v_mov_b64_e32 v[70:71], s[24:25]
	s_xor_b64 exec, exec, s[52:53]
	v_lshl_add_u32 v68, v205, 8, v204
	v_mov_b64_e32 v[70:71], s[36:37]
	s_or_b64 exec, exec, s[52:53]
	v_ashrrev_i32_e32 v69, 31, v68
	v_lshlrev_b64 v[68:69], 13, v[68:69]
	v_lshl_add_u64 v[68:69], v[70:71], 0, v[68:69]
	v_lshl_add_u64 v[68:69], v[174:175], 2, v[68:69]
	global_load_dwordx4 v[92:95], v[68:69], off offset:512
	s_and_saveexec_b64 s[2:3], s[14:15]
	s_xor_b64 s[52:53], exec, s[2:3]
	v_add3_u32 v68, v220, v208, s62
	s_or_saveexec_b64 s[52:53], s[52:53]
	v_mov_b64_e32 v[70:71], s[24:25]
	s_xor_b64 exec, exec, s[52:53]
	v_lshl_add_u32 v68, v209, 8, v208
	v_mov_b64_e32 v[70:71], s[36:37]
	s_or_b64 exec, exec, s[52:53]
	v_ashrrev_i32_e32 v69, 31, v68
	v_lshlrev_b64 v[68:69], 13, v[68:69]
	v_lshl_add_u64 v[68:69], v[70:71], 0, v[68:69]
	v_lshl_add_u64 v[68:69], v[174:175], 2, v[68:69]
	global_load_dwordx4 v[88:91], v[68:69], off offset:512
	s_and_saveexec_b64 s[2:3], s[12:13]
	s_xor_b64 s[52:53], exec, s[2:3]
	v_add3_u32 v68, v223, v210, s62
	s_or_saveexec_b64 s[52:53], s[52:53]
	v_mov_b64_e32 v[70:71], s[24:25]
	s_xor_b64 exec, exec, s[52:53]
	v_lshl_add_u32 v68, v211, 8, v210
	v_mov_b64_e32 v[70:71], s[36:37]
	s_or_b64 exec, exec, s[52:53]
	v_ashrrev_i32_e32 v69, 31, v68
	v_lshlrev_b64 v[68:69], 13, v[68:69]
	v_lshl_add_u64 v[68:69], v[70:71], 0, v[68:69]
	v_lshl_add_u64 v[68:69], v[174:175], 2, v[68:69]
	global_load_dwordx4 v[84:87], v[68:69], off offset:512
	s_and_saveexec_b64 s[2:3], s[10:11]
	s_xor_b64 s[52:53], exec, s[2:3]
	v_add3_u32 v68, v224, v213, s62
; DI void epi_resid(const Acc& acc, const P& p, int brow, int bcol, int layer, int gch, bool from_input) {
;     ...
;     for (int bj = 0; bj < 2; ++bj)
; #pragma unroll
;         for (int n = 0; n < 2; ++n) {
;             const int c0 = bcol + bj * 128 + wc * 32 + n * 16 + fq * 4;
;             const f32x4 g = *(const f32x4*)(gate + c0);
;             f32x4 xv[2][4];
; #pragma unroll
;             for (int ai = 0; ai < 2; ++ai)
; #pragma unroll
;                 for (int m = 0; m < 4; ++m) {
;                     const int r = brow + ai * 128 + wr * 64 + m * 16 + fr;
;                     const float* sp = (from_input ? inrow(p, r) : xrow(p, r)) + c0;
;                     xv[ai][m] = *(const f32x4*)sp;
;                 }
;             __builtin_amdgcn_sched_barrier(0);
; #pragma unroll
;             for (int ai = 0; ai < 2; ++ai)
; #pragma unroll
;                 for (int m = 0; m < 4; ++m) {
;                     const int r = brow + ai * 128 + wr * 64 + m * 16 + fr;
;                     *(f32x4*)(xrow(p, r) + c0) = xv[ai][m] + g * acc[ai][bj][m][n];
;                 }
;             __builtin_amdgcn_sched_barrier(0);
;         }
	s_or_saveexec_b64 s[52:53], s[52:53]
	v_mov_b64_e32 v[70:71], s[24:25]
	s_xor_b64 exec, exec, s[52:53]
	v_lshl_add_u32 v68, v214, 8, v213
	v_mov_b64_e32 v[70:71], s[36:37]
	s_or_b64 exec, exec, s[52:53]
	v_ashrrev_i32_e32 v69, 31, v68
	v_lshlrev_b64 v[68:69], 13, v[68:69]
	v_lshl_add_u64 v[68:69], v[70:71], 0, v[68:69]
	v_lshl_add_u64 v[68:69], v[174:175], 2, v[68:69]
	global_load_dwordx4 v[80:83], v[68:69], off offset:512
	s_and_saveexec_b64 s[2:3], s[8:9]
	s_xor_b64 s[52:53], exec, s[2:3]
	v_add3_u32 v68, v225, v215, s62
	s_or_saveexec_b64 s[52:53], s[52:53]
	v_mov_b64_e32 v[70:71], s[24:25]
	s_xor_b64 exec, exec, s[52:53]
	v_lshl_add_u32 v68, v216, 8, v215
	v_mov_b64_e32 v[70:71], s[36:37]
	s_or_b64 exec, exec, s[52:53]
	v_ashrrev_i32_e32 v69, 31, v68
	v_lshlrev_b64 v[68:69], 13, v[68:69]
	v_lshl_add_u64 v[68:69], v[70:71], 0, v[68:69]
	v_lshl_add_u64 v[68:69], v[174:175], 2, v[68:69]
	global_load_dwordx4 v[76:79], v[68:69], off offset:512
	s_and_saveexec_b64 s[2:3], s[6:7]
	s_xor_b64 s[52:53], exec, s[2:3]
	v_add3_u32 v68, v226, v218, s62
	s_or_saveexec_b64 s[52:53], s[52:53]
	v_mov_b64_e32 v[70:71], s[24:25]
	s_xor_b64 exec, exec, s[52:53]
	v_lshl_add_u32 v68, v219, 8, v218
	v_mov_b64_e32 v[70:71], s[36:37]
	s_or_b64 exec, exec, s[52:53]
	v_ashrrev_i32_e32 v69, 31, v68
	v_lshlrev_b64 v[68:69], 13, v[68:69]
	v_lshl_add_u64 v[68:69], v[70:71], 0, v[68:69]
	v_lshl_add_u64 v[68:69], v[174:175], 2, v[68:69]
	global_load_dwordx4 v[72:75], v[68:69], off offset:512
	s_and_saveexec_b64 s[2:3], vcc
	s_xor_b64 s[52:53], exec, s[2:3]
	v_add3_u32 v68, v227, v221, s62
	s_or_saveexec_b64 s[52:53], s[52:53]
	v_mov_b64_e32 v[70:71], s[24:25]
	s_xor_b64 exec, exec, s[52:53]
	v_lshl_add_u32 v68, v222, 8, v221
	v_mov_b64_e32 v[70:71], s[36:37]
	s_or_b64 exec, exec, s[52:53]
	v_ashrrev_i32_e32 v69, 31, v68
	v_lshlrev_b64 v[68:69], 13, v[68:69]
	v_lshl_add_u64 v[68:69], v[70:71], 0, v[68:69]
	v_lshl_add_u64 v[68:69], v[174:175], 2, v[68:69]
	global_load_dwordx4 v[68:71], v[68:69], off offset:512
	s_and_saveexec_b64 s[2:3], s[18:19]
	s_xor_b64 s[52:53], exec, s[2:3]
	v_add3_u32 v100, v212, v202, s62
	s_or_saveexec_b64 s[52:53], s[52:53]
	v_mov_b64_e32 v[102:103], s[24:25]
	s_xor_b64 exec, exec, s[52:53]
	v_lshl_add_u32 v100, v203, 8, v202
	v_mov_b64_e32 v[102:103], s[36:37]
	s_or_b64 exec, exec, s[52:53]
	v_ashrrev_i32_e32 v101, 31, v100
	s_waitcnt vmcnt(0)
	v_pk_fma_f32 v[60:61], v[60:61], v[64:65], v[96:97]
	v_lshlrev_b64 v[96:97], 13, v[100:101]
	v_lshl_add_u64 v[96:97], v[102:103], 0, v[96:97]
	v_pk_fma_f32 v[62:63], v[62:63], v[66:67], v[98:99]
	v_lshl_add_u64 v[96:97], v[174:175], 2, v[96:97]
	global_store_dwordx4 v[96:97], v[60:63], off offset:512
	s_and_saveexec_b64 s[2:3], s[16:17]
	s_xor_b64 s[52:53], exec, s[2:3]
	v_add3_u32 v60, v217, v204, s62
	s_or_saveexec_b64 s[52:53], s[52:53]
	v_mov_b64_e32 v[62:63], s[24:25]
	s_xor_b64 exec, exec, s[52:53]
	v_lshl_add_u32 v60, v205, 8, v204
	v_mov_b64_e32 v[62:63], s[36:37]
	s_or_b64 exec, exec, s[52:53]
	v_ashrrev_i32_e32 v61, 31, v60
	v_lshlrev_b64 v[60:61], 13, v[60:61]
	v_lshl_add_u64 v[60:61], v[62:63], 0, v[60:61]
	v_pk_fma_f32 v[58:59], v[58:59], v[66:67], v[94:95]
	v_pk_fma_f32 v[56:57], v[56:57], v[64:65], v[92:93]
	v_lshl_add_u64 v[60:61], v[174:175], 2, v[60:61]
	global_store_dwordx4 v[60:61], v[56:59], off offset:512
	s_and_saveexec_b64 s[2:3], s[14:15]
	s_xor_b64 s[52:53], exec, s[2:3]
	v_add3_u32 v56, v220, v208, s62
	s_or_saveexec_b64 s[52:53], s[52:53]
	v_mov_b64_e32 v[58:59], s[24:25]
	s_xor_b64 exec, exec, s[52:53]
	v_lshl_add_u32 v56, v209, 8, v208
	v_mov_b64_e32 v[58:59], s[36:37]
	s_or_b64 exec, exec, s[52:53]
	v_ashrrev_i32_e32 v57, 31, v56
	v_lshlrev_b64 v[56:57], 13, v[56:57]
	v_lshl_add_u64 v[56:57], v[58:59], 0, v[56:57]
	v_pk_fma_f32 v[54:55], v[54:55], v[66:67], v[90:91]
	v_pk_fma_f32 v[52:53], v[52:53], v[64:65], v[88:89]
	v_lshl_add_u64 v[56:57], v[174:175], 2, v[56:57]
	global_store_dwordx4 v[56:57], v[52:55], off offset:512
	s_and_saveexec_b64 s[2:3], s[12:13]
	s_xor_b64 s[52:53], exec, s[2:3]
	v_add3_u32 v52, v223, v210, s62
	s_or_saveexec_b64 s[52:53], s[52:53]
	v_mov_b64_e32 v[54:55], s[24:25]
	s_xor_b64 exec, exec, s[52:53]
	v_lshl_add_u32 v52, v211, 8, v210
	v_mov_b64_e32 v[54:55], s[36:37]
	s_or_b64 exec, exec, s[52:53]
	v_ashrrev_i32_e32 v53, 31, v52
	v_lshlrev_b64 v[52:53], 13, v[52:53]
	v_lshl_add_u64 v[52:53], v[54:55], 0, v[52:53]
	v_pk_fma_f32 v[50:51], v[50:51], v[66:67], v[86:87]
	v_pk_fma_f32 v[48:49], v[48:49], v[64:65], v[84:85]
	v_lshl_add_u64 v[52:53], v[174:175], 2, v[52:53]
	global_store_dwordx4 v[52:53], v[48:51], off offset:512
	s_and_saveexec_b64 s[2:3], s[10:11]
	s_xor_b64 s[52:53], exec, s[2:3]
	v_add3_u32 v48, v224, v213, s62
	s_or_saveexec_b64 s[52:53], s[52:53]
	v_mov_b64_e32 v[50:51], s[24:25]
	s_xor_b64 exec, exec, s[52:53]
	v_lshl_add_u32 v48, v214, 8, v213
	v_mov_b64_e32 v[50:51], s[36:37]
	s_or_b64 exec, exec, s[52:53]
	v_ashrrev_i32_e32 v49, 31, v48
	v_lshlrev_b64 v[48:49], 13, v[48:49]
	v_lshl_add_u64 v[48:49], v[50:51], 0, v[48:49]
	v_pk_fma_f32 v[46:47], v[46:47], v[66:67], v[82:83]
	v_pk_fma_f32 v[44:45], v[44:45], v[64:65], v[80:81]
	v_lshl_add_u64 v[48:49], v[174:175], 2, v[48:49]
	global_store_dwordx4 v[48:49], v[44:47], off offset:512
	s_and_saveexec_b64 s[2:3], s[8:9]
	s_xor_b64 s[52:53], exec, s[2:3]
	v_add3_u32 v44, v225, v215, s62
	s_or_saveexec_b64 s[52:53], s[52:53]
	v_mov_b64_e32 v[46:47], s[24:25]
	s_xor_b64 exec, exec, s[52:53]
	v_lshl_add_u32 v44, v216, 8, v215
	v_mov_b64_e32 v[46:47], s[36:37]
	s_or_b64 exec, exec, s[52:53]
	v_ashrrev_i32_e32 v45, 31, v44
	v_lshlrev_b64 v[44:45], 13, v[44:45]
; DI void epi_resid(const Acc& acc, const P& p, int brow, int bcol, int layer, int gch, bool from_input) {
;     ...
;     for (int bj = 0; bj < 2; ++bj)
; #pragma unroll
;         for (int n = 0; n < 2; ++n) {
;             const int c0 = bcol + bj * 128 + wc * 32 + n * 16 + fq * 4;
;             const f32x4 g = *(const f32x4*)(gate + c0);
;             f32x4 xv[2][4];
; #pragma unroll
;             for (int ai = 0; ai < 2; ++ai)
; #pragma unroll
;                 for (int m = 0; m < 4; ++m) {
;                     const int r = brow + ai * 128 + wr * 64 + m * 16 + fr;
;                     const float* sp = (from_input ? inrow(p, r) : xrow(p, r)) + c0;
;                     xv[ai][m] = *(const f32x4*)sp;
;                 }
;             __builtin_amdgcn_sched_barrier(0);
; #pragma unroll
;             for (int ai = 0; ai < 2; ++ai)
; #pragma unroll
;                 for (int m = 0; m < 4; ++m) {
;                     const int r = brow + ai * 128 + wr * 64 + m * 16 + fr;
;                     *(f32x4*)(xrow(p, r) + c0) = xv[ai][m] + g * acc[ai][bj][m][n];
;                 }
;             __builtin_amdgcn_sched_barrier(0);
;         }
	v_lshl_add_u64 v[44:45], v[46:47], 0, v[44:45]
	v_pk_fma_f32 v[42:43], v[42:43], v[66:67], v[78:79]
	v_pk_fma_f32 v[40:41], v[40:41], v[64:65], v[76:77]
	v_lshl_add_u64 v[44:45], v[174:175], 2, v[44:45]
	global_store_dwordx4 v[44:45], v[40:43], off offset:512
	s_and_saveexec_b64 s[2:3], s[6:7]
	s_xor_b64 s[52:53], exec, s[2:3]
	v_add3_u32 v40, v226, v218, s62
	s_or_saveexec_b64 s[52:53], s[52:53]
	v_mov_b64_e32 v[42:43], s[24:25]
	s_xor_b64 exec, exec, s[52:53]
	v_lshl_add_u32 v40, v219, 8, v218
	v_mov_b64_e32 v[42:43], s[36:37]
	s_or_b64 exec, exec, s[52:53]
	v_ashrrev_i32_e32 v41, 31, v40
	v_lshlrev_b64 v[40:41], 13, v[40:41]
	v_lshl_add_u64 v[40:41], v[42:43], 0, v[40:41]
	v_pk_fma_f32 v[38:39], v[38:39], v[66:67], v[74:75]
	v_pk_fma_f32 v[36:37], v[36:37], v[64:65], v[72:73]
	v_lshl_add_u64 v[40:41], v[174:175], 2, v[40:41]
	global_store_dwordx4 v[40:41], v[36:39], off offset:512
	s_and_saveexec_b64 s[2:3], vcc
	s_xor_b64 s[52:53], exec, s[2:3]
	v_add3_u32 v36, v227, v221, s62
	s_or_saveexec_b64 s[52:53], s[52:53]
	v_mov_b64_e32 v[38:39], s[24:25]
	s_xor_b64 exec, exec, s[52:53]
	v_lshl_add_u32 v36, v222, 8, v221
	v_mov_b64_e32 v[38:39], s[36:37]
	s_or_b64 exec, exec, s[52:53]
	v_ashrrev_i32_e32 v37, 31, v36
	v_lshlrev_b64 v[36:37], 13, v[36:37]
	v_lshl_add_u64 v[36:37], v[38:39], 0, v[36:37]
	v_pk_fma_f32 v[34:35], v[34:35], v[66:67], v[70:71]
	v_pk_fma_f32 v[32:33], v[32:33], v[64:65], v[68:69]
	v_lshl_add_u64 v[36:37], v[174:175], 2, v[36:37]
	global_store_dwordx4 v[36:37], v[32:35], off offset:512
	global_load_dwordx4 v[32:35], v[192:193], off offset:576
	s_and_saveexec_b64 s[2:3], s[18:19]
	s_xor_b64 s[52:53], exec, s[2:3]
	v_add3_u32 v36, v212, v202, s62
	s_or_saveexec_b64 s[52:53], s[52:53]
	v_mov_b64_e32 v[38:39], s[24:25]
	s_xor_b64 exec, exec, s[52:53]
	v_lshl_add_u32 v36, v203, 8, v202
	v_mov_b64_e32 v[38:39], s[36:37]
	s_or_b64 exec, exec, s[52:53]
	v_ashrrev_i32_e32 v37, 31, v36
	v_lshlrev_b64 v[36:37], 13, v[36:37]
	v_lshl_add_u64 v[36:37], v[38:39], 0, v[36:37]
	v_lshl_add_u64 v[36:37], v[174:175], 2, v[36:37]
	global_load_dwordx4 v[64:67], v[36:37], off offset:576
	s_and_saveexec_b64 s[2:3], s[16:17]
	s_xor_b64 s[52:53], exec, s[2:3]
	v_add3_u32 v36, v217, v204, s62
	s_or_saveexec_b64 s[52:53], s[52:53]
	v_mov_b64_e32 v[38:39], s[24:25]
	s_xor_b64 exec, exec, s[52:53]
	v_lshl_add_u32 v36, v205, 8, v204
	v_mov_b64_e32 v[38:39], s[36:37]
	s_or_b64 exec, exec, s[52:53]
	v_ashrrev_i32_e32 v37, 31, v36
	v_lshlrev_b64 v[36:37], 13, v[36:37]
	v_lshl_add_u64 v[36:37], v[38:39], 0, v[36:37]
	v_lshl_add_u64 v[36:37], v[174:175], 2, v[36:37]
	global_load_dwordx4 v[60:63], v[36:37], off offset:576
	s_and_saveexec_b64 s[2:3], s[14:15]
	s_xor_b64 s[52:53], exec, s[2:3]
	v_add3_u32 v36, v220, v208, s62
	s_or_saveexec_b64 s[52:53], s[52:53]
	v_mov_b64_e32 v[38:39], s[24:25]
	s_xor_b64 exec, exec, s[52:53]
	v_lshl_add_u32 v36, v209, 8, v208
	v_mov_b64_e32 v[38:39], s[36:37]
	s_or_b64 exec, exec, s[52:53]
	v_ashrrev_i32_e32 v37, 31, v36
	v_lshlrev_b64 v[36:37], 13, v[36:37]
	v_lshl_add_u64 v[36:37], v[38:39], 0, v[36:37]
	v_lshl_add_u64 v[36:37], v[174:175], 2, v[36:37]
	global_load_dwordx4 v[56:59], v[36:37], off offset:576
	s_and_saveexec_b64 s[2:3], s[12:13]
	s_xor_b64 s[52:53], exec, s[2:3]
	v_add3_u32 v36, v223, v210, s62
	s_or_saveexec_b64 s[52:53], s[52:53]
	v_mov_b64_e32 v[38:39], s[24:25]
	s_xor_b64 exec, exec, s[52:53]
	v_lshl_add_u32 v36, v211, 8, v210
	v_mov_b64_e32 v[38:39], s[36:37]
	s_or_b64 exec, exec, s[52:53]
	v_ashrrev_i32_e32 v37, 31, v36
	v_lshlrev_b64 v[36:37], 13, v[36:37]
	v_lshl_add_u64 v[36:37], v[38:39], 0, v[36:37]
	v_lshl_add_u64 v[36:37], v[174:175], 2, v[36:37]
	global_load_dwordx4 v[52:55], v[36:37], off offset:576
	s_and_saveexec_b64 s[2:3], s[10:11]
	s_xor_b64 s[52:53], exec, s[2:3]
	v_add3_u32 v36, v224, v213, s62
	s_or_saveexec_b64 s[52:53], s[52:53]
	v_mov_b64_e32 v[38:39], s[24:25]
	s_xor_b64 exec, exec, s[52:53]
	v_lshl_add_u32 v36, v214, 8, v213
	v_mov_b64_e32 v[38:39], s[36:37]
	s_or_b64 exec, exec, s[52:53]
	v_ashrrev_i32_e32 v37, 31, v36
	v_lshlrev_b64 v[36:37], 13, v[36:37]
	v_lshl_add_u64 v[36:37], v[38:39], 0, v[36:37]
	v_lshl_add_u64 v[36:37], v[174:175], 2, v[36:37]
	global_load_dwordx4 v[48:51], v[36:37], off offset:576
	s_and_saveexec_b64 s[2:3], s[8:9]
	s_xor_b64 s[52:53], exec, s[2:3]
	v_add3_u32 v36, v225, v215, s62
	s_or_saveexec_b64 s[52:53], s[52:53]
	v_mov_b64_e32 v[38:39], s[24:25]
	s_xor_b64 exec, exec, s[52:53]
	v_lshl_add_u32 v36, v216, 8, v215
	v_mov_b64_e32 v[38:39], s[36:37]
	s_or_b64 exec, exec, s[52:53]
	v_ashrrev_i32_e32 v37, 31, v36
	v_lshlrev_b64 v[36:37], 13, v[36:37]
	v_lshl_add_u64 v[36:37], v[38:39], 0, v[36:37]
	v_lshl_add_u64 v[36:37], v[174:175], 2, v[36:37]
	global_load_dwordx4 v[44:47], v[36:37], off offset:576
	s_and_saveexec_b64 s[2:3], s[6:7]
	s_xor_b64 s[52:53], exec, s[2:3]
	v_add3_u32 v36, v226, v218, s62
	s_or_saveexec_b64 s[52:53], s[52:53]
	v_mov_b64_e32 v[38:39], s[24:25]
	s_xor_b64 exec, exec, s[52:53]
	v_lshl_add_u32 v36, v219, 8, v218
	v_mov_b64_e32 v[38:39], s[36:37]
	s_or_b64 exec, exec, s[52:53]
	v_ashrrev_i32_e32 v37, 31, v36
	v_lshlrev_b64 v[36:37], 13, v[36:37]
	v_lshl_add_u64 v[36:37], v[38:39], 0, v[36:37]
	v_lshl_add_u64 v[36:37], v[174:175], 2, v[36:37]
	global_load_dwordx4 v[40:43], v[36:37], off offset:576
	s_and_saveexec_b64 s[2:3], vcc
	s_xor_b64 s[52:53], exec, s[2:3]
	v_add3_u32 v36, v227, v221, s62
	s_or_saveexec_b64 s[52:53], s[52:53]
	v_mov_b64_e32 v[38:39], s[24:25]
	s_xor_b64 exec, exec, s[52:53]
	v_lshl_add_u32 v36, v222, 8, v221
	v_mov_b64_e32 v[38:39], s[36:37]
	s_or_b64 exec, exec, s[52:53]
	v_ashrrev_i32_e32 v37, 31, v36
	v_lshlrev_b64 v[36:37], 13, v[36:37]
	v_lshl_add_u64 v[36:37], v[38:39], 0, v[36:37]
	v_lshl_add_u64 v[36:37], v[174:175], 2, v[36:37]
	global_load_dwordx4 v[36:39], v[36:37], off offset:576
	s_and_saveexec_b64 s[2:3], s[18:19]
	s_xor_b64 s[18:19], exec, s[2:3]
	s_or_saveexec_b64 s[18:19], s[18:19]
	v_mov_b64_e32 v[68:69], s[24:25]
	s_xor_b64 exec, exec, s[18:19]
	v_mov_b64_e32 v[68:69], s[36:37]
	v_mov_b32_e32 v190, v191
	s_or_b64 exec, exec, s[18:19]
	v_ashrrev_i32_e32 v191, 31, v190
	s_waitcnt vmcnt(0)
; DI void epi_resid(const Acc& acc, const P& p, int brow, int bcol, int layer, int gch, bool from_input) {
;     ...
; #pragma unroll
;             for (int ai = 0; ai < 2; ++ai)
; #pragma unroll
;                 for (int m = 0; m < 4; ++m) {
;                     const int r = brow + ai * 128 + wr * 64 + m * 16 + fr;
;                     *(f32x4*)(xrow(p, r) + c0) = xv[ai][m] + g * acc[ai][bj][m][n];
;                 }
	v_pk_fma_f32 v[28:29], v[28:29], v[32:33], v[64:65]
	v_lshlrev_b64 v[64:65], 13, v[190:191]
	v_lshl_add_u64 v[64:65], v[68:69], 0, v[64:65]
	v_pk_fma_f32 v[30:31], v[30:31], v[34:35], v[66:67]
	v_lshl_add_u64 v[64:65], v[174:175], 2, v[64:65]
	global_store_dwordx4 v[64:65], v[28:31], off offset:576
	s_and_saveexec_b64 s[2:3], s[16:17]
	s_xor_b64 s[16:17], exec, s[2:3]
	s_or_saveexec_b64 s[16:17], s[16:17]
	v_mov_b64_e32 v[28:29], s[24:25]
	s_xor_b64 exec, exec, s[16:17]
	v_mov_b64_e32 v[28:29], s[36:37]
	v_mov_b32_e32 v188, v189
	s_or_b64 exec, exec, s[16:17]
	v_ashrrev_i32_e32 v189, 31, v188
	v_lshlrev_b64 v[30:31], 13, v[188:189]
	v_lshl_add_u64 v[28:29], v[28:29], 0, v[30:31]
	v_pk_fma_f32 v[26:27], v[26:27], v[34:35], v[62:63]
	v_pk_fma_f32 v[24:25], v[24:25], v[32:33], v[60:61]
	v_lshl_add_u64 v[28:29], v[174:175], 2, v[28:29]
	global_store_dwordx4 v[28:29], v[24:27], off offset:576
	s_and_saveexec_b64 s[2:3], s[14:15]
	s_xor_b64 s[14:15], exec, s[2:3]
	s_or_saveexec_b64 s[14:15], s[14:15]
	v_mov_b64_e32 v[24:25], s[24:25]
	s_xor_b64 exec, exec, s[14:15]
	v_mov_b64_e32 v[24:25], s[36:37]
	v_mov_b32_e32 v186, v187
	s_or_b64 exec, exec, s[14:15]
	v_ashrrev_i32_e32 v187, 31, v186
	v_lshlrev_b64 v[26:27], 13, v[186:187]
	v_lshl_add_u64 v[24:25], v[24:25], 0, v[26:27]
	v_pk_fma_f32 v[22:23], v[22:23], v[34:35], v[58:59]
	v_pk_fma_f32 v[20:21], v[20:21], v[32:33], v[56:57]
	v_lshl_add_u64 v[24:25], v[174:175], 2, v[24:25]
	global_store_dwordx4 v[24:25], v[20:23], off offset:576
	s_and_saveexec_b64 s[2:3], s[12:13]
	s_xor_b64 s[12:13], exec, s[2:3]
	s_or_saveexec_b64 s[12:13], s[12:13]
	v_mov_b64_e32 v[20:21], s[24:25]
	s_xor_b64 exec, exec, s[12:13]
	v_mov_b64_e32 v[20:21], s[36:37]
	v_mov_b32_e32 v184, v185
	s_or_b64 exec, exec, s[12:13]
	v_ashrrev_i32_e32 v185, 31, v184
	v_lshlrev_b64 v[22:23], 13, v[184:185]
	v_lshl_add_u64 v[20:21], v[20:21], 0, v[22:23]
	v_pk_fma_f32 v[18:19], v[18:19], v[34:35], v[54:55]
	v_pk_fma_f32 v[16:17], v[16:17], v[32:33], v[52:53]
	v_lshl_add_u64 v[20:21], v[174:175], 2, v[20:21]
	global_store_dwordx4 v[20:21], v[16:19], off offset:576
	s_and_saveexec_b64 s[2:3], s[10:11]
	s_xor_b64 s[10:11], exec, s[2:3]
	s_or_saveexec_b64 s[10:11], s[10:11]
	v_mov_b64_e32 v[16:17], s[24:25]
	s_xor_b64 exec, exec, s[10:11]
	v_mov_b64_e32 v[16:17], s[36:37]
	v_mov_b32_e32 v182, v183
	s_or_b64 exec, exec, s[10:11]
	v_ashrrev_i32_e32 v183, 31, v182
	v_lshlrev_b64 v[18:19], 13, v[182:183]
	v_lshl_add_u64 v[16:17], v[16:17], 0, v[18:19]
	v_pk_fma_f32 v[14:15], v[14:15], v[34:35], v[50:51]
	v_pk_fma_f32 v[12:13], v[12:13], v[32:33], v[48:49]
	v_lshl_add_u64 v[16:17], v[174:175], 2, v[16:17]
	global_store_dwordx4 v[16:17], v[12:15], off offset:576
	s_and_saveexec_b64 s[2:3], s[8:9]
	s_xor_b64 s[8:9], exec, s[2:3]
	s_or_saveexec_b64 s[8:9], s[8:9]
	v_mov_b64_e32 v[12:13], s[24:25]
	s_xor_b64 exec, exec, s[8:9]
	v_mov_b64_e32 v[12:13], s[36:37]
	v_mov_b32_e32 v180, v181
	s_or_b64 exec, exec, s[8:9]
	v_ashrrev_i32_e32 v181, 31, v180
	v_lshlrev_b64 v[14:15], 13, v[180:181]
	v_lshl_add_u64 v[12:13], v[12:13], 0, v[14:15]
	v_pk_fma_f32 v[10:11], v[10:11], v[34:35], v[46:47]
	v_pk_fma_f32 v[8:9], v[8:9], v[32:33], v[44:45]
	v_lshl_add_u64 v[12:13], v[174:175], 2, v[12:13]
	global_store_dwordx4 v[12:13], v[8:11], off offset:576
	s_and_saveexec_b64 s[2:3], s[6:7]
	s_xor_b64 s[6:7], exec, s[2:3]
	s_or_saveexec_b64 s[6:7], s[6:7]
	v_mov_b64_e32 v[8:9], s[24:25]
	s_xor_b64 exec, exec, s[6:7]
	v_mov_b64_e32 v[8:9], s[36:37]
	v_mov_b32_e32 v178, v179
	s_or_b64 exec, exec, s[6:7]
	v_ashrrev_i32_e32 v179, 31, v178
	v_lshlrev_b64 v[10:11], 13, v[178:179]
	v_lshl_add_u64 v[8:9], v[8:9], 0, v[10:11]
	v_pk_fma_f32 v[6:7], v[6:7], v[34:35], v[42:43]
	v_pk_fma_f32 v[4:5], v[4:5], v[32:33], v[40:41]
	v_lshl_add_u64 v[8:9], v[174:175], 2, v[8:9]
	global_store_dwordx4 v[8:9], v[4:7], off offset:576
	s_and_saveexec_b64 s[2:3], vcc
	s_xor_b64 s[6:7], exec, s[2:3]
	s_or_saveexec_b64 s[6:7], s[6:7]
	v_mov_b64_e32 v[4:5], s[24:25]
	s_xor_b64 exec, exec, s[6:7]
	s_cbranch_execz .LBB0_1693
	v_mov_b64_e32 v[4:5], s[36:37]
	v_mov_b32_e32 v176, v177
	s_branch .LBB0_1693

; #define WAIT_V(n) asm volatile("s_waitcnt vmcnt(" #n ")" ::: "memory")
; #define WAIT_L(n) asm volatile("s_waitcnt lgkmcnt(" #n ")" ::: "memory")
; #define BAR __builtin_amdgcn_s_barrier()
; #define SCHED __builtin_amdgcn_sched_barrier(0)
; template <class Get, class Epi>
; DI void gemm_stream(LAS unsigned char* lds, const int K, const int ld, Get get, Epi epi) {
;     ...
;             LDB(B0, 0, 0); SCHED; LDA(At, 0, 0); STAGE(SAo(1, 1), a1 + hstep);
;             WAIT_L(8); BAR; WAIT_L(0); MMA(0, 0, At, B0); BAR; SCHED;
;             LDB(B1, 0, 1); STAGE(SBo(0, 0), b2);
;             BAR; WAIT_L(0); MMA(0, 1, At, B1); BAR;
;             LDA(At, 0, 1); STAGE(SAo(0, 0), a2);
;             BAR; WAIT_L(0); MMA(1, 0, At, B0); BAR; SCHED;
;             STAGE(SBo(0, 1), b2 + hstep);
;             WAIT_V(6); BAR; MMA(1, 1, At, B1); BAR;
.LBB0_1964:
	ds_read_b128 v[144:147], v141
	ds_read_b128 v[148:151], v141 offset:1024
	ds_read_b128 v[152:155], v141 offset:2048
	ds_read_b128 v[156:159], v141 offset:3072
	s_add_u32 s38, s36, 0x100
	s_addc_u32 s39, s37, 0
	s_cmp_eq_u32 s77, 4
	s_cselect_b32 s53, s17, s39
	s_cselect_b32 s52, s16, s38
	s_cselect_b32 s41, s19, s76
	s_cselect_b32 s40, s18, s0
	v_lshl_add_u64 v[192:193], s[36:37], 0, v[134:135]
	s_add_i32 m0, s20, 0xc000
	ds_read_b128 v[160:163], v142
	ds_read_b128 v[164:167], v142 offset:1024
	ds_read_b128 v[168:171], v142 offset:2048
	ds_read_b128 v[172:175], v142 offset:3072
	ds_read_b128 v[176:179], v142 offset:4096
	ds_read_b128 v[180:183], v142 offset:5120
	ds_read_b128 v[184:187], v142 offset:6144
	ds_read_b128 v[188:191], v142 offset:7168
	global_load_lds_dwordx4 v[192:193], off
	v_lshl_add_u64 v[192:193], s[36:37], 0, v[136:137]
	s_add_i32 m0, s20, 0xe000
	s_nop 0
	global_load_lds_dwordx4 v[192:193], off
	s_waitcnt lgkmcnt(8)
	s_barrier
	s_waitcnt lgkmcnt(0)
	v_mfma_f32_16x16x32_bf16 v[124:127], v[144:147], v[160:163], v[124:127]
	v_mfma_f32_16x16x32_bf16 v[120:123], v[152:155], v[160:163], v[120:123]
	v_mfma_f32_16x16x32_bf16 v[116:119], v[144:147], v[168:171], v[116:119]
	v_mfma_f32_16x16x32_bf16 v[112:115], v[152:155], v[168:171], v[112:115]
	v_mfma_f32_16x16x32_bf16 v[104:107], v[144:147], v[176:179], v[104:107]
	v_mfma_f32_16x16x32_bf16 v[96:99], v[152:155], v[176:179], v[96:99]
	v_mfma_f32_16x16x32_bf16 v[88:91], v[144:147], v[184:187], v[88:91]
	v_mfma_f32_16x16x32_bf16 v[80:83], v[152:155], v[184:187], v[80:83]
	v_mfma_f32_16x16x32_bf16 v[124:127], v[148:151], v[164:167], v[124:127]
	v_mfma_f32_16x16x32_bf16 v[120:123], v[156:159], v[164:167], v[120:123]
	v_mfma_f32_16x16x32_bf16 v[116:119], v[148:151], v[172:175], v[116:119]
	v_mfma_f32_16x16x32_bf16 v[112:115], v[156:159], v[172:175], v[112:115]
	v_mfma_f32_16x16x32_bf16 v[104:107], v[148:151], v[180:183], v[104:107]
	v_mfma_f32_16x16x32_bf16 v[96:99], v[156:159], v[180:183], v[96:99]
	v_mfma_f32_16x16x32_bf16 v[88:91], v[148:151], v[188:191], v[88:91]
	v_mfma_f32_16x16x32_bf16 v[80:83], v[156:159], v[188:191], v[80:83]
	s_barrier
	s_add_i32 s36, s56, s3
	v_lshl_add_u64 v[204:205], s[40:41], 0, v[130:131]
	s_mov_b32 m0, s36
	ds_read_b128 v[192:195], v143
	ds_read_b128 v[196:199], v143 offset:1024
	ds_read_b128 v[200:203], v143 offset:2048
	ds_read_b128 v[208:211], v143 offset:3072
	global_load_lds_dwordx4 v[204:205], off
	v_lshl_add_u64 v[212:213], s[40:41], 0, v[128:129]
	s_add_i32 m0, s36, 0x2000
	s_nop 0
	global_load_lds_dwordx4 v[212:213], off
	s_barrier
	s_waitcnt lgkmcnt(0)
	v_mfma_f32_16x16x32_bf16 v[108:111], v[192:195], v[160:163], v[108:111]
	v_mfma_f32_16x16x32_bf16 v[100:103], v[200:203], v[160:163], v[100:103]
	v_mfma_f32_16x16x32_bf16 v[92:95], v[192:195], v[168:171], v[92:95]
	v_mfma_f32_16x16x32_bf16 v[84:87], v[200:203], v[168:171], v[84:87]
	v_mfma_f32_16x16x32_bf16 v[76:79], v[192:195], v[176:179], v[76:79]
	v_mfma_f32_16x16x32_bf16 v[72:75], v[200:203], v[176:179], v[72:75]
	v_mfma_f32_16x16x32_bf16 v[68:71], v[192:195], v[184:187], v[68:71]
	v_mfma_f32_16x16x32_bf16 v[64:67], v[200:203], v[184:187], v[64:67]
	v_mfma_f32_16x16x32_bf16 v[108:111], v[196:199], v[164:167], v[108:111]
	v_mfma_f32_16x16x32_bf16 v[100:103], v[208:211], v[164:167], v[100:103]
	v_mfma_f32_16x16x32_bf16 v[92:95], v[196:199], v[172:175], v[92:95]
	v_mfma_f32_16x16x32_bf16 v[84:87], v[208:211], v[172:175], v[84:87]
	v_mfma_f32_16x16x32_bf16 v[76:79], v[196:199], v[180:183], v[76:79]
	v_mfma_f32_16x16x32_bf16 v[72:75], v[208:211], v[180:183], v[72:75]
	v_mfma_f32_16x16x32_bf16 v[68:71], v[196:199], v[188:191], v[68:71]
	v_mfma_f32_16x16x32_bf16 v[64:67], v[208:211], v[188:191], v[64:67]
	s_mov_b32 m0, s20
	v_lshl_add_u64 v[214:215], s[52:53], 0, v[130:131]
	s_barrier
	ds_read_b128 v[160:163], v142 offset:16384
	ds_read_b128 v[164:167], v142 offset:17408
	ds_read_b128 v[168:171], v142 offset:18432
	ds_read_b128 v[172:175], v142 offset:19456
	ds_read_b128 v[176:179], v142 offset:20480
	ds_read_b128 v[180:183], v142 offset:21504
	ds_read_b128 v[184:187], v142 offset:22528
	ds_read_b128 v[188:191], v142 offset:23552
	global_load_lds_dwordx4 v[214:215], off
	s_mov_b32 m0, s21
	v_lshl_add_u64 v[216:217], s[52:53], 0, v[128:129]
	global_load_lds_dwordx4 v[216:217], off
	s_barrier
	s_waitcnt lgkmcnt(0)
	v_mfma_f32_16x16x32_bf16 v[60:63], v[144:147], v[160:163], v[60:63]
	v_mfma_f32_16x16x32_bf16 v[56:59], v[152:155], v[160:163], v[56:59]
	v_mfma_f32_16x16x32_bf16 v[52:55], v[144:147], v[168:171], v[52:55]
	v_mfma_f32_16x16x32_bf16 v[48:51], v[152:155], v[168:171], v[48:51]
	v_mfma_f32_16x16x32_bf16 v[40:43], v[144:147], v[176:179], v[40:43]
	v_mfma_f32_16x16x32_bf16 v[32:35], v[152:155], v[176:179], v[32:35]
	v_mfma_f32_16x16x32_bf16 v[24:27], v[144:147], v[184:187], v[24:27]
	v_mfma_f32_16x16x32_bf16 v[16:19], v[152:155], v[184:187], v[16:19]
	v_mfma_f32_16x16x32_bf16 v[60:63], v[148:151], v[164:167], v[60:63]
	v_mfma_f32_16x16x32_bf16 v[56:59], v[156:159], v[164:167], v[56:59]
	v_mfma_f32_16x16x32_bf16 v[52:55], v[148:151], v[172:175], v[52:55]
	v_mfma_f32_16x16x32_bf16 v[48:51], v[156:159], v[172:175], v[48:51]
	v_mfma_f32_16x16x32_bf16 v[40:43], v[148:151], v[180:183], v[40:43]
	v_mfma_f32_16x16x32_bf16 v[32:35], v[156:159], v[180:183], v[32:35]
	v_mfma_f32_16x16x32_bf16 v[24:27], v[148:151], v[188:191], v[24:27]
	v_mfma_f32_16x16x32_bf16 v[16:19], v[156:159], v[188:191], v[16:19]
	s_barrier
	s_add_u32 s36, s40, 0x160000
	s_addc_u32 s37, s41, 0
	s_add_i32 s78, s57, s3
	s_mov_b32 m0, s78
	v_lshl_add_u64 v[144:145], s[36:37], 0, v[130:131]
	global_load_lds_dwordx4 v[144:145], off
	v_lshl_add_u64 v[144:145], s[36:37], 0, v[128:129]
	s_add_i32 m0, s78, 0x2000
	s_nop 0
	global_load_lds_dwordx4 v[144:145], off
	s_waitcnt vmcnt(6)
	s_barrier
; #define WAIT_V(n) asm volatile("s_waitcnt vmcnt(" #n ")" ::: "memory")
; #define WAIT_L(n) asm volatile("s_waitcnt lgkmcnt(" #n ")" ::: "memory")
; #define BAR __builtin_amdgcn_s_barrier()
; #define SCHED __builtin_amdgcn_sched_barrier(0)
; template <class Get, class Epi>
; DI void gemm_stream(LAS unsigned char* lds, const int K, const int ld, Get get, Epi epi) {
;     ...
;             WAIT_V(6); BAR; MMA(1, 1, At, B1); BAR;
;             LDB(B0, 1, 0); SCHED; LDA(At, 1, 0); STAGE(SAo(0, 1), a2 + hstep);
;             WAIT_L(8); BAR; WAIT_L(0); MMA(0, 0, At, B0); BAR; SCHED;
;             LDB(B1, 1, 1); STAGE(SBo(1, 0), b3);
;             BAR; WAIT_L(0); MMA(0, 1, At, B1); BAR;
;             LDA(At, 1, 1); STAGE(SAo(1, 0), a3);
;             BAR; WAIT_L(0); MMA(1, 0, At, B0); BAR; SCHED;
	v_mfma_f32_16x16x32_bf16 v[44:47], v[192:195], v[160:163], v[44:47]
	v_mfma_f32_16x16x32_bf16 v[36:39], v[200:203], v[160:163], v[36:39]
	v_mfma_f32_16x16x32_bf16 v[28:31], v[192:195], v[168:171], v[28:31]
	v_mfma_f32_16x16x32_bf16 v[20:23], v[200:203], v[168:171], v[20:23]
	v_mfma_f32_16x16x32_bf16 v[12:15], v[192:195], v[176:179], v[12:15]
	v_mfma_f32_16x16x32_bf16 v[8:11], v[200:203], v[176:179], v[8:11]
	v_mfma_f32_16x16x32_bf16 v[4:7], v[192:195], v[184:187], v[4:7]
	v_mfma_f32_16x16x32_bf16 v[0:3], v[200:203], v[184:187], v[0:3]
	v_mfma_f32_16x16x32_bf16 v[44:47], v[196:199], v[164:167], v[44:47]
	v_mfma_f32_16x16x32_bf16 v[36:39], v[208:211], v[164:167], v[36:39]
	v_mfma_f32_16x16x32_bf16 v[28:31], v[196:199], v[172:175], v[28:31]
	v_mfma_f32_16x16x32_bf16 v[20:23], v[208:211], v[172:175], v[20:23]
	v_mfma_f32_16x16x32_bf16 v[12:15], v[196:199], v[180:183], v[12:15]
	v_mfma_f32_16x16x32_bf16 v[8:11], v[208:211], v[180:183], v[8:11]
	v_mfma_f32_16x16x32_bf16 v[4:7], v[196:199], v[188:191], v[4:7]
	v_mfma_f32_16x16x32_bf16 v[0:3], v[208:211], v[188:191], v[0:3]
	s_add_i32 s78, 16, 0x18000
	v_add_u32_e32 v132, s78, v140
	s_barrier
	ds_read_b128 v[144:147], v132
	ds_read_b128 v[148:151], v132 offset:1024
	ds_read_b128 v[152:155], v132 offset:2048
	ds_read_b128 v[156:159], v132 offset:3072
	s_add_u32 s36, s52, 0x160000
	s_addc_u32 s37, s53, 0
	s_mov_b32 m0, s23
	v_lshl_add_u64 v[192:193], s[36:37], 0, v[130:131]
	ds_read_b128 v[160:163], v142 offset:32768
	ds_read_b128 v[164:167], v142 offset:33792
	ds_read_b128 v[168:171], v142 offset:34816
	ds_read_b128 v[172:175], v142 offset:35840
	ds_read_b128 v[176:179], v142 offset:36864
	ds_read_b128 v[180:183], v142 offset:37888
	ds_read_b128 v[184:187], v142 offset:38912
	ds_read_b128 v[188:191], v142 offset:39936
	global_load_lds_dwordx4 v[192:193], off
	s_mov_b32 m0, s28
	v_lshl_add_u64 v[192:193], s[36:37], 0, v[128:129]
	global_load_lds_dwordx4 v[192:193], off
	s_waitcnt lgkmcnt(8)
	s_barrier
	s_waitcnt lgkmcnt(0)
	v_mfma_f32_16x16x32_bf16 v[124:127], v[144:147], v[160:163], v[124:127]
	v_mfma_f32_16x16x32_bf16 v[120:123], v[152:155], v[160:163], v[120:123]
	v_mfma_f32_16x16x32_bf16 v[116:119], v[144:147], v[168:171], v[116:119]
	v_mfma_f32_16x16x32_bf16 v[112:115], v[152:155], v[168:171], v[112:115]
	v_mfma_f32_16x16x32_bf16 v[104:107], v[144:147], v[176:179], v[104:107]
	v_mfma_f32_16x16x32_bf16 v[96:99], v[152:155], v[176:179], v[96:99]
	v_mfma_f32_16x16x32_bf16 v[88:91], v[144:147], v[184:187], v[88:91]
	v_mfma_f32_16x16x32_bf16 v[80:83], v[152:155], v[184:187], v[80:83]
	v_mfma_f32_16x16x32_bf16 v[124:127], v[148:151], v[164:167], v[124:127]
	v_mfma_f32_16x16x32_bf16 v[120:123], v[156:159], v[164:167], v[120:123]
	v_mfma_f32_16x16x32_bf16 v[116:119], v[148:151], v[172:175], v[116:119]
	v_mfma_f32_16x16x32_bf16 v[112:115], v[156:159], v[172:175], v[112:115]
	v_mfma_f32_16x16x32_bf16 v[104:107], v[148:151], v[180:183], v[104:107]
	v_mfma_f32_16x16x32_bf16 v[96:99], v[156:159], v[180:183], v[96:99]
	v_mfma_f32_16x16x32_bf16 v[88:91], v[148:151], v[188:191], v[88:91]
	v_mfma_f32_16x16x32_bf16 v[80:83], v[156:159], v[188:191], v[80:83]
	s_barrier
	s_add_i32 s52, 16, 0x1c000
	s_add_i32 s36, s78, s3
	v_add_u32_e32 v132, s52, v140
	v_lshl_add_u64 v[204:205], v[204:205], 0, s[8:9]
	s_mov_b32 m0, s36
	ds_read_b128 v[192:195], v132
	ds_read_b128 v[196:199], v132 offset:1024
	ds_read_b128 v[200:203], v132 offset:2048
	ds_read_b128 v[208:211], v132 offset:3072
	global_load_lds_dwordx4 v[204:205], off
	v_lshl_add_u64 v[204:205], v[212:213], 0, s[8:9]
	s_add_i32 m0, s36, 0x2000
	s_nop 0
	global_load_lds_dwordx4 v[204:205], off
	s_barrier
	s_waitcnt lgkmcnt(0)
	v_mfma_f32_16x16x32_bf16 v[108:111], v[192:195], v[160:163], v[108:111]
	v_mfma_f32_16x16x32_bf16 v[100:103], v[200:203], v[160:163], v[100:103]
	v_mfma_f32_16x16x32_bf16 v[92:95], v[192:195], v[168:171], v[92:95]
	v_mfma_f32_16x16x32_bf16 v[84:87], v[200:203], v[168:171], v[84:87]
	v_mfma_f32_16x16x32_bf16 v[76:79], v[192:195], v[176:179], v[76:79]
	v_mfma_f32_16x16x32_bf16 v[72:75], v[200:203], v[176:179], v[72:75]
	v_mfma_f32_16x16x32_bf16 v[68:71], v[192:195], v[184:187], v[68:71]
	v_mfma_f32_16x16x32_bf16 v[64:67], v[200:203], v[184:187], v[64:67]
	v_mfma_f32_16x16x32_bf16 v[108:111], v[196:199], v[164:167], v[108:111]
	v_mfma_f32_16x16x32_bf16 v[100:103], v[208:211], v[164:167], v[100:103]
	v_mfma_f32_16x16x32_bf16 v[92:95], v[196:199], v[172:175], v[92:95]
	v_mfma_f32_16x16x32_bf16 v[84:87], v[208:211], v[172:175], v[84:87]
	v_mfma_f32_16x16x32_bf16 v[76:79], v[196:199], v[180:183], v[76:79]
	v_mfma_f32_16x16x32_bf16 v[72:75], v[208:211], v[180:183], v[72:75]
	v_mfma_f32_16x16x32_bf16 v[68:71], v[196:199], v[188:191], v[68:71]
	v_mfma_f32_16x16x32_bf16 v[64:67], v[208:211], v[188:191], v[64:67]
	s_mov_b32 m0, s29
	v_lshl_add_u64 v[204:205], v[214:215], 0, s[8:9]
	s_barrier
	ds_read_b128 v[160:163], v142 offset:49152
	ds_read_b128 v[164:167], v142 offset:50176
	ds_read_b128 v[168:171], v142 offset:51200
	ds_read_b128 v[172:175], v142 offset:52224
	ds_read_b128 v[176:179], v142 offset:53248
	ds_read_b128 v[180:183], v142 offset:54272
	ds_read_b128 v[184:187], v142 offset:55296
	ds_read_b128 v[188:191], v142 offset:56320
	global_load_lds_dwordx4 v[204:205], off
	s_mov_b32 m0, s35
	v_lshl_add_u64 v[204:205], v[216:217], 0, s[8:9]
	global_load_lds_dwordx4 v[204:205], off
	s_barrier
; #define WAIT_V(n) asm volatile("s_waitcnt vmcnt(" #n ")" ::: "memory")
; #define WAIT_L(n) asm volatile("s_waitcnt lgkmcnt(" #n ")" ::: "memory")
; #define BAR __builtin_amdgcn_s_barrier()
; #define SCHED __builtin_amdgcn_sched_barrier(0)
; #define EPI_DONE do { } while (0)
; template <class Get, class Epi>
; DI void gemm_stream(LAS unsigned char* lds, const int K, const int ld, Get get, Epi epi) {
;     ...
;             BAR; WAIT_L(0); MMA(1, 0, At, B0); BAR; SCHED;
;             STAGE(SBo(1, 1), b3 + hstep);
;             WAIT_V(6); BAR; MMA(1, 1, At, B1); BAR;
;         }
; DI void epi_part(const Acc& acc, const P& p, int brow, int bcol, int sl) {
;     EPI_IDX
;     const int b = brow / PB;
;     float* part = (float*)(p.ws + O_PART) + ((size_t)sl * (NBATCH * CTXL) + b * CTXL) * DM;
; #pragma unroll
;     for (int ai = 0; ai < 2; ++ai)
; #pragma unroll
;         for (int m = 0; m < 4; ++m) {
;             float* rp = part + (size_t)(ai * 128 + wr * 64 + m * 16 + fr) * DM + bcol + wc * 32 + fq * 4;
; #pragma unroll
;             for (int bj = 0; bj < 2; ++bj)
; #pragma unroll
;                 for (int n = 0; n < 2; ++n) *(f32x4*)(rp + bj * 128 + n * 16) = acc[ai][bj][m][n];
;         }
;     EPI_DONE;
; }
	s_waitcnt lgkmcnt(0)
	v_mfma_f32_16x16x32_bf16 v[60:63], v[144:147], v[160:163], v[60:63]
	v_mfma_f32_16x16x32_bf16 v[56:59], v[152:155], v[160:163], v[56:59]
	v_mfma_f32_16x16x32_bf16 v[52:55], v[144:147], v[168:171], v[52:55]
	v_mfma_f32_16x16x32_bf16 v[48:51], v[152:155], v[168:171], v[48:51]
	v_mfma_f32_16x16x32_bf16 v[40:43], v[144:147], v[176:179], v[40:43]
	v_mfma_f32_16x16x32_bf16 v[32:35], v[152:155], v[176:179], v[32:35]
	v_mfma_f32_16x16x32_bf16 v[24:27], v[144:147], v[184:187], v[24:27]
	v_mfma_f32_16x16x32_bf16 v[16:19], v[152:155], v[184:187], v[16:19]
	v_mfma_f32_16x16x32_bf16 v[60:63], v[148:151], v[164:167], v[60:63]
	v_mfma_f32_16x16x32_bf16 v[56:59], v[156:159], v[164:167], v[56:59]
	v_mfma_f32_16x16x32_bf16 v[52:55], v[148:151], v[172:175], v[52:55]
	v_mfma_f32_16x16x32_bf16 v[48:51], v[156:159], v[172:175], v[48:51]
	v_mfma_f32_16x16x32_bf16 v[40:43], v[148:151], v[180:183], v[40:43]
	v_mfma_f32_16x16x32_bf16 v[32:35], v[156:159], v[180:183], v[32:35]
	v_mfma_f32_16x16x32_bf16 v[24:27], v[148:151], v[188:191], v[24:27]
	v_mfma_f32_16x16x32_bf16 v[16:19], v[156:159], v[188:191], v[16:19]
	s_barrier
	s_add_u32 s36, s40, 0x160080
	s_addc_u32 s37, s41, 0
	s_add_i32 s40, s52, s3
	s_mov_b32 m0, s40
	v_lshl_add_u64 v[144:145], s[36:37], 0, v[130:131]
	global_load_lds_dwordx4 v[144:145], off
	v_lshl_add_u64 v[144:145], s[36:37], 0, v[128:129]
	s_add_i32 m0, s40, 0x2000
	s_nop 0
	global_load_lds_dwordx4 v[144:145], off
	s_waitcnt vmcnt(6)
	s_barrier
	v_mfma_f32_16x16x32_bf16 v[44:47], v[192:195], v[160:163], v[44:47]
	v_mfma_f32_16x16x32_bf16 v[36:39], v[200:203], v[160:163], v[36:39]
	v_mfma_f32_16x16x32_bf16 v[28:31], v[192:195], v[168:171], v[28:31]
	v_mfma_f32_16x16x32_bf16 v[20:23], v[200:203], v[168:171], v[20:23]
	v_mfma_f32_16x16x32_bf16 v[12:15], v[192:195], v[176:179], v[12:15]
	v_mfma_f32_16x16x32_bf16 v[8:11], v[200:203], v[176:179], v[8:11]
	v_mfma_f32_16x16x32_bf16 v[4:7], v[192:195], v[184:187], v[4:7]
	v_mfma_f32_16x16x32_bf16 v[0:3], v[200:203], v[184:187], v[0:3]
	v_mfma_f32_16x16x32_bf16 v[44:47], v[196:199], v[164:167], v[44:47]
	v_mfma_f32_16x16x32_bf16 v[36:39], v[208:211], v[164:167], v[36:39]
	v_mfma_f32_16x16x32_bf16 v[28:31], v[196:199], v[172:175], v[28:31]
	v_mfma_f32_16x16x32_bf16 v[20:23], v[208:211], v[172:175], v[20:23]
	v_mfma_f32_16x16x32_bf16 v[12:15], v[196:199], v[180:183], v[12:15]
	v_mfma_f32_16x16x32_bf16 v[8:11], v[208:211], v[180:183], v[8:11]
	v_mfma_f32_16x16x32_bf16 v[4:7], v[196:199], v[188:191], v[4:7]
	v_mfma_f32_16x16x32_bf16 v[0:3], v[208:211], v[188:191], v[0:3]
	s_add_i32 s77, s77, 2
	s_add_u32 s0, s0, 0x100
	s_addc_u32 s76, s76, 0
	s_cmp_gt_u32 s77, 5
	s_mov_b64 s[36:37], s[38:39]
	s_barrier
	s_cbranch_scc0 .LBB0_1964
	s_mul_hi_i32 s0, s75, 0x78787879
	s_lshr_b32 s37, s0, 31
	s_lshr_b32 s0, s0, 3
	s_ashr_i32 s36, s61, 4
	s_add_i32 s0, s0, s37
	s_ashr_i32 s37, s36, 31
	s_lshl_b32 s38, s0, 8
	s_ashr_i32 s39, s38, 31
	s_lshl_b64 s[36:37], s[36:37], 23
	s_add_u32 s0, s54, s36
	s_addc_u32 s40, s55, s37
	s_lshl_b64 s[36:37], s[38:39], 13
	s_add_u32 s0, s0, s36
	v_mov_b32_e32 v145, v206
	s_addc_u32 s37, s40, s37
	s_lshl_b32 s36, s61, 10
	s_and_b32 s36, s36, 0x3c00
	v_and_b32_e32 v132, 15, v145
	v_ashrrev_i32_e32 v144, 2, v145
	v_and_or_b32 v144, v144, s58, v132
	s_add_u32 s36, s0, s36
	v_lshlrev_b32_e32 v132, 1, v145
	s_addc_u32 s37, s37, 0
	v_and_b32_e32 v132, 0x180, v132
	v_lshl_add_u64 v[146:147], s[36:37], 0, v[132:133]
	v_and_b32_e32 v132, 48, v145
	v_ashrrev_i32_e32 v145, 31, v144
	v_lshl_add_u64 v[146:147], v[146:147], 0, v[132:133]
	v_lshlrev_b64 v[148:149], 13, v[144:145]
	v_lshl_add_u64 v[148:149], v[146:147], 0, v[148:149]
	global_store_dwordx4 v[148:149], v[124:127], off
	global_store_dwordx4 v[148:149], v[120:123], off offset:64
	global_store_dwordx4 v[148:149], v[108:111], off offset:512
	global_store_dwordx4 v[148:149], v[100:103], off offset:576
	s_mov_b32 s61, s74
	s_mov_b32 s75, s63
	v_or_b32_e32 v100, 16, v144
	v_ashrrev_i32_e32 v101, 31, v100
	v_lshlrev_b64 v[100:101], 13, v[100:101]
	v_lshl_add_u64 v[100:101], v[146:147], 0, v[100:101]
	global_store_dwordx4 v[100:101], v[116:119], off
	global_store_dwordx4 v[100:101], v[112:115], off offset:64
	global_store_dwordx4 v[100:101], v[92:95], off offset:512
	global_store_dwordx4 v[100:101], v[84:87], off offset:576
	s_mov_b64 s[38:39], s[18:19]
	s_mov_b64 s[36:37], s[16:17]
	v_or_b32_e32 v84, 32, v144
	v_ashrrev_i32_e32 v85, 31, v84
	v_lshlrev_b64 v[84:85], 13, v[84:85]
	v_lshl_add_u64 v[84:85], v[146:147], 0, v[84:85]
	global_store_dwordx4 v[84:85], v[104:107], off
	global_store_dwordx4 v[84:85], v[96:99], off offset:64
	global_store_dwordx4 v[84:85], v[76:79], off offset:512
	global_store_dwordx4 v[84:85], v[72:75], off offset:576
	s_nop 1
	v_or_b32_e32 v72, 48, v144
	v_ashrrev_i32_e32 v73, 31, v72
	v_lshlrev_b64 v[72:73], 13, v[72:73]
	v_lshl_add_u64 v[72:73], v[146:147], 0, v[72:73]
	global_store_dwordx4 v[72:73], v[88:91], off
	global_store_dwordx4 v[72:73], v[80:83], off offset:64
	global_store_dwordx4 v[72:73], v[68:71], off offset:512
	global_store_dwordx4 v[72:73], v[64:67], off offset:576
	s_nop 1
	v_add_co_u32_e32 v66, vcc, s59, v148
	v_lshl_add_u64 v[64:65], v[148:149], 0, s[10:11]
	s_nop 0
	v_addc_co_u32_e32 v67, vcc, 0, v149, vcc
	global_store_dwordx4 v[66:67], v[60:63], off
	global_store_dwordx4 v[64:65], v[56:59], off offset:64
	global_store_dwordx4 v[64:65], v[44:47], off offset:512
	global_store_dwordx4 v[64:65], v[36:39], off offset:576
	s_nop 1
	v_add_co_u32_e32 v38, vcc, s60, v148
	v_lshl_add_u64 v[36:37], v[148:149], 0, s[12:13]
	s_nop 0
	v_addc_co_u32_e32 v39, vcc, 0, v149, vcc
	global_store_dwordx4 v[38:39], v[52:55], off
	global_store_dwordx4 v[36:37], v[48:51], off offset:64
	global_store_dwordx4 v[36:37], v[28:31], off offset:512
	global_store_dwordx4 v[36:37], v[20:23], off offset:576
	s_nop 1
	v_add_co_u32_e32 v22, vcc, 0x140000, v148
	v_lshl_add_u64 v[20:21], v[148:149], 0, s[14:15]
	s_nop 0
	v_addc_co_u32_e32 v23, vcc, 0, v149, vcc
	global_store_dwordx4 v[22:23], v[40:43], off
	global_store_dwordx4 v[20:21], v[32:35], off offset:64
	global_store_dwordx4 v[20:21], v[12:15], off offset:512
	global_store_dwordx4 v[20:21], v[8:11], off offset:576
	s_nop 1
	v_add_co_u32_e32 v10, vcc, 0x160000, v148
	v_lshl_add_u64 v[8:9], v[148:149], 0, s[6:7]
	s_nop 0
	v_addc_co_u32_e32 v11, vcc, 0, v149, vcc
	s_and_b64 vcc, exec, s[4:5]
	global_store_dwordx4 v[10:11], v[24:27], off
	global_store_dwordx4 v[8:9], v[16:19], off offset:64
	global_store_dwordx4 v[8:9], v[4:7], off offset:512
	global_store_dwordx4 v[8:9], v[0:3], off offset:576
	s_cbranch_vccz .LBB0_1961
	s_waitcnt vmcnt(0)
	s_cmpk_gt_u32 s2, 0xff
	s_cbranch_scc1 .LBB0_1968
	s_barrier

; #define WAIT_V(n) asm volatile("s_waitcnt vmcnt(" #n ")" ::: "memory")
; #define WAIT_L(n) asm volatile("s_waitcnt lgkmcnt(" #n ")" ::: "memory")
; #define BAR __builtin_amdgcn_s_barrier()
; #define SCHED __builtin_amdgcn_sched_barrier(0)
; template <class Get, class Epi>
; DI void gemm_stream(LAS unsigned char* lds, const int K, const int ld, Get get, Epi epi) {
;     ...
;             LDB(B0, 0, 0); SCHED; LDA(At, 0, 0); STAGE(SAo(1, 1), a1 + hstep);
;             WAIT_L(8); BAR; WAIT_L(0); MMA(0, 0, At, B0); BAR; SCHED;
;             LDB(B1, 0, 1); STAGE(SBo(0, 0), b2);
;             BAR; WAIT_L(0); MMA(0, 1, At, B1); BAR;
;             LDA(At, 0, 1); STAGE(SAo(0, 0), a2);
;             BAR; WAIT_L(0); MMA(1, 0, At, B0); BAR; SCHED;
;             STAGE(SBo(0, 1), b2 + hstep);
;             WAIT_V(6); BAR; MMA(1, 1, At, B1); BAR;
.LBB0_2102:
	ds_read_b128 v[128:131], v209
	ds_read_b128 v[132:135], v209 offset:1024
	ds_read_b128 v[136:139], v209 offset:2048
	ds_read_b128 v[156:159], v209 offset:3072
	s_add_u32 s28, s64, 0xfff80080
	s_addc_u32 s29, s65, -1
	s_cmp_eq_u32 s7, 28
	s_cselect_b32 s77, s59, s29
	s_cselect_b32 s76, s58, s28
	s_cselect_b32 s75, s61, s3
	s_cselect_b32 s74, s60, s2
	v_lshl_add_u64 v[140:141], s[64:65], 0, v[148:149]
	s_add_i32 m0, s23, 0xc000
	ds_read_b128 v[160:163], v210
	ds_read_b128 v[164:167], v210 offset:1024
	ds_read_b128 v[168:171], v210 offset:2048
	ds_read_b128 v[172:175], v210 offset:3072
	ds_read_b128 v[176:179], v210 offset:4096
	ds_read_b128 v[180:183], v210 offset:5120
	ds_read_b128 v[184:187], v210 offset:6144
	ds_read_b128 v[188:191], v210 offset:7168
	global_load_lds_dwordx4 v[140:141], off
	v_lshl_add_u64 v[140:141], s[64:65], 0, v[150:151]
	s_add_i32 m0, s23, 0xe000
	s_nop 0
	global_load_lds_dwordx4 v[140:141], off
	s_waitcnt lgkmcnt(8)
	s_barrier
	s_waitcnt lgkmcnt(0)
	v_mfma_f32_16x16x32_bf16 v[124:127], v[128:131], v[160:163], v[124:127]
	v_mfma_f32_16x16x32_bf16 v[116:119], v[136:139], v[160:163], v[116:119]
	v_mfma_f32_16x16x32_bf16 v[108:111], v[128:131], v[168:171], v[108:111]
	v_mfma_f32_16x16x32_bf16 v[100:103], v[136:139], v[168:171], v[100:103]
	v_mfma_f32_16x16x32_bf16 v[92:95], v[128:131], v[176:179], v[92:95]
	v_mfma_f32_16x16x32_bf16 v[84:87], v[136:139], v[176:179], v[84:87]
	v_mfma_f32_16x16x32_bf16 v[76:79], v[128:131], v[184:187], v[76:79]
	v_mfma_f32_16x16x32_bf16 v[68:71], v[136:139], v[184:187], v[68:71]
	v_mfma_f32_16x16x32_bf16 v[124:127], v[132:135], v[164:167], v[124:127]
	v_mfma_f32_16x16x32_bf16 v[116:119], v[156:159], v[164:167], v[116:119]
	v_mfma_f32_16x16x32_bf16 v[108:111], v[132:135], v[172:175], v[108:111]
	v_mfma_f32_16x16x32_bf16 v[100:103], v[156:159], v[172:175], v[100:103]
	v_mfma_f32_16x16x32_bf16 v[92:95], v[132:135], v[180:183], v[92:95]
	v_mfma_f32_16x16x32_bf16 v[84:87], v[156:159], v[180:183], v[84:87]
	v_mfma_f32_16x16x32_bf16 v[76:79], v[132:135], v[188:191], v[76:79]
	v_mfma_f32_16x16x32_bf16 v[68:71], v[156:159], v[188:191], v[68:71]
	s_barrier
	s_add_i32 s28, s90, s21
	v_lshl_add_u64 v[140:141], s[74:75], 0, v[142:143]
	s_mov_b32 m0, s28
	ds_read_b128 v[192:195], v211
	ds_read_b128 v[196:199], v211 offset:1024
	ds_read_b128 v[200:203], v211 offset:2048
	ds_read_b128 v[212:215], v211 offset:3072
	global_load_lds_dwordx4 v[140:141], off
	v_lshl_add_u64 v[204:205], s[74:75], 0, v[144:145]
	s_add_i32 m0, s28, 0x2000
	s_nop 0
	global_load_lds_dwordx4 v[204:205], off
	s_barrier
	s_waitcnt lgkmcnt(0)
	v_mfma_f32_16x16x32_bf16 v[120:123], v[192:195], v[160:163], v[120:123]
	v_mfma_f32_16x16x32_bf16 v[112:115], v[200:203], v[160:163], v[112:115]
	v_mfma_f32_16x16x32_bf16 v[104:107], v[192:195], v[168:171], v[104:107]
	v_mfma_f32_16x16x32_bf16 v[96:99], v[200:203], v[168:171], v[96:99]
	v_mfma_f32_16x16x32_bf16 v[88:91], v[192:195], v[176:179], v[88:91]
	v_mfma_f32_16x16x32_bf16 v[80:83], v[200:203], v[176:179], v[80:83]
	v_mfma_f32_16x16x32_bf16 v[72:75], v[192:195], v[184:187], v[72:75]
	v_mfma_f32_16x16x32_bf16 v[64:67], v[200:203], v[184:187], v[64:67]
	v_mfma_f32_16x16x32_bf16 v[120:123], v[196:199], v[164:167], v[120:123]
	v_mfma_f32_16x16x32_bf16 v[112:115], v[212:215], v[164:167], v[112:115]
	v_mfma_f32_16x16x32_bf16 v[104:107], v[196:199], v[172:175], v[104:107]
	v_mfma_f32_16x16x32_bf16 v[96:99], v[212:215], v[172:175], v[96:99]
	v_mfma_f32_16x16x32_bf16 v[88:91], v[196:199], v[180:183], v[88:91]
	v_mfma_f32_16x16x32_bf16 v[80:83], v[212:215], v[180:183], v[80:83]
	v_mfma_f32_16x16x32_bf16 v[72:75], v[196:199], v[188:191], v[72:75]
	v_mfma_f32_16x16x32_bf16 v[64:67], v[212:215], v[188:191], v[64:67]
	s_mov_b32 m0, s23
	v_lshl_add_u64 v[216:217], s[76:77], 0, v[142:143]
	s_barrier
	ds_read_b128 v[160:163], v210 offset:16384
	ds_read_b128 v[164:167], v210 offset:17408
	ds_read_b128 v[168:171], v210 offset:18432
	ds_read_b128 v[172:175], v210 offset:19456
	ds_read_b128 v[176:179], v210 offset:20480
	ds_read_b128 v[180:183], v210 offset:21504
	ds_read_b128 v[184:187], v210 offset:22528
	ds_read_b128 v[188:191], v210 offset:23552
	global_load_lds_dwordx4 v[216:217], off
	s_mov_b32 m0, s35
	v_lshl_add_u64 v[218:219], s[76:77], 0, v[144:145]
	global_load_lds_dwordx4 v[218:219], off
	s_barrier
	s_waitcnt lgkmcnt(0)
	v_mfma_f32_16x16x32_bf16 v[60:63], v[128:131], v[160:163], v[60:63]
	v_mfma_f32_16x16x32_bf16 v[52:55], v[136:139], v[160:163], v[52:55]
	v_mfma_f32_16x16x32_bf16 v[44:47], v[128:131], v[168:171], v[44:47]
	v_mfma_f32_16x16x32_bf16 v[36:39], v[136:139], v[168:171], v[36:39]
	v_mfma_f32_16x16x32_bf16 v[28:31], v[128:131], v[176:179], v[28:31]
	v_mfma_f32_16x16x32_bf16 v[20:23], v[136:139], v[176:179], v[20:23]
	v_mfma_f32_16x16x32_bf16 v[12:15], v[128:131], v[184:187], v[12:15]
	v_mfma_f32_16x16x32_bf16 v[4:7], v[136:139], v[184:187], v[4:7]
	v_mfma_f32_16x16x32_bf16 v[60:63], v[132:135], v[164:167], v[60:63]
	v_mfma_f32_16x16x32_bf16 v[52:55], v[156:159], v[164:167], v[52:55]
	v_mfma_f32_16x16x32_bf16 v[44:47], v[132:135], v[172:175], v[44:47]
	v_mfma_f32_16x16x32_bf16 v[36:39], v[156:159], v[172:175], v[36:39]
	v_mfma_f32_16x16x32_bf16 v[28:31], v[132:135], v[180:183], v[28:31]
	v_mfma_f32_16x16x32_bf16 v[20:23], v[156:159], v[180:183], v[20:23]
	v_mfma_f32_16x16x32_bf16 v[12:15], v[132:135], v[188:191], v[12:15]
	v_mfma_f32_16x16x32_bf16 v[4:7], v[156:159], v[188:191], v[4:7]
	s_barrier
	s_add_u32 s28, s74, 0x80000
	s_addc_u32 s29, s75, 0
	s_add_i32 s57, s91, s21
	s_mov_b32 m0, s57
	v_lshl_add_u64 v[128:129], s[28:29], 0, v[142:143]
	global_load_lds_dwordx4 v[128:129], off
	v_lshl_add_u64 v[128:129], s[28:29], 0, v[144:145]
	s_add_i32 m0, s57, 0x2000
	s_nop 0
	global_load_lds_dwordx4 v[128:129], off
	s_waitcnt vmcnt(6)
	s_barrier
; #define WAIT_V(n) asm volatile("s_waitcnt vmcnt(" #n ")" ::: "memory")
; #define WAIT_L(n) asm volatile("s_waitcnt lgkmcnt(" #n ")" ::: "memory")
; #define BAR __builtin_amdgcn_s_barrier()
; #define SCHED __builtin_amdgcn_sched_barrier(0)
; template <class Get, class Epi>
; DI void gemm_stream(LAS unsigned char* lds, const int K, const int ld, Get get, Epi epi) {
;     ...
;             WAIT_V(6); BAR; MMA(1, 1, At, B1); BAR;
;             LDB(B0, 1, 0); SCHED; LDA(At, 1, 0); STAGE(SAo(0, 1), a2 + hstep);
;             WAIT_L(8); BAR; WAIT_L(0); MMA(0, 0, At, B0); BAR; SCHED;
;             LDB(B1, 1, 1); STAGE(SBo(1, 0), b3);
;             BAR; WAIT_L(0); MMA(0, 1, At, B1); BAR;
;             LDA(At, 1, 1); STAGE(SAo(1, 0), a3);
;             BAR; WAIT_L(0); MMA(1, 0, At, B0); BAR; SCHED;
	v_mfma_f32_16x16x32_bf16 v[56:59], v[192:195], v[160:163], v[56:59]
	v_mfma_f32_16x16x32_bf16 v[48:51], v[200:203], v[160:163], v[48:51]
	v_mfma_f32_16x16x32_bf16 v[40:43], v[192:195], v[168:171], v[40:43]
	v_mfma_f32_16x16x32_bf16 v[32:35], v[200:203], v[168:171], v[32:35]
	v_mfma_f32_16x16x32_bf16 v[24:27], v[192:195], v[176:179], v[24:27]
	v_mfma_f32_16x16x32_bf16 v[16:19], v[200:203], v[176:179], v[16:19]
	v_mfma_f32_16x16x32_bf16 v[8:11], v[192:195], v[184:187], v[8:11]
	v_mfma_f32_16x16x32_bf16 v[0:3], v[200:203], v[184:187], v[0:3]
	v_mfma_f32_16x16x32_bf16 v[56:59], v[196:199], v[164:167], v[56:59]
	v_mfma_f32_16x16x32_bf16 v[48:51], v[212:215], v[164:167], v[48:51]
	v_mfma_f32_16x16x32_bf16 v[40:43], v[196:199], v[172:175], v[40:43]
	v_mfma_f32_16x16x32_bf16 v[32:35], v[212:215], v[172:175], v[32:35]
	v_mfma_f32_16x16x32_bf16 v[24:27], v[196:199], v[180:183], v[24:27]
	v_mfma_f32_16x16x32_bf16 v[16:19], v[212:215], v[180:183], v[16:19]
	v_mfma_f32_16x16x32_bf16 v[8:11], v[196:199], v[188:191], v[8:11]
	v_mfma_f32_16x16x32_bf16 v[0:3], v[212:215], v[188:191], v[0:3]
	s_add_i32 s57, 16, 0x18000
	v_add_u32_e32 v146, s57, v208
	s_barrier
	ds_read_b128 v[128:131], v146
	ds_read_b128 v[132:135], v146 offset:1024
	ds_read_b128 v[136:139], v146 offset:2048
	ds_read_b128 v[156:159], v146 offset:3072
	s_add_u32 s28, s76, 0x80000
	s_addc_u32 s29, s77, 0
	s_mov_b32 m0, s55
	v_lshl_add_u64 v[192:193], s[28:29], 0, v[142:143]
	ds_read_b128 v[160:163], v210 offset:32768
	ds_read_b128 v[164:167], v210 offset:33792
	ds_read_b128 v[168:171], v210 offset:34816
	ds_read_b128 v[172:175], v210 offset:35840
	ds_read_b128 v[176:179], v210 offset:36864
	ds_read_b128 v[180:183], v210 offset:37888
	ds_read_b128 v[184:187], v210 offset:38912
	ds_read_b128 v[188:191], v210 offset:39936
	global_load_lds_dwordx4 v[192:193], off
	s_mov_b32 m0, s82
	v_lshl_add_u64 v[192:193], s[28:29], 0, v[144:145]
	global_load_lds_dwordx4 v[192:193], off
	s_waitcnt lgkmcnt(8)
	s_barrier
	s_waitcnt lgkmcnt(0)
	v_mfma_f32_16x16x32_bf16 v[124:127], v[128:131], v[160:163], v[124:127]
	v_mfma_f32_16x16x32_bf16 v[116:119], v[136:139], v[160:163], v[116:119]
	v_mfma_f32_16x16x32_bf16 v[108:111], v[128:131], v[168:171], v[108:111]
	v_mfma_f32_16x16x32_bf16 v[100:103], v[136:139], v[168:171], v[100:103]
	v_mfma_f32_16x16x32_bf16 v[92:95], v[128:131], v[176:179], v[92:95]
	v_mfma_f32_16x16x32_bf16 v[84:87], v[136:139], v[176:179], v[84:87]
	v_mfma_f32_16x16x32_bf16 v[76:79], v[128:131], v[184:187], v[76:79]
	v_mfma_f32_16x16x32_bf16 v[68:71], v[136:139], v[184:187], v[68:71]
	v_mfma_f32_16x16x32_bf16 v[124:127], v[132:135], v[164:167], v[124:127]
	v_mfma_f32_16x16x32_bf16 v[116:119], v[156:159], v[164:167], v[116:119]
	v_mfma_f32_16x16x32_bf16 v[108:111], v[132:135], v[172:175], v[108:111]
	v_mfma_f32_16x16x32_bf16 v[100:103], v[156:159], v[172:175], v[100:103]
	v_mfma_f32_16x16x32_bf16 v[92:95], v[132:135], v[180:183], v[92:95]
	v_mfma_f32_16x16x32_bf16 v[84:87], v[156:159], v[180:183], v[84:87]
	v_mfma_f32_16x16x32_bf16 v[76:79], v[132:135], v[188:191], v[76:79]
	v_mfma_f32_16x16x32_bf16 v[68:71], v[156:159], v[188:191], v[68:71]
	s_barrier
	s_add_i32 s63, 16, 0x1c000
	s_add_i32 s28, s57, s21
	v_add_u32_e32 v146, s63, v208
	v_lshl_add_u64 v[140:141], v[140:141], 0, s[0:1]
	s_mov_b32 m0, s28
	ds_read_b128 v[192:195], v146
	ds_read_b128 v[196:199], v146 offset:1024
	ds_read_b128 v[200:203], v146 offset:2048
	ds_read_b128 v[212:215], v146 offset:3072
	global_load_lds_dwordx4 v[140:141], off
	v_lshl_add_u64 v[140:141], v[204:205], 0, s[0:1]
	s_add_i32 m0, s28, 0x2000
	s_nop 0
	global_load_lds_dwordx4 v[140:141], off
	s_barrier
	s_waitcnt lgkmcnt(0)
	v_mfma_f32_16x16x32_bf16 v[120:123], v[192:195], v[160:163], v[120:123]
	v_mfma_f32_16x16x32_bf16 v[112:115], v[200:203], v[160:163], v[112:115]
	v_mfma_f32_16x16x32_bf16 v[104:107], v[192:195], v[168:171], v[104:107]
	v_mfma_f32_16x16x32_bf16 v[96:99], v[200:203], v[168:171], v[96:99]
	v_mfma_f32_16x16x32_bf16 v[88:91], v[192:195], v[176:179], v[88:91]
	v_mfma_f32_16x16x32_bf16 v[80:83], v[200:203], v[176:179], v[80:83]
	v_mfma_f32_16x16x32_bf16 v[72:75], v[192:195], v[184:187], v[72:75]
	v_mfma_f32_16x16x32_bf16 v[64:67], v[200:203], v[184:187], v[64:67]
	v_mfma_f32_16x16x32_bf16 v[120:123], v[196:199], v[164:167], v[120:123]
	v_mfma_f32_16x16x32_bf16 v[112:115], v[212:215], v[164:167], v[112:115]
	v_mfma_f32_16x16x32_bf16 v[104:107], v[196:199], v[172:175], v[104:107]
	v_mfma_f32_16x16x32_bf16 v[96:99], v[212:215], v[172:175], v[96:99]
	v_mfma_f32_16x16x32_bf16 v[88:91], v[196:199], v[180:183], v[88:91]
	v_mfma_f32_16x16x32_bf16 v[80:83], v[212:215], v[180:183], v[80:83]
	v_mfma_f32_16x16x32_bf16 v[72:75], v[196:199], v[188:191], v[72:75]
	v_mfma_f32_16x16x32_bf16 v[64:67], v[212:215], v[188:191], v[64:67]
	s_mov_b32 m0, s83
	v_lshl_add_u64 v[140:141], v[216:217], 0, s[0:1]
	s_barrier
	ds_read_b128 v[160:163], v210 offset:49152
	ds_read_b128 v[164:167], v210 offset:50176
	ds_read_b128 v[168:171], v210 offset:51200
	ds_read_b128 v[172:175], v210 offset:52224
	ds_read_b128 v[176:179], v210 offset:53248
	ds_read_b128 v[180:183], v210 offset:54272
	ds_read_b128 v[184:187], v210 offset:55296
	ds_read_b128 v[188:191], v210 offset:56320
	global_load_lds_dwordx4 v[140:141], off
	s_mov_b32 m0, s85
	v_lshl_add_u64 v[140:141], v[218:219], 0, s[0:1]
	global_load_lds_dwordx4 v[140:141], off
	s_barrier
; #define WAIT_V(n) asm volatile("s_waitcnt vmcnt(" #n ")" ::: "memory")
; #define WAIT_L(n) asm volatile("s_waitcnt lgkmcnt(" #n ")" ::: "memory")
; #define BAR __builtin_amdgcn_s_barrier()
; #define SCHED __builtin_amdgcn_sched_barrier(0)
; template <class Get, class Epi>
; DI void gemm_stream(LAS unsigned char* lds, const int K, const int ld, Get get, Epi epi) {
;     ...
;             BAR; WAIT_L(0); MMA(1, 0, At, B0); BAR; SCHED;
;             STAGE(SBo(1, 1), b3 + hstep);
;             WAIT_V(6); BAR; MMA(1, 1, At, B1); BAR;
;         }
; DI void phase_inproj1(const P& p, char* shm) {
;     ...
;     auto epi = [&](const Acc& acc, const Unit& u) {
;         const int brow = u.pm * 256, pn = u.pn;
;         const int b = u.pm / 17, pt = u.pm % 17;
;         const size_t latrow0 = (size_t)b * SEQ + (pt - 1) * 256;
;         if (pn < 8) epi_rope256(acc, p, brow, (bf16_t*)(p.ws + O_Q1), latrow0, pn * 256, 1.f);
;         else if (pn < 16) epi_rope256(acc, p, brow, (bf16_t*)(p.ws + O_K1), (size_t)brow, (pn - 8) * 256, 0.0625f);
;         else if (pn < 32) epi_T<32>(acc, (pn - 16) * 256, brow, (bf16_t*)(p.ws + O_V1T), 4096, nullptr);
;         else epi_plain(acc, 0, (bf16_t*)(p.ws + O_G1) + latrow0 * 4096, 4096, (pn - 32) * 256, nullptr);
	s_waitcnt lgkmcnt(0)
	v_mfma_f32_16x16x32_bf16 v[60:63], v[128:131], v[160:163], v[60:63]
	v_mfma_f32_16x16x32_bf16 v[52:55], v[136:139], v[160:163], v[52:55]
	v_mfma_f32_16x16x32_bf16 v[44:47], v[128:131], v[168:171], v[44:47]
	v_mfma_f32_16x16x32_bf16 v[36:39], v[136:139], v[168:171], v[36:39]
	v_mfma_f32_16x16x32_bf16 v[28:31], v[128:131], v[176:179], v[28:31]
	v_mfma_f32_16x16x32_bf16 v[20:23], v[136:139], v[176:179], v[20:23]
	v_mfma_f32_16x16x32_bf16 v[12:15], v[128:131], v[184:187], v[12:15]
	v_mfma_f32_16x16x32_bf16 v[4:7], v[136:139], v[184:187], v[4:7]
	v_mfma_f32_16x16x32_bf16 v[60:63], v[132:135], v[164:167], v[60:63]
	v_mfma_f32_16x16x32_bf16 v[52:55], v[156:159], v[164:167], v[52:55]
	v_mfma_f32_16x16x32_bf16 v[44:47], v[132:135], v[172:175], v[44:47]
	v_mfma_f32_16x16x32_bf16 v[36:39], v[156:159], v[172:175], v[36:39]
	v_mfma_f32_16x16x32_bf16 v[28:31], v[132:135], v[180:183], v[28:31]
	v_mfma_f32_16x16x32_bf16 v[20:23], v[156:159], v[180:183], v[20:23]
	v_mfma_f32_16x16x32_bf16 v[12:15], v[132:135], v[188:191], v[12:15]
	v_mfma_f32_16x16x32_bf16 v[4:7], v[156:159], v[188:191], v[4:7]
	s_barrier
	s_add_u32 s28, s74, 0x80080
	s_addc_u32 s29, s75, 0
	s_add_i32 s57, s63, s21
	s_mov_b32 m0, s57
	v_lshl_add_u64 v[128:129], s[28:29], 0, v[142:143]
	global_load_lds_dwordx4 v[128:129], off
	v_lshl_add_u64 v[128:129], s[28:29], 0, v[144:145]
	s_add_i32 m0, s57, 0x2000
	s_nop 0
	global_load_lds_dwordx4 v[128:129], off
	s_waitcnt vmcnt(6)
	s_barrier
	v_mfma_f32_16x16x32_bf16 v[56:59], v[192:195], v[160:163], v[56:59]
	v_mfma_f32_16x16x32_bf16 v[48:51], v[200:203], v[160:163], v[48:51]
	v_mfma_f32_16x16x32_bf16 v[40:43], v[192:195], v[168:171], v[40:43]
	v_mfma_f32_16x16x32_bf16 v[32:35], v[200:203], v[168:171], v[32:35]
	v_mfma_f32_16x16x32_bf16 v[24:27], v[192:195], v[176:179], v[24:27]
	v_mfma_f32_16x16x32_bf16 v[16:19], v[200:203], v[176:179], v[16:19]
	v_mfma_f32_16x16x32_bf16 v[8:11], v[192:195], v[184:187], v[8:11]
	v_mfma_f32_16x16x32_bf16 v[0:3], v[200:203], v[184:187], v[0:3]
	v_mfma_f32_16x16x32_bf16 v[56:59], v[196:199], v[164:167], v[56:59]
	v_mfma_f32_16x16x32_bf16 v[48:51], v[212:215], v[164:167], v[48:51]
	v_mfma_f32_16x16x32_bf16 v[40:43], v[196:199], v[172:175], v[40:43]
	v_mfma_f32_16x16x32_bf16 v[32:35], v[212:215], v[172:175], v[32:35]
	v_mfma_f32_16x16x32_bf16 v[24:27], v[196:199], v[180:183], v[24:27]
	v_mfma_f32_16x16x32_bf16 v[16:19], v[212:215], v[180:183], v[16:19]
	v_mfma_f32_16x16x32_bf16 v[8:11], v[196:199], v[188:191], v[8:11]
	v_mfma_f32_16x16x32_bf16 v[0:3], v[212:215], v[188:191], v[0:3]
	s_add_i32 s7, s7, 2
	s_add_u32 s64, s64, 0x100
	s_addc_u32 s65, s65, 0
	s_add_u32 s2, s2, 0x100
	s_addc_u32 s3, s3, 0
	s_cmp_gt_u32 s7, 29
	s_barrier
	s_cbranch_scc0 .LBB0_2102
	s_mul_hi_i32 s2, s6, 0x78787879
	s_lshr_b32 s3, s2, 31
	s_ashr_i32 s2, s2, 3
	s_add_i32 s76, s2, s3
	s_mul_i32 s2, s76, 17
	s_lshl_b32 s74, s6, 8
	s_sub_i32 s6, s6, s2
	s_lshl_b32 s6, s6, 8
	s_ashr_i32 s77, s76, 31
	s_addk_i32 s6, 0xff00
	s_lshl_b64 s[2:3], s[76:77], 12
	s_ashr_i32 s7, s6, 31
	s_add_u32 s64, s2, s6
	s_addc_u32 s65, s3, s7
	s_cmp_gt_i32 s62, 7
	s_mov_b64 s[6:7], -1
	s_cbranch_scc0 .LBB0_2145
	s_cmp_gt_u32 s62, 15
	s_cbranch_scc0 .LBB0_2110
	s_cmp_gt_u32 s62, 31
	v_cvt_pk_bf16_f32 v204, v124, v125
	v_cvt_pk_bf16_f32 v205, v126, v127
	v_cvt_pk_bf16_f32 v202, v116, v117
	v_cvt_pk_bf16_f32 v203, v118, v119
	v_cvt_pk_bf16_f32 v200, v120, v121
	v_cvt_pk_bf16_f32 v201, v122, v123
	v_cvt_pk_bf16_f32 v198, v112, v113
	v_cvt_pk_bf16_f32 v199, v114, v115
	v_cvt_pk_bf16_f32 v196, v108, v109
	v_cvt_pk_bf16_f32 v197, v110, v111
	v_cvt_pk_bf16_f32 v194, v100, v101
	v_cvt_pk_bf16_f32 v195, v102, v103
	v_cvt_pk_bf16_f32 v192, v104, v105
	v_cvt_pk_bf16_f32 v193, v106, v107
	v_cvt_pk_bf16_f32 v190, v96, v97
	v_cvt_pk_bf16_f32 v191, v98, v99
	v_cvt_pk_bf16_f32 v188, v92, v93
	v_cvt_pk_bf16_f32 v189, v94, v95
	v_cvt_pk_bf16_f32 v186, v84, v85
	v_cvt_pk_bf16_f32 v187, v86, v87
	v_cvt_pk_bf16_f32 v184, v88, v89
	v_cvt_pk_bf16_f32 v185, v90, v91
	v_cvt_pk_bf16_f32 v182, v80, v81
	v_cvt_pk_bf16_f32 v183, v82, v83
	v_cvt_pk_bf16_f32 v180, v76, v77
	v_cvt_pk_bf16_f32 v181, v78, v79
	v_cvt_pk_bf16_f32 v178, v68, v69
	v_cvt_pk_bf16_f32 v179, v70, v71
	v_cvt_pk_bf16_f32 v176, v72, v73
	v_cvt_pk_bf16_f32 v177, v74, v75
	v_cvt_pk_bf16_f32 v174, v64, v65
	v_cvt_pk_bf16_f32 v175, v66, v67
	v_cvt_pk_bf16_f32 v172, v60, v61
	v_cvt_pk_bf16_f32 v173, v62, v63
	v_cvt_pk_bf16_f32 v170, v52, v53
	v_cvt_pk_bf16_f32 v171, v54, v55
	v_cvt_pk_bf16_f32 v168, v56, v57
	v_cvt_pk_bf16_f32 v169, v58, v59
	v_cvt_pk_bf16_f32 v166, v48, v49
	v_cvt_pk_bf16_f32 v167, v50, v51
	v_cvt_pk_bf16_f32 v164, v44, v45
	v_cvt_pk_bf16_f32 v165, v46, v47
	v_cvt_pk_bf16_f32 v162, v36, v37
	v_cvt_pk_bf16_f32 v163, v38, v39
	v_cvt_pk_bf16_f32 v160, v40, v41
	v_cvt_pk_bf16_f32 v161, v42, v43
	v_cvt_pk_bf16_f32 v158, v32, v33
	v_cvt_pk_bf16_f32 v159, v34, v35
	v_cvt_pk_bf16_f32 v156, v28, v29
	v_cvt_pk_bf16_f32 v157, v30, v31
	v_cvt_pk_bf16_f32 v140, v20, v21
	v_cvt_pk_bf16_f32 v141, v22, v23
	v_cvt_pk_bf16_f32 v138, v24, v25
	v_cvt_pk_bf16_f32 v139, v26, v27
	v_cvt_pk_bf16_f32 v136, v16, v17
	v_cvt_pk_bf16_f32 v137, v18, v19
	v_cvt_pk_bf16_f32 v134, v12, v13
	v_cvt_pk_bf16_f32 v135, v14, v15
	v_cvt_pk_bf16_f32 v132, v4, v5
	v_cvt_pk_bf16_f32 v133, v6, v7
	v_cvt_pk_bf16_f32 v130, v8, v9
	v_cvt_pk_bf16_f32 v131, v10, v11
	v_cvt_pk_bf16_f32 v128, v0, v1
	v_cvt_pk_bf16_f32 v129, v2, v3
	s_cbranch_scc0 .LBB0_2107
; DI void epi_plain(const Acc& acc, int brow, bf16_t* dst, int ld, int coff, const float* rs) {
;     ...
;         for (int m = 0; m < 4; ++m) {
;             const int lr = ai * 128 + wr * 64 + m * 16 + fr;
;             const float s = rs ? rs[lr] : 1.f;
;             bf16_t* rp = dst + (size_t)(brow + lr) * ld + coff + wc * 32 + fq * 4;
; #pragma unroll
;             for (int bj = 0; bj < 2; ++bj)
; #pragma unroll
;                 for (int n = 0; n < 2; ++n) { const f32x4 v = acc[ai][bj][m][n]; st4(rp + bj * 128 + n * 16, v[0] * s, v[1] * s, v[2] * s, v[3] * s); }
;         }
	s_lshl_b64 s[2:3], s[64:65], 13
	s_add_u32 s2, s26, s2
	s_addc_u32 s3, s27, s3
	v_mov_b32_e32 v146, v206
	s_lshl_b32 s6, s62, 9
	s_add_u32 s2, s2, s6
	v_and_b32_e32 v212, 15, v146
	v_ashrrev_i32_e32 v213, 2, v146
	v_and_or_b32 v212, v213, s92, v212
	s_addc_u32 s3, s3, 0
	v_lshrrev_b32_e32 v213, 1, v146
	v_and_b32_e32 v146, 0xc0, v146
	v_lshl_add_u64 v[214:215], s[2:3], 0, v[146:147]
	v_and_b32_e32 v146, 24, v213
	v_or_b32_e32 v218, 16, v212
	v_lshl_add_u64 v[214:215], v[214:215], 0, v[146:147]
	s_mov_b64 s[2:3], 0x1a3fc000
	v_ashrrev_i32_e32 v213, 31, v212
	v_ashrrev_i32_e32 v219, 31, v218
	v_lshl_add_u64 v[214:215], v[214:215], 0, s[2:3]
	v_lshlrev_b64 v[216:217], 13, v[212:213]
	v_lshlrev_b64 v[218:219], 13, v[218:219]
	v_lshl_add_u64 v[216:217], v[214:215], 0, v[216:217]
	v_lshl_add_u64 v[218:219], v[214:215], 0, v[218:219]
	global_store_dwordx2 v[216:217], v[204:205], off
	global_store_dwordx2 v[216:217], v[202:203], off offset:32
	global_store_dwordx2 v[216:217], v[200:201], off offset:256
	global_store_dwordx2 v[216:217], v[198:199], off offset:288
	global_store_dwordx2 v[218:219], v[196:197], off
	global_store_dwordx2 v[218:219], v[194:195], off offset:32
	global_store_dwordx2 v[218:219], v[192:193], off offset:256
	global_store_dwordx2 v[218:219], v[190:191], off offset:288
	v_or_b32_e32 v218, 32, v212
	v_or_b32_e32 v212, 48, v212
	v_ashrrev_i32_e32 v219, 31, v218
	v_ashrrev_i32_e32 v213, 31, v212
	v_lshlrev_b64 v[218:219], 13, v[218:219]
	v_lshlrev_b64 v[212:213], 13, v[212:213]
	v_lshl_add_u64 v[218:219], v[214:215], 0, v[218:219]
	v_lshl_add_u64 v[212:213], v[214:215], 0, v[212:213]
	s_mov_b64 s[2:3], 0x100000
	global_store_dwordx2 v[218:219], v[188:189], off
	global_store_dwordx2 v[218:219], v[186:187], off offset:32
	global_store_dwordx2 v[218:219], v[184:185], off offset:256
	global_store_dwordx2 v[218:219], v[182:183], off offset:288
	global_store_dwordx2 v[212:213], v[180:181], off
	global_store_dwordx2 v[212:213], v[178:179], off offset:32
	global_store_dwordx2 v[212:213], v[176:177], off offset:256
	global_store_dwordx2 v[212:213], v[174:175], off offset:288
	v_lshl_add_u64 v[212:213], v[216:217], 0, s[2:3]
	s_mov_b32 s2, 0x100000
	v_add_co_u32_e32 v214, vcc, s2, v216
	s_mov_b64 s[2:3], 0x120000
	s_nop 0
	v_addc_co_u32_e32 v215, vcc, 0, v217, vcc
	global_store_dwordx2 v[214:215], v[172:173], off
	global_store_dwordx2 v[212:213], v[170:171], off offset:32
	global_store_dwordx2 v[212:213], v[168:169], off offset:256
	global_store_dwordx2 v[212:213], v[166:167], off offset:288
	v_add_co_u32_e32 v214, vcc, s93, v216
	v_lshl_add_u64 v[212:213], v[216:217], 0, s[2:3]
	s_nop 0
	v_addc_co_u32_e32 v215, vcc, 0, v217, vcc
	global_store_dwordx2 v[214:215], v[164:165], off
	global_store_dwordx2 v[212:213], v[162:163], off offset:32
	global_store_dwordx2 v[212:213], v[160:161], off offset:256
	global_store_dwordx2 v[212:213], v[158:159], off offset:288
	v_add_co_u32_e32 v214, vcc, s94, v216
	v_lshl_add_u64 v[212:213], v[216:217], 0, s[16:17]
	s_nop 0
	v_addc_co_u32_e32 v215, vcc, 0, v217, vcc
	global_store_dwordx2 v[214:215], v[156:157], off
	global_store_dwordx2 v[212:213], v[140:141], off offset:32
	global_store_dwordx2 v[212:213], v[138:139], off offset:256
	global_store_dwordx2 v[212:213], v[136:137], off offset:288
	v_add_co_u32_e32 v214, vcc, s95, v216
	v_lshl_add_u64 v[212:213], v[216:217], 0, s[18:19]
	s_nop 0
	v_addc_co_u32_e32 v215, vcc, 0, v217, vcc
	global_store_dwordx2 v[214:215], v[134:135], off
	global_store_dwordx2 v[212:213], v[132:133], off offset:32
	global_store_dwordx2 v[212:213], v[130:131], off offset:256
	global_store_dwordx2 v[212:213], v[128:129], off offset:288
	s_mov_b64 s[6:7], 0

; #define WAIT_V(n) asm volatile("s_waitcnt vmcnt(" #n ")" ::: "memory")
; #define WAIT_L(n) asm volatile("s_waitcnt lgkmcnt(" #n ")" ::: "memory")
; #define BAR __builtin_amdgcn_s_barrier()
; #define SCHED __builtin_amdgcn_sched_barrier(0)
; template <class Get, class Epi>
; DI void gemm_stream(LAS unsigned char* lds, const int K, const int ld, Get get, Epi epi) {
;     ...
;             LDB(B0, 0, 0); SCHED; LDA(At, 0, 0); STAGE(SAo(1, 1), a1 + hstep);
;             WAIT_L(8); BAR; WAIT_L(0); MMA(0, 0, At, B0); BAR; SCHED;
;             LDB(B1, 0, 1); STAGE(SBo(0, 0), b2);
;             BAR; WAIT_L(0); MMA(0, 1, At, B1); BAR;
;             LDA(At, 0, 1); STAGE(SAo(0, 0), a2);
;             BAR; WAIT_L(0); MMA(1, 0, At, B0); BAR; SCHED;
;             STAGE(SBo(0, 1), b2 + hstep);
;             WAIT_V(6); BAR; MMA(1, 1, At, B1); BAR;
.LBB0_2670:
	ds_read_b128 v[128:131], v198
	ds_read_b128 v[132:135], v198 offset:1024
	ds_read_b128 v[136:139], v198 offset:2048
	ds_read_b128 v[140:143], v198 offset:3072
	s_add_u32 s8, s6, 0x100
	s_addc_u32 s9, s7, 0
	s_cmp_eq_u32 s16, 60
	s_cselect_b32 s13, s39, s9
	s_cselect_b32 s12, s38, s8
	s_cselect_b32 s11, s41, s15
	s_cselect_b32 s10, s40, s14
	s_mov_b32 m0, s52
	v_lshl_add_u64 v[186:187], s[6:7], 0, v[168:169]
	ds_read_b128 v[144:147], v199
	ds_read_b128 v[148:151], v199 offset:1024
	ds_read_b128 v[152:155], v199 offset:2048
	ds_read_b128 v[156:159], v199 offset:3072
	ds_read_b128 v[160:163], v199 offset:4096
	ds_read_b128 v[174:177], v199 offset:5120
	ds_read_b128 v[178:181], v199 offset:6144
	ds_read_b128 v[182:185], v199 offset:7168
	global_load_lds_dwordx4 v[186:187], off
	s_mov_b32 m0, s53
	v_lshl_add_u64 v[186:187], s[6:7], 0, v[170:171]
	global_load_lds_dwordx4 v[186:187], off
	s_waitcnt lgkmcnt(8)
	s_barrier
	s_waitcnt lgkmcnt(0)
	v_mfma_f32_16x16x32_bf16 v[124:127], v[128:131], v[144:147], v[124:127]
	v_mfma_f32_16x16x32_bf16 v[92:95], v[136:139], v[144:147], v[92:95]
	v_mfma_f32_16x16x32_bf16 v[120:123], v[128:131], v[152:155], v[120:123]
	v_mfma_f32_16x16x32_bf16 v[88:91], v[136:139], v[152:155], v[88:91]
	v_mfma_f32_16x16x32_bf16 v[116:119], v[128:131], v[160:163], v[116:119]
	v_mfma_f32_16x16x32_bf16 v[84:87], v[136:139], v[160:163], v[84:87]
	v_mfma_f32_16x16x32_bf16 v[112:115], v[128:131], v[178:181], v[112:115]
	v_mfma_f32_16x16x32_bf16 v[80:83], v[136:139], v[178:181], v[80:83]
	v_mfma_f32_16x16x32_bf16 v[124:127], v[132:135], v[148:151], v[124:127]
	v_mfma_f32_16x16x32_bf16 v[92:95], v[140:143], v[148:151], v[92:95]
	v_mfma_f32_16x16x32_bf16 v[120:123], v[132:135], v[156:159], v[120:123]
	v_mfma_f32_16x16x32_bf16 v[88:91], v[140:143], v[156:159], v[88:91]
	v_mfma_f32_16x16x32_bf16 v[116:119], v[132:135], v[174:177], v[116:119]
	v_mfma_f32_16x16x32_bf16 v[84:87], v[140:143], v[174:177], v[84:87]
	v_mfma_f32_16x16x32_bf16 v[112:115], v[132:135], v[182:185], v[112:115]
	v_mfma_f32_16x16x32_bf16 v[80:83], v[140:143], v[182:185], v[80:83]
	s_barrier
	s_mov_b32 m0, s58
	v_lshl_add_u64 v[204:205], s[10:11], 0, v[164:165]
	ds_read_b128 v[186:189], v200
	ds_read_b128 v[190:193], v200 offset:1024
	ds_read_b128 v[194:197], v200 offset:2048
	ds_read_b128 v[208:211], v200 offset:3072
	global_load_lds_dwordx4 v[204:205], off
	s_mov_b32 m0, s59
	v_lshl_add_u64 v[212:213], s[10:11], 0, v[166:167]
	global_load_lds_dwordx4 v[212:213], off
	s_barrier
	s_waitcnt lgkmcnt(0)
	v_mfma_f32_16x16x32_bf16 v[60:63], v[186:189], v[144:147], v[60:63]
	v_mfma_f32_16x16x32_bf16 v[28:31], v[194:197], v[144:147], v[28:31]
	v_mfma_f32_16x16x32_bf16 v[56:59], v[186:189], v[152:155], v[56:59]
	v_mfma_f32_16x16x32_bf16 v[24:27], v[194:197], v[152:155], v[24:27]
	v_mfma_f32_16x16x32_bf16 v[52:55], v[186:189], v[160:163], v[52:55]
	v_mfma_f32_16x16x32_bf16 v[20:23], v[194:197], v[160:163], v[20:23]
	v_mfma_f32_16x16x32_bf16 v[48:51], v[186:189], v[178:181], v[48:51]
	v_mfma_f32_16x16x32_bf16 v[16:19], v[194:197], v[178:181], v[16:19]
	v_mfma_f32_16x16x32_bf16 v[60:63], v[190:193], v[148:151], v[60:63]
	v_mfma_f32_16x16x32_bf16 v[28:31], v[208:211], v[148:151], v[28:31]
	v_mfma_f32_16x16x32_bf16 v[56:59], v[190:193], v[156:159], v[56:59]
	v_mfma_f32_16x16x32_bf16 v[24:27], v[208:211], v[156:159], v[24:27]
	v_mfma_f32_16x16x32_bf16 v[52:55], v[190:193], v[174:177], v[52:55]
	v_mfma_f32_16x16x32_bf16 v[20:23], v[208:211], v[174:177], v[20:23]
	v_mfma_f32_16x16x32_bf16 v[48:51], v[190:193], v[182:185], v[48:51]
	v_mfma_f32_16x16x32_bf16 v[16:19], v[208:211], v[182:185], v[16:19]
	s_mov_b32 m0, s35
	v_lshl_add_u64 v[214:215], s[12:13], 0, v[164:165]
	s_barrier
	ds_read_b128 v[144:147], v199 offset:16384
	ds_read_b128 v[148:151], v199 offset:17408
	ds_read_b128 v[152:155], v199 offset:18432
	ds_read_b128 v[156:159], v199 offset:19456
	ds_read_b128 v[160:163], v199 offset:20480
	ds_read_b128 v[174:177], v199 offset:21504
	ds_read_b128 v[178:181], v199 offset:22528
	ds_read_b128 v[182:185], v199 offset:23552
	global_load_lds_dwordx4 v[214:215], off
	s_mov_b32 m0, s44
	v_lshl_add_u64 v[216:217], s[12:13], 0, v[166:167]
	global_load_lds_dwordx4 v[216:217], off
	s_barrier
	s_waitcnt lgkmcnt(0)
	v_mfma_f32_16x16x32_bf16 v[108:111], v[128:131], v[144:147], v[108:111]
	v_mfma_f32_16x16x32_bf16 v[76:79], v[136:139], v[144:147], v[76:79]
	v_mfma_f32_16x16x32_bf16 v[104:107], v[128:131], v[152:155], v[104:107]
	v_mfma_f32_16x16x32_bf16 v[72:75], v[136:139], v[152:155], v[72:75]
	v_mfma_f32_16x16x32_bf16 v[100:103], v[128:131], v[160:163], v[100:103]
	v_mfma_f32_16x16x32_bf16 v[68:71], v[136:139], v[160:163], v[68:71]
	v_mfma_f32_16x16x32_bf16 v[96:99], v[128:131], v[178:181], v[96:99]
	v_mfma_f32_16x16x32_bf16 v[64:67], v[136:139], v[178:181], v[64:67]
	v_mfma_f32_16x16x32_bf16 v[108:111], v[132:135], v[148:151], v[108:111]
	v_mfma_f32_16x16x32_bf16 v[76:79], v[140:143], v[148:151], v[76:79]
	v_mfma_f32_16x16x32_bf16 v[104:107], v[132:135], v[156:159], v[104:107]
	v_mfma_f32_16x16x32_bf16 v[72:75], v[140:143], v[156:159], v[72:75]
	v_mfma_f32_16x16x32_bf16 v[100:103], v[132:135], v[174:177], v[100:103]
	v_mfma_f32_16x16x32_bf16 v[68:71], v[140:143], v[174:177], v[68:71]
	v_mfma_f32_16x16x32_bf16 v[96:99], v[132:135], v[182:185], v[96:99]
	v_mfma_f32_16x16x32_bf16 v[64:67], v[140:143], v[182:185], v[64:67]
	s_barrier
	s_add_u32 s6, s10, 0x100000
	s_addc_u32 s7, s11, 0
	s_mov_b32 m0, s60
	v_lshl_add_u64 v[128:129], s[6:7], 0, v[164:165]
	global_load_lds_dwordx4 v[128:129], off
	s_mov_b32 m0, s61
	v_lshl_add_u64 v[128:129], s[6:7], 0, v[166:167]
	global_load_lds_dwordx4 v[128:129], off
	s_waitcnt vmcnt(6)
	s_barrier
; #define WAIT_V(n) asm volatile("s_waitcnt vmcnt(" #n ")" ::: "memory")
; #define WAIT_L(n) asm volatile("s_waitcnt lgkmcnt(" #n ")" ::: "memory")
; #define BAR __builtin_amdgcn_s_barrier()
; #define SCHED __builtin_amdgcn_sched_barrier(0)
; template <class Get, class Epi>
; DI void gemm_stream(LAS unsigned char* lds, const int K, const int ld, Get get, Epi epi) {
;     ...
;             WAIT_V(6); BAR; MMA(1, 1, At, B1); BAR;
;             LDB(B0, 1, 0); SCHED; LDA(At, 1, 0); STAGE(SAo(0, 1), a2 + hstep);
;             WAIT_L(8); BAR; WAIT_L(0); MMA(0, 0, At, B0); BAR; SCHED;
;             LDB(B1, 1, 1); STAGE(SBo(1, 0), b3);
;             BAR; WAIT_L(0); MMA(0, 1, At, B1); BAR;
;             LDA(At, 1, 1); STAGE(SAo(1, 0), a3);
;             BAR; WAIT_L(0); MMA(1, 0, At, B0); BAR; SCHED;
	v_mfma_f32_16x16x32_bf16 v[44:47], v[186:189], v[144:147], v[44:47]
	v_mfma_f32_16x16x32_bf16 v[12:15], v[194:197], v[144:147], v[12:15]
	v_mfma_f32_16x16x32_bf16 v[40:43], v[186:189], v[152:155], v[40:43]
	v_mfma_f32_16x16x32_bf16 v[8:11], v[194:197], v[152:155], v[8:11]
	v_mfma_f32_16x16x32_bf16 v[36:39], v[186:189], v[160:163], v[36:39]
	v_mfma_f32_16x16x32_bf16 v[4:7], v[194:197], v[160:163], v[4:7]
	v_mfma_f32_16x16x32_bf16 v[32:35], v[186:189], v[178:181], v[32:35]
	v_mfma_f32_16x16x32_bf16 v[0:3], v[194:197], v[178:181], v[0:3]
	v_mfma_f32_16x16x32_bf16 v[44:47], v[190:193], v[148:151], v[44:47]
	v_mfma_f32_16x16x32_bf16 v[12:15], v[208:211], v[148:151], v[12:15]
	v_mfma_f32_16x16x32_bf16 v[40:43], v[190:193], v[156:159], v[40:43]
	v_mfma_f32_16x16x32_bf16 v[8:11], v[208:211], v[156:159], v[8:11]
	v_mfma_f32_16x16x32_bf16 v[36:39], v[190:193], v[174:177], v[36:39]
	v_mfma_f32_16x16x32_bf16 v[4:7], v[208:211], v[174:177], v[4:7]
	v_mfma_f32_16x16x32_bf16 v[32:35], v[190:193], v[182:185], v[32:35]
	v_mfma_f32_16x16x32_bf16 v[0:3], v[208:211], v[182:185], v[0:3]
	s_barrier
	ds_read_b128 v[128:131], v201
	ds_read_b128 v[132:135], v201 offset:1024
	ds_read_b128 v[136:139], v201 offset:2048
	ds_read_b128 v[140:143], v201 offset:3072
	s_add_u32 s6, s12, 0x100000
	s_addc_u32 s7, s13, 0
	s_mov_b32 m0, s45
	v_lshl_add_u64 v[186:187], s[6:7], 0, v[164:165]
	ds_read_b128 v[144:147], v199 offset:32768
	ds_read_b128 v[148:151], v199 offset:33792
	ds_read_b128 v[152:155], v199 offset:34816
	ds_read_b128 v[156:159], v199 offset:35840
	ds_read_b128 v[160:163], v199 offset:36864
	ds_read_b128 v[174:177], v199 offset:37888
	ds_read_b128 v[178:181], v199 offset:38912
	ds_read_b128 v[182:185], v199 offset:39936
	global_load_lds_dwordx4 v[186:187], off
	s_mov_b32 m0, s46
	v_lshl_add_u64 v[186:187], s[6:7], 0, v[166:167]
	global_load_lds_dwordx4 v[186:187], off
	s_waitcnt lgkmcnt(8)
	s_barrier
	s_waitcnt lgkmcnt(0)
	v_mfma_f32_16x16x32_bf16 v[124:127], v[128:131], v[144:147], v[124:127]
	v_mfma_f32_16x16x32_bf16 v[92:95], v[136:139], v[144:147], v[92:95]
	v_mfma_f32_16x16x32_bf16 v[120:123], v[128:131], v[152:155], v[120:123]
	v_mfma_f32_16x16x32_bf16 v[88:91], v[136:139], v[152:155], v[88:91]
	v_mfma_f32_16x16x32_bf16 v[116:119], v[128:131], v[160:163], v[116:119]
	v_mfma_f32_16x16x32_bf16 v[84:87], v[136:139], v[160:163], v[84:87]
	v_mfma_f32_16x16x32_bf16 v[112:115], v[128:131], v[178:181], v[112:115]
	v_mfma_f32_16x16x32_bf16 v[80:83], v[136:139], v[178:181], v[80:83]
	v_mfma_f32_16x16x32_bf16 v[124:127], v[132:135], v[148:151], v[124:127]
	v_mfma_f32_16x16x32_bf16 v[92:95], v[140:143], v[148:151], v[92:95]
	v_mfma_f32_16x16x32_bf16 v[120:123], v[132:135], v[156:159], v[120:123]
	v_mfma_f32_16x16x32_bf16 v[88:91], v[140:143], v[156:159], v[88:91]
	v_mfma_f32_16x16x32_bf16 v[116:119], v[132:135], v[174:177], v[116:119]
	v_mfma_f32_16x16x32_bf16 v[84:87], v[140:143], v[174:177], v[84:87]
	v_mfma_f32_16x16x32_bf16 v[112:115], v[132:135], v[182:185], v[112:115]
	v_mfma_f32_16x16x32_bf16 v[80:83], v[140:143], v[182:185], v[80:83]
	s_barrier
	s_mov_b32 m0, s64
	v_lshl_add_u64 v[204:205], v[204:205], 0, s[0:1]
	ds_read_b128 v[186:189], v202
	ds_read_b128 v[190:193], v202 offset:1024
	ds_read_b128 v[194:197], v202 offset:2048
	ds_read_b128 v[208:211], v202 offset:3072
	global_load_lds_dwordx4 v[204:205], off
	s_mov_b32 m0, s65
	v_lshl_add_u64 v[204:205], v[212:213], 0, s[0:1]
	global_load_lds_dwordx4 v[204:205], off
	s_barrier
	s_waitcnt lgkmcnt(0)
	v_mfma_f32_16x16x32_bf16 v[60:63], v[186:189], v[144:147], v[60:63]
	v_mfma_f32_16x16x32_bf16 v[28:31], v[194:197], v[144:147], v[28:31]
	v_mfma_f32_16x16x32_bf16 v[56:59], v[186:189], v[152:155], v[56:59]
	v_mfma_f32_16x16x32_bf16 v[24:27], v[194:197], v[152:155], v[24:27]
	v_mfma_f32_16x16x32_bf16 v[52:55], v[186:189], v[160:163], v[52:55]
	v_mfma_f32_16x16x32_bf16 v[20:23], v[194:197], v[160:163], v[20:23]
	v_mfma_f32_16x16x32_bf16 v[48:51], v[186:189], v[178:181], v[48:51]
	v_mfma_f32_16x16x32_bf16 v[16:19], v[194:197], v[178:181], v[16:19]
	v_mfma_f32_16x16x32_bf16 v[60:63], v[190:193], v[148:151], v[60:63]
	v_mfma_f32_16x16x32_bf16 v[28:31], v[208:211], v[148:151], v[28:31]
	v_mfma_f32_16x16x32_bf16 v[56:59], v[190:193], v[156:159], v[56:59]
	v_mfma_f32_16x16x32_bf16 v[24:27], v[208:211], v[156:159], v[24:27]
	v_mfma_f32_16x16x32_bf16 v[52:55], v[190:193], v[174:177], v[52:55]
	v_mfma_f32_16x16x32_bf16 v[20:23], v[208:211], v[174:177], v[20:23]
	v_mfma_f32_16x16x32_bf16 v[48:51], v[190:193], v[182:185], v[48:51]
	v_mfma_f32_16x16x32_bf16 v[16:19], v[208:211], v[182:185], v[16:19]
	s_mov_b32 m0, s47
	v_lshl_add_u64 v[204:205], v[214:215], 0, s[0:1]
	s_barrier
	ds_read_b128 v[144:147], v199 offset:49152
	ds_read_b128 v[148:151], v199 offset:50176
	ds_read_b128 v[152:155], v199 offset:51200
	ds_read_b128 v[156:159], v199 offset:52224
	ds_read_b128 v[160:163], v199 offset:53248
	ds_read_b128 v[174:177], v199 offset:54272
	ds_read_b128 v[178:181], v199 offset:55296
	ds_read_b128 v[182:185], v199 offset:56320
	global_load_lds_dwordx4 v[204:205], off
	s_mov_b32 m0, s48
	v_lshl_add_u64 v[204:205], v[216:217], 0, s[0:1]
	global_load_lds_dwordx4 v[204:205], off
	s_barrier
; #define WAIT_V(n) asm volatile("s_waitcnt vmcnt(" #n ")" ::: "memory")
; #define WAIT_L(n) asm volatile("s_waitcnt lgkmcnt(" #n ")" ::: "memory")
; #define BAR __builtin_amdgcn_s_barrier()
; #define SCHED __builtin_amdgcn_sched_barrier(0)
; template <class Get, class Epi>
; DI void gemm_stream(LAS unsigned char* lds, const int K, const int ld, Get get, Epi epi) {
;     ...
;             BAR; WAIT_L(0); MMA(1, 0, At, B0); BAR; SCHED;
;             STAGE(SBo(1, 1), b3 + hstep);
;             WAIT_V(6); BAR; MMA(1, 1, At, B1); BAR;
;         }
; DI void epi_resid(const Acc& acc, const P& p, int brow, int bcol, int layer, int gch, bool from_input) {
;     ...
;     const float* gate = modv(p, layer, brow, gch);
; #pragma unroll
;     for (int bj = 0; bj < 2; ++bj)
; #pragma unroll
;         for (int n = 0; n < 2; ++n) {
;             const int c0 = bcol + bj * 128 + wc * 32 + n * 16 + fq * 4;
;             const f32x4 g = *(const f32x4*)(gate + c0);
;             f32x4 xv[2][4];
; #pragma unroll
;             for (int ai = 0; ai < 2; ++ai)
; #pragma unroll
;                 for (int m = 0; m < 4; ++m) {
;                     const int r = brow + ai * 128 + wr * 64 + m * 16 + fr;
;                     const float* sp = (from_input ? inrow(p, r) : xrow(p, r)) + c0;
;                     xv[ai][m] = *(const f32x4*)sp;
	s_waitcnt lgkmcnt(0)
	v_mfma_f32_16x16x32_bf16 v[108:111], v[128:131], v[144:147], v[108:111]
	v_mfma_f32_16x16x32_bf16 v[76:79], v[136:139], v[144:147], v[76:79]
	v_mfma_f32_16x16x32_bf16 v[104:107], v[128:131], v[152:155], v[104:107]
	v_mfma_f32_16x16x32_bf16 v[72:75], v[136:139], v[152:155], v[72:75]
	v_mfma_f32_16x16x32_bf16 v[100:103], v[128:131], v[160:163], v[100:103]
	v_mfma_f32_16x16x32_bf16 v[68:71], v[136:139], v[160:163], v[68:71]
	v_mfma_f32_16x16x32_bf16 v[96:99], v[128:131], v[178:181], v[96:99]
	v_mfma_f32_16x16x32_bf16 v[64:67], v[136:139], v[178:181], v[64:67]
	v_mfma_f32_16x16x32_bf16 v[108:111], v[132:135], v[148:151], v[108:111]
	v_mfma_f32_16x16x32_bf16 v[76:79], v[140:143], v[148:151], v[76:79]
	v_mfma_f32_16x16x32_bf16 v[104:107], v[132:135], v[156:159], v[104:107]
	v_mfma_f32_16x16x32_bf16 v[72:75], v[140:143], v[156:159], v[72:75]
	v_mfma_f32_16x16x32_bf16 v[100:103], v[132:135], v[174:177], v[100:103]
	v_mfma_f32_16x16x32_bf16 v[68:71], v[140:143], v[174:177], v[68:71]
	v_mfma_f32_16x16x32_bf16 v[96:99], v[132:135], v[182:185], v[96:99]
	v_mfma_f32_16x16x32_bf16 v[64:67], v[140:143], v[182:185], v[64:67]
	s_barrier
	s_add_u32 s6, s10, 0x100080
	s_addc_u32 s7, s11, 0
	s_mov_b32 m0, s68
	v_lshl_add_u64 v[128:129], s[6:7], 0, v[164:165]
	global_load_lds_dwordx4 v[128:129], off
	s_mov_b32 m0, s69
	v_lshl_add_u64 v[128:129], s[6:7], 0, v[166:167]
	global_load_lds_dwordx4 v[128:129], off
	s_waitcnt vmcnt(6)
	s_barrier
	v_mfma_f32_16x16x32_bf16 v[44:47], v[186:189], v[144:147], v[44:47]
	v_mfma_f32_16x16x32_bf16 v[12:15], v[194:197], v[144:147], v[12:15]
	v_mfma_f32_16x16x32_bf16 v[40:43], v[186:189], v[152:155], v[40:43]
	v_mfma_f32_16x16x32_bf16 v[8:11], v[194:197], v[152:155], v[8:11]
	v_mfma_f32_16x16x32_bf16 v[36:39], v[186:189], v[160:163], v[36:39]
	v_mfma_f32_16x16x32_bf16 v[4:7], v[194:197], v[160:163], v[4:7]
	v_mfma_f32_16x16x32_bf16 v[32:35], v[186:189], v[178:181], v[32:35]
	v_mfma_f32_16x16x32_bf16 v[0:3], v[194:197], v[178:181], v[0:3]
	v_mfma_f32_16x16x32_bf16 v[44:47], v[190:193], v[148:151], v[44:47]
	v_mfma_f32_16x16x32_bf16 v[12:15], v[208:211], v[148:151], v[12:15]
	v_mfma_f32_16x16x32_bf16 v[40:43], v[190:193], v[156:159], v[40:43]
	v_mfma_f32_16x16x32_bf16 v[8:11], v[208:211], v[156:159], v[8:11]
	v_mfma_f32_16x16x32_bf16 v[36:39], v[190:193], v[174:177], v[36:39]
	v_mfma_f32_16x16x32_bf16 v[4:7], v[208:211], v[174:177], v[4:7]
	v_mfma_f32_16x16x32_bf16 v[32:35], v[190:193], v[182:185], v[32:35]
	v_mfma_f32_16x16x32_bf16 v[0:3], v[208:211], v[182:185], v[0:3]
	s_add_i32 s16, s16, 2
	s_add_u32 s14, s14, 0x100
	s_addc_u32 s15, s15, 0
	s_cmp_gt_u32 s16, 61
	s_mov_b64 s[6:7], s[8:9]
	s_barrier
	s_cbranch_scc0 .LBB0_2670
	s_lshr_b32 s6, s3, 4
	s_lshl_b32 s3, s3, 8
	s_mulk_i32 s6, 0x1100
	s_and_b32 s3, s3, 0xf00
	s_add_i32 s3, s6, s3
	s_add_i32 s6, s3, 0x100
	s_lshl_b32 s7, s2, 8
	s_mul_hi_i32 s2, s6, 0x78787879
	s_lshr_b32 s3, s2, 31
	s_ashr_i32 s2, s2, 11
	s_add_i32 s2, s2, s3
	s_mul_i32 s3, s2, 0xffffef00
	s_mul_i32 s2, s2, 6
	s_add_i32 s3, s3, s6
	s_add_i32 s2, s2, 32
	s_cmpk_gt_i32 s3, 0xff
	v_mov_b32_e32 v132, v206
	s_cselect_b32 s2, s2, 56
	s_ashr_i32 s3, s2, 31
	v_lshrrev_b32_e32 v128, 1, v132
	v_lshrrev_b32_e32 v129, 2, v132
	s_lshl_b64 s[2:3], s[2:3], 13
	v_and_b32_e32 v128, 0x60, v128
	v_and_b32_e32 v129, 12, v129
	s_add_u32 s2, s26, s2
	v_or3_b32 v174, v128, s7, v129
	s_addc_u32 s3, s27, s3
	v_ashrrev_i32_e32 v175, 31, v174
	v_lshl_add_u64 v[192:193], v[174:175], 2, s[2:3]
	global_load_dwordx4 v[128:131], v[192:193], off
	v_ashrrev_i32_e32 v133, 2, v132
	v_and_b32_e32 v133, 0xffffffc0, v133
	v_and_or_b32 v132, v132, 15, s6
	v_add_u32_e32 v176, v132, v133
	v_mul_hi_i32 v132, v176, s54
	v_lshrrev_b32_e32 v133, 31, v132
	v_ashrrev_i32_e32 v132, 11, v132
	v_add_u32_e32 v204, v132, v133
	v_mad_i32_i24 v203, v204, s55, v176
	v_lshlrev_b32_e32 v213, 12, v204
	v_cmp_lt_i32_e64 s[18:19], s56, v203
	v_add3_u32 v190, v213, v203, s57
	s_and_saveexec_b64 s[2:3], s[18:19]
	s_xor_b64 s[6:7], exec, s[2:3]
	v_add3_u32 v132, v213, v203, s57
	s_or_saveexec_b64 s[6:7], s[6:7]
	v_mov_b64_e32 v[134:135], s[24:25]
	v_lshl_add_u32 v191, v204, 8, v203
	s_xor_b64 exec, exec, s[6:7]
	v_lshl_add_u32 v132, v204, 8, v203
	v_mov_b64_e32 v[134:135], s[36:37]
	s_or_b64 exec, exec, s[6:7]
	v_ashrrev_i32_e32 v133, 31, v132
	v_lshlrev_b64 v[132:133], 13, v[132:133]
	v_lshl_add_u64 v[132:133], v[134:135], 0, v[132:133]
	v_lshl_add_u64 v[132:133], v[174:175], 2, v[132:133]
	global_load_dwordx4 v[160:163], v[132:133], off
	v_or_b32_e32 v132, 16, v176
	v_mul_hi_i32 v133, v132, s54
	v_lshrrev_b32_e32 v134, 31, v133
	v_ashrrev_i32_e32 v133, 11, v133
	v_add_u32_e32 v208, v133, v134
	v_mad_i32_i24 v205, v208, s55, v132
	v_lshlrev_b32_e32 v218, 12, v208
	v_cmp_lt_i32_e64 s[16:17], s56, v205
	v_add3_u32 v188, v218, v205, s57
	s_and_saveexec_b64 s[2:3], s[16:17]
	s_xor_b64 s[6:7], exec, s[2:3]
	v_add3_u32 v132, v218, v205, s57
	s_or_saveexec_b64 s[6:7], s[6:7]
	v_mov_b64_e32 v[134:135], s[24:25]
	v_lshl_add_u32 v189, v208, 8, v205
	s_xor_b64 exec, exec, s[6:7]
	v_lshl_add_u32 v132, v208, 8, v205
	v_mov_b64_e32 v[134:135], s[36:37]
	s_or_b64 exec, exec, s[6:7]
	v_ashrrev_i32_e32 v133, 31, v132
	v_lshlrev_b64 v[132:133], 13, v[132:133]
	v_lshl_add_u64 v[132:133], v[134:135], 0, v[132:133]
	v_lshl_add_u64 v[132:133], v[174:175], 2, v[132:133]
	global_load_dwordx4 v[156:159], v[132:133], off
	v_or_b32_e32 v132, 32, v176
	v_mul_hi_i32 v133, v132, s54
	v_lshrrev_b32_e32 v134, 31, v133
	v_ashrrev_i32_e32 v133, 11, v133
	v_add_u32_e32 v210, v133, v134
	v_mad_i32_i24 v209, v210, s55, v132
	v_lshlrev_b32_e32 v221, 12, v210
; DI void epi_resid(const Acc& acc, const P& p, int brow, int bcol, int layer, int gch, bool from_input) {
;     ...
;             f32x4 xv[2][4];
; #pragma unroll
;             for (int ai = 0; ai < 2; ++ai)
; #pragma unroll
;                 for (int m = 0; m < 4; ++m) {
;                     const int r = brow + ai * 128 + wr * 64 + m * 16 + fr;
;                     const float* sp = (from_input ? inrow(p, r) : xrow(p, r)) + c0;
;                     xv[ai][m] = *(const f32x4*)sp;
	v_cmp_lt_i32_e64 s[14:15], s56, v209
	v_add3_u32 v186, v221, v209, s57
	s_and_saveexec_b64 s[2:3], s[14:15]
	s_xor_b64 s[6:7], exec, s[2:3]
	v_add3_u32 v132, v221, v209, s57
	s_or_saveexec_b64 s[6:7], s[6:7]
	v_mov_b64_e32 v[134:135], s[24:25]
	v_lshl_add_u32 v187, v210, 8, v209
	s_xor_b64 exec, exec, s[6:7]
	v_lshl_add_u32 v132, v210, 8, v209
	v_mov_b64_e32 v[134:135], s[36:37]
	s_or_b64 exec, exec, s[6:7]
	v_ashrrev_i32_e32 v133, 31, v132
	v_lshlrev_b64 v[132:133], 13, v[132:133]
	v_lshl_add_u64 v[132:133], v[134:135], 0, v[132:133]
	v_lshl_add_u64 v[132:133], v[174:175], 2, v[132:133]
	global_load_dwordx4 v[152:155], v[132:133], off
	v_or_b32_e32 v132, 48, v176
	v_mul_hi_i32 v133, v132, s54
	v_lshrrev_b32_e32 v134, 31, v133
	v_ashrrev_i32_e32 v133, 11, v133
	v_add_u32_e32 v212, v133, v134
	v_mad_i32_i24 v211, v212, s55, v132
	v_lshlrev_b32_e32 v224, 12, v212
	v_cmp_lt_i32_e64 s[12:13], s56, v211
	v_add3_u32 v184, v224, v211, s57
	s_and_saveexec_b64 s[2:3], s[12:13]
	s_xor_b64 s[6:7], exec, s[2:3]
	v_add3_u32 v132, v224, v211, s57
	s_or_saveexec_b64 s[6:7], s[6:7]
	v_mov_b64_e32 v[134:135], s[24:25]
	v_lshl_add_u32 v185, v212, 8, v211
	s_xor_b64 exec, exec, s[6:7]
	v_lshl_add_u32 v132, v212, 8, v211
	v_mov_b64_e32 v[134:135], s[36:37]
	s_or_b64 exec, exec, s[6:7]
	v_ashrrev_i32_e32 v133, 31, v132
	v_lshlrev_b64 v[132:133], 13, v[132:133]
	v_lshl_add_u64 v[132:133], v[134:135], 0, v[132:133]
	v_lshl_add_u64 v[132:133], v[174:175], 2, v[132:133]
	global_load_dwordx4 v[148:151], v[132:133], off
	v_add_u32_e32 v132, 0x80, v176
	v_mul_hi_i32 v133, v132, s54
	v_lshrrev_b32_e32 v134, 31, v133
	v_ashrrev_i32_e32 v133, 11, v133
	v_add_u32_e32 v215, v133, v134
	v_mad_i32_i24 v214, v215, s55, v132
	v_lshlrev_b32_e32 v225, 12, v215
	v_cmp_lt_i32_e64 s[10:11], s56, v214
	v_add3_u32 v182, v225, v214, s57
	s_and_saveexec_b64 s[2:3], s[10:11]
	s_xor_b64 s[6:7], exec, s[2:3]
	v_add3_u32 v132, v225, v214, s57
	s_or_saveexec_b64 s[6:7], s[6:7]
	v_mov_b64_e32 v[134:135], s[24:25]
	v_lshl_add_u32 v183, v215, 8, v214
	s_xor_b64 exec, exec, s[6:7]
	v_lshl_add_u32 v132, v215, 8, v214
	v_mov_b64_e32 v[134:135], s[36:37]
	s_or_b64 exec, exec, s[6:7]
	v_ashrrev_i32_e32 v133, 31, v132
	v_lshlrev_b64 v[132:133], 13, v[132:133]
	v_lshl_add_u64 v[132:133], v[134:135], 0, v[132:133]
	v_lshl_add_u64 v[132:133], v[174:175], 2, v[132:133]
	global_load_dwordx4 v[144:147], v[132:133], off
	v_add_u32_e32 v132, 0x90, v176
	v_mul_hi_i32 v133, v132, s54
	v_lshrrev_b32_e32 v134, 31, v133
	v_ashrrev_i32_e32 v133, 11, v133
	v_add_u32_e32 v217, v133, v134
	v_mad_i32_i24 v216, v217, s55, v132
	v_lshlrev_b32_e32 v226, 12, v217
	v_cmp_lt_i32_e64 s[8:9], s56, v216
	v_add3_u32 v180, v226, v216, s57
	s_and_saveexec_b64 s[2:3], s[8:9]
	s_xor_b64 s[6:7], exec, s[2:3]
	v_add3_u32 v132, v226, v216, s57
	s_or_saveexec_b64 s[6:7], s[6:7]
	v_mov_b64_e32 v[134:135], s[24:25]
	v_lshl_add_u32 v181, v217, 8, v216
	s_xor_b64 exec, exec, s[6:7]
	v_lshl_add_u32 v132, v217, 8, v216
	v_mov_b64_e32 v[134:135], s[36:37]
	s_or_b64 exec, exec, s[6:7]
	v_ashrrev_i32_e32 v133, 31, v132
	v_lshlrev_b64 v[132:133], 13, v[132:133]
	v_lshl_add_u64 v[132:133], v[134:135], 0, v[132:133]
	v_lshl_add_u64 v[132:133], v[174:175], 2, v[132:133]
	global_load_dwordx4 v[140:143], v[132:133], off
	v_add_u32_e32 v132, 0xa0, v176
	v_mul_hi_i32 v133, v132, s54
	v_lshrrev_b32_e32 v134, 31, v133
	v_ashrrev_i32_e32 v133, 11, v133
	v_add_u32_e32 v220, v133, v134
	v_mad_i32_i24 v219, v220, s55, v132
	v_lshlrev_b32_e32 v227, 12, v220
	v_cmp_lt_i32_e64 s[6:7], s56, v219
	v_add3_u32 v178, v227, v219, s57
	s_and_saveexec_b64 s[2:3], s[6:7]
	s_xor_b64 s[42:43], exec, s[2:3]
	v_add3_u32 v132, v227, v219, s57
	s_or_saveexec_b64 s[42:43], s[42:43]
	v_mov_b64_e32 v[134:135], s[24:25]
	v_lshl_add_u32 v179, v220, 8, v219
	s_xor_b64 exec, exec, s[42:43]
	v_lshl_add_u32 v132, v220, 8, v219
	v_mov_b64_e32 v[134:135], s[36:37]
	s_or_b64 exec, exec, s[42:43]
	v_ashrrev_i32_e32 v133, 31, v132
	v_lshlrev_b64 v[132:133], 13, v[132:133]
	v_lshl_add_u64 v[132:133], v[134:135], 0, v[132:133]
	v_lshl_add_u64 v[132:133], v[174:175], 2, v[132:133]
	global_load_dwordx4 v[136:139], v[132:133], off
	v_add_u32_e32 v132, 0xb0, v176
	v_mul_hi_i32 v133, v132, s54
	v_lshrrev_b32_e32 v134, 31, v133
	v_ashrrev_i32_e32 v133, 11, v133
	v_add_u32_e32 v223, v133, v134
	v_mad_i32_i24 v222, v223, s55, v132
	v_lshlrev_b32_e32 v228, 12, v223
	v_cmp_lt_i32_e32 vcc, s56, v222
	v_add3_u32 v176, v228, v222, s57
	s_and_saveexec_b64 s[2:3], vcc
	s_xor_b64 s[42:43], exec, s[2:3]
	v_add3_u32 v132, v228, v222, s57
	s_or_saveexec_b64 s[42:43], s[42:43]
	v_mov_b64_e32 v[134:135], s[24:25]
	v_lshl_add_u32 v177, v223, 8, v222
	s_xor_b64 exec, exec, s[42:43]
	v_lshl_add_u32 v132, v223, 8, v222
	v_mov_b64_e32 v[134:135], s[36:37]
	s_or_b64 exec, exec, s[42:43]
	v_ashrrev_i32_e32 v133, 31, v132
	v_lshlrev_b64 v[132:133], 13, v[132:133]
	v_lshl_add_u64 v[132:133], v[134:135], 0, v[132:133]
	v_lshl_add_u64 v[132:133], v[174:175], 2, v[132:133]
	global_load_dwordx4 v[132:135], v[132:133], off
	s_and_saveexec_b64 s[2:3], s[18:19]
	s_xor_b64 s[42:43], exec, s[2:3]
	v_add3_u32 v194, v213, v203, s57
	s_or_saveexec_b64 s[42:43], s[42:43]
	v_mov_b64_e32 v[196:197], s[24:25]
	s_xor_b64 exec, exec, s[42:43]
	v_lshl_add_u32 v194, v204, 8, v203
	v_mov_b64_e32 v[196:197], s[36:37]
	s_or_b64 exec, exec, s[42:43]
	v_ashrrev_i32_e32 v195, 31, v194
	s_waitcnt vmcnt(0)
; DI void epi_resid(const Acc& acc, const P& p, int brow, int bcol, int layer, int gch, bool from_input) {
;     ...
;     for (int bj = 0; bj < 2; ++bj)
; #pragma unroll
;         for (int n = 0; n < 2; ++n) {
;             const int c0 = bcol + bj * 128 + wc * 32 + n * 16 + fq * 4;
;             const f32x4 g = *(const f32x4*)(gate + c0);
;             f32x4 xv[2][4];
; #pragma unroll
;             for (int ai = 0; ai < 2; ++ai)
; #pragma unroll
;                 for (int m = 0; m < 4; ++m) {
;                     const int r = brow + ai * 128 + wr * 64 + m * 16 + fr;
;                     const float* sp = (from_input ? inrow(p, r) : xrow(p, r)) + c0;
;                     xv[ai][m] = *(const f32x4*)sp;
;                 }
;             __builtin_amdgcn_sched_barrier(0);
; #pragma unroll
;             for (int ai = 0; ai < 2; ++ai)
; #pragma unroll
;                 for (int m = 0; m < 4; ++m) {
;                     const int r = brow + ai * 128 + wr * 64 + m * 16 + fr;
;                     *(f32x4*)(xrow(p, r) + c0) = xv[ai][m] + g * acc[ai][bj][m][n];
;                 }
;             __builtin_amdgcn_sched_barrier(0);
;         }
	v_pk_fma_f32 v[124:125], v[124:125], v[128:129], v[160:161]
	v_lshlrev_b64 v[160:161], 13, v[194:195]
	v_lshl_add_u64 v[160:161], v[196:197], 0, v[160:161]
	v_pk_fma_f32 v[126:127], v[126:127], v[130:131], v[162:163]
	v_lshl_add_u64 v[160:161], v[174:175], 2, v[160:161]
	global_store_dwordx4 v[160:161], v[124:127], off
	s_and_saveexec_b64 s[2:3], s[16:17]
	s_xor_b64 s[42:43], exec, s[2:3]
	v_add3_u32 v124, v218, v205, s57
	s_or_saveexec_b64 s[42:43], s[42:43]
	v_mov_b64_e32 v[126:127], s[24:25]
	s_xor_b64 exec, exec, s[42:43]
	v_lshl_add_u32 v124, v208, 8, v205
	v_mov_b64_e32 v[126:127], s[36:37]
	s_or_b64 exec, exec, s[42:43]
	v_ashrrev_i32_e32 v125, 31, v124
	v_lshlrev_b64 v[124:125], 13, v[124:125]
	v_lshl_add_u64 v[124:125], v[126:127], 0, v[124:125]
	v_pk_fma_f32 v[122:123], v[122:123], v[130:131], v[158:159]
	v_pk_fma_f32 v[120:121], v[120:121], v[128:129], v[156:157]
	v_lshl_add_u64 v[124:125], v[174:175], 2, v[124:125]
	global_store_dwordx4 v[124:125], v[120:123], off
	s_and_saveexec_b64 s[2:3], s[14:15]
	s_xor_b64 s[42:43], exec, s[2:3]
	v_add3_u32 v120, v221, v209, s57
	s_or_saveexec_b64 s[42:43], s[42:43]
	v_mov_b64_e32 v[122:123], s[24:25]
	s_xor_b64 exec, exec, s[42:43]
	v_lshl_add_u32 v120, v210, 8, v209
	v_mov_b64_e32 v[122:123], s[36:37]
	s_or_b64 exec, exec, s[42:43]
	v_ashrrev_i32_e32 v121, 31, v120
	v_lshlrev_b64 v[120:121], 13, v[120:121]
	v_lshl_add_u64 v[120:121], v[122:123], 0, v[120:121]
	v_pk_fma_f32 v[118:119], v[118:119], v[130:131], v[154:155]
	v_pk_fma_f32 v[116:117], v[116:117], v[128:129], v[152:153]
	v_lshl_add_u64 v[120:121], v[174:175], 2, v[120:121]
	global_store_dwordx4 v[120:121], v[116:119], off
	s_and_saveexec_b64 s[2:3], s[12:13]
	s_xor_b64 s[42:43], exec, s[2:3]
	v_add3_u32 v116, v224, v211, s57
	s_or_saveexec_b64 s[42:43], s[42:43]
	v_mov_b64_e32 v[118:119], s[24:25]
	s_xor_b64 exec, exec, s[42:43]
	v_lshl_add_u32 v116, v212, 8, v211
	v_mov_b64_e32 v[118:119], s[36:37]
	s_or_b64 exec, exec, s[42:43]
	v_ashrrev_i32_e32 v117, 31, v116
	v_lshlrev_b64 v[116:117], 13, v[116:117]
	v_lshl_add_u64 v[116:117], v[118:119], 0, v[116:117]
	v_pk_fma_f32 v[114:115], v[114:115], v[130:131], v[150:151]
	v_pk_fma_f32 v[112:113], v[112:113], v[128:129], v[148:149]
	v_lshl_add_u64 v[116:117], v[174:175], 2, v[116:117]
	global_store_dwordx4 v[116:117], v[112:115], off
	s_and_saveexec_b64 s[2:3], s[10:11]
	s_xor_b64 s[42:43], exec, s[2:3]
	v_add3_u32 v112, v225, v214, s57
	s_or_saveexec_b64 s[42:43], s[42:43]
	v_mov_b64_e32 v[114:115], s[24:25]
	s_xor_b64 exec, exec, s[42:43]
	v_lshl_add_u32 v112, v215, 8, v214
	v_mov_b64_e32 v[114:115], s[36:37]
	s_or_b64 exec, exec, s[42:43]
	v_ashrrev_i32_e32 v113, 31, v112
	v_lshlrev_b64 v[112:113], 13, v[112:113]
	v_lshl_add_u64 v[112:113], v[114:115], 0, v[112:113]
	v_pk_fma_f32 v[110:111], v[110:111], v[130:131], v[146:147]
	v_pk_fma_f32 v[108:109], v[108:109], v[128:129], v[144:145]
	v_lshl_add_u64 v[112:113], v[174:175], 2, v[112:113]
	global_store_dwordx4 v[112:113], v[108:111], off
	s_and_saveexec_b64 s[2:3], s[8:9]
	s_xor_b64 s[42:43], exec, s[2:3]
	v_add3_u32 v108, v226, v216, s57
	s_or_saveexec_b64 s[42:43], s[42:43]
	v_mov_b64_e32 v[110:111], s[24:25]
	s_xor_b64 exec, exec, s[42:43]
	v_lshl_add_u32 v108, v217, 8, v216
	v_mov_b64_e32 v[110:111], s[36:37]
	s_or_b64 exec, exec, s[42:43]
	v_ashrrev_i32_e32 v109, 31, v108
	v_lshlrev_b64 v[108:109], 13, v[108:109]
	v_lshl_add_u64 v[108:109], v[110:111], 0, v[108:109]
	v_pk_fma_f32 v[106:107], v[106:107], v[130:131], v[142:143]
	v_pk_fma_f32 v[104:105], v[104:105], v[128:129], v[140:141]
	v_lshl_add_u64 v[108:109], v[174:175], 2, v[108:109]
	global_store_dwordx4 v[108:109], v[104:107], off
	s_and_saveexec_b64 s[2:3], s[6:7]
	s_xor_b64 s[42:43], exec, s[2:3]
	v_add3_u32 v104, v227, v219, s57
	s_or_saveexec_b64 s[42:43], s[42:43]
	v_mov_b64_e32 v[106:107], s[24:25]
	s_xor_b64 exec, exec, s[42:43]
	v_lshl_add_u32 v104, v220, 8, v219
	v_mov_b64_e32 v[106:107], s[36:37]
	s_or_b64 exec, exec, s[42:43]
	v_ashrrev_i32_e32 v105, 31, v104
	v_lshlrev_b64 v[104:105], 13, v[104:105]
	v_lshl_add_u64 v[104:105], v[106:107], 0, v[104:105]
	v_pk_fma_f32 v[102:103], v[102:103], v[130:131], v[138:139]
	v_pk_fma_f32 v[100:101], v[100:101], v[128:129], v[136:137]
	v_lshl_add_u64 v[104:105], v[174:175], 2, v[104:105]
	global_store_dwordx4 v[104:105], v[100:103], off
	s_and_saveexec_b64 s[2:3], vcc
	s_xor_b64 s[42:43], exec, s[2:3]
	v_add3_u32 v100, v228, v222, s57
	s_or_saveexec_b64 s[42:43], s[42:43]
	v_mov_b64_e32 v[102:103], s[24:25]
	s_xor_b64 exec, exec, s[42:43]
	v_lshl_add_u32 v100, v223, 8, v222
	v_mov_b64_e32 v[102:103], s[36:37]
	s_or_b64 exec, exec, s[42:43]
	v_ashrrev_i32_e32 v101, 31, v100
	v_lshlrev_b64 v[100:101], 13, v[100:101]
	v_lshl_add_u64 v[100:101], v[102:103], 0, v[100:101]
	v_pk_fma_f32 v[98:99], v[98:99], v[130:131], v[134:135]
	v_pk_fma_f32 v[96:97], v[96:97], v[128:129], v[132:133]
	v_lshl_add_u64 v[100:101], v[174:175], 2, v[100:101]
	global_store_dwordx4 v[100:101], v[96:99], off
	global_load_dwordx4 v[96:99], v[192:193], off offset:64
	s_and_saveexec_b64 s[2:3], s[18:19]
	s_xor_b64 s[42:43], exec, s[2:3]
	v_add3_u32 v100, v213, v203, s57
	s_or_saveexec_b64 s[42:43], s[42:43]
	v_mov_b64_e32 v[102:103], s[24:25]
	s_xor_b64 exec, exec, s[42:43]
	v_lshl_add_u32 v100, v204, 8, v203
	v_mov_b64_e32 v[102:103], s[36:37]
	s_or_b64 exec, exec, s[42:43]
	v_ashrrev_i32_e32 v101, 31, v100
	v_lshlrev_b64 v[100:101], 13, v[100:101]
	v_lshl_add_u64 v[100:101], v[102:103], 0, v[100:101]
	v_lshl_add_u64 v[100:101], v[174:175], 2, v[100:101]
	global_load_dwordx4 v[128:131], v[100:101], off offset:64
	s_and_saveexec_b64 s[2:3], s[16:17]
; DI void epi_resid(const Acc& acc, const P& p, int brow, int bcol, int layer, int gch, bool from_input) {
;     ...
;     for (int bj = 0; bj < 2; ++bj)
; #pragma unroll
;         for (int n = 0; n < 2; ++n) {
;             const int c0 = bcol + bj * 128 + wc * 32 + n * 16 + fq * 4;
;             const f32x4 g = *(const f32x4*)(gate + c0);
;             f32x4 xv[2][4];
; #pragma unroll
;             for (int ai = 0; ai < 2; ++ai)
; #pragma unroll
;                 for (int m = 0; m < 4; ++m) {
;                     const int r = brow + ai * 128 + wr * 64 + m * 16 + fr;
;                     const float* sp = (from_input ? inrow(p, r) : xrow(p, r)) + c0;
;                     xv[ai][m] = *(const f32x4*)sp;
;                 }
;             __builtin_amdgcn_sched_barrier(0);
; #pragma unroll
;             for (int ai = 0; ai < 2; ++ai)
; #pragma unroll
;                 for (int m = 0; m < 4; ++m) {
;                     const int r = brow + ai * 128 + wr * 64 + m * 16 + fr;
;                     *(f32x4*)(xrow(p, r) + c0) = xv[ai][m] + g * acc[ai][bj][m][n];
;                 }
;             __builtin_amdgcn_sched_barrier(0);
;         }
	s_xor_b64 s[42:43], exec, s[2:3]
	v_add3_u32 v100, v218, v205, s57
	s_or_saveexec_b64 s[42:43], s[42:43]
	v_mov_b64_e32 v[102:103], s[24:25]
	s_xor_b64 exec, exec, s[42:43]
	v_lshl_add_u32 v100, v208, 8, v205
	v_mov_b64_e32 v[102:103], s[36:37]
	s_or_b64 exec, exec, s[42:43]
	v_ashrrev_i32_e32 v101, 31, v100
	v_lshlrev_b64 v[100:101], 13, v[100:101]
	v_lshl_add_u64 v[100:101], v[102:103], 0, v[100:101]
	v_lshl_add_u64 v[100:101], v[174:175], 2, v[100:101]
	global_load_dwordx4 v[124:127], v[100:101], off offset:64
	s_and_saveexec_b64 s[2:3], s[14:15]
	s_xor_b64 s[42:43], exec, s[2:3]
	v_add3_u32 v100, v221, v209, s57
	s_or_saveexec_b64 s[42:43], s[42:43]
	v_mov_b64_e32 v[102:103], s[24:25]
	s_xor_b64 exec, exec, s[42:43]
	v_lshl_add_u32 v100, v210, 8, v209
	v_mov_b64_e32 v[102:103], s[36:37]
	s_or_b64 exec, exec, s[42:43]
	v_ashrrev_i32_e32 v101, 31, v100
	v_lshlrev_b64 v[100:101], 13, v[100:101]
	v_lshl_add_u64 v[100:101], v[102:103], 0, v[100:101]
	v_lshl_add_u64 v[100:101], v[174:175], 2, v[100:101]
	global_load_dwordx4 v[120:123], v[100:101], off offset:64
	s_and_saveexec_b64 s[2:3], s[12:13]
	s_xor_b64 s[42:43], exec, s[2:3]
	v_add3_u32 v100, v224, v211, s57
	s_or_saveexec_b64 s[42:43], s[42:43]
	v_mov_b64_e32 v[102:103], s[24:25]
	s_xor_b64 exec, exec, s[42:43]
	v_lshl_add_u32 v100, v212, 8, v211
	v_mov_b64_e32 v[102:103], s[36:37]
	s_or_b64 exec, exec, s[42:43]
	v_ashrrev_i32_e32 v101, 31, v100
	v_lshlrev_b64 v[100:101], 13, v[100:101]
	v_lshl_add_u64 v[100:101], v[102:103], 0, v[100:101]
	v_lshl_add_u64 v[100:101], v[174:175], 2, v[100:101]
	global_load_dwordx4 v[116:119], v[100:101], off offset:64
	s_and_saveexec_b64 s[2:3], s[10:11]
	s_xor_b64 s[42:43], exec, s[2:3]
	v_add3_u32 v100, v225, v214, s57
	s_or_saveexec_b64 s[42:43], s[42:43]
	v_mov_b64_e32 v[102:103], s[24:25]
	s_xor_b64 exec, exec, s[42:43]
	v_lshl_add_u32 v100, v215, 8, v214
	v_mov_b64_e32 v[102:103], s[36:37]
	s_or_b64 exec, exec, s[42:43]
	v_ashrrev_i32_e32 v101, 31, v100
	v_lshlrev_b64 v[100:101], 13, v[100:101]
	v_lshl_add_u64 v[100:101], v[102:103], 0, v[100:101]
	v_lshl_add_u64 v[100:101], v[174:175], 2, v[100:101]
	global_load_dwordx4 v[112:115], v[100:101], off offset:64
	s_and_saveexec_b64 s[2:3], s[8:9]
	s_xor_b64 s[42:43], exec, s[2:3]
	v_add3_u32 v100, v226, v216, s57
	s_or_saveexec_b64 s[42:43], s[42:43]
	v_mov_b64_e32 v[102:103], s[24:25]
	s_xor_b64 exec, exec, s[42:43]
	v_lshl_add_u32 v100, v217, 8, v216
	v_mov_b64_e32 v[102:103], s[36:37]
	s_or_b64 exec, exec, s[42:43]
	v_ashrrev_i32_e32 v101, 31, v100
	v_lshlrev_b64 v[100:101], 13, v[100:101]
	v_lshl_add_u64 v[100:101], v[102:103], 0, v[100:101]
	v_lshl_add_u64 v[100:101], v[174:175], 2, v[100:101]
	global_load_dwordx4 v[108:111], v[100:101], off offset:64
	s_and_saveexec_b64 s[2:3], s[6:7]
	s_xor_b64 s[42:43], exec, s[2:3]
	v_add3_u32 v100, v227, v219, s57
	s_or_saveexec_b64 s[42:43], s[42:43]
	v_mov_b64_e32 v[102:103], s[24:25]
	s_xor_b64 exec, exec, s[42:43]
	v_lshl_add_u32 v100, v220, 8, v219
	v_mov_b64_e32 v[102:103], s[36:37]
	s_or_b64 exec, exec, s[42:43]
	v_ashrrev_i32_e32 v101, 31, v100
	v_lshlrev_b64 v[100:101], 13, v[100:101]
	v_lshl_add_u64 v[100:101], v[102:103], 0, v[100:101]
	v_lshl_add_u64 v[100:101], v[174:175], 2, v[100:101]
	global_load_dwordx4 v[104:107], v[100:101], off offset:64
	s_and_saveexec_b64 s[2:3], vcc
	s_xor_b64 s[42:43], exec, s[2:3]
	v_add3_u32 v100, v228, v222, s57
	s_or_saveexec_b64 s[42:43], s[42:43]
	v_mov_b64_e32 v[102:103], s[24:25]
	s_xor_b64 exec, exec, s[42:43]
	v_lshl_add_u32 v100, v223, 8, v222
	v_mov_b64_e32 v[102:103], s[36:37]
	s_or_b64 exec, exec, s[42:43]
	v_ashrrev_i32_e32 v101, 31, v100
	v_lshlrev_b64 v[100:101], 13, v[100:101]
	v_lshl_add_u64 v[100:101], v[102:103], 0, v[100:101]
	v_lshl_add_u64 v[100:101], v[174:175], 2, v[100:101]
	global_load_dwordx4 v[100:103], v[100:101], off offset:64
	s_and_saveexec_b64 s[2:3], s[18:19]
	s_xor_b64 s[42:43], exec, s[2:3]
	v_add3_u32 v132, v213, v203, s57
	s_or_saveexec_b64 s[42:43], s[42:43]
	v_mov_b64_e32 v[134:135], s[24:25]
	s_xor_b64 exec, exec, s[42:43]
	v_lshl_add_u32 v132, v204, 8, v203
	v_mov_b64_e32 v[134:135], s[36:37]
	s_or_b64 exec, exec, s[42:43]
	v_ashrrev_i32_e32 v133, 31, v132
	s_waitcnt vmcnt(0)
	v_pk_fma_f32 v[92:93], v[92:93], v[96:97], v[128:129]
	v_lshlrev_b64 v[128:129], 13, v[132:133]
	v_lshl_add_u64 v[128:129], v[134:135], 0, v[128:129]
	v_pk_fma_f32 v[94:95], v[94:95], v[98:99], v[130:131]
	v_lshl_add_u64 v[128:129], v[174:175], 2, v[128:129]
	global_store_dwordx4 v[128:129], v[92:95], off offset:64
	s_and_saveexec_b64 s[2:3], s[16:17]
	s_xor_b64 s[42:43], exec, s[2:3]
	v_add3_u32 v92, v218, v205, s57
	s_or_saveexec_b64 s[42:43], s[42:43]
	v_mov_b64_e32 v[94:95], s[24:25]
	s_xor_b64 exec, exec, s[42:43]
	v_lshl_add_u32 v92, v208, 8, v205
	v_mov_b64_e32 v[94:95], s[36:37]
	s_or_b64 exec, exec, s[42:43]
	v_ashrrev_i32_e32 v93, 31, v92
	v_lshlrev_b64 v[92:93], 13, v[92:93]
	v_lshl_add_u64 v[92:93], v[94:95], 0, v[92:93]
	v_pk_fma_f32 v[90:91], v[90:91], v[98:99], v[126:127]
	v_pk_fma_f32 v[88:89], v[88:89], v[96:97], v[124:125]
	v_lshl_add_u64 v[92:93], v[174:175], 2, v[92:93]
	global_store_dwordx4 v[92:93], v[88:91], off offset:64
	s_and_saveexec_b64 s[2:3], s[14:15]
	s_xor_b64 s[42:43], exec, s[2:3]
	v_add3_u32 v88, v221, v209, s57
	s_or_saveexec_b64 s[42:43], s[42:43]
	v_mov_b64_e32 v[90:91], s[24:25]
	s_xor_b64 exec, exec, s[42:43]
	v_lshl_add_u32 v88, v210, 8, v209
	v_mov_b64_e32 v[90:91], s[36:37]
	s_or_b64 exec, exec, s[42:43]
	v_ashrrev_i32_e32 v89, 31, v88
	v_lshlrev_b64 v[88:89], 13, v[88:89]
	v_lshl_add_u64 v[88:89], v[90:91], 0, v[88:89]
	v_pk_fma_f32 v[86:87], v[86:87], v[98:99], v[122:123]
; DI void epi_resid(const Acc& acc, const P& p, int brow, int bcol, int layer, int gch, bool from_input) {
;     ...
;     for (int bj = 0; bj < 2; ++bj)
; #pragma unroll
;         for (int n = 0; n < 2; ++n) {
;             const int c0 = bcol + bj * 128 + wc * 32 + n * 16 + fq * 4;
;             const f32x4 g = *(const f32x4*)(gate + c0);
;             f32x4 xv[2][4];
; #pragma unroll
;             for (int ai = 0; ai < 2; ++ai)
; #pragma unroll
;                 for (int m = 0; m < 4; ++m) {
;                     const int r = brow + ai * 128 + wr * 64 + m * 16 + fr;
;                     const float* sp = (from_input ? inrow(p, r) : xrow(p, r)) + c0;
;                     xv[ai][m] = *(const f32x4*)sp;
;                 }
;             __builtin_amdgcn_sched_barrier(0);
; #pragma unroll
;             for (int ai = 0; ai < 2; ++ai)
; #pragma unroll
;                 for (int m = 0; m < 4; ++m) {
;                     const int r = brow + ai * 128 + wr * 64 + m * 16 + fr;
;                     *(f32x4*)(xrow(p, r) + c0) = xv[ai][m] + g * acc[ai][bj][m][n];
;                 }
;             __builtin_amdgcn_sched_barrier(0);
;         }
	v_pk_fma_f32 v[84:85], v[84:85], v[96:97], v[120:121]
	v_lshl_add_u64 v[88:89], v[174:175], 2, v[88:89]
	global_store_dwordx4 v[88:89], v[84:87], off offset:64
	s_and_saveexec_b64 s[2:3], s[12:13]
	s_xor_b64 s[42:43], exec, s[2:3]
	v_add3_u32 v84, v224, v211, s57
	s_or_saveexec_b64 s[42:43], s[42:43]
	v_mov_b64_e32 v[86:87], s[24:25]
	s_xor_b64 exec, exec, s[42:43]
	v_lshl_add_u32 v84, v212, 8, v211
	v_mov_b64_e32 v[86:87], s[36:37]
	s_or_b64 exec, exec, s[42:43]
	v_ashrrev_i32_e32 v85, 31, v84
	v_lshlrev_b64 v[84:85], 13, v[84:85]
	v_lshl_add_u64 v[84:85], v[86:87], 0, v[84:85]
	v_pk_fma_f32 v[82:83], v[82:83], v[98:99], v[118:119]
	v_pk_fma_f32 v[80:81], v[80:81], v[96:97], v[116:117]
	v_lshl_add_u64 v[84:85], v[174:175], 2, v[84:85]
	global_store_dwordx4 v[84:85], v[80:83], off offset:64
	s_and_saveexec_b64 s[2:3], s[10:11]
	s_xor_b64 s[42:43], exec, s[2:3]
	v_add3_u32 v80, v225, v214, s57
	s_or_saveexec_b64 s[42:43], s[42:43]
	v_mov_b64_e32 v[82:83], s[24:25]
	s_xor_b64 exec, exec, s[42:43]
	v_lshl_add_u32 v80, v215, 8, v214
	v_mov_b64_e32 v[82:83], s[36:37]
	s_or_b64 exec, exec, s[42:43]
	v_ashrrev_i32_e32 v81, 31, v80
	v_lshlrev_b64 v[80:81], 13, v[80:81]
	v_lshl_add_u64 v[80:81], v[82:83], 0, v[80:81]
	v_pk_fma_f32 v[78:79], v[78:79], v[98:99], v[114:115]
	v_pk_fma_f32 v[76:77], v[76:77], v[96:97], v[112:113]
	v_lshl_add_u64 v[80:81], v[174:175], 2, v[80:81]
	global_store_dwordx4 v[80:81], v[76:79], off offset:64
	s_and_saveexec_b64 s[2:3], s[8:9]
	s_xor_b64 s[42:43], exec, s[2:3]
	v_add3_u32 v76, v226, v216, s57
	s_or_saveexec_b64 s[42:43], s[42:43]
	v_mov_b64_e32 v[78:79], s[24:25]
	s_xor_b64 exec, exec, s[42:43]
	v_lshl_add_u32 v76, v217, 8, v216
	v_mov_b64_e32 v[78:79], s[36:37]
	s_or_b64 exec, exec, s[42:43]
	v_ashrrev_i32_e32 v77, 31, v76
	v_lshlrev_b64 v[76:77], 13, v[76:77]
	v_lshl_add_u64 v[76:77], v[78:79], 0, v[76:77]
	v_pk_fma_f32 v[74:75], v[74:75], v[98:99], v[110:111]
	v_pk_fma_f32 v[72:73], v[72:73], v[96:97], v[108:109]
	v_lshl_add_u64 v[76:77], v[174:175], 2, v[76:77]
	global_store_dwordx4 v[76:77], v[72:75], off offset:64
	s_and_saveexec_b64 s[2:3], s[6:7]
	s_xor_b64 s[42:43], exec, s[2:3]
	v_add3_u32 v72, v227, v219, s57
	s_or_saveexec_b64 s[42:43], s[42:43]
	v_mov_b64_e32 v[74:75], s[24:25]
	s_xor_b64 exec, exec, s[42:43]
	v_lshl_add_u32 v72, v220, 8, v219
	v_mov_b64_e32 v[74:75], s[36:37]
	s_or_b64 exec, exec, s[42:43]
	v_ashrrev_i32_e32 v73, 31, v72
	v_lshlrev_b64 v[72:73], 13, v[72:73]
	v_lshl_add_u64 v[72:73], v[74:75], 0, v[72:73]
	v_pk_fma_f32 v[70:71], v[70:71], v[98:99], v[106:107]
	v_pk_fma_f32 v[68:69], v[68:69], v[96:97], v[104:105]
	v_lshl_add_u64 v[72:73], v[174:175], 2, v[72:73]
	global_store_dwordx4 v[72:73], v[68:71], off offset:64
	s_and_saveexec_b64 s[2:3], vcc
	s_xor_b64 s[42:43], exec, s[2:3]
	v_add3_u32 v68, v228, v222, s57
	s_or_saveexec_b64 s[42:43], s[42:43]
	v_mov_b64_e32 v[70:71], s[24:25]
	s_xor_b64 exec, exec, s[42:43]
	v_lshl_add_u32 v68, v223, 8, v222
	v_mov_b64_e32 v[70:71], s[36:37]
	s_or_b64 exec, exec, s[42:43]
	v_ashrrev_i32_e32 v69, 31, v68
	v_lshlrev_b64 v[68:69], 13, v[68:69]
	v_lshl_add_u64 v[68:69], v[70:71], 0, v[68:69]
	v_pk_fma_f32 v[66:67], v[66:67], v[98:99], v[102:103]
	v_pk_fma_f32 v[64:65], v[64:65], v[96:97], v[100:101]
	v_lshl_add_u64 v[68:69], v[174:175], 2, v[68:69]
	global_store_dwordx4 v[68:69], v[64:67], off offset:64
	global_load_dwordx4 v[64:67], v[192:193], off offset:512
	s_and_saveexec_b64 s[2:3], s[18:19]
	s_xor_b64 s[42:43], exec, s[2:3]
	v_add3_u32 v68, v213, v203, s57
	s_or_saveexec_b64 s[42:43], s[42:43]
	v_mov_b64_e32 v[70:71], s[24:25]
	s_xor_b64 exec, exec, s[42:43]
	v_lshl_add_u32 v68, v204, 8, v203
	v_mov_b64_e32 v[70:71], s[36:37]
	s_or_b64 exec, exec, s[42:43]
	v_ashrrev_i32_e32 v69, 31, v68
	v_lshlrev_b64 v[68:69], 13, v[68:69]
	v_lshl_add_u64 v[68:69], v[70:71], 0, v[68:69]
	v_lshl_add_u64 v[68:69], v[174:175], 2, v[68:69]
	global_load_dwordx4 v[96:99], v[68:69], off offset:512
	s_and_saveexec_b64 s[2:3], s[16:17]
	s_xor_b64 s[42:43], exec, s[2:3]
	v_add3_u32 v68, v218, v205, s57
	s_or_saveexec_b64 s[42:43], s[42:43]
	v_mov_b64_e32 v[70:71], s[24:25]
	s_xor_b64 exec, exec, s[42:43]
	v_lshl_add_u32 v68, v208, 8, v205
	v_mov_b64_e32 v[70:71], s[36:37]
	s_or_b64 exec, exec, s[42:43]
	v_ashrrev_i32_e32 v69, 31, v68
	v_lshlrev_b64 v[68:69], 13, v[68:69]
	v_lshl_add_u64 v[68:69], v[70:71], 0, v[68:69]
	v_lshl_add_u64 v[68:69], v[174:175], 2, v[68:69]
	global_load_dwordx4 v[92:95], v[68:69], off offset:512
	s_and_saveexec_b64 s[2:3], s[14:15]
	s_xor_b64 s[42:43], exec, s[2:3]
	v_add3_u32 v68, v221, v209, s57
	s_or_saveexec_b64 s[42:43], s[42:43]
	v_mov_b64_e32 v[70:71], s[24:25]
	s_xor_b64 exec, exec, s[42:43]
	v_lshl_add_u32 v68, v210, 8, v209
	v_mov_b64_e32 v[70:71], s[36:37]
	s_or_b64 exec, exec, s[42:43]
	v_ashrrev_i32_e32 v69, 31, v68
	v_lshlrev_b64 v[68:69], 13, v[68:69]
	v_lshl_add_u64 v[68:69], v[70:71], 0, v[68:69]
	v_lshl_add_u64 v[68:69], v[174:175], 2, v[68:69]
	global_load_dwordx4 v[88:91], v[68:69], off offset:512
	s_and_saveexec_b64 s[2:3], s[12:13]
	s_xor_b64 s[42:43], exec, s[2:3]
	v_add3_u32 v68, v224, v211, s57
	s_or_saveexec_b64 s[42:43], s[42:43]
	v_mov_b64_e32 v[70:71], s[24:25]
	s_xor_b64 exec, exec, s[42:43]
	v_lshl_add_u32 v68, v212, 8, v211
	v_mov_b64_e32 v[70:71], s[36:37]
	s_or_b64 exec, exec, s[42:43]
	v_ashrrev_i32_e32 v69, 31, v68
	v_lshlrev_b64 v[68:69], 13, v[68:69]
	v_lshl_add_u64 v[68:69], v[70:71], 0, v[68:69]
	v_lshl_add_u64 v[68:69], v[174:175], 2, v[68:69]
	global_load_dwordx4 v[84:87], v[68:69], off offset:512
	s_and_saveexec_b64 s[2:3], s[10:11]
	s_xor_b64 s[42:43], exec, s[2:3]
	v_add3_u32 v68, v225, v214, s57
; DI void epi_resid(const Acc& acc, const P& p, int brow, int bcol, int layer, int gch, bool from_input) {
;     ...
;     for (int bj = 0; bj < 2; ++bj)
; #pragma unroll
;         for (int n = 0; n < 2; ++n) {
;             const int c0 = bcol + bj * 128 + wc * 32 + n * 16 + fq * 4;
;             const f32x4 g = *(const f32x4*)(gate + c0);
;             f32x4 xv[2][4];
; #pragma unroll
;             for (int ai = 0; ai < 2; ++ai)
; #pragma unroll
;                 for (int m = 0; m < 4; ++m) {
;                     const int r = brow + ai * 128 + wr * 64 + m * 16 + fr;
;                     const float* sp = (from_input ? inrow(p, r) : xrow(p, r)) + c0;
;                     xv[ai][m] = *(const f32x4*)sp;
;                 }
;             __builtin_amdgcn_sched_barrier(0);
; #pragma unroll
;             for (int ai = 0; ai < 2; ++ai)
; #pragma unroll
;                 for (int m = 0; m < 4; ++m) {
;                     const int r = brow + ai * 128 + wr * 64 + m * 16 + fr;
;                     *(f32x4*)(xrow(p, r) + c0) = xv[ai][m] + g * acc[ai][bj][m][n];
;                 }
;             __builtin_amdgcn_sched_barrier(0);
;         }
	s_or_saveexec_b64 s[42:43], s[42:43]
	v_mov_b64_e32 v[70:71], s[24:25]
	s_xor_b64 exec, exec, s[42:43]
	v_lshl_add_u32 v68, v215, 8, v214
	v_mov_b64_e32 v[70:71], s[36:37]
	s_or_b64 exec, exec, s[42:43]
	v_ashrrev_i32_e32 v69, 31, v68
	v_lshlrev_b64 v[68:69], 13, v[68:69]
	v_lshl_add_u64 v[68:69], v[70:71], 0, v[68:69]
	v_lshl_add_u64 v[68:69], v[174:175], 2, v[68:69]
	global_load_dwordx4 v[80:83], v[68:69], off offset:512
	s_and_saveexec_b64 s[2:3], s[8:9]
	s_xor_b64 s[42:43], exec, s[2:3]
	v_add3_u32 v68, v226, v216, s57
	s_or_saveexec_b64 s[42:43], s[42:43]
	v_mov_b64_e32 v[70:71], s[24:25]
	s_xor_b64 exec, exec, s[42:43]
	v_lshl_add_u32 v68, v217, 8, v216
	v_mov_b64_e32 v[70:71], s[36:37]
	s_or_b64 exec, exec, s[42:43]
	v_ashrrev_i32_e32 v69, 31, v68
	v_lshlrev_b64 v[68:69], 13, v[68:69]
	v_lshl_add_u64 v[68:69], v[70:71], 0, v[68:69]
	v_lshl_add_u64 v[68:69], v[174:175], 2, v[68:69]
	global_load_dwordx4 v[76:79], v[68:69], off offset:512
	s_and_saveexec_b64 s[2:3], s[6:7]
	s_xor_b64 s[42:43], exec, s[2:3]
	v_add3_u32 v68, v227, v219, s57
	s_or_saveexec_b64 s[42:43], s[42:43]
	v_mov_b64_e32 v[70:71], s[24:25]
	s_xor_b64 exec, exec, s[42:43]
	v_lshl_add_u32 v68, v220, 8, v219
	v_mov_b64_e32 v[70:71], s[36:37]
	s_or_b64 exec, exec, s[42:43]
	v_ashrrev_i32_e32 v69, 31, v68
	v_lshlrev_b64 v[68:69], 13, v[68:69]
	v_lshl_add_u64 v[68:69], v[70:71], 0, v[68:69]
	v_lshl_add_u64 v[68:69], v[174:175], 2, v[68:69]
	global_load_dwordx4 v[72:75], v[68:69], off offset:512
	s_and_saveexec_b64 s[2:3], vcc
	s_xor_b64 s[42:43], exec, s[2:3]
	v_add3_u32 v68, v228, v222, s57
	s_or_saveexec_b64 s[42:43], s[42:43]
	v_mov_b64_e32 v[70:71], s[24:25]
	s_xor_b64 exec, exec, s[42:43]
	v_lshl_add_u32 v68, v223, 8, v222
	v_mov_b64_e32 v[70:71], s[36:37]
	s_or_b64 exec, exec, s[42:43]
	v_ashrrev_i32_e32 v69, 31, v68
	v_lshlrev_b64 v[68:69], 13, v[68:69]
	v_lshl_add_u64 v[68:69], v[70:71], 0, v[68:69]
	v_lshl_add_u64 v[68:69], v[174:175], 2, v[68:69]
	global_load_dwordx4 v[68:71], v[68:69], off offset:512
	s_and_saveexec_b64 s[2:3], s[18:19]
	s_xor_b64 s[42:43], exec, s[2:3]
	v_add3_u32 v100, v213, v203, s57
	s_or_saveexec_b64 s[42:43], s[42:43]
	v_mov_b64_e32 v[102:103], s[24:25]
	s_xor_b64 exec, exec, s[42:43]
	v_lshl_add_u32 v100, v204, 8, v203
	v_mov_b64_e32 v[102:103], s[36:37]
	s_or_b64 exec, exec, s[42:43]
	v_ashrrev_i32_e32 v101, 31, v100
	s_waitcnt vmcnt(0)
	v_pk_fma_f32 v[60:61], v[60:61], v[64:65], v[96:97]
	v_lshlrev_b64 v[96:97], 13, v[100:101]
	v_lshl_add_u64 v[96:97], v[102:103], 0, v[96:97]
	v_pk_fma_f32 v[62:63], v[62:63], v[66:67], v[98:99]
	v_lshl_add_u64 v[96:97], v[174:175], 2, v[96:97]
	global_store_dwordx4 v[96:97], v[60:63], off offset:512
	s_and_saveexec_b64 s[2:3], s[16:17]
	s_xor_b64 s[42:43], exec, s[2:3]
	v_add3_u32 v60, v218, v205, s57
	s_or_saveexec_b64 s[42:43], s[42:43]
	v_mov_b64_e32 v[62:63], s[24:25]
	s_xor_b64 exec, exec, s[42:43]
	v_lshl_add_u32 v60, v208, 8, v205
	v_mov_b64_e32 v[62:63], s[36:37]
	s_or_b64 exec, exec, s[42:43]
	v_ashrrev_i32_e32 v61, 31, v60
	v_lshlrev_b64 v[60:61], 13, v[60:61]
	v_lshl_add_u64 v[60:61], v[62:63], 0, v[60:61]
	v_pk_fma_f32 v[58:59], v[58:59], v[66:67], v[94:95]
	v_pk_fma_f32 v[56:57], v[56:57], v[64:65], v[92:93]
	v_lshl_add_u64 v[60:61], v[174:175], 2, v[60:61]
	global_store_dwordx4 v[60:61], v[56:59], off offset:512
	s_and_saveexec_b64 s[2:3], s[14:15]
	s_xor_b64 s[42:43], exec, s[2:3]
	v_add3_u32 v56, v221, v209, s57
	s_or_saveexec_b64 s[42:43], s[42:43]
	v_mov_b64_e32 v[58:59], s[24:25]
	s_xor_b64 exec, exec, s[42:43]
	v_lshl_add_u32 v56, v210, 8, v209
	v_mov_b64_e32 v[58:59], s[36:37]
	s_or_b64 exec, exec, s[42:43]
	v_ashrrev_i32_e32 v57, 31, v56
	v_lshlrev_b64 v[56:57], 13, v[56:57]
	v_lshl_add_u64 v[56:57], v[58:59], 0, v[56:57]
	v_pk_fma_f32 v[54:55], v[54:55], v[66:67], v[90:91]
	v_pk_fma_f32 v[52:53], v[52:53], v[64:65], v[88:89]
	v_lshl_add_u64 v[56:57], v[174:175], 2, v[56:57]
	global_store_dwordx4 v[56:57], v[52:55], off offset:512
	s_and_saveexec_b64 s[2:3], s[12:13]
	s_xor_b64 s[42:43], exec, s[2:3]
	v_add3_u32 v52, v224, v211, s57
	s_or_saveexec_b64 s[42:43], s[42:43]
	v_mov_b64_e32 v[54:55], s[24:25]
	s_xor_b64 exec, exec, s[42:43]
	v_lshl_add_u32 v52, v212, 8, v211
	v_mov_b64_e32 v[54:55], s[36:37]
	s_or_b64 exec, exec, s[42:43]
	v_ashrrev_i32_e32 v53, 31, v52
	v_lshlrev_b64 v[52:53], 13, v[52:53]
	v_lshl_add_u64 v[52:53], v[54:55], 0, v[52:53]
	v_pk_fma_f32 v[50:51], v[50:51], v[66:67], v[86:87]
	v_pk_fma_f32 v[48:49], v[48:49], v[64:65], v[84:85]
	v_lshl_add_u64 v[52:53], v[174:175], 2, v[52:53]
	global_store_dwordx4 v[52:53], v[48:51], off offset:512
	s_and_saveexec_b64 s[2:3], s[10:11]
	s_xor_b64 s[42:43], exec, s[2:3]
	v_add3_u32 v48, v225, v214, s57
	s_or_saveexec_b64 s[42:43], s[42:43]
	v_mov_b64_e32 v[50:51], s[24:25]
	s_xor_b64 exec, exec, s[42:43]
	v_lshl_add_u32 v48, v215, 8, v214
	v_mov_b64_e32 v[50:51], s[36:37]
	s_or_b64 exec, exec, s[42:43]
	v_ashrrev_i32_e32 v49, 31, v48
	v_lshlrev_b64 v[48:49], 13, v[48:49]
	v_lshl_add_u64 v[48:49], v[50:51], 0, v[48:49]
	v_pk_fma_f32 v[46:47], v[46:47], v[66:67], v[82:83]
	v_pk_fma_f32 v[44:45], v[44:45], v[64:65], v[80:81]
	v_lshl_add_u64 v[48:49], v[174:175], 2, v[48:49]
	global_store_dwordx4 v[48:49], v[44:47], off offset:512
	s_and_saveexec_b64 s[2:3], s[8:9]
	s_xor_b64 s[42:43], exec, s[2:3]
	v_add3_u32 v44, v226, v216, s57
	s_or_saveexec_b64 s[42:43], s[42:43]
	v_mov_b64_e32 v[46:47], s[24:25]
	s_xor_b64 exec, exec, s[42:43]
	v_lshl_add_u32 v44, v217, 8, v216
	v_mov_b64_e32 v[46:47], s[36:37]
	s_or_b64 exec, exec, s[42:43]
	v_ashrrev_i32_e32 v45, 31, v44
	v_lshlrev_b64 v[44:45], 13, v[44:45]
; DI void epi_resid(const Acc& acc, const P& p, int brow, int bcol, int layer, int gch, bool from_input) {
;     ...
;     for (int bj = 0; bj < 2; ++bj)
; #pragma unroll
;         for (int n = 0; n < 2; ++n) {
;             const int c0 = bcol + bj * 128 + wc * 32 + n * 16 + fq * 4;
;             const f32x4 g = *(const f32x4*)(gate + c0);
;             f32x4 xv[2][4];
; #pragma unroll
;             for (int ai = 0; ai < 2; ++ai)
; #pragma unroll
;                 for (int m = 0; m < 4; ++m) {
;                     const int r = brow + ai * 128 + wr * 64 + m * 16 + fr;
;                     const float* sp = (from_input ? inrow(p, r) : xrow(p, r)) + c0;
;                     xv[ai][m] = *(const f32x4*)sp;
;                 }
;             __builtin_amdgcn_sched_barrier(0);
; #pragma unroll
;             for (int ai = 0; ai < 2; ++ai)
; #pragma unroll
;                 for (int m = 0; m < 4; ++m) {
;                     const int r = brow + ai * 128 + wr * 64 + m * 16 + fr;
;                     *(f32x4*)(xrow(p, r) + c0) = xv[ai][m] + g * acc[ai][bj][m][n];
;                 }
;             __builtin_amdgcn_sched_barrier(0);
;         }
	v_lshl_add_u64 v[44:45], v[46:47], 0, v[44:45]
	v_pk_fma_f32 v[42:43], v[42:43], v[66:67], v[78:79]
	v_pk_fma_f32 v[40:41], v[40:41], v[64:65], v[76:77]
	v_lshl_add_u64 v[44:45], v[174:175], 2, v[44:45]
	global_store_dwordx4 v[44:45], v[40:43], off offset:512
	s_and_saveexec_b64 s[2:3], s[6:7]
	s_xor_b64 s[42:43], exec, s[2:3]
	v_add3_u32 v40, v227, v219, s57
	s_or_saveexec_b64 s[42:43], s[42:43]
	v_mov_b64_e32 v[42:43], s[24:25]
	s_xor_b64 exec, exec, s[42:43]
	v_lshl_add_u32 v40, v220, 8, v219
	v_mov_b64_e32 v[42:43], s[36:37]
	s_or_b64 exec, exec, s[42:43]
	v_ashrrev_i32_e32 v41, 31, v40
	v_lshlrev_b64 v[40:41], 13, v[40:41]
	v_lshl_add_u64 v[40:41], v[42:43], 0, v[40:41]
	v_pk_fma_f32 v[38:39], v[38:39], v[66:67], v[74:75]
	v_pk_fma_f32 v[36:37], v[36:37], v[64:65], v[72:73]
	v_lshl_add_u64 v[40:41], v[174:175], 2, v[40:41]
	global_store_dwordx4 v[40:41], v[36:39], off offset:512
	s_and_saveexec_b64 s[2:3], vcc
	s_xor_b64 s[42:43], exec, s[2:3]
	v_add3_u32 v36, v228, v222, s57
	s_or_saveexec_b64 s[42:43], s[42:43]
	v_mov_b64_e32 v[38:39], s[24:25]
	s_xor_b64 exec, exec, s[42:43]
	v_lshl_add_u32 v36, v223, 8, v222
	v_mov_b64_e32 v[38:39], s[36:37]
	s_or_b64 exec, exec, s[42:43]
	v_ashrrev_i32_e32 v37, 31, v36
	v_lshlrev_b64 v[36:37], 13, v[36:37]
	v_lshl_add_u64 v[36:37], v[38:39], 0, v[36:37]
	v_pk_fma_f32 v[34:35], v[34:35], v[66:67], v[70:71]
	v_pk_fma_f32 v[32:33], v[32:33], v[64:65], v[68:69]
	v_lshl_add_u64 v[36:37], v[174:175], 2, v[36:37]
	global_store_dwordx4 v[36:37], v[32:35], off offset:512
	global_load_dwordx4 v[32:35], v[192:193], off offset:576
	s_and_saveexec_b64 s[2:3], s[18:19]
	s_xor_b64 s[42:43], exec, s[2:3]
	v_add3_u32 v36, v213, v203, s57
	s_or_saveexec_b64 s[42:43], s[42:43]
	v_mov_b64_e32 v[38:39], s[24:25]
	s_xor_b64 exec, exec, s[42:43]
	v_lshl_add_u32 v36, v204, 8, v203
	v_mov_b64_e32 v[38:39], s[36:37]
	s_or_b64 exec, exec, s[42:43]
	v_ashrrev_i32_e32 v37, 31, v36
	v_lshlrev_b64 v[36:37], 13, v[36:37]
	v_lshl_add_u64 v[36:37], v[38:39], 0, v[36:37]
	v_lshl_add_u64 v[36:37], v[174:175], 2, v[36:37]
	global_load_dwordx4 v[64:67], v[36:37], off offset:576
	s_and_saveexec_b64 s[2:3], s[16:17]
	s_xor_b64 s[42:43], exec, s[2:3]
	v_add3_u32 v36, v218, v205, s57
	s_or_saveexec_b64 s[42:43], s[42:43]
	v_mov_b64_e32 v[38:39], s[24:25]
	s_xor_b64 exec, exec, s[42:43]
	v_lshl_add_u32 v36, v208, 8, v205
	v_mov_b64_e32 v[38:39], s[36:37]
	s_or_b64 exec, exec, s[42:43]
	v_ashrrev_i32_e32 v37, 31, v36
	v_lshlrev_b64 v[36:37], 13, v[36:37]
	v_lshl_add_u64 v[36:37], v[38:39], 0, v[36:37]
	v_lshl_add_u64 v[36:37], v[174:175], 2, v[36:37]
	global_load_dwordx4 v[60:63], v[36:37], off offset:576
	s_and_saveexec_b64 s[2:3], s[14:15]
	s_xor_b64 s[42:43], exec, s[2:3]
	v_add3_u32 v36, v221, v209, s57
	s_or_saveexec_b64 s[42:43], s[42:43]
	v_mov_b64_e32 v[38:39], s[24:25]
	s_xor_b64 exec, exec, s[42:43]
	v_lshl_add_u32 v36, v210, 8, v209
	v_mov_b64_e32 v[38:39], s[36:37]
	s_or_b64 exec, exec, s[42:43]
	v_ashrrev_i32_e32 v37, 31, v36
	v_lshlrev_b64 v[36:37], 13, v[36:37]
	v_lshl_add_u64 v[36:37], v[38:39], 0, v[36:37]
	v_lshl_add_u64 v[36:37], v[174:175], 2, v[36:37]
	global_load_dwordx4 v[56:59], v[36:37], off offset:576
	s_and_saveexec_b64 s[2:3], s[12:13]
	s_xor_b64 s[42:43], exec, s[2:3]
	v_add3_u32 v36, v224, v211, s57
	s_or_saveexec_b64 s[42:43], s[42:43]
	v_mov_b64_e32 v[38:39], s[24:25]
	s_xor_b64 exec, exec, s[42:43]
	v_lshl_add_u32 v36, v212, 8, v211
	v_mov_b64_e32 v[38:39], s[36:37]
	s_or_b64 exec, exec, s[42:43]
	v_ashrrev_i32_e32 v37, 31, v36
	v_lshlrev_b64 v[36:37], 13, v[36:37]
	v_lshl_add_u64 v[36:37], v[38:39], 0, v[36:37]
	v_lshl_add_u64 v[36:37], v[174:175], 2, v[36:37]
	global_load_dwordx4 v[52:55], v[36:37], off offset:576
	s_and_saveexec_b64 s[2:3], s[10:11]
	s_xor_b64 s[42:43], exec, s[2:3]
	v_add3_u32 v36, v225, v214, s57
	s_or_saveexec_b64 s[42:43], s[42:43]
	v_mov_b64_e32 v[38:39], s[24:25]
	s_xor_b64 exec, exec, s[42:43]
	v_lshl_add_u32 v36, v215, 8, v214
	v_mov_b64_e32 v[38:39], s[36:37]
	s_or_b64 exec, exec, s[42:43]
	v_ashrrev_i32_e32 v37, 31, v36
	v_lshlrev_b64 v[36:37], 13, v[36:37]
	v_lshl_add_u64 v[36:37], v[38:39], 0, v[36:37]
	v_lshl_add_u64 v[36:37], v[174:175], 2, v[36:37]
	global_load_dwordx4 v[48:51], v[36:37], off offset:576
	s_and_saveexec_b64 s[2:3], s[8:9]
	s_xor_b64 s[42:43], exec, s[2:3]
	v_add3_u32 v36, v226, v216, s57
	s_or_saveexec_b64 s[42:43], s[42:43]
	v_mov_b64_e32 v[38:39], s[24:25]
	s_xor_b64 exec, exec, s[42:43]
	v_lshl_add_u32 v36, v217, 8, v216
	v_mov_b64_e32 v[38:39], s[36:37]
	s_or_b64 exec, exec, s[42:43]
	v_ashrrev_i32_e32 v37, 31, v36
	v_lshlrev_b64 v[36:37], 13, v[36:37]
	v_lshl_add_u64 v[36:37], v[38:39], 0, v[36:37]
	v_lshl_add_u64 v[36:37], v[174:175], 2, v[36:37]
	global_load_dwordx4 v[44:47], v[36:37], off offset:576
	s_and_saveexec_b64 s[2:3], s[6:7]
	s_xor_b64 s[42:43], exec, s[2:3]
	v_add3_u32 v36, v227, v219, s57
	s_or_saveexec_b64 s[42:43], s[42:43]
	v_mov_b64_e32 v[38:39], s[24:25]
	s_xor_b64 exec, exec, s[42:43]
	v_lshl_add_u32 v36, v220, 8, v219
	v_mov_b64_e32 v[38:39], s[36:37]
	s_or_b64 exec, exec, s[42:43]
	v_ashrrev_i32_e32 v37, 31, v36
	v_lshlrev_b64 v[36:37], 13, v[36:37]
	v_lshl_add_u64 v[36:37], v[38:39], 0, v[36:37]
	v_lshl_add_u64 v[36:37], v[174:175], 2, v[36:37]
	global_load_dwordx4 v[40:43], v[36:37], off offset:576
	s_and_saveexec_b64 s[2:3], vcc
	s_xor_b64 s[42:43], exec, s[2:3]
	v_add3_u32 v36, v228, v222, s57
	s_or_saveexec_b64 s[42:43], s[42:43]
	v_mov_b64_e32 v[38:39], s[24:25]
	s_xor_b64 exec, exec, s[42:43]
	v_lshl_add_u32 v36, v223, 8, v222
	v_mov_b64_e32 v[38:39], s[36:37]
	s_or_b64 exec, exec, s[42:43]
	v_ashrrev_i32_e32 v37, 31, v36
	v_lshlrev_b64 v[36:37], 13, v[36:37]
	v_lshl_add_u64 v[36:37], v[38:39], 0, v[36:37]
	v_lshl_add_u64 v[36:37], v[174:175], 2, v[36:37]
	global_load_dwordx4 v[36:39], v[36:37], off offset:576
	s_and_saveexec_b64 s[2:3], s[18:19]
	s_xor_b64 s[18:19], exec, s[2:3]
	s_or_saveexec_b64 s[18:19], s[18:19]
	v_mov_b64_e32 v[68:69], s[24:25]
	s_xor_b64 exec, exec, s[18:19]
	v_mov_b64_e32 v[68:69], s[36:37]
	v_mov_b32_e32 v190, v191
	s_or_b64 exec, exec, s[18:19]
	v_ashrrev_i32_e32 v191, 31, v190
	s_waitcnt vmcnt(0)
; DI void epi_resid(const Acc& acc, const P& p, int brow, int bcol, int layer, int gch, bool from_input) {
;     ...
; #pragma unroll
;             for (int ai = 0; ai < 2; ++ai)
; #pragma unroll
;                 for (int m = 0; m < 4; ++m) {
;                     const int r = brow + ai * 128 + wr * 64 + m * 16 + fr;
;                     *(f32x4*)(xrow(p, r) + c0) = xv[ai][m] + g * acc[ai][bj][m][n];
;                 }
	v_pk_fma_f32 v[28:29], v[28:29], v[32:33], v[64:65]
	v_lshlrev_b64 v[64:65], 13, v[190:191]
	v_lshl_add_u64 v[64:65], v[68:69], 0, v[64:65]
	v_pk_fma_f32 v[30:31], v[30:31], v[34:35], v[66:67]
	v_lshl_add_u64 v[64:65], v[174:175], 2, v[64:65]
	global_store_dwordx4 v[64:65], v[28:31], off offset:576
	s_and_saveexec_b64 s[2:3], s[16:17]
	s_xor_b64 s[16:17], exec, s[2:3]
	s_or_saveexec_b64 s[16:17], s[16:17]
	v_mov_b64_e32 v[28:29], s[24:25]
	s_xor_b64 exec, exec, s[16:17]
	v_mov_b64_e32 v[28:29], s[36:37]
	v_mov_b32_e32 v188, v189
	s_or_b64 exec, exec, s[16:17]
	v_ashrrev_i32_e32 v189, 31, v188
	v_lshlrev_b64 v[30:31], 13, v[188:189]
	v_lshl_add_u64 v[28:29], v[28:29], 0, v[30:31]
	v_pk_fma_f32 v[26:27], v[26:27], v[34:35], v[62:63]
	v_pk_fma_f32 v[24:25], v[24:25], v[32:33], v[60:61]
	v_lshl_add_u64 v[28:29], v[174:175], 2, v[28:29]
	global_store_dwordx4 v[28:29], v[24:27], off offset:576
	s_and_saveexec_b64 s[2:3], s[14:15]
	s_xor_b64 s[14:15], exec, s[2:3]
	s_or_saveexec_b64 s[14:15], s[14:15]
	v_mov_b64_e32 v[24:25], s[24:25]
	s_xor_b64 exec, exec, s[14:15]
	v_mov_b64_e32 v[24:25], s[36:37]
	v_mov_b32_e32 v186, v187
	s_or_b64 exec, exec, s[14:15]
	v_ashrrev_i32_e32 v187, 31, v186
	v_lshlrev_b64 v[26:27], 13, v[186:187]
	v_lshl_add_u64 v[24:25], v[24:25], 0, v[26:27]
	v_pk_fma_f32 v[22:23], v[22:23], v[34:35], v[58:59]
	v_pk_fma_f32 v[20:21], v[20:21], v[32:33], v[56:57]
	v_lshl_add_u64 v[24:25], v[174:175], 2, v[24:25]
	global_store_dwordx4 v[24:25], v[20:23], off offset:576
	s_and_saveexec_b64 s[2:3], s[12:13]
	s_xor_b64 s[12:13], exec, s[2:3]
	s_or_saveexec_b64 s[12:13], s[12:13]
	v_mov_b64_e32 v[20:21], s[24:25]
	s_xor_b64 exec, exec, s[12:13]
	v_mov_b64_e32 v[20:21], s[36:37]
	v_mov_b32_e32 v184, v185
	s_or_b64 exec, exec, s[12:13]
	v_ashrrev_i32_e32 v185, 31, v184
	v_lshlrev_b64 v[22:23], 13, v[184:185]
	v_lshl_add_u64 v[20:21], v[20:21], 0, v[22:23]
	v_pk_fma_f32 v[18:19], v[18:19], v[34:35], v[54:55]
	v_pk_fma_f32 v[16:17], v[16:17], v[32:33], v[52:53]
	v_lshl_add_u64 v[20:21], v[174:175], 2, v[20:21]
	global_store_dwordx4 v[20:21], v[16:19], off offset:576
	s_and_saveexec_b64 s[2:3], s[10:11]
	s_xor_b64 s[10:11], exec, s[2:3]
	s_or_saveexec_b64 s[10:11], s[10:11]
	v_mov_b64_e32 v[16:17], s[24:25]
	s_xor_b64 exec, exec, s[10:11]
	v_mov_b64_e32 v[16:17], s[36:37]
	v_mov_b32_e32 v182, v183
	s_or_b64 exec, exec, s[10:11]
	v_ashrrev_i32_e32 v183, 31, v182
	v_lshlrev_b64 v[18:19], 13, v[182:183]
	v_lshl_add_u64 v[16:17], v[16:17], 0, v[18:19]
	v_pk_fma_f32 v[14:15], v[14:15], v[34:35], v[50:51]
	v_pk_fma_f32 v[12:13], v[12:13], v[32:33], v[48:49]
	v_lshl_add_u64 v[16:17], v[174:175], 2, v[16:17]
	global_store_dwordx4 v[16:17], v[12:15], off offset:576
	s_and_saveexec_b64 s[2:3], s[8:9]
	s_xor_b64 s[8:9], exec, s[2:3]
	s_or_saveexec_b64 s[8:9], s[8:9]
	v_mov_b64_e32 v[12:13], s[24:25]
	s_xor_b64 exec, exec, s[8:9]
	v_mov_b64_e32 v[12:13], s[36:37]
	v_mov_b32_e32 v180, v181
	s_or_b64 exec, exec, s[8:9]
	v_ashrrev_i32_e32 v181, 31, v180
	v_lshlrev_b64 v[14:15], 13, v[180:181]
	v_lshl_add_u64 v[12:13], v[12:13], 0, v[14:15]
	v_pk_fma_f32 v[10:11], v[10:11], v[34:35], v[46:47]
	v_pk_fma_f32 v[8:9], v[8:9], v[32:33], v[44:45]
	v_lshl_add_u64 v[12:13], v[174:175], 2, v[12:13]
	global_store_dwordx4 v[12:13], v[8:11], off offset:576
	s_and_saveexec_b64 s[2:3], s[6:7]
	s_xor_b64 s[6:7], exec, s[2:3]
	s_or_saveexec_b64 s[6:7], s[6:7]
	v_mov_b64_e32 v[8:9], s[24:25]
	s_xor_b64 exec, exec, s[6:7]
	v_mov_b64_e32 v[8:9], s[36:37]
	v_mov_b32_e32 v178, v179
	s_or_b64 exec, exec, s[6:7]
	v_ashrrev_i32_e32 v179, 31, v178
	v_lshlrev_b64 v[10:11], 13, v[178:179]
	v_lshl_add_u64 v[8:9], v[8:9], 0, v[10:11]
	v_pk_fma_f32 v[6:7], v[6:7], v[34:35], v[42:43]
	v_pk_fma_f32 v[4:5], v[4:5], v[32:33], v[40:41]
	v_lshl_add_u64 v[8:9], v[174:175], 2, v[8:9]
	global_store_dwordx4 v[8:9], v[4:7], off offset:576
	s_and_saveexec_b64 s[2:3], vcc
	s_xor_b64 s[6:7], exec, s[2:3]
	s_or_saveexec_b64 s[6:7], s[6:7]
	v_mov_b64_e32 v[4:5], s[24:25]
	s_xor_b64 exec, exec, s[6:7]
	s_cbranch_execz .LBB0_2666
	v_mov_b64_e32 v[4:5], s[36:37]
	v_mov_b32_e32 v176, v177
	s_branch .LBB0_2666

; #define WAIT_V(n) asm volatile("s_waitcnt vmcnt(" #n ")" ::: "memory")
; #define WAIT_L(n) asm volatile("s_waitcnt lgkmcnt(" #n ")" ::: "memory")
; #define BAR __builtin_amdgcn_s_barrier()
; #define SCHED __builtin_amdgcn_sched_barrier(0)
; template <class Get, class Epi>
; DI void gemm_stream(LAS unsigned char* lds, const int K, const int ld, Get get, Epi epi) {
;     ...
;             LDB(B0, 0, 0); SCHED; LDA(At, 0, 0); STAGE(SAo(1, 1), a1 + hstep);
;             WAIT_L(8); BAR; WAIT_L(0); MMA(0, 0, At, B0); BAR; SCHED;
;             LDB(B1, 0, 1); STAGE(SBo(0, 0), b2);
;             BAR; WAIT_L(0); MMA(0, 1, At, B1); BAR;
;             LDA(At, 0, 1); STAGE(SAo(0, 0), a2);
;             BAR; WAIT_L(0); MMA(1, 0, At, B0); BAR; SCHED;
;             STAGE(SBo(0, 1), b2 + hstep);
;             WAIT_V(6); BAR; MMA(1, 1, At, B1); BAR;
.LBB0_3046:
	ds_read_b128 v[148:151], v142
	ds_read_b128 v[152:155], v142 offset:1024
	ds_read_b128 v[156:159], v142 offset:2048
	ds_read_b128 v[160:163], v142 offset:3072
	s_add_u32 s14, s12, 0xfff80080
	s_addc_u32 s15, s13, -1
	s_cmp_eq_u32 s56, 28
	s_cselect_b32 s17, s9, s15
	s_cselect_b32 s16, s8, s14
	s_cselect_b32 s15, s11, s55
	s_cselect_b32 s14, s10, s0
	s_mov_b32 m0, s38
	v_lshl_add_u64 v[140:141], s[12:13], 0, v[134:135]
	ds_read_b128 v[164:167], v143
	ds_read_b128 v[168:171], v143 offset:1024
	ds_read_b128 v[172:175], v143 offset:2048
	ds_read_b128 v[176:179], v143 offset:3072
	ds_read_b128 v[180:183], v143 offset:4096
	ds_read_b128 v[184:187], v143 offset:5120
	ds_read_b128 v[188:191], v143 offset:6144
	ds_read_b128 v[192:195], v143 offset:7168
	global_load_lds_dwordx4 v[140:141], off
	s_mov_b32 m0, s39
	v_lshl_add_u64 v[140:141], s[12:13], 0, v[136:137]
	global_load_lds_dwordx4 v[140:141], off
	s_waitcnt lgkmcnt(8)
	s_barrier
	s_waitcnt lgkmcnt(0)
	v_mfma_f32_16x16x32_bf16 v[124:127], v[148:151], v[164:167], v[124:127]
	v_mfma_f32_16x16x32_bf16 v[116:119], v[156:159], v[164:167], v[116:119]
	v_mfma_f32_16x16x32_bf16 v[108:111], v[148:151], v[172:175], v[108:111]
	v_mfma_f32_16x16x32_bf16 v[100:103], v[156:159], v[172:175], v[100:103]
	v_mfma_f32_16x16x32_bf16 v[92:95], v[148:151], v[180:183], v[92:95]
	v_mfma_f32_16x16x32_bf16 v[84:87], v[156:159], v[180:183], v[84:87]
	v_mfma_f32_16x16x32_bf16 v[76:79], v[148:151], v[188:191], v[76:79]
	v_mfma_f32_16x16x32_bf16 v[68:71], v[156:159], v[188:191], v[68:71]
	v_mfma_f32_16x16x32_bf16 v[124:127], v[152:155], v[168:171], v[124:127]
	v_mfma_f32_16x16x32_bf16 v[116:119], v[160:163], v[168:171], v[116:119]
	v_mfma_f32_16x16x32_bf16 v[108:111], v[152:155], v[176:179], v[108:111]
	v_mfma_f32_16x16x32_bf16 v[100:103], v[160:163], v[176:179], v[100:103]
	v_mfma_f32_16x16x32_bf16 v[92:95], v[152:155], v[184:187], v[92:95]
	v_mfma_f32_16x16x32_bf16 v[84:87], v[160:163], v[184:187], v[84:87]
	v_mfma_f32_16x16x32_bf16 v[76:79], v[152:155], v[192:195], v[76:79]
	v_mfma_f32_16x16x32_bf16 v[68:71], v[160:163], v[192:195], v[68:71]
	s_barrier
	s_mov_b32 m0, s40
	v_lshl_add_u64 v[140:141], s[14:15], 0, v[130:131]
	ds_read_b128 v[196:199], v144
	ds_read_b128 v[200:203], v144 offset:1024
	ds_read_b128 v[208:211], v144 offset:2048
	ds_read_b128 v[212:215], v144 offset:3072
	global_load_lds_dwordx4 v[140:141], off
	s_mov_b32 m0, s41
	v_lshl_add_u64 v[204:205], s[14:15], 0, v[128:129]
	global_load_lds_dwordx4 v[204:205], off
	s_barrier
	s_waitcnt lgkmcnt(0)
	v_mfma_f32_16x16x32_bf16 v[120:123], v[196:199], v[164:167], v[120:123]
	v_mfma_f32_16x16x32_bf16 v[112:115], v[208:211], v[164:167], v[112:115]
	v_mfma_f32_16x16x32_bf16 v[104:107], v[196:199], v[172:175], v[104:107]
	v_mfma_f32_16x16x32_bf16 v[96:99], v[208:211], v[172:175], v[96:99]
	v_mfma_f32_16x16x32_bf16 v[88:91], v[196:199], v[180:183], v[88:91]
	v_mfma_f32_16x16x32_bf16 v[80:83], v[208:211], v[180:183], v[80:83]
	v_mfma_f32_16x16x32_bf16 v[72:75], v[196:199], v[188:191], v[72:75]
	v_mfma_f32_16x16x32_bf16 v[64:67], v[208:211], v[188:191], v[64:67]
	v_mfma_f32_16x16x32_bf16 v[120:123], v[200:203], v[168:171], v[120:123]
	v_mfma_f32_16x16x32_bf16 v[112:115], v[212:215], v[168:171], v[112:115]
	v_mfma_f32_16x16x32_bf16 v[104:107], v[200:203], v[176:179], v[104:107]
	v_mfma_f32_16x16x32_bf16 v[96:99], v[212:215], v[176:179], v[96:99]
	v_mfma_f32_16x16x32_bf16 v[88:91], v[200:203], v[184:187], v[88:91]
	v_mfma_f32_16x16x32_bf16 v[80:83], v[212:215], v[184:187], v[80:83]
	v_mfma_f32_16x16x32_bf16 v[72:75], v[200:203], v[192:195], v[72:75]
	v_mfma_f32_16x16x32_bf16 v[64:67], v[212:215], v[192:195], v[64:67]
	s_mov_b32 m0, s19
	v_lshl_add_u64 v[216:217], s[16:17], 0, v[130:131]
	s_barrier
	ds_read_b128 v[164:167], v143 offset:16384
	ds_read_b128 v[168:171], v143 offset:17408
	ds_read_b128 v[172:175], v143 offset:18432
	ds_read_b128 v[176:179], v143 offset:19456
	ds_read_b128 v[180:183], v143 offset:20480
	ds_read_b128 v[184:187], v143 offset:21504
	ds_read_b128 v[188:191], v143 offset:22528
	ds_read_b128 v[192:195], v143 offset:23552
	global_load_lds_dwordx4 v[216:217], off
	s_mov_b32 m0, s20
	v_lshl_add_u64 v[218:219], s[16:17], 0, v[128:129]
	global_load_lds_dwordx4 v[218:219], off
	s_barrier
	s_waitcnt lgkmcnt(0)
	v_mfma_f32_16x16x32_bf16 v[60:63], v[148:151], v[164:167], v[60:63]
	v_mfma_f32_16x16x32_bf16 v[52:55], v[156:159], v[164:167], v[52:55]
	v_mfma_f32_16x16x32_bf16 v[44:47], v[148:151], v[172:175], v[44:47]
	v_mfma_f32_16x16x32_bf16 v[36:39], v[156:159], v[172:175], v[36:39]
	v_mfma_f32_16x16x32_bf16 v[28:31], v[148:151], v[180:183], v[28:31]
	v_mfma_f32_16x16x32_bf16 v[20:23], v[156:159], v[180:183], v[20:23]
	v_mfma_f32_16x16x32_bf16 v[12:15], v[148:151], v[188:191], v[12:15]
	v_mfma_f32_16x16x32_bf16 v[4:7], v[156:159], v[188:191], v[4:7]
	v_mfma_f32_16x16x32_bf16 v[60:63], v[152:155], v[168:171], v[60:63]
	v_mfma_f32_16x16x32_bf16 v[52:55], v[160:163], v[168:171], v[52:55]
	v_mfma_f32_16x16x32_bf16 v[44:47], v[152:155], v[176:179], v[44:47]
	v_mfma_f32_16x16x32_bf16 v[36:39], v[160:163], v[176:179], v[36:39]
	v_mfma_f32_16x16x32_bf16 v[28:31], v[152:155], v[184:187], v[28:31]
	v_mfma_f32_16x16x32_bf16 v[20:23], v[160:163], v[184:187], v[20:23]
	v_mfma_f32_16x16x32_bf16 v[12:15], v[152:155], v[192:195], v[12:15]
	v_mfma_f32_16x16x32_bf16 v[4:7], v[160:163], v[192:195], v[4:7]
	s_barrier
	s_add_u32 s58, s14, 0x80000
	s_addc_u32 s59, s15, 0
	s_mov_b32 m0, s42
	v_lshl_add_u64 v[148:149], s[58:59], 0, v[130:131]
	global_load_lds_dwordx4 v[148:149], off
	s_mov_b32 m0, s43
	v_lshl_add_u64 v[148:149], s[58:59], 0, v[128:129]
	global_load_lds_dwordx4 v[148:149], off
	s_waitcnt vmcnt(6)
	s_barrier
; #define WAIT_V(n) asm volatile("s_waitcnt vmcnt(" #n ")" ::: "memory")
; #define WAIT_L(n) asm volatile("s_waitcnt lgkmcnt(" #n ")" ::: "memory")
; #define BAR __builtin_amdgcn_s_barrier()
; #define SCHED __builtin_amdgcn_sched_barrier(0)
; template <class Get, class Epi>
; DI void gemm_stream(LAS unsigned char* lds, const int K, const int ld, Get get, Epi epi) {
;     ...
;             LDB(B0, 1, 0); SCHED; LDA(At, 1, 0); STAGE(SAo(0, 1), a2 + hstep);
;             WAIT_L(8); BAR; WAIT_L(0); MMA(0, 0, At, B0); BAR; SCHED;
;             LDB(B1, 1, 1); STAGE(SBo(1, 0), b3);
;             BAR; WAIT_L(0); MMA(0, 1, At, B1); BAR;
;             LDA(At, 1, 1); STAGE(SAo(1, 0), a3);
;             BAR; WAIT_L(0); MMA(1, 0, At, B0); BAR; SCHED;
;             STAGE(SBo(1, 1), b3 + hstep);
;             WAIT_V(6); BAR; MMA(1, 1, At, B1); BAR;
	v_mfma_f32_16x16x32_bf16 v[56:59], v[196:199], v[164:167], v[56:59]
	v_mfma_f32_16x16x32_bf16 v[48:51], v[208:211], v[164:167], v[48:51]
	v_mfma_f32_16x16x32_bf16 v[40:43], v[196:199], v[172:175], v[40:43]
	v_mfma_f32_16x16x32_bf16 v[32:35], v[208:211], v[172:175], v[32:35]
	v_mfma_f32_16x16x32_bf16 v[24:27], v[196:199], v[180:183], v[24:27]
	v_mfma_f32_16x16x32_bf16 v[16:19], v[208:211], v[180:183], v[16:19]
	v_mfma_f32_16x16x32_bf16 v[8:11], v[196:199], v[188:191], v[8:11]
	v_mfma_f32_16x16x32_bf16 v[0:3], v[208:211], v[188:191], v[0:3]
	v_mfma_f32_16x16x32_bf16 v[56:59], v[200:203], v[168:171], v[56:59]
	v_mfma_f32_16x16x32_bf16 v[48:51], v[212:215], v[168:171], v[48:51]
	v_mfma_f32_16x16x32_bf16 v[40:43], v[200:203], v[176:179], v[40:43]
	v_mfma_f32_16x16x32_bf16 v[32:35], v[212:215], v[176:179], v[32:35]
	v_mfma_f32_16x16x32_bf16 v[24:27], v[200:203], v[184:187], v[24:27]
	v_mfma_f32_16x16x32_bf16 v[16:19], v[212:215], v[184:187], v[16:19]
	v_mfma_f32_16x16x32_bf16 v[8:11], v[200:203], v[192:195], v[8:11]
	v_mfma_f32_16x16x32_bf16 v[0:3], v[212:215], v[192:195], v[0:3]
	s_barrier
	ds_read_b128 v[148:151], v145
	ds_read_b128 v[152:155], v145 offset:1024
	ds_read_b128 v[156:159], v145 offset:2048
	ds_read_b128 v[160:163], v145 offset:3072
	s_add_u32 s16, s16, 0x80000
	s_addc_u32 s17, s17, 0
	s_mov_b32 m0, s21
	v_lshl_add_u64 v[196:197], s[16:17], 0, v[130:131]
	ds_read_b128 v[164:167], v143 offset:32768
	ds_read_b128 v[168:171], v143 offset:33792
	ds_read_b128 v[172:175], v143 offset:34816
	ds_read_b128 v[176:179], v143 offset:35840
	ds_read_b128 v[180:183], v143 offset:36864
	ds_read_b128 v[184:187], v143 offset:37888
	ds_read_b128 v[188:191], v143 offset:38912
	ds_read_b128 v[192:195], v143 offset:39936
	global_load_lds_dwordx4 v[196:197], off
	s_mov_b32 m0, s28
	v_lshl_add_u64 v[196:197], s[16:17], 0, v[128:129]
	global_load_lds_dwordx4 v[196:197], off
	s_waitcnt lgkmcnt(8)
	s_barrier
	s_waitcnt lgkmcnt(0)
	v_mfma_f32_16x16x32_bf16 v[124:127], v[148:151], v[164:167], v[124:127]
	v_mfma_f32_16x16x32_bf16 v[116:119], v[156:159], v[164:167], v[116:119]
	v_mfma_f32_16x16x32_bf16 v[108:111], v[148:151], v[172:175], v[108:111]
	v_mfma_f32_16x16x32_bf16 v[100:103], v[156:159], v[172:175], v[100:103]
	v_mfma_f32_16x16x32_bf16 v[92:95], v[148:151], v[180:183], v[92:95]
	v_mfma_f32_16x16x32_bf16 v[84:87], v[156:159], v[180:183], v[84:87]
	v_mfma_f32_16x16x32_bf16 v[76:79], v[148:151], v[188:191], v[76:79]
	v_mfma_f32_16x16x32_bf16 v[68:71], v[156:159], v[188:191], v[68:71]
	v_mfma_f32_16x16x32_bf16 v[124:127], v[152:155], v[168:171], v[124:127]
	v_mfma_f32_16x16x32_bf16 v[116:119], v[160:163], v[168:171], v[116:119]
	v_mfma_f32_16x16x32_bf16 v[108:111], v[152:155], v[176:179], v[108:111]
	v_mfma_f32_16x16x32_bf16 v[100:103], v[160:163], v[176:179], v[100:103]
	v_mfma_f32_16x16x32_bf16 v[92:95], v[152:155], v[184:187], v[92:95]
	v_mfma_f32_16x16x32_bf16 v[84:87], v[160:163], v[184:187], v[84:87]
	v_mfma_f32_16x16x32_bf16 v[76:79], v[152:155], v[192:195], v[76:79]
	v_mfma_f32_16x16x32_bf16 v[68:71], v[160:163], v[192:195], v[68:71]
	s_barrier
	s_mov_b32 m0, s44
	v_lshl_add_u64 v[140:141], v[140:141], 0, s[6:7]
	ds_read_b128 v[196:199], v146
	ds_read_b128 v[200:203], v146 offset:1024
	ds_read_b128 v[208:211], v146 offset:2048
	ds_read_b128 v[212:215], v146 offset:3072
	global_load_lds_dwordx4 v[140:141], off
	s_mov_b32 m0, s45
	v_lshl_add_u64 v[140:141], v[204:205], 0, s[6:7]
	global_load_lds_dwordx4 v[140:141], off
	s_barrier
	s_waitcnt lgkmcnt(0)
	v_mfma_f32_16x16x32_bf16 v[120:123], v[196:199], v[164:167], v[120:123]
	v_mfma_f32_16x16x32_bf16 v[112:115], v[208:211], v[164:167], v[112:115]
	v_mfma_f32_16x16x32_bf16 v[104:107], v[196:199], v[172:175], v[104:107]
	v_mfma_f32_16x16x32_bf16 v[96:99], v[208:211], v[172:175], v[96:99]
	v_mfma_f32_16x16x32_bf16 v[88:91], v[196:199], v[180:183], v[88:91]
	v_mfma_f32_16x16x32_bf16 v[80:83], v[208:211], v[180:183], v[80:83]
	v_mfma_f32_16x16x32_bf16 v[72:75], v[196:199], v[188:191], v[72:75]
	v_mfma_f32_16x16x32_bf16 v[64:67], v[208:211], v[188:191], v[64:67]
	v_mfma_f32_16x16x32_bf16 v[120:123], v[200:203], v[168:171], v[120:123]
	v_mfma_f32_16x16x32_bf16 v[112:115], v[212:215], v[168:171], v[112:115]
	v_mfma_f32_16x16x32_bf16 v[104:107], v[200:203], v[176:179], v[104:107]
	v_mfma_f32_16x16x32_bf16 v[96:99], v[212:215], v[176:179], v[96:99]
	v_mfma_f32_16x16x32_bf16 v[88:91], v[200:203], v[184:187], v[88:91]
	v_mfma_f32_16x16x32_bf16 v[80:83], v[212:215], v[184:187], v[80:83]
	v_mfma_f32_16x16x32_bf16 v[72:75], v[200:203], v[192:195], v[72:75]
	v_mfma_f32_16x16x32_bf16 v[64:67], v[212:215], v[192:195], v[64:67]
	s_mov_b32 m0, s29
	v_lshl_add_u64 v[140:141], v[216:217], 0, s[6:7]
	s_barrier
	ds_read_b128 v[164:167], v143 offset:49152
	ds_read_b128 v[168:171], v143 offset:50176
	ds_read_b128 v[172:175], v143 offset:51200
	ds_read_b128 v[176:179], v143 offset:52224
	ds_read_b128 v[180:183], v143 offset:53248
	ds_read_b128 v[184:187], v143 offset:54272
	ds_read_b128 v[188:191], v143 offset:55296
	ds_read_b128 v[192:195], v143 offset:56320
	global_load_lds_dwordx4 v[140:141], off
	s_mov_b32 m0, s36
	v_lshl_add_u64 v[140:141], v[218:219], 0, s[6:7]
	global_load_lds_dwordx4 v[140:141], off
	s_barrier
; DI float silu_f(float g) { return g * __builtin_amdgcn_rcpf(1.f + __builtin_amdgcn_exp2f(-LOG2E * g)); }
; #define WAIT_V(n) asm volatile("s_waitcnt vmcnt(" #n ")" ::: "memory")
; #define WAIT_L(n) asm volatile("s_waitcnt lgkmcnt(" #n ")" ::: "memory")
; #define BAR __builtin_amdgcn_s_barrier()
; #define SCHED __builtin_amdgcn_sched_barrier(0)
; template <class Get, class Epi>
; DI void gemm_stream(LAS unsigned char* lds, const int K, const int ld, Get get, Epi epi) {
;     ...
;             BAR; WAIT_L(0); MMA(1, 0, At, B0); BAR; SCHED;
;             STAGE(SBo(1, 1), b3 + hstep);
;             WAIT_V(6); BAR; MMA(1, 1, At, B1); BAR;
; DI void epi_swiglu(const Acc& acc, int brow, int pn, bf16_t* hid) {
;     EPI_IDX
; #pragma unroll
;     for (int ai = 0; ai < 2; ++ai)
; #pragma unroll
;         for (int m = 0; m < 4; ++m) {
;             const int r = brow + ai * 128 + wr * 64 + m * 16 + fr;
;             bf16_t* rp = hid + (size_t)r * FF + pn * 128 + wc * 32 + fq * 4;
; #pragma unroll
;             for (int n = 0; n < 2; ++n) {
;                 const f32x4 g = acc[ai][0][m][n], u = acc[ai][1][m][n];
;                 float o[4];
; #pragma unroll
;                 for (int j = 0; j < 4; ++j) o[j] = silu_f(g[j]) * u[j];
;                 st4(rp + n * 16, o[0], o[1], o[2], o[3]);
	s_waitcnt lgkmcnt(0)
	v_mfma_f32_16x16x32_bf16 v[60:63], v[148:151], v[164:167], v[60:63]
	v_mfma_f32_16x16x32_bf16 v[52:55], v[156:159], v[164:167], v[52:55]
	v_mfma_f32_16x16x32_bf16 v[44:47], v[148:151], v[172:175], v[44:47]
	v_mfma_f32_16x16x32_bf16 v[36:39], v[156:159], v[172:175], v[36:39]
	v_mfma_f32_16x16x32_bf16 v[28:31], v[148:151], v[180:183], v[28:31]
	v_mfma_f32_16x16x32_bf16 v[20:23], v[156:159], v[180:183], v[20:23]
	v_mfma_f32_16x16x32_bf16 v[12:15], v[148:151], v[188:191], v[12:15]
	v_mfma_f32_16x16x32_bf16 v[4:7], v[156:159], v[188:191], v[4:7]
	v_mfma_f32_16x16x32_bf16 v[60:63], v[152:155], v[168:171], v[60:63]
	v_mfma_f32_16x16x32_bf16 v[52:55], v[160:163], v[168:171], v[52:55]
	v_mfma_f32_16x16x32_bf16 v[44:47], v[152:155], v[176:179], v[44:47]
	v_mfma_f32_16x16x32_bf16 v[36:39], v[160:163], v[176:179], v[36:39]
	v_mfma_f32_16x16x32_bf16 v[28:31], v[152:155], v[184:187], v[28:31]
	v_mfma_f32_16x16x32_bf16 v[20:23], v[160:163], v[184:187], v[20:23]
	v_mfma_f32_16x16x32_bf16 v[12:15], v[152:155], v[192:195], v[12:15]
	v_mfma_f32_16x16x32_bf16 v[4:7], v[160:163], v[192:195], v[4:7]
	s_barrier
	s_add_u32 s14, s14, 0x80080
	s_addc_u32 s15, s15, 0
	s_mov_b32 m0, s46
	v_lshl_add_u64 v[140:141], s[14:15], 0, v[130:131]
	global_load_lds_dwordx4 v[140:141], off
	s_mov_b32 m0, s47
	v_lshl_add_u64 v[140:141], s[14:15], 0, v[128:129]
	global_load_lds_dwordx4 v[140:141], off
	s_waitcnt vmcnt(6)
	s_barrier
	v_mfma_f32_16x16x32_bf16 v[56:59], v[196:199], v[164:167], v[56:59]
	v_mfma_f32_16x16x32_bf16 v[48:51], v[208:211], v[164:167], v[48:51]
	v_mfma_f32_16x16x32_bf16 v[40:43], v[196:199], v[172:175], v[40:43]
	v_mfma_f32_16x16x32_bf16 v[32:35], v[208:211], v[172:175], v[32:35]
	v_mfma_f32_16x16x32_bf16 v[24:27], v[196:199], v[180:183], v[24:27]
	v_mfma_f32_16x16x32_bf16 v[16:19], v[208:211], v[180:183], v[16:19]
	v_mfma_f32_16x16x32_bf16 v[8:11], v[196:199], v[188:191], v[8:11]
	v_mfma_f32_16x16x32_bf16 v[0:3], v[208:211], v[188:191], v[0:3]
	v_mfma_f32_16x16x32_bf16 v[56:59], v[200:203], v[168:171], v[56:59]
	v_mfma_f32_16x16x32_bf16 v[48:51], v[212:215], v[168:171], v[48:51]
	v_mfma_f32_16x16x32_bf16 v[40:43], v[200:203], v[176:179], v[40:43]
	v_mfma_f32_16x16x32_bf16 v[32:35], v[212:215], v[176:179], v[32:35]
	v_mfma_f32_16x16x32_bf16 v[24:27], v[200:203], v[184:187], v[24:27]
	v_mfma_f32_16x16x32_bf16 v[16:19], v[212:215], v[184:187], v[16:19]
	v_mfma_f32_16x16x32_bf16 v[8:11], v[200:203], v[192:195], v[8:11]
	v_mfma_f32_16x16x32_bf16 v[0:3], v[212:215], v[192:195], v[0:3]
	s_add_i32 s56, s56, 2
	s_add_u32 s12, s12, 0x100
	s_addc_u32 s13, s13, 0
	s_add_u32 s0, s0, 0x100
	s_addc_u32 s55, s55, 0
	s_cmp_gt_u32 s56, 29
	s_barrier
	s_cbranch_scc0 .LBB0_3046
	s_lshr_b32 s0, s53, 4
	s_lshl_b32 s12, s53, 8
	s_mulk_i32 s0, 0x1100
	s_and_b32 s12, s12, 0xf00
	s_add_i32 s0, s0, s12
	s_lshl_b32 s12, s54, 7
	s_ashr_i32 s13, s12, 31
	s_addk_i32 s0, 0x100
	v_mov_b32_e32 v132, v206
	s_lshl_b64 s[12:13], s[12:13], 1
	s_add_u32 s12, s23, s12
	v_ashrrev_i32_e32 v140, 2, v132
	v_and_b32_e32 v140, 0xffffffc0, v140
	v_and_or_b32 v141, v132, 15, s0
	s_addc_u32 s13, s35, s13
	v_lshrrev_b32_e32 v148, 1, v132
	v_and_b32_e32 v132, 0xc0, v132
	v_add_u32_e32 v147, v141, v140
	v_lshl_add_u64 v[140:141], s[12:13], 0, v[132:133]
	v_and_b32_e32 v132, 24, v148
	v_mul_f32_e32 v148, 0xbfb8aa3b, v124
	v_exp_f32_e32 v148, v148
	v_mul_f32_e32 v149, 0xbfb8aa3b, v125
	v_exp_f32_e32 v149, v149
	v_lshl_add_u64 v[140:141], v[140:141], 0, v[132:133]
	v_add_f32_e32 v132, 1.0, v148
	v_rcp_f32_e32 v148, v132
	v_add_f32_e32 v132, 1.0, v149
	v_mul_f32_e32 v149, 0xbfb8aa3b, v126
	v_exp_f32_e32 v150, v149
	v_mul_f32_e32 v149, 0xbfb8aa3b, v127
	v_exp_f32_e32 v151, v149
	v_rcp_f32_e32 v149, v132
	v_add_f32_e32 v132, 1.0, v150
	v_rcp_f32_e32 v150, v132
	v_add_f32_e32 v132, 1.0, v151
	v_rcp_f32_e32 v151, v132
	v_pk_mul_f32 v[124:125], v[124:125], v[148:149]
	v_mad_i64_i32 v[152:153], s[12:13], v147, s37, v[140:141]
	v_pk_mul_f32 v[120:121], v[124:125], v[120:121]
	v_pk_mul_f32 v[124:125], v[126:127], v[150:151]
	v_cvt_pk_bf16_f32 v120, v120, v121
	v_mul_f32_e32 v121, 0xbfb8aa3b, v116
	v_pk_mul_f32 v[122:123], v[124:125], v[122:123]
	v_exp_f32_e32 v124, v121
	v_mul_f32_e32 v121, 0xbfb8aa3b, v117
	v_exp_f32_e32 v125, v121
	v_cvt_pk_bf16_f32 v121, v122, v123
	v_add_f32_e32 v122, 1.0, v124
	v_mul_f32_e32 v124, 0xbfb8aa3b, v118
	v_add_f32_e32 v123, 1.0, v125
	v_mul_f32_e32 v125, 0xbfb8aa3b, v119
	v_exp_f32_e32 v124, v124
	v_exp_f32_e32 v125, v125
	v_rcp_f32_e32 v122, v122
	v_rcp_f32_e32 v123, v123
	v_add_f32_e32 v124, 1.0, v124
	v_add_f32_e32 v125, 1.0, v125
	v_rcp_f32_e32 v124, v124
	v_rcp_f32_e32 v125, v125
	v_pk_mul_f32 v[116:117], v[116:117], v[122:123]
	s_and_b64 vcc, exec, s[4:5]
	v_pk_mul_f32 v[112:113], v[116:117], v[112:113]
	v_pk_mul_f32 v[116:117], v[118:119], v[124:125]
	v_cvt_pk_bf16_f32 v112, v112, v113
	v_pk_mul_f32 v[114:115], v[116:117], v[114:115]
	v_or_b32_e32 v116, 16, v147
	v_cvt_pk_bf16_f32 v113, v114, v115
	global_store_dwordx2 v[152:153], v[112:113], off offset:32
	v_mul_f32_e32 v112, 0xbfb8aa3b, v108
	v_mul_f32_e32 v113, 0xbfb8aa3b, v109
	v_exp_f32_e32 v112, v112
	v_exp_f32_e32 v113, v113
	v_mul_f32_e32 v114, 0xbfb8aa3b, v110
	v_mul_f32_e32 v115, 0xbfb8aa3b, v111
	v_exp_f32_e32 v114, v114
	v_exp_f32_e32 v115, v115
	v_add_f32_e32 v112, 1.0, v112
	v_add_f32_e32 v113, 1.0, v113
	v_rcp_f32_e32 v112, v112
	v_rcp_f32_e32 v113, v113
	v_add_f32_e32 v114, 1.0, v114
	v_add_f32_e32 v115, 1.0, v115
	v_rcp_f32_e32 v114, v114
	v_rcp_f32_e32 v115, v115
	v_pk_mul_f32 v[108:109], v[108:109], v[112:113]
	v_mad_i64_i32 v[116:117], s[12:13], v116, s37, v[140:141]
; DI float silu_f(float g) { return g * __builtin_amdgcn_rcpf(1.f + __builtin_amdgcn_exp2f(-LOG2E * g)); }
; DI void epi_swiglu(const Acc& acc, int brow, int pn, bf16_t* hid) {
;     ...
;     for (int ai = 0; ai < 2; ++ai)
; #pragma unroll
;         for (int m = 0; m < 4; ++m) {
;             const int r = brow + ai * 128 + wr * 64 + m * 16 + fr;
;             bf16_t* rp = hid + (size_t)r * FF + pn * 128 + wc * 32 + fq * 4;
; #pragma unroll
;             for (int n = 0; n < 2; ++n) {
;                 const f32x4 g = acc[ai][0][m][n], u = acc[ai][1][m][n];
;                 float o[4];
; #pragma unroll
;                 for (int j = 0; j < 4; ++j) o[j] = silu_f(g[j]) * u[j];
;                 st4(rp + n * 16, o[0], o[1], o[2], o[3]);
;             }
	v_pk_mul_f32 v[104:105], v[108:109], v[104:105]
	v_pk_mul_f32 v[108:109], v[110:111], v[114:115]
	v_cvt_pk_bf16_f32 v104, v104, v105
	v_mul_f32_e32 v105, 0xbfb8aa3b, v100
	v_pk_mul_f32 v[106:107], v[108:109], v[106:107]
	v_exp_f32_e32 v108, v105
	v_mul_f32_e32 v105, 0xbfb8aa3b, v101
	v_exp_f32_e32 v109, v105
	v_cvt_pk_bf16_f32 v105, v106, v107
	v_add_f32_e32 v106, 1.0, v108
	v_mul_f32_e32 v108, 0xbfb8aa3b, v102
	v_add_f32_e32 v107, 1.0, v109
	v_mul_f32_e32 v109, 0xbfb8aa3b, v103
	v_exp_f32_e32 v108, v108
	v_exp_f32_e32 v109, v109
	v_rcp_f32_e32 v106, v106
	v_rcp_f32_e32 v107, v107
	v_add_f32_e32 v108, 1.0, v108
	v_add_f32_e32 v109, 1.0, v109
	v_rcp_f32_e32 v108, v108
	v_rcp_f32_e32 v109, v109
	v_pk_mul_f32 v[100:101], v[100:101], v[106:107]
	s_mov_b32 s54, s49
	v_pk_mul_f32 v[96:97], v[100:101], v[96:97]
	v_pk_mul_f32 v[100:101], v[102:103], v[108:109]
	v_cvt_pk_bf16_f32 v96, v96, v97
	v_pk_mul_f32 v[98:99], v[100:101], v[98:99]
	v_or_b32_e32 v100, 32, v147
	v_cvt_pk_bf16_f32 v97, v98, v99
	global_store_dwordx2 v[116:117], v[96:97], off offset:32
	v_mul_f32_e32 v96, 0xbfb8aa3b, v92
	v_mul_f32_e32 v97, 0xbfb8aa3b, v93
	v_exp_f32_e32 v96, v96
	v_exp_f32_e32 v97, v97
	v_mul_f32_e32 v98, 0xbfb8aa3b, v94
	v_mul_f32_e32 v99, 0xbfb8aa3b, v95
	v_exp_f32_e32 v98, v98
	v_exp_f32_e32 v99, v99
	v_add_f32_e32 v96, 1.0, v96
	v_add_f32_e32 v97, 1.0, v97
	v_rcp_f32_e32 v96, v96
	v_rcp_f32_e32 v97, v97
	v_add_f32_e32 v98, 1.0, v98
	v_add_f32_e32 v99, 1.0, v99
	v_rcp_f32_e32 v98, v98
	v_rcp_f32_e32 v99, v99
	v_pk_mul_f32 v[92:93], v[92:93], v[96:97]
	v_mad_i64_i32 v[100:101], s[12:13], v100, s37, v[140:141]
	v_pk_mul_f32 v[88:89], v[92:93], v[88:89]
	v_pk_mul_f32 v[92:93], v[94:95], v[98:99]
	v_cvt_pk_bf16_f32 v88, v88, v89
	v_mul_f32_e32 v89, 0xbfb8aa3b, v84
	v_pk_mul_f32 v[90:91], v[92:93], v[90:91]
	v_exp_f32_e32 v92, v89
	v_mul_f32_e32 v89, 0xbfb8aa3b, v85
	v_exp_f32_e32 v93, v89
	v_cvt_pk_bf16_f32 v89, v90, v91
	v_add_f32_e32 v90, 1.0, v92
	v_mul_f32_e32 v92, 0xbfb8aa3b, v86
	v_add_f32_e32 v91, 1.0, v93
	v_mul_f32_e32 v93, 0xbfb8aa3b, v87
	v_exp_f32_e32 v92, v92
	v_exp_f32_e32 v93, v93
	v_rcp_f32_e32 v90, v90
	v_rcp_f32_e32 v91, v91
	v_add_f32_e32 v92, 1.0, v92
	v_add_f32_e32 v93, 1.0, v93
	v_rcp_f32_e32 v92, v92
	v_rcp_f32_e32 v93, v93
	v_pk_mul_f32 v[84:85], v[84:85], v[90:91]
	s_mov_b32 s53, s52
	v_pk_mul_f32 v[80:81], v[84:85], v[80:81]
	v_pk_mul_f32 v[84:85], v[86:87], v[92:93]
	v_cvt_pk_bf16_f32 v80, v80, v81
	v_pk_mul_f32 v[82:83], v[84:85], v[82:83]
	v_or_b32_e32 v84, 48, v147
	v_cvt_pk_bf16_f32 v81, v82, v83
	global_store_dwordx2 v[100:101], v[80:81], off offset:32
	v_mul_f32_e32 v80, 0xbfb8aa3b, v76
	v_mul_f32_e32 v81, 0xbfb8aa3b, v77
	v_exp_f32_e32 v80, v80
	v_exp_f32_e32 v81, v81
	v_mul_f32_e32 v82, 0xbfb8aa3b, v78
	v_mul_f32_e32 v83, 0xbfb8aa3b, v79
	v_exp_f32_e32 v82, v82
	v_exp_f32_e32 v83, v83
	v_add_f32_e32 v80, 1.0, v80
	v_add_f32_e32 v81, 1.0, v81
	v_rcp_f32_e32 v80, v80
	v_rcp_f32_e32 v81, v81
	v_add_f32_e32 v82, 1.0, v82
	v_add_f32_e32 v83, 1.0, v83
	v_rcp_f32_e32 v82, v82
	v_rcp_f32_e32 v83, v83
	v_pk_mul_f32 v[76:77], v[76:77], v[80:81]
	v_mad_i64_i32 v[84:85], s[12:13], v84, s37, v[140:141]
	v_pk_mul_f32 v[72:73], v[76:77], v[72:73]
	v_pk_mul_f32 v[76:77], v[78:79], v[82:83]
	v_cvt_pk_bf16_f32 v72, v72, v73
	v_mul_f32_e32 v73, 0xbfb8aa3b, v68
	v_pk_mul_f32 v[74:75], v[76:77], v[74:75]
	v_exp_f32_e32 v76, v73
	v_mul_f32_e32 v73, 0xbfb8aa3b, v69
	v_exp_f32_e32 v77, v73
	v_cvt_pk_bf16_f32 v73, v74, v75
	v_add_f32_e32 v74, 1.0, v76
	v_mul_f32_e32 v76, 0xbfb8aa3b, v70
	v_add_f32_e32 v75, 1.0, v77
	v_mul_f32_e32 v77, 0xbfb8aa3b, v71
	v_exp_f32_e32 v76, v76
	v_exp_f32_e32 v77, v77
	v_rcp_f32_e32 v74, v74
	v_rcp_f32_e32 v75, v75
	v_add_f32_e32 v76, 1.0, v76
	v_add_f32_e32 v77, 1.0, v77
	v_rcp_f32_e32 v76, v76
	v_rcp_f32_e32 v77, v77
	v_pk_mul_f32 v[68:69], v[68:69], v[74:75]
	s_mov_b64 s[14:15], s[10:11]
	v_pk_mul_f32 v[64:65], v[68:69], v[64:65]
	v_pk_mul_f32 v[68:69], v[70:71], v[76:77]
	v_cvt_pk_bf16_f32 v64, v64, v65
	v_pk_mul_f32 v[66:67], v[68:69], v[66:67]
	v_add_u32_e32 v68, 0x80, v147
	v_cvt_pk_bf16_f32 v65, v66, v67
	global_store_dwordx2 v[84:85], v[64:65], off offset:32
	v_mul_f32_e32 v64, 0xbfb8aa3b, v60
	v_mul_f32_e32 v65, 0xbfb8aa3b, v61
	v_exp_f32_e32 v64, v64
	v_exp_f32_e32 v65, v65
	v_mul_f32_e32 v66, 0xbfb8aa3b, v62
	v_mul_f32_e32 v67, 0xbfb8aa3b, v63
	v_exp_f32_e32 v66, v66
	v_exp_f32_e32 v67, v67
	v_add_f32_e32 v64, 1.0, v64
	v_add_f32_e32 v65, 1.0, v65
	v_rcp_f32_e32 v64, v64
	v_rcp_f32_e32 v65, v65
	v_add_f32_e32 v66, 1.0, v66
	v_add_f32_e32 v67, 1.0, v67
	v_rcp_f32_e32 v66, v66
	v_rcp_f32_e32 v67, v67
	v_pk_mul_f32 v[60:61], v[60:61], v[64:65]
	v_mad_i64_i32 v[68:69], s[12:13], v68, s37, v[140:141]
	v_pk_mul_f32 v[56:57], v[60:61], v[56:57]
	v_pk_mul_f32 v[60:61], v[62:63], v[66:67]
	v_cvt_pk_bf16_f32 v56, v56, v57
	v_mul_f32_e32 v57, 0xbfb8aa3b, v52
	v_pk_mul_f32 v[58:59], v[60:61], v[58:59]
	v_exp_f32_e32 v60, v57
	v_mul_f32_e32 v57, 0xbfb8aa3b, v53
	v_exp_f32_e32 v61, v57
	v_cvt_pk_bf16_f32 v57, v58, v59
	v_add_f32_e32 v58, 1.0, v60
	v_mul_f32_e32 v60, 0xbfb8aa3b, v54
	v_add_f32_e32 v59, 1.0, v61
	v_mul_f32_e32 v61, 0xbfb8aa3b, v55
	v_exp_f32_e32 v60, v60
	v_exp_f32_e32 v61, v61
	v_rcp_f32_e32 v58, v58
	v_rcp_f32_e32 v59, v59
	v_add_f32_e32 v60, 1.0, v60
	v_add_f32_e32 v61, 1.0, v61
	v_rcp_f32_e32 v60, v60
; DI float silu_f(float g) { return g * __builtin_amdgcn_rcpf(1.f + __builtin_amdgcn_exp2f(-LOG2E * g)); }
; #define WAIT_V(n) asm volatile("s_waitcnt vmcnt(" #n ")" ::: "memory")
; #define BAR __builtin_amdgcn_s_barrier()
; template <class Get, class Epi>
; DI void gemm_stream(LAS unsigned char* lds, const int K, const int ld, Get get, Epi epi) {
;     ...
;         if (!has_next) break;
;         ZERO_ACC;
;         cur = nxt; cA = nA; cB = nB; ++ui;
;     }
;     WAIT_V(0);
;     if (wr == 0) BAR;
;     BAR;
; DI void epi_swiglu(const Acc& acc, int brow, int pn, bf16_t* hid) {
;     ...
;     for (int ai = 0; ai < 2; ++ai)
; #pragma unroll
;         for (int m = 0; m < 4; ++m) {
;             const int r = brow + ai * 128 + wr * 64 + m * 16 + fr;
;             bf16_t* rp = hid + (size_t)r * FF + pn * 128 + wc * 32 + fq * 4;
; #pragma unroll
;             for (int n = 0; n < 2; ++n) {
;                 const f32x4 g = acc[ai][0][m][n], u = acc[ai][1][m][n];
;                 float o[4];
; #pragma unroll
;                 for (int j = 0; j < 4; ++j) o[j] = silu_f(g[j]) * u[j];
;                 st4(rp + n * 16, o[0], o[1], o[2], o[3]);
;             }
;         }
	v_rcp_f32_e32 v61, v61
	v_pk_mul_f32 v[52:53], v[52:53], v[58:59]
	global_store_dwordx2 v[152:153], v[120:121], off
	v_pk_mul_f32 v[48:49], v[52:53], v[48:49]
	v_pk_mul_f32 v[52:53], v[54:55], v[60:61]
	v_cvt_pk_bf16_f32 v48, v48, v49
	v_pk_mul_f32 v[50:51], v[52:53], v[50:51]
	v_add_u32_e32 v52, 0x90, v147
	v_cvt_pk_bf16_f32 v49, v50, v51
	global_store_dwordx2 v[68:69], v[48:49], off offset:32
	v_mul_f32_e32 v48, 0xbfb8aa3b, v44
	v_mul_f32_e32 v49, 0xbfb8aa3b, v45
	v_exp_f32_e32 v48, v48
	v_exp_f32_e32 v49, v49
	v_mul_f32_e32 v50, 0xbfb8aa3b, v46
	v_mul_f32_e32 v51, 0xbfb8aa3b, v47
	v_exp_f32_e32 v50, v50
	v_exp_f32_e32 v51, v51
	v_add_f32_e32 v48, 1.0, v48
	v_add_f32_e32 v49, 1.0, v49
	v_rcp_f32_e32 v48, v48
	v_rcp_f32_e32 v49, v49
	v_add_f32_e32 v50, 1.0, v50
	v_add_f32_e32 v51, 1.0, v51
	v_rcp_f32_e32 v50, v50
	v_rcp_f32_e32 v51, v51
	v_pk_mul_f32 v[44:45], v[44:45], v[48:49]
	v_mad_i64_i32 v[52:53], s[12:13], v52, s37, v[140:141]
	v_pk_mul_f32 v[40:41], v[44:45], v[40:41]
	v_pk_mul_f32 v[44:45], v[46:47], v[50:51]
	v_cvt_pk_bf16_f32 v40, v40, v41
	v_mul_f32_e32 v41, 0xbfb8aa3b, v36
	v_pk_mul_f32 v[42:43], v[44:45], v[42:43]
	v_exp_f32_e32 v44, v41
	v_mul_f32_e32 v41, 0xbfb8aa3b, v37
	v_exp_f32_e32 v45, v41
	v_cvt_pk_bf16_f32 v41, v42, v43
	v_add_f32_e32 v42, 1.0, v44
	v_mul_f32_e32 v44, 0xbfb8aa3b, v38
	v_add_f32_e32 v43, 1.0, v45
	v_mul_f32_e32 v45, 0xbfb8aa3b, v39
	v_exp_f32_e32 v44, v44
	v_exp_f32_e32 v45, v45
	v_rcp_f32_e32 v42, v42
	v_rcp_f32_e32 v43, v43
	v_add_f32_e32 v44, 1.0, v44
	v_add_f32_e32 v45, 1.0, v45
	v_rcp_f32_e32 v44, v44
	v_rcp_f32_e32 v45, v45
	v_pk_mul_f32 v[36:37], v[36:37], v[42:43]
	global_store_dwordx2 v[116:117], v[104:105], off
	v_pk_mul_f32 v[32:33], v[36:37], v[32:33]
	v_pk_mul_f32 v[36:37], v[38:39], v[44:45]
	v_cvt_pk_bf16_f32 v32, v32, v33
	v_pk_mul_f32 v[34:35], v[36:37], v[34:35]
	v_add_u32_e32 v36, 0xa0, v147
	v_cvt_pk_bf16_f32 v33, v34, v35
	global_store_dwordx2 v[52:53], v[32:33], off offset:32
	v_mul_f32_e32 v32, 0xbfb8aa3b, v28
	v_mul_f32_e32 v33, 0xbfb8aa3b, v29
	v_exp_f32_e32 v32, v32
	v_exp_f32_e32 v33, v33
	v_mul_f32_e32 v34, 0xbfb8aa3b, v30
	v_mul_f32_e32 v35, 0xbfb8aa3b, v31
	v_exp_f32_e32 v34, v34
	v_exp_f32_e32 v35, v35
	v_add_f32_e32 v32, 1.0, v32
	v_add_f32_e32 v33, 1.0, v33
	v_rcp_f32_e32 v32, v32
	v_rcp_f32_e32 v33, v33
	v_add_f32_e32 v34, 1.0, v34
	v_add_f32_e32 v35, 1.0, v35
	v_rcp_f32_e32 v34, v34
	v_rcp_f32_e32 v35, v35
	v_pk_mul_f32 v[28:29], v[28:29], v[32:33]
	v_mad_i64_i32 v[36:37], s[12:13], v36, s37, v[140:141]
	v_pk_mul_f32 v[24:25], v[28:29], v[24:25]
	v_pk_mul_f32 v[28:29], v[30:31], v[34:35]
	v_cvt_pk_bf16_f32 v24, v24, v25
	v_mul_f32_e32 v25, 0xbfb8aa3b, v20
	v_pk_mul_f32 v[26:27], v[28:29], v[26:27]
	v_exp_f32_e32 v28, v25
	v_mul_f32_e32 v25, 0xbfb8aa3b, v21
	v_exp_f32_e32 v29, v25
	v_cvt_pk_bf16_f32 v25, v26, v27
	v_add_f32_e32 v26, 1.0, v28
	v_mul_f32_e32 v28, 0xbfb8aa3b, v22
	v_add_f32_e32 v27, 1.0, v29
	v_mul_f32_e32 v29, 0xbfb8aa3b, v23
	v_exp_f32_e32 v28, v28
	v_exp_f32_e32 v29, v29
	v_rcp_f32_e32 v26, v26
	v_rcp_f32_e32 v27, v27
	v_add_f32_e32 v28, 1.0, v28
	v_add_f32_e32 v29, 1.0, v29
	v_rcp_f32_e32 v28, v28
	v_rcp_f32_e32 v29, v29
	v_pk_mul_f32 v[20:21], v[20:21], v[26:27]
	global_store_dwordx2 v[100:101], v[88:89], off
	v_pk_mul_f32 v[16:17], v[20:21], v[16:17]
	v_pk_mul_f32 v[20:21], v[22:23], v[28:29]
	v_cvt_pk_bf16_f32 v16, v16, v17
	v_pk_mul_f32 v[18:19], v[20:21], v[18:19]
	v_add_u32_e32 v20, 0xb0, v147
	v_cvt_pk_bf16_f32 v17, v18, v19
	global_store_dwordx2 v[36:37], v[16:17], off offset:32
	v_mul_f32_e32 v16, 0xbfb8aa3b, v12
	v_mul_f32_e32 v17, 0xbfb8aa3b, v13
	v_exp_f32_e32 v16, v16
	v_exp_f32_e32 v17, v17
	v_mul_f32_e32 v18, 0xbfb8aa3b, v14
	v_mul_f32_e32 v19, 0xbfb8aa3b, v15
	v_exp_f32_e32 v18, v18
	v_exp_f32_e32 v19, v19
	v_add_f32_e32 v16, 1.0, v16
	v_add_f32_e32 v17, 1.0, v17
	v_rcp_f32_e32 v16, v16
	v_rcp_f32_e32 v17, v17
	v_add_f32_e32 v18, 1.0, v18
	v_add_f32_e32 v19, 1.0, v19
	v_rcp_f32_e32 v18, v18
	v_rcp_f32_e32 v19, v19
	v_pk_mul_f32 v[12:13], v[12:13], v[16:17]
	v_mad_i64_i32 v[20:21], s[12:13], v20, s37, v[140:141]
	v_pk_mul_f32 v[8:9], v[12:13], v[8:9]
	v_pk_mul_f32 v[12:13], v[14:15], v[18:19]
	v_cvt_pk_bf16_f32 v8, v8, v9
	v_mul_f32_e32 v9, 0xbfb8aa3b, v4
	v_pk_mul_f32 v[10:11], v[12:13], v[10:11]
	v_exp_f32_e32 v12, v9
	v_mul_f32_e32 v9, 0xbfb8aa3b, v5
	v_exp_f32_e32 v13, v9
	v_cvt_pk_bf16_f32 v9, v10, v11
	v_add_f32_e32 v10, 1.0, v12
	v_mul_f32_e32 v12, 0xbfb8aa3b, v6
	v_add_f32_e32 v11, 1.0, v13
	v_mul_f32_e32 v13, 0xbfb8aa3b, v7
	v_exp_f32_e32 v12, v12
	v_exp_f32_e32 v13, v13
	v_rcp_f32_e32 v10, v10
	v_rcp_f32_e32 v11, v11
	v_add_f32_e32 v12, 1.0, v12
	v_add_f32_e32 v13, 1.0, v13
	v_rcp_f32_e32 v12, v12
	v_rcp_f32_e32 v13, v13
	v_pk_mul_f32 v[4:5], v[4:5], v[10:11]
	s_mov_b64 s[12:13], s[8:9]
	v_pk_mul_f32 v[0:1], v[4:5], v[0:1]
	v_pk_mul_f32 v[4:5], v[6:7], v[12:13]
	v_cvt_pk_bf16_f32 v0, v0, v1
	v_pk_mul_f32 v[2:3], v[4:5], v[2:3]
	global_store_dwordx2 v[84:85], v[72:73], off
	v_cvt_pk_bf16_f32 v1, v2, v3
	global_store_dwordx2 v[68:69], v[56:57], off
	global_store_dwordx2 v[52:53], v[40:41], off
	global_store_dwordx2 v[36:37], v[24:25], off
	global_store_dwordx2 v[20:21], v[8:9], off
	global_store_dwordx2 v[20:21], v[0:1], off offset:32
	s_cbranch_vccz .LBB0_3043
	s_waitcnt vmcnt(0)
	s_cmpk_gt_u32 s2, 0xff
	s_cbranch_scc1 .LBB0_3050
	s_barrier

; #define WAIT_V(n) asm volatile("s_waitcnt vmcnt(" #n ")" ::: "memory")
; #define WAIT_L(n) asm volatile("s_waitcnt lgkmcnt(" #n ")" ::: "memory")
; #define BAR __builtin_amdgcn_s_barrier()
; #define SCHED __builtin_amdgcn_sched_barrier(0)
; template <class Get, class Epi>
; DI void gemm_stream(LAS unsigned char* lds, const int K, const int ld, Get get, Epi epi) {
;     ...
;             LDB(B0, 0, 0); SCHED; LDA(At, 0, 0); STAGE(SAo(1, 1), a1 + hstep);
;             WAIT_L(8); BAR; WAIT_L(0); MMA(0, 0, At, B0); BAR; SCHED;
;             LDB(B1, 0, 1); STAGE(SBo(0, 0), b2);
;             BAR; WAIT_L(0); MMA(0, 1, At, B1); BAR;
;             LDA(At, 0, 1); STAGE(SAo(0, 0), a2);
;             BAR; WAIT_L(0); MMA(1, 0, At, B0); BAR; SCHED;
;             STAGE(SBo(0, 1), b2 + hstep);
;             WAIT_V(6); BAR; MMA(1, 1, At, B1); BAR;
.LBB0_3113:
	ds_read_b128 v[128:131], v199
	ds_read_b128 v[132:135], v199 offset:1024
	ds_read_b128 v[136:139], v199 offset:2048
	ds_read_b128 v[140:143], v199 offset:3072
	s_add_u32 s6, s4, 0x100
	s_addc_u32 s7, s5, 0
	s_cmpk_eq_i32 s16, 0x54
	s_cselect_b32 s11, s37, s7
	s_cselect_b32 s10, s36, s6
	s_cselect_b32 s9, s39, s15
	s_cselect_b32 s8, s38, s14
	s_mov_b32 m0, s54
	v_lshl_add_u64 v[186:187], s[4:5], 0, v[168:169]
	ds_read_b128 v[144:147], v200
	ds_read_b128 v[148:151], v200 offset:1024
	ds_read_b128 v[152:155], v200 offset:2048
	ds_read_b128 v[156:159], v200 offset:3072
	ds_read_b128 v[160:163], v200 offset:4096
	ds_read_b128 v[174:177], v200 offset:5120
	ds_read_b128 v[178:181], v200 offset:6144
	ds_read_b128 v[182:185], v200 offset:7168
	global_load_lds_dwordx4 v[186:187], off
	s_mov_b32 m0, s55
	v_lshl_add_u64 v[186:187], s[4:5], 0, v[170:171]
	global_load_lds_dwordx4 v[186:187], off
	s_waitcnt lgkmcnt(8)
	s_barrier
	s_waitcnt lgkmcnt(0)
	v_mfma_f32_16x16x32_bf16 v[124:127], v[128:131], v[144:147], v[124:127]
	v_mfma_f32_16x16x32_bf16 v[92:95], v[136:139], v[144:147], v[92:95]
	v_mfma_f32_16x16x32_bf16 v[120:123], v[128:131], v[152:155], v[120:123]
	v_mfma_f32_16x16x32_bf16 v[88:91], v[136:139], v[152:155], v[88:91]
	v_mfma_f32_16x16x32_bf16 v[116:119], v[128:131], v[160:163], v[116:119]
	v_mfma_f32_16x16x32_bf16 v[84:87], v[136:139], v[160:163], v[84:87]
	v_mfma_f32_16x16x32_bf16 v[112:115], v[128:131], v[178:181], v[112:115]
	v_mfma_f32_16x16x32_bf16 v[80:83], v[136:139], v[178:181], v[80:83]
	v_mfma_f32_16x16x32_bf16 v[124:127], v[132:135], v[148:151], v[124:127]
	v_mfma_f32_16x16x32_bf16 v[92:95], v[140:143], v[148:151], v[92:95]
	v_mfma_f32_16x16x32_bf16 v[120:123], v[132:135], v[156:159], v[120:123]
	v_mfma_f32_16x16x32_bf16 v[88:91], v[140:143], v[156:159], v[88:91]
	v_mfma_f32_16x16x32_bf16 v[116:119], v[132:135], v[174:177], v[116:119]
	v_mfma_f32_16x16x32_bf16 v[84:87], v[140:143], v[174:177], v[84:87]
	v_mfma_f32_16x16x32_bf16 v[112:115], v[132:135], v[182:185], v[112:115]
	v_mfma_f32_16x16x32_bf16 v[80:83], v[140:143], v[182:185], v[80:83]
	s_barrier
	s_mov_b32 m0, s56
	v_lshl_add_u64 v[208:209], s[8:9], 0, v[164:165]
	ds_read_b128 v[186:189], v201
	ds_read_b128 v[190:193], v201 offset:1024
	ds_read_b128 v[194:197], v201 offset:2048
	ds_read_b128 v[202:205], v201 offset:3072
	global_load_lds_dwordx4 v[208:209], off
	s_mov_b32 m0, s57
	v_lshl_add_u64 v[210:211], s[8:9], 0, v[166:167]
	global_load_lds_dwordx4 v[210:211], off
	s_barrier
	s_waitcnt lgkmcnt(0)
	v_mfma_f32_16x16x32_bf16 v[60:63], v[186:189], v[144:147], v[60:63]
	v_mfma_f32_16x16x32_bf16 v[28:31], v[194:197], v[144:147], v[28:31]
	v_mfma_f32_16x16x32_bf16 v[56:59], v[186:189], v[152:155], v[56:59]
	v_mfma_f32_16x16x32_bf16 v[24:27], v[194:197], v[152:155], v[24:27]
	v_mfma_f32_16x16x32_bf16 v[52:55], v[186:189], v[160:163], v[52:55]
	v_mfma_f32_16x16x32_bf16 v[20:23], v[194:197], v[160:163], v[20:23]
	v_mfma_f32_16x16x32_bf16 v[48:51], v[186:189], v[178:181], v[48:51]
	v_mfma_f32_16x16x32_bf16 v[16:19], v[194:197], v[178:181], v[16:19]
	v_mfma_f32_16x16x32_bf16 v[60:63], v[190:193], v[148:151], v[60:63]
	v_mfma_f32_16x16x32_bf16 v[28:31], v[202:205], v[148:151], v[28:31]
	v_mfma_f32_16x16x32_bf16 v[56:59], v[190:193], v[156:159], v[56:59]
	v_mfma_f32_16x16x32_bf16 v[24:27], v[202:205], v[156:159], v[24:27]
	v_mfma_f32_16x16x32_bf16 v[52:55], v[190:193], v[174:177], v[52:55]
	v_mfma_f32_16x16x32_bf16 v[20:23], v[202:205], v[174:177], v[20:23]
	v_mfma_f32_16x16x32_bf16 v[48:51], v[190:193], v[182:185], v[48:51]
	v_mfma_f32_16x16x32_bf16 v[16:19], v[202:205], v[182:185], v[16:19]
	s_mov_b32 m0, s33
	v_lshl_add_u64 v[212:213], s[10:11], 0, v[164:165]
	s_barrier
	ds_read_b128 v[144:147], v200 offset:16384
	ds_read_b128 v[148:151], v200 offset:17408
	ds_read_b128 v[152:155], v200 offset:18432
	ds_read_b128 v[156:159], v200 offset:19456
	ds_read_b128 v[160:163], v200 offset:20480
	ds_read_b128 v[174:177], v200 offset:21504
	ds_read_b128 v[178:181], v200 offset:22528
	ds_read_b128 v[182:185], v200 offset:23552
	global_load_lds_dwordx4 v[212:213], off
	s_mov_b32 m0, s42
	v_lshl_add_u64 v[214:215], s[10:11], 0, v[166:167]
	global_load_lds_dwordx4 v[214:215], off
	s_barrier
	s_waitcnt lgkmcnt(0)
	v_mfma_f32_16x16x32_bf16 v[108:111], v[128:131], v[144:147], v[108:111]
	v_mfma_f32_16x16x32_bf16 v[76:79], v[136:139], v[144:147], v[76:79]
	v_mfma_f32_16x16x32_bf16 v[104:107], v[128:131], v[152:155], v[104:107]
	v_mfma_f32_16x16x32_bf16 v[72:75], v[136:139], v[152:155], v[72:75]
	v_mfma_f32_16x16x32_bf16 v[100:103], v[128:131], v[160:163], v[100:103]
	v_mfma_f32_16x16x32_bf16 v[68:71], v[136:139], v[160:163], v[68:71]
	v_mfma_f32_16x16x32_bf16 v[96:99], v[128:131], v[178:181], v[96:99]
	v_mfma_f32_16x16x32_bf16 v[64:67], v[136:139], v[178:181], v[64:67]
	v_mfma_f32_16x16x32_bf16 v[108:111], v[132:135], v[148:151], v[108:111]
	v_mfma_f32_16x16x32_bf16 v[76:79], v[140:143], v[148:151], v[76:79]
	v_mfma_f32_16x16x32_bf16 v[104:107], v[132:135], v[156:159], v[104:107]
	v_mfma_f32_16x16x32_bf16 v[72:75], v[140:143], v[156:159], v[72:75]
	v_mfma_f32_16x16x32_bf16 v[100:103], v[132:135], v[174:177], v[100:103]
	v_mfma_f32_16x16x32_bf16 v[68:71], v[140:143], v[174:177], v[68:71]
	v_mfma_f32_16x16x32_bf16 v[96:99], v[132:135], v[182:185], v[96:99]
	v_mfma_f32_16x16x32_bf16 v[64:67], v[140:143], v[182:185], v[64:67]
	s_barrier
	s_add_u32 s4, s8, 0x160000
	s_addc_u32 s5, s9, 0
	s_mov_b32 m0, s58
	v_lshl_add_u64 v[128:129], s[4:5], 0, v[164:165]
	global_load_lds_dwordx4 v[128:129], off
	s_mov_b32 m0, s59
	v_lshl_add_u64 v[128:129], s[4:5], 0, v[166:167]
	global_load_lds_dwordx4 v[128:129], off
	s_waitcnt vmcnt(6)
	s_barrier
; #define WAIT_V(n) asm volatile("s_waitcnt vmcnt(" #n ")" ::: "memory")
; #define WAIT_L(n) asm volatile("s_waitcnt lgkmcnt(" #n ")" ::: "memory")
; #define BAR __builtin_amdgcn_s_barrier()
; #define SCHED __builtin_amdgcn_sched_barrier(0)
; template <class Get, class Epi>
; DI void gemm_stream(LAS unsigned char* lds, const int K, const int ld, Get get, Epi epi) {
;     ...
;             LDB(B0, 1, 0); SCHED; LDA(At, 1, 0); STAGE(SAo(0, 1), a2 + hstep);
;             WAIT_L(8); BAR; WAIT_L(0); MMA(0, 0, At, B0); BAR; SCHED;
;             LDB(B1, 1, 1); STAGE(SBo(1, 0), b3);
;             BAR; WAIT_L(0); MMA(0, 1, At, B1); BAR;
;             LDA(At, 1, 1); STAGE(SAo(1, 0), a3);
;             BAR; WAIT_L(0); MMA(1, 0, At, B0); BAR; SCHED;
;             STAGE(SBo(1, 1), b3 + hstep);
;             WAIT_V(6); BAR; MMA(1, 1, At, B1); BAR;
	v_mfma_f32_16x16x32_bf16 v[44:47], v[186:189], v[144:147], v[44:47]
	v_mfma_f32_16x16x32_bf16 v[12:15], v[194:197], v[144:147], v[12:15]
	v_mfma_f32_16x16x32_bf16 v[40:43], v[186:189], v[152:155], v[40:43]
	v_mfma_f32_16x16x32_bf16 v[8:11], v[194:197], v[152:155], v[8:11]
	v_mfma_f32_16x16x32_bf16 v[36:39], v[186:189], v[160:163], v[36:39]
	v_mfma_f32_16x16x32_bf16 v[4:7], v[194:197], v[160:163], v[4:7]
	v_mfma_f32_16x16x32_bf16 v[32:35], v[186:189], v[178:181], v[32:35]
	v_mfma_f32_16x16x32_bf16 v[0:3], v[194:197], v[178:181], v[0:3]
	v_mfma_f32_16x16x32_bf16 v[44:47], v[190:193], v[148:151], v[44:47]
	v_mfma_f32_16x16x32_bf16 v[12:15], v[202:205], v[148:151], v[12:15]
	v_mfma_f32_16x16x32_bf16 v[40:43], v[190:193], v[156:159], v[40:43]
	v_mfma_f32_16x16x32_bf16 v[8:11], v[202:205], v[156:159], v[8:11]
	v_mfma_f32_16x16x32_bf16 v[36:39], v[190:193], v[174:177], v[36:39]
	v_mfma_f32_16x16x32_bf16 v[4:7], v[202:205], v[174:177], v[4:7]
	v_mfma_f32_16x16x32_bf16 v[32:35], v[190:193], v[182:185], v[32:35]
	v_mfma_f32_16x16x32_bf16 v[0:3], v[202:205], v[182:185], v[0:3]
	s_add_i32 s17, 16, 0x18000
	v_add_u32_e32 v140, s17, v198
	s_barrier
	ds_read_b128 v[128:131], v140
	ds_read_b128 v[132:135], v140 offset:1024
	ds_read_b128 v[136:139], v140 offset:2048
	ds_read_b128 v[140:143], v140 offset:3072
	s_add_u32 s4, s10, 0x160000
	s_addc_u32 s5, s11, 0
	s_mov_b32 m0, s43
	v_lshl_add_u64 v[186:187], s[4:5], 0, v[164:165]
	ds_read_b128 v[144:147], v200 offset:32768
	ds_read_b128 v[148:151], v200 offset:33792
	ds_read_b128 v[152:155], v200 offset:34816
	ds_read_b128 v[156:159], v200 offset:35840
	ds_read_b128 v[160:163], v200 offset:36864
	ds_read_b128 v[174:177], v200 offset:37888
	ds_read_b128 v[178:181], v200 offset:38912
	ds_read_b128 v[182:185], v200 offset:39936
	global_load_lds_dwordx4 v[186:187], off
	s_mov_b32 m0, s44
	v_lshl_add_u64 v[186:187], s[4:5], 0, v[166:167]
	global_load_lds_dwordx4 v[186:187], off
	s_waitcnt lgkmcnt(8)
	s_barrier
	s_waitcnt lgkmcnt(0)
	v_mfma_f32_16x16x32_bf16 v[124:127], v[128:131], v[144:147], v[124:127]
	v_mfma_f32_16x16x32_bf16 v[92:95], v[136:139], v[144:147], v[92:95]
	v_mfma_f32_16x16x32_bf16 v[120:123], v[128:131], v[152:155], v[120:123]
	v_mfma_f32_16x16x32_bf16 v[88:91], v[136:139], v[152:155], v[88:91]
	v_mfma_f32_16x16x32_bf16 v[116:119], v[128:131], v[160:163], v[116:119]
	v_mfma_f32_16x16x32_bf16 v[84:87], v[136:139], v[160:163], v[84:87]
	v_mfma_f32_16x16x32_bf16 v[112:115], v[128:131], v[178:181], v[112:115]
	v_mfma_f32_16x16x32_bf16 v[80:83], v[136:139], v[178:181], v[80:83]
	v_mfma_f32_16x16x32_bf16 v[124:127], v[132:135], v[148:151], v[124:127]
	v_mfma_f32_16x16x32_bf16 v[92:95], v[140:143], v[148:151], v[92:95]
	v_mfma_f32_16x16x32_bf16 v[120:123], v[132:135], v[156:159], v[120:123]
	v_mfma_f32_16x16x32_bf16 v[88:91], v[140:143], v[156:159], v[88:91]
	v_mfma_f32_16x16x32_bf16 v[116:119], v[132:135], v[174:177], v[116:119]
	v_mfma_f32_16x16x32_bf16 v[84:87], v[140:143], v[174:177], v[84:87]
	v_mfma_f32_16x16x32_bf16 v[112:115], v[132:135], v[182:185], v[112:115]
	v_mfma_f32_16x16x32_bf16 v[80:83], v[140:143], v[182:185], v[80:83]
	s_barrier
	s_add_i32 s10, 16, 0x1c000
	s_add_i32 s4, s17, s21
	v_add_u32_e32 v202, s10, v198
	v_lshl_add_u64 v[208:209], v[208:209], 0, s[0:1]
	s_mov_b32 m0, s4
	ds_read_b128 v[186:189], v202
	ds_read_b128 v[190:193], v202 offset:1024
	ds_read_b128 v[194:197], v202 offset:2048
	ds_read_b128 v[202:205], v202 offset:3072
	global_load_lds_dwordx4 v[208:209], off
	v_lshl_add_u64 v[208:209], v[210:211], 0, s[0:1]
	s_add_i32 m0, s4, 0x2000
	s_nop 0
	global_load_lds_dwordx4 v[208:209], off
	s_barrier
	s_waitcnt lgkmcnt(0)
	v_mfma_f32_16x16x32_bf16 v[60:63], v[186:189], v[144:147], v[60:63]
	v_mfma_f32_16x16x32_bf16 v[28:31], v[194:197], v[144:147], v[28:31]
	v_mfma_f32_16x16x32_bf16 v[56:59], v[186:189], v[152:155], v[56:59]
	v_mfma_f32_16x16x32_bf16 v[24:27], v[194:197], v[152:155], v[24:27]
	v_mfma_f32_16x16x32_bf16 v[52:55], v[186:189], v[160:163], v[52:55]
	v_mfma_f32_16x16x32_bf16 v[20:23], v[194:197], v[160:163], v[20:23]
	v_mfma_f32_16x16x32_bf16 v[48:51], v[186:189], v[178:181], v[48:51]
	v_mfma_f32_16x16x32_bf16 v[16:19], v[194:197], v[178:181], v[16:19]
	v_mfma_f32_16x16x32_bf16 v[60:63], v[190:193], v[148:151], v[60:63]
	v_mfma_f32_16x16x32_bf16 v[28:31], v[202:205], v[148:151], v[28:31]
	v_mfma_f32_16x16x32_bf16 v[56:59], v[190:193], v[156:159], v[56:59]
	v_mfma_f32_16x16x32_bf16 v[24:27], v[202:205], v[156:159], v[24:27]
	v_mfma_f32_16x16x32_bf16 v[52:55], v[190:193], v[174:177], v[52:55]
	v_mfma_f32_16x16x32_bf16 v[20:23], v[202:205], v[174:177], v[20:23]
	v_mfma_f32_16x16x32_bf16 v[48:51], v[190:193], v[182:185], v[48:51]
	v_mfma_f32_16x16x32_bf16 v[16:19], v[202:205], v[182:185], v[16:19]
	s_mov_b32 m0, s45
	v_lshl_add_u64 v[208:209], v[212:213], 0, s[0:1]
	s_barrier
	ds_read_b128 v[144:147], v200 offset:49152
	ds_read_b128 v[148:151], v200 offset:50176
	ds_read_b128 v[152:155], v200 offset:51200
	ds_read_b128 v[156:159], v200 offset:52224
	ds_read_b128 v[160:163], v200 offset:53248
	ds_read_b128 v[174:177], v200 offset:54272
	ds_read_b128 v[178:181], v200 offset:55296
	ds_read_b128 v[182:185], v200 offset:56320
	global_load_lds_dwordx4 v[208:209], off
	s_mov_b32 m0, s46
	v_lshl_add_u64 v[208:209], v[214:215], 0, s[0:1]
	global_load_lds_dwordx4 v[208:209], off
	s_barrier
; #define WAIT_V(n) asm volatile("s_waitcnt vmcnt(" #n ")" ::: "memory")
; #define WAIT_L(n) asm volatile("s_waitcnt lgkmcnt(" #n ")" ::: "memory")
; #define BAR __builtin_amdgcn_s_barrier()
; #define SCHED __builtin_amdgcn_sched_barrier(0)
; template <class Get, class Epi>
; DI void gemm_stream(LAS unsigned char* lds, const int K, const int ld, Get get, Epi epi) {
;     ...
;             BAR; WAIT_L(0); MMA(1, 0, At, B0); BAR; SCHED;
;             STAGE(SBo(1, 1), b3 + hstep);
;             WAIT_V(6); BAR; MMA(1, 1, At, B1); BAR;
;         }
; DI void epi_resid(const Acc& acc, const P& p, int brow, int bcol, int layer, int gch, bool from_input) {
;     EPI_IDX
;     const float* gate = modv(p, layer, brow, gch);
; #pragma unroll
;     for (int bj = 0; bj < 2; ++bj)
; #pragma unroll
;         for (int n = 0; n < 2; ++n) {
;             const int c0 = bcol + bj * 128 + wc * 32 + n * 16 + fq * 4;
;             const f32x4 g = *(const f32x4*)(gate + c0);
;             f32x4 xv[2][4];
; #pragma unroll
;             for (int ai = 0; ai < 2; ++ai)
; #pragma unroll
;                 for (int m = 0; m < 4; ++m) {
;                     const int r = brow + ai * 128 + wr * 64 + m * 16 + fr;
;                     const float* sp = (from_input ? inrow(p, r) : xrow(p, r)) + c0;
;                     xv[ai][m] = *(const f32x4*)sp;
	s_waitcnt lgkmcnt(0)
	v_mfma_f32_16x16x32_bf16 v[108:111], v[128:131], v[144:147], v[108:111]
	v_mfma_f32_16x16x32_bf16 v[76:79], v[136:139], v[144:147], v[76:79]
	v_mfma_f32_16x16x32_bf16 v[104:107], v[128:131], v[152:155], v[104:107]
	v_mfma_f32_16x16x32_bf16 v[72:75], v[136:139], v[152:155], v[72:75]
	v_mfma_f32_16x16x32_bf16 v[100:103], v[128:131], v[160:163], v[100:103]
	v_mfma_f32_16x16x32_bf16 v[68:71], v[136:139], v[160:163], v[68:71]
	v_mfma_f32_16x16x32_bf16 v[96:99], v[128:131], v[178:181], v[96:99]
	v_mfma_f32_16x16x32_bf16 v[64:67], v[136:139], v[178:181], v[64:67]
	v_mfma_f32_16x16x32_bf16 v[108:111], v[132:135], v[148:151], v[108:111]
	v_mfma_f32_16x16x32_bf16 v[76:79], v[140:143], v[148:151], v[76:79]
	v_mfma_f32_16x16x32_bf16 v[104:107], v[132:135], v[156:159], v[104:107]
	v_mfma_f32_16x16x32_bf16 v[72:75], v[140:143], v[156:159], v[72:75]
	v_mfma_f32_16x16x32_bf16 v[100:103], v[132:135], v[174:177], v[100:103]
	v_mfma_f32_16x16x32_bf16 v[68:71], v[140:143], v[174:177], v[68:71]
	v_mfma_f32_16x16x32_bf16 v[96:99], v[132:135], v[182:185], v[96:99]
	v_mfma_f32_16x16x32_bf16 v[64:67], v[140:143], v[182:185], v[64:67]
	s_barrier
	s_add_u32 s4, s8, 0x160080
	s_addc_u32 s5, s9, 0
	s_add_i32 s8, s10, s21
	s_mov_b32 m0, s8
	v_lshl_add_u64 v[128:129], s[4:5], 0, v[164:165]
	global_load_lds_dwordx4 v[128:129], off
	v_lshl_add_u64 v[128:129], s[4:5], 0, v[166:167]
	s_add_i32 m0, s8, 0x2000
	s_nop 0
	global_load_lds_dwordx4 v[128:129], off
	s_waitcnt vmcnt(6)
	s_barrier
	v_mfma_f32_16x16x32_bf16 v[44:47], v[186:189], v[144:147], v[44:47]
	v_mfma_f32_16x16x32_bf16 v[12:15], v[194:197], v[144:147], v[12:15]
	v_mfma_f32_16x16x32_bf16 v[40:43], v[186:189], v[152:155], v[40:43]
	v_mfma_f32_16x16x32_bf16 v[8:11], v[194:197], v[152:155], v[8:11]
	v_mfma_f32_16x16x32_bf16 v[36:39], v[186:189], v[160:163], v[36:39]
	v_mfma_f32_16x16x32_bf16 v[4:7], v[194:197], v[160:163], v[4:7]
	v_mfma_f32_16x16x32_bf16 v[32:35], v[186:189], v[178:181], v[32:35]
	v_mfma_f32_16x16x32_bf16 v[0:3], v[194:197], v[178:181], v[0:3]
	v_mfma_f32_16x16x32_bf16 v[44:47], v[190:193], v[148:151], v[44:47]
	v_mfma_f32_16x16x32_bf16 v[12:15], v[202:205], v[148:151], v[12:15]
	v_mfma_f32_16x16x32_bf16 v[40:43], v[190:193], v[156:159], v[40:43]
	v_mfma_f32_16x16x32_bf16 v[8:11], v[202:205], v[156:159], v[8:11]
	v_mfma_f32_16x16x32_bf16 v[36:39], v[190:193], v[174:177], v[36:39]
	v_mfma_f32_16x16x32_bf16 v[4:7], v[202:205], v[174:177], v[4:7]
	v_mfma_f32_16x16x32_bf16 v[32:35], v[190:193], v[182:185], v[32:35]
	v_mfma_f32_16x16x32_bf16 v[0:3], v[202:205], v[182:185], v[0:3]
	s_add_i32 s16, s16, 2
	s_add_u32 s14, s14, 0x100
	s_addc_u32 s15, s15, 0
	s_cmpk_gt_u32 s16, 0x55
	s_mov_b64 s[4:5], s[6:7]
	s_barrier
	s_cbranch_scc0 .LBB0_3113
	s_lshr_b32 s4, s13, 4
	s_lshl_b32 s5, s13, 8
	s_mulk_i32 s4, 0x1100
	s_and_b32 s5, s5, 0xf00
	s_add_i32 s4, s4, s5
	s_add_i32 s6, s4, 0x100
	s_mul_hi_i32 s4, s6, 0x78787879
	s_lshr_b32 s5, s4, 31
	s_ashr_i32 s4, s4, 11
	s_add_i32 s4, s4, s5
	s_mul_i32 s5, s4, 0xffffef00
	s_mul_i32 s4, s4, 6
	s_lshl_b32 s7, s12, 8
	s_add_i32 s5, s5, s6
	s_add_i32 s4, s4, 35
	s_cmpk_gt_i32 s5, 0xff
	v_mov_b32_e32 v132, v206
	s_cselect_b32 s4, s4, 59
	s_ashr_i32 s5, s4, 31
	v_lshrrev_b32_e32 v128, 1, v132
	v_lshrrev_b32_e32 v129, 2, v132
	s_lshl_b64 s[4:5], s[4:5], 13
	v_and_b32_e32 v128, 0x60, v128
	v_and_b32_e32 v129, 12, v129
	s_add_u32 s4, s26, s4
	v_or3_b32 v174, v128, s7, v129
	s_addc_u32 s5, s27, s5
	v_ashrrev_i32_e32 v175, 31, v174
	v_lshl_add_u64 v[192:193], v[174:175], 2, s[4:5]
	global_load_dwordx4 v[128:131], v[192:193], off
	v_ashrrev_i32_e32 v133, 2, v132
	v_and_b32_e32 v133, 0xffffffc0, v133
	v_and_or_b32 v132, v132, 15, s6
	v_add_u32_e32 v176, v132, v133
	v_mul_hi_i32 v132, v176, s48
	v_lshrrev_b32_e32 v133, 31, v132
	v_ashrrev_i32_e32 v132, 11, v132
	v_add_u32_e32 v203, v132, v133
	v_mad_i32_i24 v202, v203, s49, v176
	v_lshlrev_b32_e32 v212, 12, v203
	v_cmp_lt_i32_e64 s[16:17], s52, v202
	v_add3_u32 v190, v212, v202, s53
	s_and_saveexec_b64 s[4:5], s[16:17]
	s_xor_b64 s[4:5], exec, s[4:5]
	v_add3_u32 v132, v212, v202, s53
	s_or_saveexec_b64 s[4:5], s[4:5]
	v_mov_b64_e32 v[134:135], s[24:25]
	v_lshl_add_u32 v191, v203, 8, v202
	s_xor_b64 exec, exec, s[4:5]
	v_lshl_add_u32 v132, v203, 8, v202
	v_mov_b64_e32 v[134:135], s[18:19]
	s_or_b64 exec, exec, s[4:5]
	v_ashrrev_i32_e32 v133, 31, v132
	v_lshlrev_b64 v[132:133], 13, v[132:133]
	v_lshl_add_u64 v[132:133], v[134:135], 0, v[132:133]
	v_lshl_add_u64 v[132:133], v[174:175], 2, v[132:133]
	global_load_dwordx4 v[160:163], v[132:133], off
	v_or_b32_e32 v132, 16, v176
	v_mul_hi_i32 v133, v132, s48
	v_lshrrev_b32_e32 v134, 31, v133
	v_ashrrev_i32_e32 v133, 11, v133
	v_add_u32_e32 v205, v133, v134
	v_mad_i32_i24 v204, v205, s49, v132
	v_lshlrev_b32_e32 v217, 12, v205
	v_cmp_lt_i32_e64 s[14:15], s52, v204
	v_add3_u32 v188, v217, v204, s53
	s_and_saveexec_b64 s[4:5], s[14:15]
	s_xor_b64 s[4:5], exec, s[4:5]
	v_add3_u32 v132, v217, v204, s53
	s_or_saveexec_b64 s[4:5], s[4:5]
	v_mov_b64_e32 v[134:135], s[24:25]
	v_lshl_add_u32 v189, v205, 8, v204
	s_xor_b64 exec, exec, s[4:5]
	v_lshl_add_u32 v132, v205, 8, v204
	v_mov_b64_e32 v[134:135], s[18:19]
	s_or_b64 exec, exec, s[4:5]
	v_ashrrev_i32_e32 v133, 31, v132
	v_lshlrev_b64 v[132:133], 13, v[132:133]
	v_lshl_add_u64 v[132:133], v[134:135], 0, v[132:133]
	v_lshl_add_u64 v[132:133], v[174:175], 2, v[132:133]
	global_load_dwordx4 v[156:159], v[132:133], off
	v_or_b32_e32 v132, 32, v176
	v_mul_hi_i32 v133, v132, s48
	v_lshrrev_b32_e32 v134, 31, v133
	v_ashrrev_i32_e32 v133, 11, v133
	v_add_u32_e32 v209, v133, v134
	v_mad_i32_i24 v208, v209, s49, v132
; DI void epi_resid(const Acc& acc, const P& p, int brow, int bcol, int layer, int gch, bool from_input) {
;     ...
; #pragma unroll
;             for (int ai = 0; ai < 2; ++ai)
; #pragma unroll
;                 for (int m = 0; m < 4; ++m) {
;                     const int r = brow + ai * 128 + wr * 64 + m * 16 + fr;
;                     const float* sp = (from_input ? inrow(p, r) : xrow(p, r)) + c0;
;                     xv[ai][m] = *(const f32x4*)sp;
;                 }
	v_lshlrev_b32_e32 v220, 12, v209
	v_cmp_lt_i32_e64 s[12:13], s52, v208
	v_add3_u32 v186, v220, v208, s53
	s_and_saveexec_b64 s[4:5], s[12:13]
	s_xor_b64 s[4:5], exec, s[4:5]
	v_add3_u32 v132, v220, v208, s53
	s_or_saveexec_b64 s[4:5], s[4:5]
	v_mov_b64_e32 v[134:135], s[24:25]
	v_lshl_add_u32 v187, v209, 8, v208
	s_xor_b64 exec, exec, s[4:5]
	v_lshl_add_u32 v132, v209, 8, v208
	v_mov_b64_e32 v[134:135], s[18:19]
	s_or_b64 exec, exec, s[4:5]
	v_ashrrev_i32_e32 v133, 31, v132
	v_lshlrev_b64 v[132:133], 13, v[132:133]
	v_lshl_add_u64 v[132:133], v[134:135], 0, v[132:133]
	v_lshl_add_u64 v[132:133], v[174:175], 2, v[132:133]
	global_load_dwordx4 v[152:155], v[132:133], off
	v_or_b32_e32 v132, 48, v176
	v_mul_hi_i32 v133, v132, s48
	v_lshrrev_b32_e32 v134, 31, v133
	v_ashrrev_i32_e32 v133, 11, v133
	v_add_u32_e32 v211, v133, v134
	v_mad_i32_i24 v210, v211, s49, v132
	v_lshlrev_b32_e32 v223, 12, v211
	v_cmp_lt_i32_e64 s[10:11], s52, v210
	v_add3_u32 v184, v223, v210, s53
	s_and_saveexec_b64 s[4:5], s[10:11]
	s_xor_b64 s[4:5], exec, s[4:5]
	v_add3_u32 v132, v223, v210, s53
	s_or_saveexec_b64 s[4:5], s[4:5]
	v_mov_b64_e32 v[134:135], s[24:25]
	v_lshl_add_u32 v185, v211, 8, v210
	s_xor_b64 exec, exec, s[4:5]
	v_lshl_add_u32 v132, v211, 8, v210
	v_mov_b64_e32 v[134:135], s[18:19]
	s_or_b64 exec, exec, s[4:5]
	v_ashrrev_i32_e32 v133, 31, v132
	v_lshlrev_b64 v[132:133], 13, v[132:133]
	v_lshl_add_u64 v[132:133], v[134:135], 0, v[132:133]
	v_lshl_add_u64 v[132:133], v[174:175], 2, v[132:133]
	global_load_dwordx4 v[148:151], v[132:133], off
	v_add_u32_e32 v132, 0x80, v176
	v_mul_hi_i32 v133, v132, s48
	v_lshrrev_b32_e32 v134, 31, v133
	v_ashrrev_i32_e32 v133, 11, v133
	v_add_u32_e32 v214, v133, v134
	v_mad_i32_i24 v213, v214, s49, v132
	v_lshlrev_b32_e32 v224, 12, v214
	v_cmp_lt_i32_e64 s[8:9], s52, v213
	v_add3_u32 v182, v224, v213, s53
	s_and_saveexec_b64 s[4:5], s[8:9]
	s_xor_b64 s[4:5], exec, s[4:5]
	v_add3_u32 v132, v224, v213, s53
	s_or_saveexec_b64 s[4:5], s[4:5]
	v_mov_b64_e32 v[134:135], s[24:25]
	v_lshl_add_u32 v183, v214, 8, v213
	s_xor_b64 exec, exec, s[4:5]
	v_lshl_add_u32 v132, v214, 8, v213
	v_mov_b64_e32 v[134:135], s[18:19]
	s_or_b64 exec, exec, s[4:5]
	v_ashrrev_i32_e32 v133, 31, v132
	v_lshlrev_b64 v[132:133], 13, v[132:133]
	v_lshl_add_u64 v[132:133], v[134:135], 0, v[132:133]
	v_lshl_add_u64 v[132:133], v[174:175], 2, v[132:133]
	global_load_dwordx4 v[144:147], v[132:133], off
	v_add_u32_e32 v132, 0x90, v176
	v_mul_hi_i32 v133, v132, s48
	v_lshrrev_b32_e32 v134, 31, v133
	v_ashrrev_i32_e32 v133, 11, v133
	v_add_u32_e32 v216, v133, v134
	v_mad_i32_i24 v215, v216, s49, v132
	v_lshlrev_b32_e32 v225, 12, v216
	v_cmp_lt_i32_e64 s[6:7], s52, v215
	v_add3_u32 v180, v225, v215, s53
	s_and_saveexec_b64 s[4:5], s[6:7]
	s_xor_b64 s[4:5], exec, s[4:5]
	v_add3_u32 v132, v225, v215, s53
	s_or_saveexec_b64 s[4:5], s[4:5]
	v_mov_b64_e32 v[134:135], s[24:25]
	v_lshl_add_u32 v181, v216, 8, v215
	s_xor_b64 exec, exec, s[4:5]
	v_lshl_add_u32 v132, v216, 8, v215
	v_mov_b64_e32 v[134:135], s[18:19]
	s_or_b64 exec, exec, s[4:5]
	v_ashrrev_i32_e32 v133, 31, v132
	v_lshlrev_b64 v[132:133], 13, v[132:133]
	v_lshl_add_u64 v[132:133], v[134:135], 0, v[132:133]
	v_lshl_add_u64 v[132:133], v[174:175], 2, v[132:133]
	global_load_dwordx4 v[140:143], v[132:133], off
	v_add_u32_e32 v132, 0xa0, v176
	v_mul_hi_i32 v133, v132, s48
	v_lshrrev_b32_e32 v134, 31, v133
	v_ashrrev_i32_e32 v133, 11, v133
	v_add_u32_e32 v219, v133, v134
	v_mad_i32_i24 v218, v219, s49, v132
	v_lshlrev_b32_e32 v226, 12, v219
	v_cmp_lt_i32_e64 s[4:5], s52, v218
	v_add3_u32 v178, v226, v218, s53
	s_and_saveexec_b64 s[28:29], s[4:5]
	s_xor_b64 s[40:41], exec, s[28:29]
	v_add3_u32 v132, v226, v218, s53
	s_or_saveexec_b64 s[40:41], s[40:41]
	v_mov_b64_e32 v[134:135], s[24:25]
	v_lshl_add_u32 v179, v219, 8, v218
	s_xor_b64 exec, exec, s[40:41]
	v_lshl_add_u32 v132, v219, 8, v218
	v_mov_b64_e32 v[134:135], s[18:19]
	s_or_b64 exec, exec, s[40:41]
	v_ashrrev_i32_e32 v133, 31, v132
	v_lshlrev_b64 v[132:133], 13, v[132:133]
	v_lshl_add_u64 v[132:133], v[134:135], 0, v[132:133]
	v_lshl_add_u64 v[132:133], v[174:175], 2, v[132:133]
	global_load_dwordx4 v[136:139], v[132:133], off
	v_add_u32_e32 v132, 0xb0, v176
	v_mul_hi_i32 v133, v132, s48
	v_lshrrev_b32_e32 v134, 31, v133
	v_ashrrev_i32_e32 v133, 11, v133
	v_add_u32_e32 v222, v133, v134
	v_mad_i32_i24 v221, v222, s49, v132
	v_lshlrev_b32_e32 v227, 12, v222
	v_cmp_lt_i32_e32 vcc, s52, v221
	v_add3_u32 v176, v227, v221, s53
	s_and_saveexec_b64 s[28:29], vcc
	s_xor_b64 s[40:41], exec, s[28:29]
	v_add3_u32 v132, v227, v221, s53
	s_or_saveexec_b64 s[40:41], s[40:41]
	v_mov_b64_e32 v[134:135], s[24:25]
	v_lshl_add_u32 v177, v222, 8, v221
	s_xor_b64 exec, exec, s[40:41]
	v_lshl_add_u32 v132, v222, 8, v221
	v_mov_b64_e32 v[134:135], s[18:19]
	s_or_b64 exec, exec, s[40:41]
	v_ashrrev_i32_e32 v133, 31, v132
	v_lshlrev_b64 v[132:133], 13, v[132:133]
	v_lshl_add_u64 v[132:133], v[134:135], 0, v[132:133]
	v_lshl_add_u64 v[132:133], v[174:175], 2, v[132:133]
	global_load_dwordx4 v[132:135], v[132:133], off
	s_and_saveexec_b64 s[28:29], s[16:17]
	s_xor_b64 s[40:41], exec, s[28:29]
	v_add3_u32 v194, v212, v202, s53
	s_or_saveexec_b64 s[40:41], s[40:41]
	v_mov_b64_e32 v[196:197], s[24:25]
	s_xor_b64 exec, exec, s[40:41]
	v_lshl_add_u32 v194, v203, 8, v202
	v_mov_b64_e32 v[196:197], s[18:19]
	s_or_b64 exec, exec, s[40:41]
	v_ashrrev_i32_e32 v195, 31, v194
	s_waitcnt vmcnt(0)
; DI void epi_resid(const Acc& acc, const P& p, int brow, int bcol, int layer, int gch, bool from_input) {
;     ...
; #pragma unroll
;             for (int ai = 0; ai < 2; ++ai)
; #pragma unroll
;                 for (int m = 0; m < 4; ++m) {
;                     const int r = brow + ai * 128 + wr * 64 + m * 16 + fr;
;                     const float* sp = (from_input ? inrow(p, r) : xrow(p, r)) + c0;
;                     xv[ai][m] = *(const f32x4*)sp;
;                 }
;     ...
; #pragma unroll
;             for (int ai = 0; ai < 2; ++ai)
; #pragma unroll
;                 for (int m = 0; m < 4; ++m) {
;                     const int r = brow + ai * 128 + wr * 64 + m * 16 + fr;
;                     *(f32x4*)(xrow(p, r) + c0) = xv[ai][m] + g * acc[ai][bj][m][n];
;                 }
	v_pk_fma_f32 v[124:125], v[124:125], v[128:129], v[160:161]
	v_lshlrev_b64 v[160:161], 13, v[194:195]
	v_lshl_add_u64 v[160:161], v[196:197], 0, v[160:161]
	v_pk_fma_f32 v[126:127], v[126:127], v[130:131], v[162:163]
	v_lshl_add_u64 v[160:161], v[174:175], 2, v[160:161]
	global_store_dwordx4 v[160:161], v[124:127], off
	s_and_saveexec_b64 s[28:29], s[14:15]
	s_xor_b64 s[40:41], exec, s[28:29]
	v_add3_u32 v124, v217, v204, s53
	s_or_saveexec_b64 s[40:41], s[40:41]
	v_mov_b64_e32 v[126:127], s[24:25]
	s_xor_b64 exec, exec, s[40:41]
	v_lshl_add_u32 v124, v205, 8, v204
	v_mov_b64_e32 v[126:127], s[18:19]
	s_or_b64 exec, exec, s[40:41]
	v_ashrrev_i32_e32 v125, 31, v124
	v_lshlrev_b64 v[124:125], 13, v[124:125]
	v_lshl_add_u64 v[124:125], v[126:127], 0, v[124:125]
	v_pk_fma_f32 v[122:123], v[122:123], v[130:131], v[158:159]
	v_pk_fma_f32 v[120:121], v[120:121], v[128:129], v[156:157]
	v_lshl_add_u64 v[124:125], v[174:175], 2, v[124:125]
	global_store_dwordx4 v[124:125], v[120:123], off
	s_and_saveexec_b64 s[28:29], s[12:13]
	s_xor_b64 s[40:41], exec, s[28:29]
	v_add3_u32 v120, v220, v208, s53
	s_or_saveexec_b64 s[40:41], s[40:41]
	v_mov_b64_e32 v[122:123], s[24:25]
	s_xor_b64 exec, exec, s[40:41]
	v_lshl_add_u32 v120, v209, 8, v208
	v_mov_b64_e32 v[122:123], s[18:19]
	s_or_b64 exec, exec, s[40:41]
	v_ashrrev_i32_e32 v121, 31, v120
	v_lshlrev_b64 v[120:121], 13, v[120:121]
	v_lshl_add_u64 v[120:121], v[122:123], 0, v[120:121]
	v_pk_fma_f32 v[118:119], v[118:119], v[130:131], v[154:155]
	v_pk_fma_f32 v[116:117], v[116:117], v[128:129], v[152:153]
	v_lshl_add_u64 v[120:121], v[174:175], 2, v[120:121]
	global_store_dwordx4 v[120:121], v[116:119], off
	s_and_saveexec_b64 s[28:29], s[10:11]
	s_xor_b64 s[40:41], exec, s[28:29]
	v_add3_u32 v116, v223, v210, s53
	s_or_saveexec_b64 s[40:41], s[40:41]
	v_mov_b64_e32 v[118:119], s[24:25]
	s_xor_b64 exec, exec, s[40:41]
	v_lshl_add_u32 v116, v211, 8, v210
	v_mov_b64_e32 v[118:119], s[18:19]
	s_or_b64 exec, exec, s[40:41]
	v_ashrrev_i32_e32 v117, 31, v116
	v_lshlrev_b64 v[116:117], 13, v[116:117]
	v_lshl_add_u64 v[116:117], v[118:119], 0, v[116:117]
	v_pk_fma_f32 v[114:115], v[114:115], v[130:131], v[150:151]
	v_pk_fma_f32 v[112:113], v[112:113], v[128:129], v[148:149]
	v_lshl_add_u64 v[116:117], v[174:175], 2, v[116:117]
	global_store_dwordx4 v[116:117], v[112:115], off
	s_and_saveexec_b64 s[28:29], s[8:9]
	s_xor_b64 s[40:41], exec, s[28:29]
	v_add3_u32 v112, v224, v213, s53
	s_or_saveexec_b64 s[40:41], s[40:41]
	v_mov_b64_e32 v[114:115], s[24:25]
	s_xor_b64 exec, exec, s[40:41]
	v_lshl_add_u32 v112, v214, 8, v213
	v_mov_b64_e32 v[114:115], s[18:19]
	s_or_b64 exec, exec, s[40:41]
	v_ashrrev_i32_e32 v113, 31, v112
	v_lshlrev_b64 v[112:113], 13, v[112:113]
	v_lshl_add_u64 v[112:113], v[114:115], 0, v[112:113]
	v_pk_fma_f32 v[110:111], v[110:111], v[130:131], v[146:147]
	v_pk_fma_f32 v[108:109], v[108:109], v[128:129], v[144:145]
	v_lshl_add_u64 v[112:113], v[174:175], 2, v[112:113]
	global_store_dwordx4 v[112:113], v[108:111], off
	s_and_saveexec_b64 s[28:29], s[6:7]
	s_xor_b64 s[40:41], exec, s[28:29]
	v_add3_u32 v108, v225, v215, s53
	s_or_saveexec_b64 s[40:41], s[40:41]
	v_mov_b64_e32 v[110:111], s[24:25]
	s_xor_b64 exec, exec, s[40:41]
	v_lshl_add_u32 v108, v216, 8, v215
	v_mov_b64_e32 v[110:111], s[18:19]
	s_or_b64 exec, exec, s[40:41]
	v_ashrrev_i32_e32 v109, 31, v108
	v_lshlrev_b64 v[108:109], 13, v[108:109]
	v_lshl_add_u64 v[108:109], v[110:111], 0, v[108:109]
	v_pk_fma_f32 v[106:107], v[106:107], v[130:131], v[142:143]
	v_pk_fma_f32 v[104:105], v[104:105], v[128:129], v[140:141]
	v_lshl_add_u64 v[108:109], v[174:175], 2, v[108:109]
	global_store_dwordx4 v[108:109], v[104:107], off
	s_and_saveexec_b64 s[28:29], s[4:5]
	s_xor_b64 s[40:41], exec, s[28:29]
	v_add3_u32 v104, v226, v218, s53
	s_or_saveexec_b64 s[40:41], s[40:41]
	v_mov_b64_e32 v[106:107], s[24:25]
	s_xor_b64 exec, exec, s[40:41]
	v_lshl_add_u32 v104, v219, 8, v218
	v_mov_b64_e32 v[106:107], s[18:19]
	s_or_b64 exec, exec, s[40:41]
	v_ashrrev_i32_e32 v105, 31, v104
	v_lshlrev_b64 v[104:105], 13, v[104:105]
	v_lshl_add_u64 v[104:105], v[106:107], 0, v[104:105]
	v_pk_fma_f32 v[102:103], v[102:103], v[130:131], v[138:139]
	v_pk_fma_f32 v[100:101], v[100:101], v[128:129], v[136:137]
	v_lshl_add_u64 v[104:105], v[174:175], 2, v[104:105]
	global_store_dwordx4 v[104:105], v[100:103], off
	s_and_saveexec_b64 s[28:29], vcc
	s_xor_b64 s[40:41], exec, s[28:29]
	v_add3_u32 v100, v227, v221, s53
	s_or_saveexec_b64 s[40:41], s[40:41]
	v_mov_b64_e32 v[102:103], s[24:25]
	s_xor_b64 exec, exec, s[40:41]
	v_lshl_add_u32 v100, v222, 8, v221
	v_mov_b64_e32 v[102:103], s[18:19]
	s_or_b64 exec, exec, s[40:41]
	v_ashrrev_i32_e32 v101, 31, v100
	v_lshlrev_b64 v[100:101], 13, v[100:101]
	v_lshl_add_u64 v[100:101], v[102:103], 0, v[100:101]
	v_pk_fma_f32 v[98:99], v[98:99], v[130:131], v[134:135]
	v_pk_fma_f32 v[96:97], v[96:97], v[128:129], v[132:133]
	v_lshl_add_u64 v[100:101], v[174:175], 2, v[100:101]
	global_store_dwordx4 v[100:101], v[96:99], off
	global_load_dwordx4 v[96:99], v[192:193], off offset:64
	s_and_saveexec_b64 s[28:29], s[16:17]
	s_xor_b64 s[40:41], exec, s[28:29]
	v_add3_u32 v100, v212, v202, s53
	s_or_saveexec_b64 s[40:41], s[40:41]
	v_mov_b64_e32 v[102:103], s[24:25]
	s_xor_b64 exec, exec, s[40:41]
	v_lshl_add_u32 v100, v203, 8, v202
	v_mov_b64_e32 v[102:103], s[18:19]
	s_or_b64 exec, exec, s[40:41]
	v_ashrrev_i32_e32 v101, 31, v100
	v_lshlrev_b64 v[100:101], 13, v[100:101]
	v_lshl_add_u64 v[100:101], v[102:103], 0, v[100:101]
	v_lshl_add_u64 v[100:101], v[174:175], 2, v[100:101]
	global_load_dwordx4 v[128:131], v[100:101], off offset:64
; DI void epi_resid(const Acc& acc, const P& p, int brow, int bcol, int layer, int gch, bool from_input) {
;     ...
; #pragma unroll
;             for (int ai = 0; ai < 2; ++ai)
; #pragma unroll
;                 for (int m = 0; m < 4; ++m) {
;                     const int r = brow + ai * 128 + wr * 64 + m * 16 + fr;
;                     const float* sp = (from_input ? inrow(p, r) : xrow(p, r)) + c0;
;                     xv[ai][m] = *(const f32x4*)sp;
;                 }
	s_and_saveexec_b64 s[28:29], s[14:15]
	s_xor_b64 s[40:41], exec, s[28:29]
	v_add3_u32 v100, v217, v204, s53
	s_or_saveexec_b64 s[40:41], s[40:41]
	v_mov_b64_e32 v[102:103], s[24:25]
	s_xor_b64 exec, exec, s[40:41]
	v_lshl_add_u32 v100, v205, 8, v204
	v_mov_b64_e32 v[102:103], s[18:19]
	s_or_b64 exec, exec, s[40:41]
	v_ashrrev_i32_e32 v101, 31, v100
	v_lshlrev_b64 v[100:101], 13, v[100:101]
	v_lshl_add_u64 v[100:101], v[102:103], 0, v[100:101]
	v_lshl_add_u64 v[100:101], v[174:175], 2, v[100:101]
	global_load_dwordx4 v[124:127], v[100:101], off offset:64
	s_and_saveexec_b64 s[28:29], s[12:13]
	s_xor_b64 s[40:41], exec, s[28:29]
	v_add3_u32 v100, v220, v208, s53
	s_or_saveexec_b64 s[40:41], s[40:41]
	v_mov_b64_e32 v[102:103], s[24:25]
	s_xor_b64 exec, exec, s[40:41]
	v_lshl_add_u32 v100, v209, 8, v208
	v_mov_b64_e32 v[102:103], s[18:19]
	s_or_b64 exec, exec, s[40:41]
	v_ashrrev_i32_e32 v101, 31, v100
	v_lshlrev_b64 v[100:101], 13, v[100:101]
	v_lshl_add_u64 v[100:101], v[102:103], 0, v[100:101]
	v_lshl_add_u64 v[100:101], v[174:175], 2, v[100:101]
	global_load_dwordx4 v[120:123], v[100:101], off offset:64
	s_and_saveexec_b64 s[28:29], s[10:11]
	s_xor_b64 s[40:41], exec, s[28:29]
	v_add3_u32 v100, v223, v210, s53
	s_or_saveexec_b64 s[40:41], s[40:41]
	v_mov_b64_e32 v[102:103], s[24:25]
	s_xor_b64 exec, exec, s[40:41]
	v_lshl_add_u32 v100, v211, 8, v210
	v_mov_b64_e32 v[102:103], s[18:19]
	s_or_b64 exec, exec, s[40:41]
	v_ashrrev_i32_e32 v101, 31, v100
	v_lshlrev_b64 v[100:101], 13, v[100:101]
	v_lshl_add_u64 v[100:101], v[102:103], 0, v[100:101]
	v_lshl_add_u64 v[100:101], v[174:175], 2, v[100:101]
	global_load_dwordx4 v[116:119], v[100:101], off offset:64
	s_and_saveexec_b64 s[28:29], s[8:9]
	s_xor_b64 s[40:41], exec, s[28:29]
	v_add3_u32 v100, v224, v213, s53
	s_or_saveexec_b64 s[40:41], s[40:41]
	v_mov_b64_e32 v[102:103], s[24:25]
	s_xor_b64 exec, exec, s[40:41]
	v_lshl_add_u32 v100, v214, 8, v213
	v_mov_b64_e32 v[102:103], s[18:19]
	s_or_b64 exec, exec, s[40:41]
	v_ashrrev_i32_e32 v101, 31, v100
	v_lshlrev_b64 v[100:101], 13, v[100:101]
	v_lshl_add_u64 v[100:101], v[102:103], 0, v[100:101]
	v_lshl_add_u64 v[100:101], v[174:175], 2, v[100:101]
	global_load_dwordx4 v[112:115], v[100:101], off offset:64
	s_and_saveexec_b64 s[28:29], s[6:7]
	s_xor_b64 s[40:41], exec, s[28:29]
	v_add3_u32 v100, v225, v215, s53
	s_or_saveexec_b64 s[40:41], s[40:41]
	v_mov_b64_e32 v[102:103], s[24:25]
	s_xor_b64 exec, exec, s[40:41]
	v_lshl_add_u32 v100, v216, 8, v215
	v_mov_b64_e32 v[102:103], s[18:19]
	s_or_b64 exec, exec, s[40:41]
	v_ashrrev_i32_e32 v101, 31, v100
	v_lshlrev_b64 v[100:101], 13, v[100:101]
	v_lshl_add_u64 v[100:101], v[102:103], 0, v[100:101]
	v_lshl_add_u64 v[100:101], v[174:175], 2, v[100:101]
	global_load_dwordx4 v[108:111], v[100:101], off offset:64
	s_and_saveexec_b64 s[28:29], s[4:5]
	s_xor_b64 s[40:41], exec, s[28:29]
	v_add3_u32 v100, v226, v218, s53
	s_or_saveexec_b64 s[40:41], s[40:41]
	v_mov_b64_e32 v[102:103], s[24:25]
	s_xor_b64 exec, exec, s[40:41]
	v_lshl_add_u32 v100, v219, 8, v218
	v_mov_b64_e32 v[102:103], s[18:19]
	s_or_b64 exec, exec, s[40:41]
	v_ashrrev_i32_e32 v101, 31, v100
	v_lshlrev_b64 v[100:101], 13, v[100:101]
	v_lshl_add_u64 v[100:101], v[102:103], 0, v[100:101]
	v_lshl_add_u64 v[100:101], v[174:175], 2, v[100:101]
	global_load_dwordx4 v[104:107], v[100:101], off offset:64
	s_and_saveexec_b64 s[28:29], vcc
	s_xor_b64 s[40:41], exec, s[28:29]
	v_add3_u32 v100, v227, v221, s53
	s_or_saveexec_b64 s[40:41], s[40:41]
	v_mov_b64_e32 v[102:103], s[24:25]
	s_xor_b64 exec, exec, s[40:41]
	v_lshl_add_u32 v100, v222, 8, v221
	v_mov_b64_e32 v[102:103], s[18:19]
	s_or_b64 exec, exec, s[40:41]
	v_ashrrev_i32_e32 v101, 31, v100
	v_lshlrev_b64 v[100:101], 13, v[100:101]
	v_lshl_add_u64 v[100:101], v[102:103], 0, v[100:101]
	v_lshl_add_u64 v[100:101], v[174:175], 2, v[100:101]
	global_load_dwordx4 v[100:103], v[100:101], off offset:64
	s_and_saveexec_b64 s[28:29], s[16:17]
	s_xor_b64 s[40:41], exec, s[28:29]
	v_add3_u32 v132, v212, v202, s53
	s_or_saveexec_b64 s[40:41], s[40:41]
	v_mov_b64_e32 v[134:135], s[24:25]
	s_xor_b64 exec, exec, s[40:41]
	v_lshl_add_u32 v132, v203, 8, v202
	v_mov_b64_e32 v[134:135], s[18:19]
	s_or_b64 exec, exec, s[40:41]
	v_ashrrev_i32_e32 v133, 31, v132
	s_waitcnt vmcnt(0)
; DI void epi_resid(const Acc& acc, const P& p, int brow, int bcol, int layer, int gch, bool from_input) {
;     ...
; #pragma unroll
;             for (int ai = 0; ai < 2; ++ai)
; #pragma unroll
;                 for (int m = 0; m < 4; ++m) {
;                     const int r = brow + ai * 128 + wr * 64 + m * 16 + fr;
;                     const float* sp = (from_input ? inrow(p, r) : xrow(p, r)) + c0;
;                     xv[ai][m] = *(const f32x4*)sp;
;                 }
;     ...
; #pragma unroll
;             for (int ai = 0; ai < 2; ++ai)
; #pragma unroll
;                 for (int m = 0; m < 4; ++m) {
;                     const int r = brow + ai * 128 + wr * 64 + m * 16 + fr;
;                     *(f32x4*)(xrow(p, r) + c0) = xv[ai][m] + g * acc[ai][bj][m][n];
;                 }
	v_pk_fma_f32 v[92:93], v[92:93], v[96:97], v[128:129]
	v_lshlrev_b64 v[128:129], 13, v[132:133]
	v_lshl_add_u64 v[128:129], v[134:135], 0, v[128:129]
	v_pk_fma_f32 v[94:95], v[94:95], v[98:99], v[130:131]
	v_lshl_add_u64 v[128:129], v[174:175], 2, v[128:129]
	global_store_dwordx4 v[128:129], v[92:95], off offset:64
	s_and_saveexec_b64 s[28:29], s[14:15]
	s_xor_b64 s[40:41], exec, s[28:29]
	v_add3_u32 v92, v217, v204, s53
	s_or_saveexec_b64 s[40:41], s[40:41]
	v_mov_b64_e32 v[94:95], s[24:25]
	s_xor_b64 exec, exec, s[40:41]
	v_lshl_add_u32 v92, v205, 8, v204
	v_mov_b64_e32 v[94:95], s[18:19]
	s_or_b64 exec, exec, s[40:41]
	v_ashrrev_i32_e32 v93, 31, v92
	v_lshlrev_b64 v[92:93], 13, v[92:93]
	v_lshl_add_u64 v[92:93], v[94:95], 0, v[92:93]
	v_pk_fma_f32 v[90:91], v[90:91], v[98:99], v[126:127]
	v_pk_fma_f32 v[88:89], v[88:89], v[96:97], v[124:125]
	v_lshl_add_u64 v[92:93], v[174:175], 2, v[92:93]
	global_store_dwordx4 v[92:93], v[88:91], off offset:64
	s_and_saveexec_b64 s[28:29], s[12:13]
	s_xor_b64 s[40:41], exec, s[28:29]
	v_add3_u32 v88, v220, v208, s53
	s_or_saveexec_b64 s[40:41], s[40:41]
	v_mov_b64_e32 v[90:91], s[24:25]
	s_xor_b64 exec, exec, s[40:41]
	v_lshl_add_u32 v88, v209, 8, v208
	v_mov_b64_e32 v[90:91], s[18:19]
	s_or_b64 exec, exec, s[40:41]
	v_ashrrev_i32_e32 v89, 31, v88
	v_lshlrev_b64 v[88:89], 13, v[88:89]
	v_lshl_add_u64 v[88:89], v[90:91], 0, v[88:89]
	v_pk_fma_f32 v[86:87], v[86:87], v[98:99], v[122:123]
	v_pk_fma_f32 v[84:85], v[84:85], v[96:97], v[120:121]
	v_lshl_add_u64 v[88:89], v[174:175], 2, v[88:89]
	global_store_dwordx4 v[88:89], v[84:87], off offset:64
	s_and_saveexec_b64 s[28:29], s[10:11]
	s_xor_b64 s[40:41], exec, s[28:29]
	v_add3_u32 v84, v223, v210, s53
	s_or_saveexec_b64 s[40:41], s[40:41]
	v_mov_b64_e32 v[86:87], s[24:25]
	s_xor_b64 exec, exec, s[40:41]
	v_lshl_add_u32 v84, v211, 8, v210
	v_mov_b64_e32 v[86:87], s[18:19]
	s_or_b64 exec, exec, s[40:41]
	v_ashrrev_i32_e32 v85, 31, v84
	v_lshlrev_b64 v[84:85], 13, v[84:85]
	v_lshl_add_u64 v[84:85], v[86:87], 0, v[84:85]
	v_pk_fma_f32 v[82:83], v[82:83], v[98:99], v[118:119]
	v_pk_fma_f32 v[80:81], v[80:81], v[96:97], v[116:117]
	v_lshl_add_u64 v[84:85], v[174:175], 2, v[84:85]
	global_store_dwordx4 v[84:85], v[80:83], off offset:64
	s_and_saveexec_b64 s[28:29], s[8:9]
	s_xor_b64 s[40:41], exec, s[28:29]
	v_add3_u32 v80, v224, v213, s53
	s_or_saveexec_b64 s[40:41], s[40:41]
	v_mov_b64_e32 v[82:83], s[24:25]
	s_xor_b64 exec, exec, s[40:41]
	v_lshl_add_u32 v80, v214, 8, v213
	v_mov_b64_e32 v[82:83], s[18:19]
	s_or_b64 exec, exec, s[40:41]
	v_ashrrev_i32_e32 v81, 31, v80
	v_lshlrev_b64 v[80:81], 13, v[80:81]
	v_lshl_add_u64 v[80:81], v[82:83], 0, v[80:81]
	v_pk_fma_f32 v[78:79], v[78:79], v[98:99], v[114:115]
	v_pk_fma_f32 v[76:77], v[76:77], v[96:97], v[112:113]
	v_lshl_add_u64 v[80:81], v[174:175], 2, v[80:81]
	global_store_dwordx4 v[80:81], v[76:79], off offset:64
	s_and_saveexec_b64 s[28:29], s[6:7]
	s_xor_b64 s[40:41], exec, s[28:29]
	v_add3_u32 v76, v225, v215, s53
	s_or_saveexec_b64 s[40:41], s[40:41]
	v_mov_b64_e32 v[78:79], s[24:25]
	s_xor_b64 exec, exec, s[40:41]
	v_lshl_add_u32 v76, v216, 8, v215
	v_mov_b64_e32 v[78:79], s[18:19]
	s_or_b64 exec, exec, s[40:41]
	v_ashrrev_i32_e32 v77, 31, v76
	v_lshlrev_b64 v[76:77], 13, v[76:77]
	v_lshl_add_u64 v[76:77], v[78:79], 0, v[76:77]
	v_pk_fma_f32 v[74:75], v[74:75], v[98:99], v[110:111]
	v_pk_fma_f32 v[72:73], v[72:73], v[96:97], v[108:109]
	v_lshl_add_u64 v[76:77], v[174:175], 2, v[76:77]
	global_store_dwordx4 v[76:77], v[72:75], off offset:64
	s_and_saveexec_b64 s[28:29], s[4:5]
	s_xor_b64 s[40:41], exec, s[28:29]
	v_add3_u32 v72, v226, v218, s53
	s_or_saveexec_b64 s[40:41], s[40:41]
	v_mov_b64_e32 v[74:75], s[24:25]
	s_xor_b64 exec, exec, s[40:41]
	v_lshl_add_u32 v72, v219, 8, v218
	v_mov_b64_e32 v[74:75], s[18:19]
	s_or_b64 exec, exec, s[40:41]
	v_ashrrev_i32_e32 v73, 31, v72
	v_lshlrev_b64 v[72:73], 13, v[72:73]
	v_lshl_add_u64 v[72:73], v[74:75], 0, v[72:73]
	v_pk_fma_f32 v[70:71], v[70:71], v[98:99], v[106:107]
	v_pk_fma_f32 v[68:69], v[68:69], v[96:97], v[104:105]
	v_lshl_add_u64 v[72:73], v[174:175], 2, v[72:73]
	global_store_dwordx4 v[72:73], v[68:71], off offset:64
	s_and_saveexec_b64 s[28:29], vcc
	s_xor_b64 s[40:41], exec, s[28:29]
	v_add3_u32 v68, v227, v221, s53
	s_or_saveexec_b64 s[40:41], s[40:41]
	v_mov_b64_e32 v[70:71], s[24:25]
	s_xor_b64 exec, exec, s[40:41]
	v_lshl_add_u32 v68, v222, 8, v221
	v_mov_b64_e32 v[70:71], s[18:19]
	s_or_b64 exec, exec, s[40:41]
	v_ashrrev_i32_e32 v69, 31, v68
	v_lshlrev_b64 v[68:69], 13, v[68:69]
	v_lshl_add_u64 v[68:69], v[70:71], 0, v[68:69]
	v_pk_fma_f32 v[66:67], v[66:67], v[98:99], v[102:103]
	v_pk_fma_f32 v[64:65], v[64:65], v[96:97], v[100:101]
	v_lshl_add_u64 v[68:69], v[174:175], 2, v[68:69]
	global_store_dwordx4 v[68:69], v[64:67], off offset:64
	global_load_dwordx4 v[64:67], v[192:193], off offset:512
	s_and_saveexec_b64 s[28:29], s[16:17]
	s_xor_b64 s[40:41], exec, s[28:29]
	v_add3_u32 v68, v212, v202, s53
	s_or_saveexec_b64 s[40:41], s[40:41]
	v_mov_b64_e32 v[70:71], s[24:25]
	s_xor_b64 exec, exec, s[40:41]
	v_lshl_add_u32 v68, v203, 8, v202
	v_mov_b64_e32 v[70:71], s[18:19]
	s_or_b64 exec, exec, s[40:41]
	v_ashrrev_i32_e32 v69, 31, v68
	v_lshlrev_b64 v[68:69], 13, v[68:69]
	v_lshl_add_u64 v[68:69], v[70:71], 0, v[68:69]
	v_lshl_add_u64 v[68:69], v[174:175], 2, v[68:69]
	global_load_dwordx4 v[96:99], v[68:69], off offset:512
	s_and_saveexec_b64 s[28:29], s[14:15]
	s_xor_b64 s[40:41], exec, s[28:29]
	v_add3_u32 v68, v217, v204, s53
	s_or_saveexec_b64 s[40:41], s[40:41]
	v_mov_b64_e32 v[70:71], s[24:25]
	s_xor_b64 exec, exec, s[40:41]
; DI void epi_resid(const Acc& acc, const P& p, int brow, int bcol, int layer, int gch, bool from_input) {
;     ...
; #pragma unroll
;             for (int ai = 0; ai < 2; ++ai)
; #pragma unroll
;                 for (int m = 0; m < 4; ++m) {
;                     const int r = brow + ai * 128 + wr * 64 + m * 16 + fr;
;                     const float* sp = (from_input ? inrow(p, r) : xrow(p, r)) + c0;
;                     xv[ai][m] = *(const f32x4*)sp;
;                 }
;             __builtin_amdgcn_sched_barrier(0);
; #pragma unroll
;             for (int ai = 0; ai < 2; ++ai)
; #pragma unroll
;                 for (int m = 0; m < 4; ++m) {
;                     const int r = brow + ai * 128 + wr * 64 + m * 16 + fr;
;                     *(f32x4*)(xrow(p, r) + c0) = xv[ai][m] + g * acc[ai][bj][m][n];
;                 }
	v_lshl_add_u32 v68, v205, 8, v204
	v_mov_b64_e32 v[70:71], s[18:19]
	s_or_b64 exec, exec, s[40:41]
	v_ashrrev_i32_e32 v69, 31, v68
	v_lshlrev_b64 v[68:69], 13, v[68:69]
	v_lshl_add_u64 v[68:69], v[70:71], 0, v[68:69]
	v_lshl_add_u64 v[68:69], v[174:175], 2, v[68:69]
	global_load_dwordx4 v[92:95], v[68:69], off offset:512
	s_and_saveexec_b64 s[28:29], s[12:13]
	s_xor_b64 s[40:41], exec, s[28:29]
	v_add3_u32 v68, v220, v208, s53
	s_or_saveexec_b64 s[40:41], s[40:41]
	v_mov_b64_e32 v[70:71], s[24:25]
	s_xor_b64 exec, exec, s[40:41]
	v_lshl_add_u32 v68, v209, 8, v208
	v_mov_b64_e32 v[70:71], s[18:19]
	s_or_b64 exec, exec, s[40:41]
	v_ashrrev_i32_e32 v69, 31, v68
	v_lshlrev_b64 v[68:69], 13, v[68:69]
	v_lshl_add_u64 v[68:69], v[70:71], 0, v[68:69]
	v_lshl_add_u64 v[68:69], v[174:175], 2, v[68:69]
	global_load_dwordx4 v[88:91], v[68:69], off offset:512
	s_and_saveexec_b64 s[28:29], s[10:11]
	s_xor_b64 s[40:41], exec, s[28:29]
	v_add3_u32 v68, v223, v210, s53
	s_or_saveexec_b64 s[40:41], s[40:41]
	v_mov_b64_e32 v[70:71], s[24:25]
	s_xor_b64 exec, exec, s[40:41]
	v_lshl_add_u32 v68, v211, 8, v210
	v_mov_b64_e32 v[70:71], s[18:19]
	s_or_b64 exec, exec, s[40:41]
	v_ashrrev_i32_e32 v69, 31, v68
	v_lshlrev_b64 v[68:69], 13, v[68:69]
	v_lshl_add_u64 v[68:69], v[70:71], 0, v[68:69]
	v_lshl_add_u64 v[68:69], v[174:175], 2, v[68:69]
	global_load_dwordx4 v[84:87], v[68:69], off offset:512
	s_and_saveexec_b64 s[28:29], s[8:9]
	s_xor_b64 s[40:41], exec, s[28:29]
	v_add3_u32 v68, v224, v213, s53
	s_or_saveexec_b64 s[40:41], s[40:41]
	v_mov_b64_e32 v[70:71], s[24:25]
	s_xor_b64 exec, exec, s[40:41]
	v_lshl_add_u32 v68, v214, 8, v213
	v_mov_b64_e32 v[70:71], s[18:19]
	s_or_b64 exec, exec, s[40:41]
	v_ashrrev_i32_e32 v69, 31, v68
	v_lshlrev_b64 v[68:69], 13, v[68:69]
	v_lshl_add_u64 v[68:69], v[70:71], 0, v[68:69]
	v_lshl_add_u64 v[68:69], v[174:175], 2, v[68:69]
	global_load_dwordx4 v[80:83], v[68:69], off offset:512
	s_and_saveexec_b64 s[28:29], s[6:7]
	s_xor_b64 s[40:41], exec, s[28:29]
	v_add3_u32 v68, v225, v215, s53
	s_or_saveexec_b64 s[40:41], s[40:41]
	v_mov_b64_e32 v[70:71], s[24:25]
	s_xor_b64 exec, exec, s[40:41]
	v_lshl_add_u32 v68, v216, 8, v215
	v_mov_b64_e32 v[70:71], s[18:19]
	s_or_b64 exec, exec, s[40:41]
	v_ashrrev_i32_e32 v69, 31, v68
	v_lshlrev_b64 v[68:69], 13, v[68:69]
	v_lshl_add_u64 v[68:69], v[70:71], 0, v[68:69]
	v_lshl_add_u64 v[68:69], v[174:175], 2, v[68:69]
	global_load_dwordx4 v[76:79], v[68:69], off offset:512
	s_and_saveexec_b64 s[28:29], s[4:5]
	s_xor_b64 s[40:41], exec, s[28:29]
	v_add3_u32 v68, v226, v218, s53
	s_or_saveexec_b64 s[40:41], s[40:41]
	v_mov_b64_e32 v[70:71], s[24:25]
	s_xor_b64 exec, exec, s[40:41]
	v_lshl_add_u32 v68, v219, 8, v218
	v_mov_b64_e32 v[70:71], s[18:19]
	s_or_b64 exec, exec, s[40:41]
	v_ashrrev_i32_e32 v69, 31, v68
	v_lshlrev_b64 v[68:69], 13, v[68:69]
	v_lshl_add_u64 v[68:69], v[70:71], 0, v[68:69]
	v_lshl_add_u64 v[68:69], v[174:175], 2, v[68:69]
	global_load_dwordx4 v[72:75], v[68:69], off offset:512
	s_and_saveexec_b64 s[28:29], vcc
	s_xor_b64 s[40:41], exec, s[28:29]
	v_add3_u32 v68, v227, v221, s53
	s_or_saveexec_b64 s[40:41], s[40:41]
	v_mov_b64_e32 v[70:71], s[24:25]
	s_xor_b64 exec, exec, s[40:41]
	v_lshl_add_u32 v68, v222, 8, v221
	v_mov_b64_e32 v[70:71], s[18:19]
	s_or_b64 exec, exec, s[40:41]
	v_ashrrev_i32_e32 v69, 31, v68
	v_lshlrev_b64 v[68:69], 13, v[68:69]
	v_lshl_add_u64 v[68:69], v[70:71], 0, v[68:69]
	v_lshl_add_u64 v[68:69], v[174:175], 2, v[68:69]
	global_load_dwordx4 v[68:71], v[68:69], off offset:512
	s_and_saveexec_b64 s[28:29], s[16:17]
	s_xor_b64 s[40:41], exec, s[28:29]
	v_add3_u32 v100, v212, v202, s53
	s_or_saveexec_b64 s[40:41], s[40:41]
	v_mov_b64_e32 v[102:103], s[24:25]
	s_xor_b64 exec, exec, s[40:41]
	v_lshl_add_u32 v100, v203, 8, v202
	v_mov_b64_e32 v[102:103], s[18:19]
	s_or_b64 exec, exec, s[40:41]
	v_ashrrev_i32_e32 v101, 31, v100
	s_waitcnt vmcnt(0)
	v_pk_fma_f32 v[60:61], v[60:61], v[64:65], v[96:97]
	v_lshlrev_b64 v[96:97], 13, v[100:101]
	v_lshl_add_u64 v[96:97], v[102:103], 0, v[96:97]
	v_pk_fma_f32 v[62:63], v[62:63], v[66:67], v[98:99]
	v_lshl_add_u64 v[96:97], v[174:175], 2, v[96:97]
	global_store_dwordx4 v[96:97], v[60:63], off offset:512
	s_and_saveexec_b64 s[28:29], s[14:15]
	s_xor_b64 s[40:41], exec, s[28:29]
	v_add3_u32 v60, v217, v204, s53
	s_or_saveexec_b64 s[40:41], s[40:41]
	v_mov_b64_e32 v[62:63], s[24:25]
	s_xor_b64 exec, exec, s[40:41]
	v_lshl_add_u32 v60, v205, 8, v204
	v_mov_b64_e32 v[62:63], s[18:19]
	s_or_b64 exec, exec, s[40:41]
	v_ashrrev_i32_e32 v61, 31, v60
	v_lshlrev_b64 v[60:61], 13, v[60:61]
	v_lshl_add_u64 v[60:61], v[62:63], 0, v[60:61]
	v_pk_fma_f32 v[58:59], v[58:59], v[66:67], v[94:95]
	v_pk_fma_f32 v[56:57], v[56:57], v[64:65], v[92:93]
	v_lshl_add_u64 v[60:61], v[174:175], 2, v[60:61]
	global_store_dwordx4 v[60:61], v[56:59], off offset:512
	s_and_saveexec_b64 s[28:29], s[12:13]
	s_xor_b64 s[40:41], exec, s[28:29]
	v_add3_u32 v56, v220, v208, s53
	s_or_saveexec_b64 s[40:41], s[40:41]
	v_mov_b64_e32 v[58:59], s[24:25]
	s_xor_b64 exec, exec, s[40:41]
	v_lshl_add_u32 v56, v209, 8, v208
	v_mov_b64_e32 v[58:59], s[18:19]
	s_or_b64 exec, exec, s[40:41]
	v_ashrrev_i32_e32 v57, 31, v56
	v_lshlrev_b64 v[56:57], 13, v[56:57]
	v_lshl_add_u64 v[56:57], v[58:59], 0, v[56:57]
	v_pk_fma_f32 v[54:55], v[54:55], v[66:67], v[90:91]
	v_pk_fma_f32 v[52:53], v[52:53], v[64:65], v[88:89]
	v_lshl_add_u64 v[56:57], v[174:175], 2, v[56:57]
	global_store_dwordx4 v[56:57], v[52:55], off offset:512
	s_and_saveexec_b64 s[28:29], s[10:11]
	s_xor_b64 s[40:41], exec, s[28:29]
	v_add3_u32 v52, v223, v210, s53
	s_or_saveexec_b64 s[40:41], s[40:41]
; DI void epi_resid(const Acc& acc, const P& p, int brow, int bcol, int layer, int gch, bool from_input) {
;     ...
; #pragma unroll
;             for (int ai = 0; ai < 2; ++ai)
; #pragma unroll
;                 for (int m = 0; m < 4; ++m) {
;                     const int r = brow + ai * 128 + wr * 64 + m * 16 + fr;
;                     const float* sp = (from_input ? inrow(p, r) : xrow(p, r)) + c0;
;                     xv[ai][m] = *(const f32x4*)sp;
;                 }
;     ...
; #pragma unroll
;             for (int ai = 0; ai < 2; ++ai)
; #pragma unroll
;                 for (int m = 0; m < 4; ++m) {
;                     const int r = brow + ai * 128 + wr * 64 + m * 16 + fr;
;                     *(f32x4*)(xrow(p, r) + c0) = xv[ai][m] + g * acc[ai][bj][m][n];
;                 }
	v_mov_b64_e32 v[54:55], s[24:25]
	s_xor_b64 exec, exec, s[40:41]
	v_lshl_add_u32 v52, v211, 8, v210
	v_mov_b64_e32 v[54:55], s[18:19]
	s_or_b64 exec, exec, s[40:41]
	v_ashrrev_i32_e32 v53, 31, v52
	v_lshlrev_b64 v[52:53], 13, v[52:53]
	v_lshl_add_u64 v[52:53], v[54:55], 0, v[52:53]
	v_pk_fma_f32 v[50:51], v[50:51], v[66:67], v[86:87]
	v_pk_fma_f32 v[48:49], v[48:49], v[64:65], v[84:85]
	v_lshl_add_u64 v[52:53], v[174:175], 2, v[52:53]
	global_store_dwordx4 v[52:53], v[48:51], off offset:512
	s_and_saveexec_b64 s[28:29], s[8:9]
	s_xor_b64 s[40:41], exec, s[28:29]
	v_add3_u32 v48, v224, v213, s53
	s_or_saveexec_b64 s[40:41], s[40:41]
	v_mov_b64_e32 v[50:51], s[24:25]
	s_xor_b64 exec, exec, s[40:41]
	v_lshl_add_u32 v48, v214, 8, v213
	v_mov_b64_e32 v[50:51], s[18:19]
	s_or_b64 exec, exec, s[40:41]
	v_ashrrev_i32_e32 v49, 31, v48
	v_lshlrev_b64 v[48:49], 13, v[48:49]
	v_lshl_add_u64 v[48:49], v[50:51], 0, v[48:49]
	v_pk_fma_f32 v[46:47], v[46:47], v[66:67], v[82:83]
	v_pk_fma_f32 v[44:45], v[44:45], v[64:65], v[80:81]
	v_lshl_add_u64 v[48:49], v[174:175], 2, v[48:49]
	global_store_dwordx4 v[48:49], v[44:47], off offset:512
	s_and_saveexec_b64 s[28:29], s[6:7]
	s_xor_b64 s[40:41], exec, s[28:29]
	v_add3_u32 v44, v225, v215, s53
	s_or_saveexec_b64 s[40:41], s[40:41]
	v_mov_b64_e32 v[46:47], s[24:25]
	s_xor_b64 exec, exec, s[40:41]
	v_lshl_add_u32 v44, v216, 8, v215
	v_mov_b64_e32 v[46:47], s[18:19]
	s_or_b64 exec, exec, s[40:41]
	v_ashrrev_i32_e32 v45, 31, v44
	v_lshlrev_b64 v[44:45], 13, v[44:45]
	v_lshl_add_u64 v[44:45], v[46:47], 0, v[44:45]
	v_pk_fma_f32 v[42:43], v[42:43], v[66:67], v[78:79]
	v_pk_fma_f32 v[40:41], v[40:41], v[64:65], v[76:77]
	v_lshl_add_u64 v[44:45], v[174:175], 2, v[44:45]
	global_store_dwordx4 v[44:45], v[40:43], off offset:512
	s_and_saveexec_b64 s[28:29], s[4:5]
	s_xor_b64 s[40:41], exec, s[28:29]
	v_add3_u32 v40, v226, v218, s53
	s_or_saveexec_b64 s[40:41], s[40:41]
	v_mov_b64_e32 v[42:43], s[24:25]
	s_xor_b64 exec, exec, s[40:41]
	v_lshl_add_u32 v40, v219, 8, v218
	v_mov_b64_e32 v[42:43], s[18:19]
	s_or_b64 exec, exec, s[40:41]
	v_ashrrev_i32_e32 v41, 31, v40
	v_lshlrev_b64 v[40:41], 13, v[40:41]
	v_lshl_add_u64 v[40:41], v[42:43], 0, v[40:41]
	v_pk_fma_f32 v[38:39], v[38:39], v[66:67], v[74:75]
	v_pk_fma_f32 v[36:37], v[36:37], v[64:65], v[72:73]
	v_lshl_add_u64 v[40:41], v[174:175], 2, v[40:41]
	global_store_dwordx4 v[40:41], v[36:39], off offset:512
	s_and_saveexec_b64 s[28:29], vcc
	s_xor_b64 s[40:41], exec, s[28:29]
	v_add3_u32 v36, v227, v221, s53
	s_or_saveexec_b64 s[40:41], s[40:41]
	v_mov_b64_e32 v[38:39], s[24:25]
	s_xor_b64 exec, exec, s[40:41]
	v_lshl_add_u32 v36, v222, 8, v221
	v_mov_b64_e32 v[38:39], s[18:19]
	s_or_b64 exec, exec, s[40:41]
	v_ashrrev_i32_e32 v37, 31, v36
	v_lshlrev_b64 v[36:37], 13, v[36:37]
	v_lshl_add_u64 v[36:37], v[38:39], 0, v[36:37]
	v_pk_fma_f32 v[34:35], v[34:35], v[66:67], v[70:71]
	v_pk_fma_f32 v[32:33], v[32:33], v[64:65], v[68:69]
	v_lshl_add_u64 v[36:37], v[174:175], 2, v[36:37]
	global_store_dwordx4 v[36:37], v[32:35], off offset:512
	global_load_dwordx4 v[32:35], v[192:193], off offset:576
	s_and_saveexec_b64 s[28:29], s[16:17]
	s_xor_b64 s[40:41], exec, s[28:29]
	v_add3_u32 v36, v212, v202, s53
	s_or_saveexec_b64 s[40:41], s[40:41]
	v_mov_b64_e32 v[38:39], s[24:25]
	s_xor_b64 exec, exec, s[40:41]
	v_lshl_add_u32 v36, v203, 8, v202
	v_mov_b64_e32 v[38:39], s[18:19]
	s_or_b64 exec, exec, s[40:41]
	v_ashrrev_i32_e32 v37, 31, v36
	v_lshlrev_b64 v[36:37], 13, v[36:37]
	v_lshl_add_u64 v[36:37], v[38:39], 0, v[36:37]
	v_lshl_add_u64 v[36:37], v[174:175], 2, v[36:37]
	global_load_dwordx4 v[64:67], v[36:37], off offset:576
	s_and_saveexec_b64 s[28:29], s[14:15]
	s_xor_b64 s[40:41], exec, s[28:29]
	v_add3_u32 v36, v217, v204, s53
	s_or_saveexec_b64 s[40:41], s[40:41]
	v_mov_b64_e32 v[38:39], s[24:25]
	s_xor_b64 exec, exec, s[40:41]
	v_lshl_add_u32 v36, v205, 8, v204
	v_mov_b64_e32 v[38:39], s[18:19]
	s_or_b64 exec, exec, s[40:41]
	v_ashrrev_i32_e32 v37, 31, v36
	v_lshlrev_b64 v[36:37], 13, v[36:37]
	v_lshl_add_u64 v[36:37], v[38:39], 0, v[36:37]
	v_lshl_add_u64 v[36:37], v[174:175], 2, v[36:37]
	global_load_dwordx4 v[60:63], v[36:37], off offset:576
	s_and_saveexec_b64 s[28:29], s[12:13]
	s_xor_b64 s[40:41], exec, s[28:29]
	v_add3_u32 v36, v220, v208, s53
	s_or_saveexec_b64 s[40:41], s[40:41]
	v_mov_b64_e32 v[38:39], s[24:25]
	s_xor_b64 exec, exec, s[40:41]
	v_lshl_add_u32 v36, v209, 8, v208
	v_mov_b64_e32 v[38:39], s[18:19]
	s_or_b64 exec, exec, s[40:41]
	v_ashrrev_i32_e32 v37, 31, v36
	v_lshlrev_b64 v[36:37], 13, v[36:37]
	v_lshl_add_u64 v[36:37], v[38:39], 0, v[36:37]
	v_lshl_add_u64 v[36:37], v[174:175], 2, v[36:37]
	global_load_dwordx4 v[56:59], v[36:37], off offset:576
	s_and_saveexec_b64 s[28:29], s[10:11]
	s_xor_b64 s[40:41], exec, s[28:29]
	v_add3_u32 v36, v223, v210, s53
	s_or_saveexec_b64 s[40:41], s[40:41]
	v_mov_b64_e32 v[38:39], s[24:25]
	s_xor_b64 exec, exec, s[40:41]
	v_lshl_add_u32 v36, v211, 8, v210
	v_mov_b64_e32 v[38:39], s[18:19]
	s_or_b64 exec, exec, s[40:41]
	v_ashrrev_i32_e32 v37, 31, v36
	v_lshlrev_b64 v[36:37], 13, v[36:37]
	v_lshl_add_u64 v[36:37], v[38:39], 0, v[36:37]
	v_lshl_add_u64 v[36:37], v[174:175], 2, v[36:37]
	global_load_dwordx4 v[52:55], v[36:37], off offset:576
	s_and_saveexec_b64 s[28:29], s[8:9]
	s_xor_b64 s[40:41], exec, s[28:29]
	v_add3_u32 v36, v224, v213, s53
	s_or_saveexec_b64 s[40:41], s[40:41]
	v_mov_b64_e32 v[38:39], s[24:25]
	s_xor_b64 exec, exec, s[40:41]
	v_lshl_add_u32 v36, v214, 8, v213
	v_mov_b64_e32 v[38:39], s[18:19]
	s_or_b64 exec, exec, s[40:41]
	v_ashrrev_i32_e32 v37, 31, v36
	v_lshlrev_b64 v[36:37], 13, v[36:37]
; DI void epi_resid(const Acc& acc, const P& p, int brow, int bcol, int layer, int gch, bool from_input) {
;     ...
; #pragma unroll
;             for (int ai = 0; ai < 2; ++ai)
; #pragma unroll
;                 for (int m = 0; m < 4; ++m) {
;                     const int r = brow + ai * 128 + wr * 64 + m * 16 + fr;
;                     const float* sp = (from_input ? inrow(p, r) : xrow(p, r)) + c0;
;                     xv[ai][m] = *(const f32x4*)sp;
;                 }
;             __builtin_amdgcn_sched_barrier(0);
; #pragma unroll
;             for (int ai = 0; ai < 2; ++ai)
; #pragma unroll
;                 for (int m = 0; m < 4; ++m) {
;                     const int r = brow + ai * 128 + wr * 64 + m * 16 + fr;
;                     *(f32x4*)(xrow(p, r) + c0) = xv[ai][m] + g * acc[ai][bj][m][n];
;                 }
	v_lshl_add_u64 v[36:37], v[38:39], 0, v[36:37]
	v_lshl_add_u64 v[36:37], v[174:175], 2, v[36:37]
	global_load_dwordx4 v[48:51], v[36:37], off offset:576
	s_and_saveexec_b64 s[28:29], s[6:7]
	s_xor_b64 s[40:41], exec, s[28:29]
	v_add3_u32 v36, v225, v215, s53
	s_or_saveexec_b64 s[40:41], s[40:41]
	v_mov_b64_e32 v[38:39], s[24:25]
	s_xor_b64 exec, exec, s[40:41]
	v_lshl_add_u32 v36, v216, 8, v215
	v_mov_b64_e32 v[38:39], s[18:19]
	s_or_b64 exec, exec, s[40:41]
	v_ashrrev_i32_e32 v37, 31, v36
	v_lshlrev_b64 v[36:37], 13, v[36:37]
	v_lshl_add_u64 v[36:37], v[38:39], 0, v[36:37]
	v_lshl_add_u64 v[36:37], v[174:175], 2, v[36:37]
	global_load_dwordx4 v[44:47], v[36:37], off offset:576
	s_and_saveexec_b64 s[28:29], s[4:5]
	s_xor_b64 s[40:41], exec, s[28:29]
	v_add3_u32 v36, v226, v218, s53
	s_or_saveexec_b64 s[40:41], s[40:41]
	v_mov_b64_e32 v[38:39], s[24:25]
	s_xor_b64 exec, exec, s[40:41]
	v_lshl_add_u32 v36, v219, 8, v218
	v_mov_b64_e32 v[38:39], s[18:19]
	s_or_b64 exec, exec, s[40:41]
	v_ashrrev_i32_e32 v37, 31, v36
	v_lshlrev_b64 v[36:37], 13, v[36:37]
	v_lshl_add_u64 v[36:37], v[38:39], 0, v[36:37]
	v_lshl_add_u64 v[36:37], v[174:175], 2, v[36:37]
	global_load_dwordx4 v[40:43], v[36:37], off offset:576
	s_and_saveexec_b64 s[28:29], vcc
	s_xor_b64 s[40:41], exec, s[28:29]
	v_add3_u32 v36, v227, v221, s53
	s_or_saveexec_b64 s[40:41], s[40:41]
	v_mov_b64_e32 v[38:39], s[24:25]
	s_xor_b64 exec, exec, s[40:41]
	v_lshl_add_u32 v36, v222, 8, v221
	v_mov_b64_e32 v[38:39], s[18:19]
	s_or_b64 exec, exec, s[40:41]
	v_ashrrev_i32_e32 v37, 31, v36
	v_lshlrev_b64 v[36:37], 13, v[36:37]
	v_lshl_add_u64 v[36:37], v[38:39], 0, v[36:37]
	v_lshl_add_u64 v[36:37], v[174:175], 2, v[36:37]
	global_load_dwordx4 v[36:39], v[36:37], off offset:576
	s_and_saveexec_b64 s[28:29], s[16:17]
	s_xor_b64 s[16:17], exec, s[28:29]
	s_or_saveexec_b64 s[16:17], s[16:17]
	v_mov_b64_e32 v[68:69], s[24:25]
	s_xor_b64 exec, exec, s[16:17]
	v_mov_b64_e32 v[68:69], s[18:19]
	v_mov_b32_e32 v190, v191
	s_or_b64 exec, exec, s[16:17]
	v_ashrrev_i32_e32 v191, 31, v190
	s_waitcnt vmcnt(0)
	v_pk_fma_f32 v[28:29], v[28:29], v[32:33], v[64:65]
	v_lshlrev_b64 v[64:65], 13, v[190:191]
	v_lshl_add_u64 v[64:65], v[68:69], 0, v[64:65]
	v_pk_fma_f32 v[30:31], v[30:31], v[34:35], v[66:67]
	v_lshl_add_u64 v[64:65], v[174:175], 2, v[64:65]
	global_store_dwordx4 v[64:65], v[28:31], off offset:576
	s_and_saveexec_b64 s[16:17], s[14:15]
	s_xor_b64 s[14:15], exec, s[16:17]
	s_or_saveexec_b64 s[14:15], s[14:15]
	v_mov_b64_e32 v[28:29], s[24:25]
	s_xor_b64 exec, exec, s[14:15]
	v_mov_b64_e32 v[28:29], s[18:19]
	v_mov_b32_e32 v188, v189
	s_or_b64 exec, exec, s[14:15]
	v_ashrrev_i32_e32 v189, 31, v188
	v_lshlrev_b64 v[30:31], 13, v[188:189]
	v_lshl_add_u64 v[28:29], v[28:29], 0, v[30:31]
	v_pk_fma_f32 v[26:27], v[26:27], v[34:35], v[62:63]
	v_pk_fma_f32 v[24:25], v[24:25], v[32:33], v[60:61]
	v_lshl_add_u64 v[28:29], v[174:175], 2, v[28:29]
	global_store_dwordx4 v[28:29], v[24:27], off offset:576
	s_and_saveexec_b64 s[16:17], s[12:13]
	s_xor_b64 s[12:13], exec, s[16:17]
	s_mov_b64 s[14:15], s[24:25]
	s_or_saveexec_b64 s[12:13], s[12:13]
	v_mov_b64_e32 v[24:25], s[14:15]
	s_xor_b64 exec, exec, s[12:13]
	v_mov_b64_e32 v[24:25], s[18:19]
	v_mov_b32_e32 v186, v187
	s_or_b64 exec, exec, s[12:13]
	v_ashrrev_i32_e32 v187, 31, v186
	v_lshlrev_b64 v[26:27], 13, v[186:187]
	v_lshl_add_u64 v[24:25], v[24:25], 0, v[26:27]
	v_pk_fma_f32 v[22:23], v[22:23], v[34:35], v[58:59]
	v_pk_fma_f32 v[20:21], v[20:21], v[32:33], v[56:57]
	v_lshl_add_u64 v[24:25], v[174:175], 2, v[24:25]
	global_store_dwordx4 v[24:25], v[20:23], off offset:576
	s_and_saveexec_b64 s[14:15], s[10:11]
	s_xor_b64 s[10:11], exec, s[14:15]
	s_mov_b64 s[12:13], s[24:25]
	s_or_saveexec_b64 s[10:11], s[10:11]
	v_mov_b64_e32 v[20:21], s[12:13]
	s_xor_b64 exec, exec, s[10:11]
	v_mov_b64_e32 v[20:21], s[18:19]
	v_mov_b32_e32 v184, v185
	s_or_b64 exec, exec, s[10:11]
	v_ashrrev_i32_e32 v185, 31, v184
	v_lshlrev_b64 v[22:23], 13, v[184:185]
	v_lshl_add_u64 v[20:21], v[20:21], 0, v[22:23]
	v_pk_fma_f32 v[18:19], v[18:19], v[34:35], v[54:55]
	v_pk_fma_f32 v[16:17], v[16:17], v[32:33], v[52:53]
	v_lshl_add_u64 v[20:21], v[174:175], 2, v[20:21]
	global_store_dwordx4 v[20:21], v[16:19], off offset:576
	s_and_saveexec_b64 s[12:13], s[8:9]
	s_xor_b64 s[8:9], exec, s[12:13]
	s_mov_b64 s[10:11], s[24:25]
	s_or_saveexec_b64 s[8:9], s[8:9]
	v_mov_b64_e32 v[16:17], s[10:11]
	s_xor_b64 exec, exec, s[8:9]
	v_mov_b64_e32 v[16:17], s[18:19]
	v_mov_b32_e32 v182, v183
	s_or_b64 exec, exec, s[8:9]
	v_ashrrev_i32_e32 v183, 31, v182
	v_lshlrev_b64 v[18:19], 13, v[182:183]
	v_lshl_add_u64 v[16:17], v[16:17], 0, v[18:19]
	v_pk_fma_f32 v[14:15], v[14:15], v[34:35], v[50:51]
	v_pk_fma_f32 v[12:13], v[12:13], v[32:33], v[48:49]
	v_lshl_add_u64 v[16:17], v[174:175], 2, v[16:17]
	global_store_dwordx4 v[16:17], v[12:15], off offset:576
	s_and_saveexec_b64 s[10:11], s[6:7]
	s_xor_b64 s[6:7], exec, s[10:11]
	s_mov_b64 s[8:9], s[24:25]
	s_or_saveexec_b64 s[6:7], s[6:7]
	v_mov_b64_e32 v[12:13], s[8:9]
	s_xor_b64 exec, exec, s[6:7]
	v_mov_b64_e32 v[12:13], s[18:19]
	v_mov_b32_e32 v180, v181
	s_or_b64 exec, exec, s[6:7]
	v_ashrrev_i32_e32 v181, 31, v180
	v_lshlrev_b64 v[14:15], 13, v[180:181]
	v_lshl_add_u64 v[12:13], v[12:13], 0, v[14:15]
	v_pk_fma_f32 v[10:11], v[10:11], v[34:35], v[46:47]
	v_pk_fma_f32 v[8:9], v[8:9], v[32:33], v[44:45]
	v_lshl_add_u64 v[12:13], v[174:175], 2, v[12:13]
	global_store_dwordx4 v[12:13], v[8:11], off offset:576
	s_and_saveexec_b64 s[8:9], s[4:5]
	s_xor_b64 s[4:5], exec, s[8:9]
	s_mov_b64 s[6:7], s[24:25]
	s_or_saveexec_b64 s[4:5], s[4:5]
	v_mov_b64_e32 v[8:9], s[6:7]
	s_xor_b64 exec, exec, s[4:5]
	v_mov_b64_e32 v[8:9], s[18:19]
	v_mov_b32_e32 v178, v179
	s_or_b64 exec, exec, s[4:5]
	v_ashrrev_i32_e32 v179, 31, v178
	v_lshlrev_b64 v[10:11], 13, v[178:179]
	v_lshl_add_u64 v[8:9], v[8:9], 0, v[10:11]
	v_pk_fma_f32 v[6:7], v[6:7], v[34:35], v[42:43]
	v_pk_fma_f32 v[4:5], v[4:5], v[32:33], v[40:41]
	v_lshl_add_u64 v[8:9], v[174:175], 2, v[8:9]
	global_store_dwordx4 v[8:9], v[4:7], off offset:576
	s_and_saveexec_b64 s[6:7], vcc
	s_xor_b64 s[6:7], exec, s[6:7]
	s_mov_b64 s[4:5], s[24:25]
	s_or_saveexec_b64 s[6:7], s[6:7]
	v_mov_b64_e32 v[4:5], s[4:5]
	s_xor_b64 exec, exec, s[6:7]
	s_cbranch_execz .LBB0_3109
	v_mov_b64_e32 v[4:5], s[18:19]
	v_mov_b32_e32 v176, v177
	s_branch .LBB0_3109
